# Hyena FFT as radix-16/16/32 register passes (3 LDS round trips), spectrum product fused, zero-padded half skipped on input, unused half skipped on output
# speedup vs baseline: 1.1048x; 1.0276x over previous
; DI f32x2 cmul(f32x2 a, f32x2 b) { return mkf2(a.x * b.x - a.y * b.y, a.x * b.y + a.y * b.x); }
; DI void fft8192(f32x2* buf, const f32x2* __restrict__ tw) {
;     ...
;   for (int ls = 0; ls < 12; ls += 2) {
;     const int s = 1 << ls;
;     f32x2 a[8], b[8], c[8], d[8];
;     __syncthreads();
; #pragma unroll
;     for (int e = 0; e < 8; ++e) {
;       const int i = tid + 256 * e;
;       const int pi = SW(i);
;       a[e] = buf[pi]; b[e] = buf[pi + 2048]; c[e] = buf[pi + 4096]; d[e] = buf[pi + 6144];
;     }
;     __syncthreads();
; #pragma unroll
;     for (int e = 0; e < 8; ++e) {
;       const int i = tid + 256 * e;
;       const int q = i & (s - 1);
;       const int ps = i - q;
;       const float rev = (float)ps * (1.f / 8192.f);
;       const f32x2 w1 = mkf2(__builtin_amdgcn_cosf(rev), -__builtin_amdgcn_sinf(rev));
;       const f32x2 w2 = cmul(w1, w1), w3 = cmul(w1, w2);
;       const f32x2 apc = mkf2(a[e].x + c[e].x, a[e].y + c[e].y), amc = mkf2(a[e].x - c[e].x, a[e].y - c[e].y);
;       const f32x2 bpd = mkf2(b[e].x + d[e].x, b[e].y + d[e].y), bmd = mkf2(b[e].x - d[e].x, b[e].y - d[e].y);
;       const int o = 4 * i - 3 * q;
;       buf[SW(o)] = mkf2(apc.x + bpd.x, apc.y + bpd.y);
;       buf[SW(o + s)] = cmul(w1, mkf2(amc.x + bmd.y, amc.y - bmd.x));
;       buf[SW(o + 2 * s)] = cmul(w2, mkf2(apc.x - bpd.x, apc.y - bpd.y));
;       buf[SW(o + 3 * s)] = cmul(w3, mkf2(amc.x - bmd.y, amc.y + bmd.x));
;     }
.LBB0_933:
	v_bfe_i32 v166, v0, 5, 1
	v_bfe_i32 v168, v0, 6, 1
	v_and_b32_e32 v166, 5, v166
	v_and_b32_e32 v168, 26, v168
	v_xor_b32_e32 v166, v166, v168
	v_xor_b32_e32 v166, v166, v0
	v_lshlrev_b32_e32 v154, 3, v166
	s_waitcnt lgkmcnt(0)
	s_barrier
	ds_read2st64_b64 v[2:5], v154 offset0:0 offset1:32
	ds_read2st64_b64 v[6:9], v154 offset0:64 offset1:96
	ds_read2st64_b64 v[10:13], v154 offset0:4 offset1:36
	ds_read2st64_b64 v[14:17], v154 offset0:68 offset1:100
	ds_read2st64_b64 v[18:21], v154 offset0:8 offset1:40
	ds_read2st64_b64 v[22:25], v154 offset0:72 offset1:104
	ds_read2st64_b64 v[26:29], v154 offset0:12 offset1:44
	ds_read2st64_b64 v[30:33], v154 offset0:76 offset1:108
	ds_read2st64_b64 v[34:37], v154 offset0:16 offset1:48
	ds_read2st64_b64 v[38:41], v154 offset0:80 offset1:112
	ds_read2st64_b64 v[42:45], v154 offset0:20 offset1:52
	ds_read2st64_b64 v[46:49], v154 offset0:84 offset1:116
	ds_read2st64_b64 v[50:53], v154 offset0:24 offset1:56
	ds_read2st64_b64 v[54:57], v154 offset0:88 offset1:120
	ds_read2st64_b64 v[58:61], v154 offset0:28 offset1:60
	ds_read2st64_b64 v[62:65], v154 offset0:92 offset1:124
	v_cvt_f32_u32_e32 v201, v0
	v_lshlrev_b32_e32 v164, 4, v0
	v_bfe_i32 v166, v164, 5, 1
	v_bfe_i32 v168, v164, 6, 1
	v_and_b32_e32 v166, 5, v166
	v_and_b32_e32 v168, 26, v168
	v_xor_b32_e32 v166, v166, v168
	v_xor_b32_e32 v166, v166, v164
	v_lshlrev_b32_e32 v164, 3, v166
	v_mul_f32_e32 v201, 0x39000000, v201
	v_cos_f32_e32 v210, v201
	v_sin_f32_e64 v211, -v201
	s_waitcnt lgkmcnt(14)
	v_pk_add_f32 v[202:203], v[2:3], v[6:7]
	v_pk_add_f32 v[2:3], v[2:3], v[6:7] neg_lo:[0,1] neg_hi:[0,1]
	v_pk_add_f32 v[204:205], v[4:5], v[8:9]
	v_pk_add_f32 v[4:5], v[4:5], v[8:9] neg_lo:[0,1] neg_hi:[0,1]
	v_pk_add_f32 v[6:7], v[202:203], v[204:205]
	v_pk_add_f32 v[8:9], v[202:203], v[204:205] neg_lo:[0,1] neg_hi:[0,1]
	v_pk_add_f32 v[202:203], v[2:3], v[4:5] op_sel:[0,1] op_sel_hi:[1,0] neg_hi:[0,1]
	v_pk_add_f32 v[204:205], v[2:3], v[4:5] op_sel:[0,1] op_sel_hi:[1,0] neg_lo:[0,1]
	v_pk_mul_f32 v[206:207], v[210:211], v[210:211] op_sel:[1,1] op_sel_hi:[1,0]
	v_pk_fma_f32 v[212:213], v[210:211], v[210:211], v[206:207] op_sel_hi:[0,1,1] neg_lo:[0,0,1]
	v_pk_mul_f32 v[206:207], v[210:211], v[212:213] op_sel:[1,1] op_sel_hi:[1,0]
	v_pk_fma_f32 v[220:221], v[210:211], v[212:213], v[206:207] op_sel_hi:[0,1,1] neg_lo:[0,0,1]
	v_pk_mul_f32 v[2:3], v[210:211], v[202:203] op_sel:[1,1] op_sel_hi:[1,0]
	v_pk_fma_f32 v[2:3], v[210:211], v[202:203], v[2:3] op_sel_hi:[0,1,1] neg_lo:[0,0,1]
	v_pk_mul_f32 v[4:5], v[212:213], v[8:9] op_sel:[1,1] op_sel_hi:[1,0]
	v_pk_fma_f32 v[4:5], v[212:213], v[8:9], v[4:5] op_sel_hi:[0,1,1] neg_lo:[0,0,1]
	v_pk_mul_f32 v[8:9], v[220:221], v[204:205] op_sel:[1,1] op_sel_hi:[1,0]
	v_pk_fma_f32 v[8:9], v[220:221], v[204:205], v[8:9] op_sel_hi:[0,1,1] neg_lo:[0,0,1]
	v_add_f32_e32 v214, 0x3d000000, v201
	v_cos_f32_e32 v210, v214
	v_sin_f32_e64 v211, -v214
	s_waitcnt lgkmcnt(12)
	v_pk_add_f32 v[202:203], v[10:11], v[14:15]
	v_pk_add_f32 v[10:11], v[10:11], v[14:15] neg_lo:[0,1] neg_hi:[0,1]
	v_pk_add_f32 v[204:205], v[12:13], v[16:17]
	v_pk_add_f32 v[12:13], v[12:13], v[16:17] neg_lo:[0,1] neg_hi:[0,1]
	v_pk_add_f32 v[14:15], v[202:203], v[204:205]
	v_pk_add_f32 v[16:17], v[202:203], v[204:205] neg_lo:[0,1] neg_hi:[0,1]
	v_pk_add_f32 v[202:203], v[10:11], v[12:13] op_sel:[0,1] op_sel_hi:[1,0] neg_hi:[0,1]
	v_pk_add_f32 v[204:205], v[10:11], v[12:13] op_sel:[0,1] op_sel_hi:[1,0] neg_lo:[0,1]
	v_pk_mul_f32 v[206:207], v[210:211], v[210:211] op_sel:[1,1] op_sel_hi:[1,0]
	v_pk_fma_f32 v[212:213], v[210:211], v[210:211], v[206:207] op_sel_hi:[0,1,1] neg_lo:[0,0,1]
	v_pk_mul_f32 v[206:207], v[210:211], v[212:213] op_sel:[1,1] op_sel_hi:[1,0]
	v_pk_fma_f32 v[220:221], v[210:211], v[212:213], v[206:207] op_sel_hi:[0,1,1] neg_lo:[0,0,1]
	v_pk_mul_f32 v[10:11], v[210:211], v[202:203] op_sel:[1,1] op_sel_hi:[1,0]
	v_pk_fma_f32 v[10:11], v[210:211], v[202:203], v[10:11] op_sel_hi:[0,1,1] neg_lo:[0,0,1]
	v_pk_mul_f32 v[12:13], v[212:213], v[16:17] op_sel:[1,1] op_sel_hi:[1,0]
	v_pk_fma_f32 v[12:13], v[212:213], v[16:17], v[12:13] op_sel_hi:[0,1,1] neg_lo:[0,0,1]
	v_pk_mul_f32 v[16:17], v[220:221], v[204:205] op_sel:[1,1] op_sel_hi:[1,0]
	v_pk_fma_f32 v[16:17], v[220:221], v[204:205], v[16:17] op_sel_hi:[0,1,1] neg_lo:[0,0,1]
	v_add_f32_e32 v214, 0x3d800000, v201
	v_cos_f32_e32 v210, v214
	v_sin_f32_e64 v211, -v214
	s_waitcnt lgkmcnt(10)
	v_pk_add_f32 v[202:203], v[18:19], v[22:23]
	v_pk_add_f32 v[18:19], v[18:19], v[22:23] neg_lo:[0,1] neg_hi:[0,1]
	v_pk_add_f32 v[204:205], v[20:21], v[24:25]
	v_pk_add_f32 v[20:21], v[20:21], v[24:25] neg_lo:[0,1] neg_hi:[0,1]
	v_pk_add_f32 v[22:23], v[202:203], v[204:205]
	v_pk_add_f32 v[24:25], v[202:203], v[204:205] neg_lo:[0,1] neg_hi:[0,1]
	v_pk_add_f32 v[202:203], v[18:19], v[20:21] op_sel:[0,1] op_sel_hi:[1,0] neg_hi:[0,1]
	v_pk_add_f32 v[204:205], v[18:19], v[20:21] op_sel:[0,1] op_sel_hi:[1,0] neg_lo:[0,1]
	v_pk_mul_f32 v[206:207], v[210:211], v[210:211] op_sel:[1,1] op_sel_hi:[1,0]
	v_pk_fma_f32 v[212:213], v[210:211], v[210:211], v[206:207] op_sel_hi:[0,1,1] neg_lo:[0,0,1]
	v_pk_mul_f32 v[206:207], v[210:211], v[212:213] op_sel:[1,1] op_sel_hi:[1,0]
	v_pk_fma_f32 v[220:221], v[210:211], v[212:213], v[206:207] op_sel_hi:[0,1,1] neg_lo:[0,0,1]
	v_pk_mul_f32 v[18:19], v[210:211], v[202:203] op_sel:[1,1] op_sel_hi:[1,0]
	v_pk_fma_f32 v[18:19], v[210:211], v[202:203], v[18:19] op_sel_hi:[0,1,1] neg_lo:[0,0,1]
	v_pk_mul_f32 v[20:21], v[212:213], v[24:25] op_sel:[1,1] op_sel_hi:[1,0]
	v_pk_fma_f32 v[20:21], v[212:213], v[24:25], v[20:21] op_sel_hi:[0,1,1] neg_lo:[0,0,1]
	v_pk_mul_f32 v[24:25], v[220:221], v[204:205] op_sel:[1,1] op_sel_hi:[1,0]
	v_pk_fma_f32 v[24:25], v[220:221], v[204:205], v[24:25] op_sel_hi:[0,1,1] neg_lo:[0,0,1]
	v_add_f32_e32 v214, 0x3dc00000, v201
	v_cos_f32_e32 v210, v214
	v_sin_f32_e64 v211, -v214
	s_waitcnt lgkmcnt(8)
; DI f32x2 cmul(f32x2 a, f32x2 b) { return mkf2(a.x * b.x - a.y * b.y, a.x * b.y + a.y * b.x); }
; DI void fft8192(f32x2* buf, const f32x2* __restrict__ tw) {
;     ...
; #pragma unroll
;     for (int e = 0; e < 8; ++e) {
;       const int i = tid + 256 * e;
;       const int q = i & (s - 1);
;       const int ps = i - q;
;       const float rev = (float)ps * (1.f / 8192.f);
;       const f32x2 w1 = mkf2(__builtin_amdgcn_cosf(rev), -__builtin_amdgcn_sinf(rev));
;       const f32x2 w2 = cmul(w1, w1), w3 = cmul(w1, w2);
;       const f32x2 apc = mkf2(a[e].x + c[e].x, a[e].y + c[e].y), amc = mkf2(a[e].x - c[e].x, a[e].y - c[e].y);
;       const f32x2 bpd = mkf2(b[e].x + d[e].x, b[e].y + d[e].y), bmd = mkf2(b[e].x - d[e].x, b[e].y - d[e].y);
;       const int o = 4 * i - 3 * q;
;       buf[SW(o)] = mkf2(apc.x + bpd.x, apc.y + bpd.y);
;       buf[SW(o + s)] = cmul(w1, mkf2(amc.x + bmd.y, amc.y - bmd.x));
;       buf[SW(o + 2 * s)] = cmul(w2, mkf2(apc.x - bpd.x, apc.y - bpd.y));
;       buf[SW(o + 3 * s)] = cmul(w3, mkf2(amc.x - bmd.y, amc.y + bmd.x));
;     }
	v_pk_add_f32 v[202:203], v[26:27], v[30:31]
	v_pk_add_f32 v[26:27], v[26:27], v[30:31] neg_lo:[0,1] neg_hi:[0,1]
	v_pk_add_f32 v[204:205], v[28:29], v[32:33]
	v_pk_add_f32 v[28:29], v[28:29], v[32:33] neg_lo:[0,1] neg_hi:[0,1]
	v_pk_add_f32 v[30:31], v[202:203], v[204:205]
	v_pk_add_f32 v[32:33], v[202:203], v[204:205] neg_lo:[0,1] neg_hi:[0,1]
	v_pk_add_f32 v[202:203], v[26:27], v[28:29] op_sel:[0,1] op_sel_hi:[1,0] neg_hi:[0,1]
	v_pk_add_f32 v[204:205], v[26:27], v[28:29] op_sel:[0,1] op_sel_hi:[1,0] neg_lo:[0,1]
	v_pk_mul_f32 v[206:207], v[210:211], v[210:211] op_sel:[1,1] op_sel_hi:[1,0]
	v_pk_fma_f32 v[212:213], v[210:211], v[210:211], v[206:207] op_sel_hi:[0,1,1] neg_lo:[0,0,1]
	v_pk_mul_f32 v[206:207], v[210:211], v[212:213] op_sel:[1,1] op_sel_hi:[1,0]
	v_pk_fma_f32 v[220:221], v[210:211], v[212:213], v[206:207] op_sel_hi:[0,1,1] neg_lo:[0,0,1]
	v_pk_mul_f32 v[26:27], v[210:211], v[202:203] op_sel:[1,1] op_sel_hi:[1,0]
	v_pk_fma_f32 v[26:27], v[210:211], v[202:203], v[26:27] op_sel_hi:[0,1,1] neg_lo:[0,0,1]
	v_pk_mul_f32 v[28:29], v[212:213], v[32:33] op_sel:[1,1] op_sel_hi:[1,0]
	v_pk_fma_f32 v[28:29], v[212:213], v[32:33], v[28:29] op_sel_hi:[0,1,1] neg_lo:[0,0,1]
	v_pk_mul_f32 v[32:33], v[220:221], v[204:205] op_sel:[1,1] op_sel_hi:[1,0]
	v_pk_fma_f32 v[32:33], v[220:221], v[204:205], v[32:33] op_sel_hi:[0,1,1] neg_lo:[0,0,1]
	v_add_f32_e32 v214, 0x3e000000, v201
	v_cos_f32_e32 v210, v214
	v_sin_f32_e64 v211, -v214
	s_waitcnt lgkmcnt(6)
	v_pk_add_f32 v[202:203], v[34:35], v[38:39]
	v_pk_add_f32 v[34:35], v[34:35], v[38:39] neg_lo:[0,1] neg_hi:[0,1]
	v_pk_add_f32 v[204:205], v[36:37], v[40:41]
	v_pk_add_f32 v[36:37], v[36:37], v[40:41] neg_lo:[0,1] neg_hi:[0,1]
	v_pk_add_f32 v[38:39], v[202:203], v[204:205]
	v_pk_add_f32 v[40:41], v[202:203], v[204:205] neg_lo:[0,1] neg_hi:[0,1]
	v_pk_add_f32 v[202:203], v[34:35], v[36:37] op_sel:[0,1] op_sel_hi:[1,0] neg_hi:[0,1]
	v_pk_add_f32 v[204:205], v[34:35], v[36:37] op_sel:[0,1] op_sel_hi:[1,0] neg_lo:[0,1]
	v_pk_mul_f32 v[206:207], v[210:211], v[210:211] op_sel:[1,1] op_sel_hi:[1,0]
	v_pk_fma_f32 v[212:213], v[210:211], v[210:211], v[206:207] op_sel_hi:[0,1,1] neg_lo:[0,0,1]
	v_pk_mul_f32 v[206:207], v[210:211], v[212:213] op_sel:[1,1] op_sel_hi:[1,0]
	v_pk_fma_f32 v[220:221], v[210:211], v[212:213], v[206:207] op_sel_hi:[0,1,1] neg_lo:[0,0,1]
	v_pk_mul_f32 v[34:35], v[210:211], v[202:203] op_sel:[1,1] op_sel_hi:[1,0]
	v_pk_fma_f32 v[34:35], v[210:211], v[202:203], v[34:35] op_sel_hi:[0,1,1] neg_lo:[0,0,1]
	v_pk_mul_f32 v[36:37], v[212:213], v[40:41] op_sel:[1,1] op_sel_hi:[1,0]
	v_pk_fma_f32 v[36:37], v[212:213], v[40:41], v[36:37] op_sel_hi:[0,1,1] neg_lo:[0,0,1]
	v_pk_mul_f32 v[40:41], v[220:221], v[204:205] op_sel:[1,1] op_sel_hi:[1,0]
	v_pk_fma_f32 v[40:41], v[220:221], v[204:205], v[40:41] op_sel_hi:[0,1,1] neg_lo:[0,0,1]
	v_add_f32_e32 v214, 0x3e200000, v201
	v_cos_f32_e32 v210, v214
	v_sin_f32_e64 v211, -v214
	s_waitcnt lgkmcnt(4)
	v_pk_add_f32 v[202:203], v[42:43], v[46:47]
	v_pk_add_f32 v[42:43], v[42:43], v[46:47] neg_lo:[0,1] neg_hi:[0,1]
	v_pk_add_f32 v[204:205], v[44:45], v[48:49]
	v_pk_add_f32 v[44:45], v[44:45], v[48:49] neg_lo:[0,1] neg_hi:[0,1]
	v_pk_add_f32 v[46:47], v[202:203], v[204:205]
	v_pk_add_f32 v[48:49], v[202:203], v[204:205] neg_lo:[0,1] neg_hi:[0,1]
	v_pk_add_f32 v[202:203], v[42:43], v[44:45] op_sel:[0,1] op_sel_hi:[1,0] neg_hi:[0,1]
	v_pk_add_f32 v[204:205], v[42:43], v[44:45] op_sel:[0,1] op_sel_hi:[1,0] neg_lo:[0,1]
	v_pk_mul_f32 v[206:207], v[210:211], v[210:211] op_sel:[1,1] op_sel_hi:[1,0]
	v_pk_fma_f32 v[212:213], v[210:211], v[210:211], v[206:207] op_sel_hi:[0,1,1] neg_lo:[0,0,1]
	v_pk_mul_f32 v[206:207], v[210:211], v[212:213] op_sel:[1,1] op_sel_hi:[1,0]
	v_pk_fma_f32 v[220:221], v[210:211], v[212:213], v[206:207] op_sel_hi:[0,1,1] neg_lo:[0,0,1]
	v_pk_mul_f32 v[42:43], v[210:211], v[202:203] op_sel:[1,1] op_sel_hi:[1,0]
	v_pk_fma_f32 v[42:43], v[210:211], v[202:203], v[42:43] op_sel_hi:[0,1,1] neg_lo:[0,0,1]
	v_pk_mul_f32 v[44:45], v[212:213], v[48:49] op_sel:[1,1] op_sel_hi:[1,0]
	v_pk_fma_f32 v[44:45], v[212:213], v[48:49], v[44:45] op_sel_hi:[0,1,1] neg_lo:[0,0,1]
	v_pk_mul_f32 v[48:49], v[220:221], v[204:205] op_sel:[1,1] op_sel_hi:[1,0]
	v_pk_fma_f32 v[48:49], v[220:221], v[204:205], v[48:49] op_sel_hi:[0,1,1] neg_lo:[0,0,1]
	v_add_f32_e32 v214, 0x3e400000, v201
	v_cos_f32_e32 v210, v214
	v_sin_f32_e64 v211, -v214
	s_waitcnt lgkmcnt(2)
	v_pk_add_f32 v[202:203], v[50:51], v[54:55]
	v_pk_add_f32 v[50:51], v[50:51], v[54:55] neg_lo:[0,1] neg_hi:[0,1]
	v_pk_add_f32 v[204:205], v[52:53], v[56:57]
	v_pk_add_f32 v[52:53], v[52:53], v[56:57] neg_lo:[0,1] neg_hi:[0,1]
	v_pk_add_f32 v[54:55], v[202:203], v[204:205]
	v_pk_add_f32 v[56:57], v[202:203], v[204:205] neg_lo:[0,1] neg_hi:[0,1]
	v_pk_add_f32 v[202:203], v[50:51], v[52:53] op_sel:[0,1] op_sel_hi:[1,0] neg_hi:[0,1]
	v_pk_add_f32 v[204:205], v[50:51], v[52:53] op_sel:[0,1] op_sel_hi:[1,0] neg_lo:[0,1]
	v_pk_mul_f32 v[206:207], v[210:211], v[210:211] op_sel:[1,1] op_sel_hi:[1,0]
	v_pk_fma_f32 v[212:213], v[210:211], v[210:211], v[206:207] op_sel_hi:[0,1,1] neg_lo:[0,0,1]
	v_pk_mul_f32 v[206:207], v[210:211], v[212:213] op_sel:[1,1] op_sel_hi:[1,0]
	v_pk_fma_f32 v[220:221], v[210:211], v[212:213], v[206:207] op_sel_hi:[0,1,1] neg_lo:[0,0,1]
	v_pk_mul_f32 v[50:51], v[210:211], v[202:203] op_sel:[1,1] op_sel_hi:[1,0]
	v_pk_fma_f32 v[50:51], v[210:211], v[202:203], v[50:51] op_sel_hi:[0,1,1] neg_lo:[0,0,1]
	v_pk_mul_f32 v[52:53], v[212:213], v[56:57] op_sel:[1,1] op_sel_hi:[1,0]
	v_pk_fma_f32 v[52:53], v[212:213], v[56:57], v[52:53] op_sel_hi:[0,1,1] neg_lo:[0,0,1]
	v_pk_mul_f32 v[56:57], v[220:221], v[204:205] op_sel:[1,1] op_sel_hi:[1,0]
	v_pk_fma_f32 v[56:57], v[220:221], v[204:205], v[56:57] op_sel_hi:[0,1,1] neg_lo:[0,0,1]
	v_add_f32_e32 v214, 0x3e600000, v201
	v_cos_f32_e32 v210, v214
	v_sin_f32_e64 v211, -v214
	s_waitcnt lgkmcnt(0)
; DI f32x2 cmul(f32x2 a, f32x2 b) { return mkf2(a.x * b.x - a.y * b.y, a.x * b.y + a.y * b.x); }
; DI void fft8192(f32x2* buf, const f32x2* __restrict__ tw) {
;     ...
; #pragma unroll
;     for (int e = 0; e < 8; ++e) {
;       const int i = tid + 256 * e;
;       const int q = i & (s - 1);
;       const int ps = i - q;
;       const float rev = (float)ps * (1.f / 8192.f);
;       const f32x2 w1 = mkf2(__builtin_amdgcn_cosf(rev), -__builtin_amdgcn_sinf(rev));
;       const f32x2 w2 = cmul(w1, w1), w3 = cmul(w1, w2);
;       const f32x2 apc = mkf2(a[e].x + c[e].x, a[e].y + c[e].y), amc = mkf2(a[e].x - c[e].x, a[e].y - c[e].y);
;       const f32x2 bpd = mkf2(b[e].x + d[e].x, b[e].y + d[e].y), bmd = mkf2(b[e].x - d[e].x, b[e].y - d[e].y);
;       const int o = 4 * i - 3 * q;
;       buf[SW(o)] = mkf2(apc.x + bpd.x, apc.y + bpd.y);
;       buf[SW(o + s)] = cmul(w1, mkf2(amc.x + bmd.y, amc.y - bmd.x));
;       buf[SW(o + 2 * s)] = cmul(w2, mkf2(apc.x - bpd.x, apc.y - bpd.y));
;       buf[SW(o + 3 * s)] = cmul(w3, mkf2(amc.x - bmd.y, amc.y + bmd.x));
;     }
	v_pk_add_f32 v[202:203], v[58:59], v[62:63]
	v_pk_add_f32 v[58:59], v[58:59], v[62:63] neg_lo:[0,1] neg_hi:[0,1]
	v_pk_add_f32 v[204:205], v[60:61], v[64:65]
	v_pk_add_f32 v[60:61], v[60:61], v[64:65] neg_lo:[0,1] neg_hi:[0,1]
	v_pk_add_f32 v[62:63], v[202:203], v[204:205]
	v_pk_add_f32 v[64:65], v[202:203], v[204:205] neg_lo:[0,1] neg_hi:[0,1]
	v_pk_add_f32 v[202:203], v[58:59], v[60:61] op_sel:[0,1] op_sel_hi:[1,0] neg_hi:[0,1]
	v_pk_add_f32 v[204:205], v[58:59], v[60:61] op_sel:[0,1] op_sel_hi:[1,0] neg_lo:[0,1]
	v_pk_mul_f32 v[206:207], v[210:211], v[210:211] op_sel:[1,1] op_sel_hi:[1,0]
	v_pk_fma_f32 v[212:213], v[210:211], v[210:211], v[206:207] op_sel_hi:[0,1,1] neg_lo:[0,0,1]
	v_pk_mul_f32 v[206:207], v[210:211], v[212:213] op_sel:[1,1] op_sel_hi:[1,0]
	v_pk_fma_f32 v[220:221], v[210:211], v[212:213], v[206:207] op_sel_hi:[0,1,1] neg_lo:[0,0,1]
	v_pk_mul_f32 v[58:59], v[210:211], v[202:203] op_sel:[1,1] op_sel_hi:[1,0]
	v_pk_fma_f32 v[58:59], v[210:211], v[202:203], v[58:59] op_sel_hi:[0,1,1] neg_lo:[0,0,1]
	v_pk_mul_f32 v[60:61], v[212:213], v[64:65] op_sel:[1,1] op_sel_hi:[1,0]
	v_pk_fma_f32 v[60:61], v[212:213], v[64:65], v[60:61] op_sel_hi:[0,1,1] neg_lo:[0,0,1]
	v_pk_mul_f32 v[64:65], v[220:221], v[204:205] op_sel:[1,1] op_sel_hi:[1,0]
	v_pk_fma_f32 v[64:65], v[220:221], v[204:205], v[64:65] op_sel_hi:[0,1,1] neg_lo:[0,0,1]
	s_barrier
	v_mul_f32_e32 v214, 4.0, v201
	v_cos_f32_e32 v224, v214
	v_sin_f32_e64 v225, -v214
	s_nop 0
	v_pk_mul_f32 v[206:207], v[224:225], v[224:225] op_sel:[1,1] op_sel_hi:[1,0]
	v_pk_fma_f32 v[226:227], v[224:225], v[224:225], v[206:207] op_sel_hi:[0,1,1] neg_lo:[0,0,1]
	v_pk_mul_f32 v[206:207], v[224:225], v[226:227] op_sel:[1,1] op_sel_hi:[1,0]
	v_pk_fma_f32 v[230:231], v[224:225], v[226:227], v[206:207] op_sel_hi:[0,1,1] neg_lo:[0,0,1]
	v_pk_add_f32 v[202:203], v[6:7], v[38:39]
	v_pk_add_f32 v[6:7], v[6:7], v[38:39] neg_lo:[0,1] neg_hi:[0,1]
	v_pk_add_f32 v[204:205], v[22:23], v[54:55]
	v_pk_add_f32 v[22:23], v[22:23], v[54:55] neg_lo:[0,1] neg_hi:[0,1]
	v_pk_add_f32 v[38:39], v[202:203], v[204:205]
	v_pk_add_f32 v[54:55], v[202:203], v[204:205] neg_lo:[0,1] neg_hi:[0,1]
	v_pk_add_f32 v[202:203], v[6:7], v[22:23] op_sel:[0,1] op_sel_hi:[1,0] neg_hi:[0,1]
	v_pk_add_f32 v[204:205], v[6:7], v[22:23] op_sel:[0,1] op_sel_hi:[1,0] neg_lo:[0,1]
	v_pk_mul_f32 v[6:7], v[224:225], v[202:203] op_sel:[1,1] op_sel_hi:[1,0]
	v_pk_fma_f32 v[6:7], v[224:225], v[202:203], v[6:7] op_sel_hi:[0,1,1] neg_lo:[0,0,1]
	v_pk_mul_f32 v[22:23], v[226:227], v[54:55] op_sel:[1,1] op_sel_hi:[1,0]
	v_pk_fma_f32 v[22:23], v[226:227], v[54:55], v[22:23] op_sel_hi:[0,1,1] neg_lo:[0,0,1]
	v_pk_mul_f32 v[54:55], v[230:231], v[204:205] op_sel:[1,1] op_sel_hi:[1,0]
	v_pk_fma_f32 v[54:55], v[230:231], v[204:205], v[54:55] op_sel_hi:[0,1,1] neg_lo:[0,0,1]
	v_pk_add_f32 v[202:203], v[2:3], v[34:35]
	v_pk_add_f32 v[2:3], v[2:3], v[34:35] neg_lo:[0,1] neg_hi:[0,1]
	v_pk_add_f32 v[204:205], v[18:19], v[50:51]
	v_pk_add_f32 v[18:19], v[18:19], v[50:51] neg_lo:[0,1] neg_hi:[0,1]
	v_pk_add_f32 v[34:35], v[202:203], v[204:205]
	v_pk_add_f32 v[50:51], v[202:203], v[204:205] neg_lo:[0,1] neg_hi:[0,1]
	v_pk_add_f32 v[202:203], v[2:3], v[18:19] op_sel:[0,1] op_sel_hi:[1,0] neg_hi:[0,1]
	v_pk_add_f32 v[204:205], v[2:3], v[18:19] op_sel:[0,1] op_sel_hi:[1,0] neg_lo:[0,1]
	v_pk_mul_f32 v[2:3], v[224:225], v[202:203] op_sel:[1,1] op_sel_hi:[1,0]
	v_pk_fma_f32 v[2:3], v[224:225], v[202:203], v[2:3] op_sel_hi:[0,1,1] neg_lo:[0,0,1]
	v_pk_mul_f32 v[18:19], v[226:227], v[50:51] op_sel:[1,1] op_sel_hi:[1,0]
	v_pk_fma_f32 v[18:19], v[226:227], v[50:51], v[18:19] op_sel_hi:[0,1,1] neg_lo:[0,0,1]
	v_pk_mul_f32 v[50:51], v[230:231], v[204:205] op_sel:[1,1] op_sel_hi:[1,0]
	v_pk_fma_f32 v[50:51], v[230:231], v[204:205], v[50:51] op_sel_hi:[0,1,1] neg_lo:[0,0,1]
	v_pk_add_f32 v[202:203], v[4:5], v[36:37]
	v_pk_add_f32 v[4:5], v[4:5], v[36:37] neg_lo:[0,1] neg_hi:[0,1]
	v_pk_add_f32 v[204:205], v[20:21], v[52:53]
	v_pk_add_f32 v[20:21], v[20:21], v[52:53] neg_lo:[0,1] neg_hi:[0,1]
	v_pk_add_f32 v[36:37], v[202:203], v[204:205]
	v_pk_add_f32 v[52:53], v[202:203], v[204:205] neg_lo:[0,1] neg_hi:[0,1]
	v_pk_add_f32 v[202:203], v[4:5], v[20:21] op_sel:[0,1] op_sel_hi:[1,0] neg_hi:[0,1]
	v_pk_add_f32 v[204:205], v[4:5], v[20:21] op_sel:[0,1] op_sel_hi:[1,0] neg_lo:[0,1]
	v_pk_mul_f32 v[4:5], v[224:225], v[202:203] op_sel:[1,1] op_sel_hi:[1,0]
	v_pk_fma_f32 v[4:5], v[224:225], v[202:203], v[4:5] op_sel_hi:[0,1,1] neg_lo:[0,0,1]
	v_pk_mul_f32 v[20:21], v[226:227], v[52:53] op_sel:[1,1] op_sel_hi:[1,0]
	v_pk_fma_f32 v[20:21], v[226:227], v[52:53], v[20:21] op_sel_hi:[0,1,1] neg_lo:[0,0,1]
	v_pk_mul_f32 v[52:53], v[230:231], v[204:205] op_sel:[1,1] op_sel_hi:[1,0]
	v_pk_fma_f32 v[52:53], v[230:231], v[204:205], v[52:53] op_sel_hi:[0,1,1] neg_lo:[0,0,1]
	v_pk_add_f32 v[202:203], v[8:9], v[40:41]
	v_pk_add_f32 v[8:9], v[8:9], v[40:41] neg_lo:[0,1] neg_hi:[0,1]
	v_pk_add_f32 v[204:205], v[24:25], v[56:57]
	v_pk_add_f32 v[24:25], v[24:25], v[56:57] neg_lo:[0,1] neg_hi:[0,1]
	v_pk_add_f32 v[40:41], v[202:203], v[204:205]
	v_pk_add_f32 v[56:57], v[202:203], v[204:205] neg_lo:[0,1] neg_hi:[0,1]
	v_pk_add_f32 v[202:203], v[8:9], v[24:25] op_sel:[0,1] op_sel_hi:[1,0] neg_hi:[0,1]
	v_pk_add_f32 v[204:205], v[8:9], v[24:25] op_sel:[0,1] op_sel_hi:[1,0] neg_lo:[0,1]
	v_pk_mul_f32 v[8:9], v[224:225], v[202:203] op_sel:[1,1] op_sel_hi:[1,0]
	v_pk_fma_f32 v[8:9], v[224:225], v[202:203], v[8:9] op_sel_hi:[0,1,1] neg_lo:[0,0,1]
	v_pk_mul_f32 v[24:25], v[226:227], v[56:57] op_sel:[1,1] op_sel_hi:[1,0]
	v_pk_fma_f32 v[24:25], v[226:227], v[56:57], v[24:25] op_sel_hi:[0,1,1] neg_lo:[0,0,1]
; DI f32x2 cmul(f32x2 a, f32x2 b) { return mkf2(a.x * b.x - a.y * b.y, a.x * b.y + a.y * b.x); }
; DI void fft8192(f32x2* buf, const f32x2* __restrict__ tw) {
;     ...
; #pragma unroll
;     for (int e = 0; e < 8; ++e) {
;       const int i = tid + 256 * e;
;       const int q = i & (s - 1);
;       const int ps = i - q;
;       const float rev = (float)ps * (1.f / 8192.f);
;       const f32x2 w1 = mkf2(__builtin_amdgcn_cosf(rev), -__builtin_amdgcn_sinf(rev));
;       const f32x2 w2 = cmul(w1, w1), w3 = cmul(w1, w2);
;       const f32x2 apc = mkf2(a[e].x + c[e].x, a[e].y + c[e].y), amc = mkf2(a[e].x - c[e].x, a[e].y - c[e].y);
;       const f32x2 bpd = mkf2(b[e].x + d[e].x, b[e].y + d[e].y), bmd = mkf2(b[e].x - d[e].x, b[e].y - d[e].y);
;       const int o = 4 * i - 3 * q;
;       buf[SW(o)] = mkf2(apc.x + bpd.x, apc.y + bpd.y);
;       buf[SW(o + s)] = cmul(w1, mkf2(amc.x + bmd.y, amc.y - bmd.x));
;       buf[SW(o + 2 * s)] = cmul(w2, mkf2(apc.x - bpd.x, apc.y - bpd.y));
;       buf[SW(o + 3 * s)] = cmul(w3, mkf2(amc.x - bmd.y, amc.y + bmd.x));
;     }
	v_pk_mul_f32 v[56:57], v[230:231], v[204:205] op_sel:[1,1] op_sel_hi:[1,0]
	v_pk_fma_f32 v[56:57], v[230:231], v[204:205], v[56:57] op_sel_hi:[0,1,1] neg_lo:[0,0,1]
	v_mul_f32_e32 v214, 4.0, v201
	v_add_f32_e32 v214, 0x3e000000, v214
	v_cos_f32_e32 v224, v214
	v_sin_f32_e64 v225, -v214
	s_nop 0
	v_pk_mul_f32 v[206:207], v[224:225], v[224:225] op_sel:[1,1] op_sel_hi:[1,0]
	v_pk_fma_f32 v[226:227], v[224:225], v[224:225], v[206:207] op_sel_hi:[0,1,1] neg_lo:[0,0,1]
	v_pk_mul_f32 v[206:207], v[224:225], v[226:227] op_sel:[1,1] op_sel_hi:[1,0]
	v_pk_fma_f32 v[230:231], v[224:225], v[226:227], v[206:207] op_sel_hi:[0,1,1] neg_lo:[0,0,1]
	v_pk_add_f32 v[202:203], v[14:15], v[46:47]
	v_pk_add_f32 v[14:15], v[14:15], v[46:47] neg_lo:[0,1] neg_hi:[0,1]
	v_pk_add_f32 v[204:205], v[30:31], v[62:63]
	v_pk_add_f32 v[30:31], v[30:31], v[62:63] neg_lo:[0,1] neg_hi:[0,1]
	v_pk_add_f32 v[46:47], v[202:203], v[204:205]
	v_pk_add_f32 v[62:63], v[202:203], v[204:205] neg_lo:[0,1] neg_hi:[0,1]
	v_pk_add_f32 v[202:203], v[14:15], v[30:31] op_sel:[0,1] op_sel_hi:[1,0] neg_hi:[0,1]
	v_pk_add_f32 v[204:205], v[14:15], v[30:31] op_sel:[0,1] op_sel_hi:[1,0] neg_lo:[0,1]
	v_pk_mul_f32 v[14:15], v[224:225], v[202:203] op_sel:[1,1] op_sel_hi:[1,0]
	v_pk_fma_f32 v[14:15], v[224:225], v[202:203], v[14:15] op_sel_hi:[0,1,1] neg_lo:[0,0,1]
	v_pk_mul_f32 v[30:31], v[226:227], v[62:63] op_sel:[1,1] op_sel_hi:[1,0]
	v_pk_fma_f32 v[30:31], v[226:227], v[62:63], v[30:31] op_sel_hi:[0,1,1] neg_lo:[0,0,1]
	v_pk_mul_f32 v[62:63], v[230:231], v[204:205] op_sel:[1,1] op_sel_hi:[1,0]
	v_pk_fma_f32 v[62:63], v[230:231], v[204:205], v[62:63] op_sel_hi:[0,1,1] neg_lo:[0,0,1]
	v_pk_add_f32 v[202:203], v[10:11], v[42:43]
	v_pk_add_f32 v[10:11], v[10:11], v[42:43] neg_lo:[0,1] neg_hi:[0,1]
	v_pk_add_f32 v[204:205], v[26:27], v[58:59]
	v_pk_add_f32 v[26:27], v[26:27], v[58:59] neg_lo:[0,1] neg_hi:[0,1]
	v_pk_add_f32 v[42:43], v[202:203], v[204:205]
	v_pk_add_f32 v[58:59], v[202:203], v[204:205] neg_lo:[0,1] neg_hi:[0,1]
	v_pk_add_f32 v[202:203], v[10:11], v[26:27] op_sel:[0,1] op_sel_hi:[1,0] neg_hi:[0,1]
	v_pk_add_f32 v[204:205], v[10:11], v[26:27] op_sel:[0,1] op_sel_hi:[1,0] neg_lo:[0,1]
	v_pk_mul_f32 v[10:11], v[224:225], v[202:203] op_sel:[1,1] op_sel_hi:[1,0]
	v_pk_fma_f32 v[10:11], v[224:225], v[202:203], v[10:11] op_sel_hi:[0,1,1] neg_lo:[0,0,1]
	v_pk_mul_f32 v[26:27], v[226:227], v[58:59] op_sel:[1,1] op_sel_hi:[1,0]
	v_pk_fma_f32 v[26:27], v[226:227], v[58:59], v[26:27] op_sel_hi:[0,1,1] neg_lo:[0,0,1]
	v_pk_mul_f32 v[58:59], v[230:231], v[204:205] op_sel:[1,1] op_sel_hi:[1,0]
	v_pk_fma_f32 v[58:59], v[230:231], v[204:205], v[58:59] op_sel_hi:[0,1,1] neg_lo:[0,0,1]
	v_pk_add_f32 v[202:203], v[12:13], v[44:45]
	v_pk_add_f32 v[12:13], v[12:13], v[44:45] neg_lo:[0,1] neg_hi:[0,1]
	v_pk_add_f32 v[204:205], v[28:29], v[60:61]
	v_pk_add_f32 v[28:29], v[28:29], v[60:61] neg_lo:[0,1] neg_hi:[0,1]
	v_pk_add_f32 v[44:45], v[202:203], v[204:205]
	v_pk_add_f32 v[60:61], v[202:203], v[204:205] neg_lo:[0,1] neg_hi:[0,1]
	v_pk_add_f32 v[202:203], v[12:13], v[28:29] op_sel:[0,1] op_sel_hi:[1,0] neg_hi:[0,1]
	v_pk_add_f32 v[204:205], v[12:13], v[28:29] op_sel:[0,1] op_sel_hi:[1,0] neg_lo:[0,1]
	v_pk_mul_f32 v[12:13], v[224:225], v[202:203] op_sel:[1,1] op_sel_hi:[1,0]
	v_pk_fma_f32 v[12:13], v[224:225], v[202:203], v[12:13] op_sel_hi:[0,1,1] neg_lo:[0,0,1]
	v_pk_mul_f32 v[28:29], v[226:227], v[60:61] op_sel:[1,1] op_sel_hi:[1,0]
	v_pk_fma_f32 v[28:29], v[226:227], v[60:61], v[28:29] op_sel_hi:[0,1,1] neg_lo:[0,0,1]
	v_pk_mul_f32 v[60:61], v[230:231], v[204:205] op_sel:[1,1] op_sel_hi:[1,0]
	v_pk_fma_f32 v[60:61], v[230:231], v[204:205], v[60:61] op_sel_hi:[0,1,1] neg_lo:[0,0,1]
	v_pk_add_f32 v[202:203], v[16:17], v[48:49]
	v_pk_add_f32 v[16:17], v[16:17], v[48:49] neg_lo:[0,1] neg_hi:[0,1]
	v_pk_add_f32 v[204:205], v[32:33], v[64:65]
	v_pk_add_f32 v[32:33], v[32:33], v[64:65] neg_lo:[0,1] neg_hi:[0,1]
	v_pk_add_f32 v[48:49], v[202:203], v[204:205]
	v_pk_add_f32 v[64:65], v[202:203], v[204:205] neg_lo:[0,1] neg_hi:[0,1]
	v_pk_add_f32 v[202:203], v[16:17], v[32:33] op_sel:[0,1] op_sel_hi:[1,0] neg_hi:[0,1]
	v_pk_add_f32 v[204:205], v[16:17], v[32:33] op_sel:[0,1] op_sel_hi:[1,0] neg_lo:[0,1]
	v_pk_mul_f32 v[16:17], v[224:225], v[202:203] op_sel:[1,1] op_sel_hi:[1,0]
	v_pk_fma_f32 v[16:17], v[224:225], v[202:203], v[16:17] op_sel_hi:[0,1,1] neg_lo:[0,0,1]
	v_pk_mul_f32 v[32:33], v[226:227], v[64:65] op_sel:[1,1] op_sel_hi:[1,0]
	v_pk_fma_f32 v[32:33], v[226:227], v[64:65], v[32:33] op_sel_hi:[0,1,1] neg_lo:[0,0,1]
	v_pk_mul_f32 v[64:65], v[230:231], v[204:205] op_sel:[1,1] op_sel_hi:[1,0]
	v_pk_fma_f32 v[64:65], v[230:231], v[204:205], v[64:65] op_sel_hi:[0,1,1] neg_lo:[0,0,1]
	ds_write_b64 v164, v[38:39] offset:0
	v_xor_b32_e32 v156, 8, v164
	ds_write_b64 v156, v[34:35] offset:0
	v_xor_b32_e32 v158, 16, v164
	ds_write_b64 v158, v[36:37] offset:0
	v_xor_b32_e32 v160, 24, v164
	ds_write_b64 v160, v[40:41] offset:0
	v_xor_b32_e32 v162, 32, v164
	ds_write_b64 v162, v[6:7] offset:0
	v_xor_b32_e32 v156, 40, v164
	ds_write_b64 v156, v[2:3] offset:0
	v_xor_b32_e32 v158, 48, v164
	ds_write_b64 v158, v[4:5] offset:0
	v_xor_b32_e32 v160, 56, v164
	ds_write_b64 v160, v[8:9] offset:0
	v_xor_b32_e32 v162, 64, v164
	ds_write_b64 v162, v[22:23] offset:0
	v_xor_b32_e32 v156, 0x48, v164
	ds_write_b64 v156, v[18:19] offset:0
	v_xor_b32_e32 v158, 0x50, v164
	ds_write_b64 v158, v[20:21] offset:0
	v_xor_b32_e32 v160, 0x58, v164
	ds_write_b64 v160, v[24:25] offset:0
	v_xor_b32_e32 v162, 0x60, v164
	ds_write_b64 v162, v[54:55] offset:0
	v_xor_b32_e32 v156, 0x68, v164
	ds_write_b64 v156, v[50:51] offset:0
	v_xor_b32_e32 v158, 0x70, v164
	ds_write_b64 v158, v[52:53] offset:0
	v_xor_b32_e32 v160, 0x78, v164
	ds_write_b64 v160, v[56:57] offset:0
	ds_write_b64 v164, v[46:47] offset:32768
	v_xor_b32_e32 v162, 8, v164
	ds_write_b64 v162, v[42:43] offset:32768
	v_xor_b32_e32 v156, 16, v164
	ds_write_b64 v156, v[44:45] offset:32768
	v_xor_b32_e32 v158, 24, v164
	ds_write_b64 v158, v[48:49] offset:32768
	v_xor_b32_e32 v160, 32, v164
	ds_write_b64 v160, v[14:15] offset:32768
	v_xor_b32_e32 v162, 40, v164
	ds_write_b64 v162, v[10:11] offset:32768
	v_xor_b32_e32 v156, 48, v164
	ds_write_b64 v156, v[12:13] offset:32768
	v_xor_b32_e32 v158, 56, v164
	ds_write_b64 v158, v[16:17] offset:32768
	v_xor_b32_e32 v160, 64, v164
	ds_write_b64 v160, v[30:31] offset:32768
	v_xor_b32_e32 v162, 0x48, v164
	ds_write_b64 v162, v[26:27] offset:32768
	v_xor_b32_e32 v156, 0x50, v164
	ds_write_b64 v156, v[28:29] offset:32768
	v_xor_b32_e32 v158, 0x58, v164
	ds_write_b64 v158, v[32:33] offset:32768
	v_xor_b32_e32 v160, 0x60, v164
	ds_write_b64 v160, v[62:63] offset:32768
	v_xor_b32_e32 v162, 0x68, v164
	ds_write_b64 v162, v[58:59] offset:32768
	v_xor_b32_e32 v156, 0x70, v164
	ds_write_b64 v156, v[60:61] offset:32768
	v_xor_b32_e32 v158, 0x78, v164
	ds_write_b64 v158, v[64:65] offset:32768
	s_waitcnt lgkmcnt(0)
	s_barrier
; DI f32x2 cmul(f32x2 a, f32x2 b) { return mkf2(a.x * b.x - a.y * b.y, a.x * b.y + a.y * b.x); }
; DI void fft8192(f32x2* buf, const f32x2* __restrict__ tw) {
;     ...
;   for (int ls = 0; ls < 12; ls += 2) {
;     const int s = 1 << ls;
;     f32x2 a[8], b[8], c[8], d[8];
;     __syncthreads();
; #pragma unroll
;     for (int e = 0; e < 8; ++e) {
;       const int i = tid + 256 * e;
;       const int pi = SW(i);
;       a[e] = buf[pi]; b[e] = buf[pi + 2048]; c[e] = buf[pi + 4096]; d[e] = buf[pi + 6144];
;     }
;     __syncthreads();
; #pragma unroll
;     for (int e = 0; e < 8; ++e) {
;       const int i = tid + 256 * e;
;       const int q = i & (s - 1);
;       const int ps = i - q;
;       const float rev = (float)ps * (1.f / 8192.f);
;       const f32x2 w1 = mkf2(__builtin_amdgcn_cosf(rev), -__builtin_amdgcn_sinf(rev));
;       const f32x2 w2 = cmul(w1, w1), w3 = cmul(w1, w2);
;       const f32x2 apc = mkf2(a[e].x + c[e].x, a[e].y + c[e].y), amc = mkf2(a[e].x - c[e].x, a[e].y - c[e].y);
;       const f32x2 bpd = mkf2(b[e].x + d[e].x, b[e].y + d[e].y), bmd = mkf2(b[e].x - d[e].x, b[e].y - d[e].y);
	ds_read2st64_b64 v[2:5], v154 offset0:0 offset1:32
	ds_read2st64_b64 v[6:9], v154 offset0:64 offset1:96
	ds_read2st64_b64 v[10:13], v154 offset0:4 offset1:36
	ds_read2st64_b64 v[14:17], v154 offset0:68 offset1:100
	ds_read2st64_b64 v[18:21], v154 offset0:8 offset1:40
	ds_read2st64_b64 v[22:25], v154 offset0:72 offset1:104
	ds_read2st64_b64 v[26:29], v154 offset0:12 offset1:44
	ds_read2st64_b64 v[30:33], v154 offset0:76 offset1:108
	ds_read2st64_b64 v[34:37], v154 offset0:16 offset1:48
	ds_read2st64_b64 v[38:41], v154 offset0:80 offset1:112
	ds_read2st64_b64 v[42:45], v154 offset0:20 offset1:52
	ds_read2st64_b64 v[46:49], v154 offset0:84 offset1:116
	ds_read2st64_b64 v[50:53], v154 offset0:24 offset1:56
	ds_read2st64_b64 v[54:57], v154 offset0:88 offset1:120
	ds_read2st64_b64 v[58:61], v154 offset0:28 offset1:60
	ds_read2st64_b64 v[62:65], v154 offset0:92 offset1:124
	v_and_b32_e32 v166, 15, v0
	v_sub_u32_e32 v168, v0, v166
	v_cvt_f32_u32_e32 v201, v168
	v_lshl_add_u32 v164, v168, 4, v166
	v_lshlrev_b32_e32 v164, 3, v164
	v_mul_f32_e32 v201, 0x39000000, v201
	v_cos_f32_e32 v210, v201
	v_sin_f32_e64 v211, -v201
	s_waitcnt lgkmcnt(14)
	v_pk_add_f32 v[202:203], v[2:3], v[6:7]
	v_pk_add_f32 v[2:3], v[2:3], v[6:7] neg_lo:[0,1] neg_hi:[0,1]
	v_pk_add_f32 v[204:205], v[4:5], v[8:9]
	v_pk_add_f32 v[4:5], v[4:5], v[8:9] neg_lo:[0,1] neg_hi:[0,1]
	v_pk_add_f32 v[6:7], v[202:203], v[204:205]
	v_pk_add_f32 v[8:9], v[202:203], v[204:205] neg_lo:[0,1] neg_hi:[0,1]
	v_pk_add_f32 v[202:203], v[2:3], v[4:5] op_sel:[0,1] op_sel_hi:[1,0] neg_hi:[0,1]
	v_pk_add_f32 v[204:205], v[2:3], v[4:5] op_sel:[0,1] op_sel_hi:[1,0] neg_lo:[0,1]
	v_pk_mul_f32 v[206:207], v[210:211], v[210:211] op_sel:[1,1] op_sel_hi:[1,0]
	v_pk_fma_f32 v[212:213], v[210:211], v[210:211], v[206:207] op_sel_hi:[0,1,1] neg_lo:[0,0,1]
	v_pk_mul_f32 v[206:207], v[210:211], v[212:213] op_sel:[1,1] op_sel_hi:[1,0]
	v_pk_fma_f32 v[220:221], v[210:211], v[212:213], v[206:207] op_sel_hi:[0,1,1] neg_lo:[0,0,1]
	v_pk_mul_f32 v[2:3], v[210:211], v[202:203] op_sel:[1,1] op_sel_hi:[1,0]
	v_pk_fma_f32 v[2:3], v[210:211], v[202:203], v[2:3] op_sel_hi:[0,1,1] neg_lo:[0,0,1]
	v_pk_mul_f32 v[4:5], v[212:213], v[8:9] op_sel:[1,1] op_sel_hi:[1,0]
	v_pk_fma_f32 v[4:5], v[212:213], v[8:9], v[4:5] op_sel_hi:[0,1,1] neg_lo:[0,0,1]
	v_pk_mul_f32 v[8:9], v[220:221], v[204:205] op_sel:[1,1] op_sel_hi:[1,0]
	v_pk_fma_f32 v[8:9], v[220:221], v[204:205], v[8:9] op_sel_hi:[0,1,1] neg_lo:[0,0,1]
	v_add_f32_e32 v214, 0x3d000000, v201
	v_cos_f32_e32 v210, v214
	v_sin_f32_e64 v211, -v214
	s_waitcnt lgkmcnt(12)
	v_pk_add_f32 v[202:203], v[10:11], v[14:15]
	v_pk_add_f32 v[10:11], v[10:11], v[14:15] neg_lo:[0,1] neg_hi:[0,1]
	v_pk_add_f32 v[204:205], v[12:13], v[16:17]
	v_pk_add_f32 v[12:13], v[12:13], v[16:17] neg_lo:[0,1] neg_hi:[0,1]
	v_pk_add_f32 v[14:15], v[202:203], v[204:205]
	v_pk_add_f32 v[16:17], v[202:203], v[204:205] neg_lo:[0,1] neg_hi:[0,1]
	v_pk_add_f32 v[202:203], v[10:11], v[12:13] op_sel:[0,1] op_sel_hi:[1,0] neg_hi:[0,1]
	v_pk_add_f32 v[204:205], v[10:11], v[12:13] op_sel:[0,1] op_sel_hi:[1,0] neg_lo:[0,1]
	v_pk_mul_f32 v[206:207], v[210:211], v[210:211] op_sel:[1,1] op_sel_hi:[1,0]
	v_pk_fma_f32 v[212:213], v[210:211], v[210:211], v[206:207] op_sel_hi:[0,1,1] neg_lo:[0,0,1]
	v_pk_mul_f32 v[206:207], v[210:211], v[212:213] op_sel:[1,1] op_sel_hi:[1,0]
	v_pk_fma_f32 v[220:221], v[210:211], v[212:213], v[206:207] op_sel_hi:[0,1,1] neg_lo:[0,0,1]
	v_pk_mul_f32 v[10:11], v[210:211], v[202:203] op_sel:[1,1] op_sel_hi:[1,0]
	v_pk_fma_f32 v[10:11], v[210:211], v[202:203], v[10:11] op_sel_hi:[0,1,1] neg_lo:[0,0,1]
	v_pk_mul_f32 v[12:13], v[212:213], v[16:17] op_sel:[1,1] op_sel_hi:[1,0]
	v_pk_fma_f32 v[12:13], v[212:213], v[16:17], v[12:13] op_sel_hi:[0,1,1] neg_lo:[0,0,1]
	v_pk_mul_f32 v[16:17], v[220:221], v[204:205] op_sel:[1,1] op_sel_hi:[1,0]
	v_pk_fma_f32 v[16:17], v[220:221], v[204:205], v[16:17] op_sel_hi:[0,1,1] neg_lo:[0,0,1]
	v_add_f32_e32 v214, 0x3d800000, v201
	v_cos_f32_e32 v210, v214
	v_sin_f32_e64 v211, -v214
	s_waitcnt lgkmcnt(10)
	v_pk_add_f32 v[202:203], v[18:19], v[22:23]
	v_pk_add_f32 v[18:19], v[18:19], v[22:23] neg_lo:[0,1] neg_hi:[0,1]
	v_pk_add_f32 v[204:205], v[20:21], v[24:25]
	v_pk_add_f32 v[20:21], v[20:21], v[24:25] neg_lo:[0,1] neg_hi:[0,1]
	v_pk_add_f32 v[22:23], v[202:203], v[204:205]
	v_pk_add_f32 v[24:25], v[202:203], v[204:205] neg_lo:[0,1] neg_hi:[0,1]
	v_pk_add_f32 v[202:203], v[18:19], v[20:21] op_sel:[0,1] op_sel_hi:[1,0] neg_hi:[0,1]
	v_pk_add_f32 v[204:205], v[18:19], v[20:21] op_sel:[0,1] op_sel_hi:[1,0] neg_lo:[0,1]
	v_pk_mul_f32 v[206:207], v[210:211], v[210:211] op_sel:[1,1] op_sel_hi:[1,0]
	v_pk_fma_f32 v[212:213], v[210:211], v[210:211], v[206:207] op_sel_hi:[0,1,1] neg_lo:[0,0,1]
	v_pk_mul_f32 v[206:207], v[210:211], v[212:213] op_sel:[1,1] op_sel_hi:[1,0]
	v_pk_fma_f32 v[220:221], v[210:211], v[212:213], v[206:207] op_sel_hi:[0,1,1] neg_lo:[0,0,1]
	v_pk_mul_f32 v[18:19], v[210:211], v[202:203] op_sel:[1,1] op_sel_hi:[1,0]
	v_pk_fma_f32 v[18:19], v[210:211], v[202:203], v[18:19] op_sel_hi:[0,1,1] neg_lo:[0,0,1]
	v_pk_mul_f32 v[20:21], v[212:213], v[24:25] op_sel:[1,1] op_sel_hi:[1,0]
	v_pk_fma_f32 v[20:21], v[212:213], v[24:25], v[20:21] op_sel_hi:[0,1,1] neg_lo:[0,0,1]
	v_pk_mul_f32 v[24:25], v[220:221], v[204:205] op_sel:[1,1] op_sel_hi:[1,0]
	v_pk_fma_f32 v[24:25], v[220:221], v[204:205], v[24:25] op_sel_hi:[0,1,1] neg_lo:[0,0,1]
	v_add_f32_e32 v214, 0x3dc00000, v201
	v_cos_f32_e32 v210, v214
	v_sin_f32_e64 v211, -v214
	s_waitcnt lgkmcnt(8)
; DI f32x2 cmul(f32x2 a, f32x2 b) { return mkf2(a.x * b.x - a.y * b.y, a.x * b.y + a.y * b.x); }
; DI void fft8192(f32x2* buf, const f32x2* __restrict__ tw) {
;     ...
; #pragma unroll
;     for (int e = 0; e < 8; ++e) {
;       const int i = tid + 256 * e;
;       const int q = i & (s - 1);
;       const int ps = i - q;
;       const float rev = (float)ps * (1.f / 8192.f);
;       const f32x2 w1 = mkf2(__builtin_amdgcn_cosf(rev), -__builtin_amdgcn_sinf(rev));
;       const f32x2 w2 = cmul(w1, w1), w3 = cmul(w1, w2);
;       const f32x2 apc = mkf2(a[e].x + c[e].x, a[e].y + c[e].y), amc = mkf2(a[e].x - c[e].x, a[e].y - c[e].y);
;       const f32x2 bpd = mkf2(b[e].x + d[e].x, b[e].y + d[e].y), bmd = mkf2(b[e].x - d[e].x, b[e].y - d[e].y);
;       const int o = 4 * i - 3 * q;
;       buf[SW(o)] = mkf2(apc.x + bpd.x, apc.y + bpd.y);
;       buf[SW(o + s)] = cmul(w1, mkf2(amc.x + bmd.y, amc.y - bmd.x));
;       buf[SW(o + 2 * s)] = cmul(w2, mkf2(apc.x - bpd.x, apc.y - bpd.y));
;       buf[SW(o + 3 * s)] = cmul(w3, mkf2(amc.x - bmd.y, amc.y + bmd.x));
;     }
	v_pk_add_f32 v[202:203], v[26:27], v[30:31]
	v_pk_add_f32 v[26:27], v[26:27], v[30:31] neg_lo:[0,1] neg_hi:[0,1]
	v_pk_add_f32 v[204:205], v[28:29], v[32:33]
	v_pk_add_f32 v[28:29], v[28:29], v[32:33] neg_lo:[0,1] neg_hi:[0,1]
	v_pk_add_f32 v[30:31], v[202:203], v[204:205]
	v_pk_add_f32 v[32:33], v[202:203], v[204:205] neg_lo:[0,1] neg_hi:[0,1]
	v_pk_add_f32 v[202:203], v[26:27], v[28:29] op_sel:[0,1] op_sel_hi:[1,0] neg_hi:[0,1]
	v_pk_add_f32 v[204:205], v[26:27], v[28:29] op_sel:[0,1] op_sel_hi:[1,0] neg_lo:[0,1]
	v_pk_mul_f32 v[206:207], v[210:211], v[210:211] op_sel:[1,1] op_sel_hi:[1,0]
	v_pk_fma_f32 v[212:213], v[210:211], v[210:211], v[206:207] op_sel_hi:[0,1,1] neg_lo:[0,0,1]
	v_pk_mul_f32 v[206:207], v[210:211], v[212:213] op_sel:[1,1] op_sel_hi:[1,0]
	v_pk_fma_f32 v[220:221], v[210:211], v[212:213], v[206:207] op_sel_hi:[0,1,1] neg_lo:[0,0,1]
	v_pk_mul_f32 v[26:27], v[210:211], v[202:203] op_sel:[1,1] op_sel_hi:[1,0]
	v_pk_fma_f32 v[26:27], v[210:211], v[202:203], v[26:27] op_sel_hi:[0,1,1] neg_lo:[0,0,1]
	v_pk_mul_f32 v[28:29], v[212:213], v[32:33] op_sel:[1,1] op_sel_hi:[1,0]
	v_pk_fma_f32 v[28:29], v[212:213], v[32:33], v[28:29] op_sel_hi:[0,1,1] neg_lo:[0,0,1]
	v_pk_mul_f32 v[32:33], v[220:221], v[204:205] op_sel:[1,1] op_sel_hi:[1,0]
	v_pk_fma_f32 v[32:33], v[220:221], v[204:205], v[32:33] op_sel_hi:[0,1,1] neg_lo:[0,0,1]
	v_add_f32_e32 v214, 0x3e000000, v201
	v_cos_f32_e32 v210, v214
	v_sin_f32_e64 v211, -v214
	s_waitcnt lgkmcnt(6)
	v_pk_add_f32 v[202:203], v[34:35], v[38:39]
	v_pk_add_f32 v[34:35], v[34:35], v[38:39] neg_lo:[0,1] neg_hi:[0,1]
	v_pk_add_f32 v[204:205], v[36:37], v[40:41]
	v_pk_add_f32 v[36:37], v[36:37], v[40:41] neg_lo:[0,1] neg_hi:[0,1]
	v_pk_add_f32 v[38:39], v[202:203], v[204:205]
	v_pk_add_f32 v[40:41], v[202:203], v[204:205] neg_lo:[0,1] neg_hi:[0,1]
	v_pk_add_f32 v[202:203], v[34:35], v[36:37] op_sel:[0,1] op_sel_hi:[1,0] neg_hi:[0,1]
	v_pk_add_f32 v[204:205], v[34:35], v[36:37] op_sel:[0,1] op_sel_hi:[1,0] neg_lo:[0,1]
	v_pk_mul_f32 v[206:207], v[210:211], v[210:211] op_sel:[1,1] op_sel_hi:[1,0]
	v_pk_fma_f32 v[212:213], v[210:211], v[210:211], v[206:207] op_sel_hi:[0,1,1] neg_lo:[0,0,1]
	v_pk_mul_f32 v[206:207], v[210:211], v[212:213] op_sel:[1,1] op_sel_hi:[1,0]
	v_pk_fma_f32 v[220:221], v[210:211], v[212:213], v[206:207] op_sel_hi:[0,1,1] neg_lo:[0,0,1]
	v_pk_mul_f32 v[34:35], v[210:211], v[202:203] op_sel:[1,1] op_sel_hi:[1,0]
	v_pk_fma_f32 v[34:35], v[210:211], v[202:203], v[34:35] op_sel_hi:[0,1,1] neg_lo:[0,0,1]
	v_pk_mul_f32 v[36:37], v[212:213], v[40:41] op_sel:[1,1] op_sel_hi:[1,0]
	v_pk_fma_f32 v[36:37], v[212:213], v[40:41], v[36:37] op_sel_hi:[0,1,1] neg_lo:[0,0,1]
	v_pk_mul_f32 v[40:41], v[220:221], v[204:205] op_sel:[1,1] op_sel_hi:[1,0]
	v_pk_fma_f32 v[40:41], v[220:221], v[204:205], v[40:41] op_sel_hi:[0,1,1] neg_lo:[0,0,1]
	v_add_f32_e32 v214, 0x3e200000, v201
	v_cos_f32_e32 v210, v214
	v_sin_f32_e64 v211, -v214
	s_waitcnt lgkmcnt(4)
	v_pk_add_f32 v[202:203], v[42:43], v[46:47]
	v_pk_add_f32 v[42:43], v[42:43], v[46:47] neg_lo:[0,1] neg_hi:[0,1]
	v_pk_add_f32 v[204:205], v[44:45], v[48:49]
	v_pk_add_f32 v[44:45], v[44:45], v[48:49] neg_lo:[0,1] neg_hi:[0,1]
	v_pk_add_f32 v[46:47], v[202:203], v[204:205]
	v_pk_add_f32 v[48:49], v[202:203], v[204:205] neg_lo:[0,1] neg_hi:[0,1]
	v_pk_add_f32 v[202:203], v[42:43], v[44:45] op_sel:[0,1] op_sel_hi:[1,0] neg_hi:[0,1]
	v_pk_add_f32 v[204:205], v[42:43], v[44:45] op_sel:[0,1] op_sel_hi:[1,0] neg_lo:[0,1]
	v_pk_mul_f32 v[206:207], v[210:211], v[210:211] op_sel:[1,1] op_sel_hi:[1,0]
	v_pk_fma_f32 v[212:213], v[210:211], v[210:211], v[206:207] op_sel_hi:[0,1,1] neg_lo:[0,0,1]
	v_pk_mul_f32 v[206:207], v[210:211], v[212:213] op_sel:[1,1] op_sel_hi:[1,0]
	v_pk_fma_f32 v[220:221], v[210:211], v[212:213], v[206:207] op_sel_hi:[0,1,1] neg_lo:[0,0,1]
	v_pk_mul_f32 v[42:43], v[210:211], v[202:203] op_sel:[1,1] op_sel_hi:[1,0]
	v_pk_fma_f32 v[42:43], v[210:211], v[202:203], v[42:43] op_sel_hi:[0,1,1] neg_lo:[0,0,1]
	v_pk_mul_f32 v[44:45], v[212:213], v[48:49] op_sel:[1,1] op_sel_hi:[1,0]
	v_pk_fma_f32 v[44:45], v[212:213], v[48:49], v[44:45] op_sel_hi:[0,1,1] neg_lo:[0,0,1]
	v_pk_mul_f32 v[48:49], v[220:221], v[204:205] op_sel:[1,1] op_sel_hi:[1,0]
	v_pk_fma_f32 v[48:49], v[220:221], v[204:205], v[48:49] op_sel_hi:[0,1,1] neg_lo:[0,0,1]
	v_add_f32_e32 v214, 0x3e400000, v201
	v_cos_f32_e32 v210, v214
	v_sin_f32_e64 v211, -v214
	s_waitcnt lgkmcnt(2)
	v_pk_add_f32 v[202:203], v[50:51], v[54:55]
	v_pk_add_f32 v[50:51], v[50:51], v[54:55] neg_lo:[0,1] neg_hi:[0,1]
	v_pk_add_f32 v[204:205], v[52:53], v[56:57]
	v_pk_add_f32 v[52:53], v[52:53], v[56:57] neg_lo:[0,1] neg_hi:[0,1]
	v_pk_add_f32 v[54:55], v[202:203], v[204:205]
	v_pk_add_f32 v[56:57], v[202:203], v[204:205] neg_lo:[0,1] neg_hi:[0,1]
	v_pk_add_f32 v[202:203], v[50:51], v[52:53] op_sel:[0,1] op_sel_hi:[1,0] neg_hi:[0,1]
	v_pk_add_f32 v[204:205], v[50:51], v[52:53] op_sel:[0,1] op_sel_hi:[1,0] neg_lo:[0,1]
	v_pk_mul_f32 v[206:207], v[210:211], v[210:211] op_sel:[1,1] op_sel_hi:[1,0]
	v_pk_fma_f32 v[212:213], v[210:211], v[210:211], v[206:207] op_sel_hi:[0,1,1] neg_lo:[0,0,1]
	v_pk_mul_f32 v[206:207], v[210:211], v[212:213] op_sel:[1,1] op_sel_hi:[1,0]
	v_pk_fma_f32 v[220:221], v[210:211], v[212:213], v[206:207] op_sel_hi:[0,1,1] neg_lo:[0,0,1]
	v_pk_mul_f32 v[50:51], v[210:211], v[202:203] op_sel:[1,1] op_sel_hi:[1,0]
	v_pk_fma_f32 v[50:51], v[210:211], v[202:203], v[50:51] op_sel_hi:[0,1,1] neg_lo:[0,0,1]
	v_pk_mul_f32 v[52:53], v[212:213], v[56:57] op_sel:[1,1] op_sel_hi:[1,0]
	v_pk_fma_f32 v[52:53], v[212:213], v[56:57], v[52:53] op_sel_hi:[0,1,1] neg_lo:[0,0,1]
	v_pk_mul_f32 v[56:57], v[220:221], v[204:205] op_sel:[1,1] op_sel_hi:[1,0]
	v_pk_fma_f32 v[56:57], v[220:221], v[204:205], v[56:57] op_sel_hi:[0,1,1] neg_lo:[0,0,1]
	v_add_f32_e32 v214, 0x3e600000, v201
	v_cos_f32_e32 v210, v214
	v_sin_f32_e64 v211, -v214
	s_waitcnt lgkmcnt(0)
; DI f32x2 cmul(f32x2 a, f32x2 b) { return mkf2(a.x * b.x - a.y * b.y, a.x * b.y + a.y * b.x); }
; DI void fft8192(f32x2* buf, const f32x2* __restrict__ tw) {
;     ...
; #pragma unroll
;     for (int e = 0; e < 8; ++e) {
;       const int i = tid + 256 * e;
;       const int q = i & (s - 1);
;       const int ps = i - q;
;       const float rev = (float)ps * (1.f / 8192.f);
;       const f32x2 w1 = mkf2(__builtin_amdgcn_cosf(rev), -__builtin_amdgcn_sinf(rev));
;       const f32x2 w2 = cmul(w1, w1), w3 = cmul(w1, w2);
;       const f32x2 apc = mkf2(a[e].x + c[e].x, a[e].y + c[e].y), amc = mkf2(a[e].x - c[e].x, a[e].y - c[e].y);
;       const f32x2 bpd = mkf2(b[e].x + d[e].x, b[e].y + d[e].y), bmd = mkf2(b[e].x - d[e].x, b[e].y - d[e].y);
;       const int o = 4 * i - 3 * q;
;       buf[SW(o)] = mkf2(apc.x + bpd.x, apc.y + bpd.y);
;       buf[SW(o + s)] = cmul(w1, mkf2(amc.x + bmd.y, amc.y - bmd.x));
;       buf[SW(o + 2 * s)] = cmul(w2, mkf2(apc.x - bpd.x, apc.y - bpd.y));
;       buf[SW(o + 3 * s)] = cmul(w3, mkf2(amc.x - bmd.y, amc.y + bmd.x));
;     }
	v_pk_add_f32 v[202:203], v[58:59], v[62:63]
	v_pk_add_f32 v[58:59], v[58:59], v[62:63] neg_lo:[0,1] neg_hi:[0,1]
	v_pk_add_f32 v[204:205], v[60:61], v[64:65]
	v_pk_add_f32 v[60:61], v[60:61], v[64:65] neg_lo:[0,1] neg_hi:[0,1]
	v_pk_add_f32 v[62:63], v[202:203], v[204:205]
	v_pk_add_f32 v[64:65], v[202:203], v[204:205] neg_lo:[0,1] neg_hi:[0,1]
	v_pk_add_f32 v[202:203], v[58:59], v[60:61] op_sel:[0,1] op_sel_hi:[1,0] neg_hi:[0,1]
	v_pk_add_f32 v[204:205], v[58:59], v[60:61] op_sel:[0,1] op_sel_hi:[1,0] neg_lo:[0,1]
	v_pk_mul_f32 v[206:207], v[210:211], v[210:211] op_sel:[1,1] op_sel_hi:[1,0]
	v_pk_fma_f32 v[212:213], v[210:211], v[210:211], v[206:207] op_sel_hi:[0,1,1] neg_lo:[0,0,1]
	v_pk_mul_f32 v[206:207], v[210:211], v[212:213] op_sel:[1,1] op_sel_hi:[1,0]
	v_pk_fma_f32 v[220:221], v[210:211], v[212:213], v[206:207] op_sel_hi:[0,1,1] neg_lo:[0,0,1]
	v_pk_mul_f32 v[58:59], v[210:211], v[202:203] op_sel:[1,1] op_sel_hi:[1,0]
	v_pk_fma_f32 v[58:59], v[210:211], v[202:203], v[58:59] op_sel_hi:[0,1,1] neg_lo:[0,0,1]
	v_pk_mul_f32 v[60:61], v[212:213], v[64:65] op_sel:[1,1] op_sel_hi:[1,0]
	v_pk_fma_f32 v[60:61], v[212:213], v[64:65], v[60:61] op_sel_hi:[0,1,1] neg_lo:[0,0,1]
	v_pk_mul_f32 v[64:65], v[220:221], v[204:205] op_sel:[1,1] op_sel_hi:[1,0]
	v_pk_fma_f32 v[64:65], v[220:221], v[204:205], v[64:65] op_sel_hi:[0,1,1] neg_lo:[0,0,1]
	s_barrier
	v_mul_f32_e32 v214, 4.0, v201
	v_cos_f32_e32 v224, v214
	v_sin_f32_e64 v225, -v214
	s_nop 0
	v_pk_mul_f32 v[206:207], v[224:225], v[224:225] op_sel:[1,1] op_sel_hi:[1,0]
	v_pk_fma_f32 v[226:227], v[224:225], v[224:225], v[206:207] op_sel_hi:[0,1,1] neg_lo:[0,0,1]
	v_pk_mul_f32 v[206:207], v[224:225], v[226:227] op_sel:[1,1] op_sel_hi:[1,0]
	v_pk_fma_f32 v[230:231], v[224:225], v[226:227], v[206:207] op_sel_hi:[0,1,1] neg_lo:[0,0,1]
	v_pk_add_f32 v[202:203], v[6:7], v[38:39]
	v_pk_add_f32 v[6:7], v[6:7], v[38:39] neg_lo:[0,1] neg_hi:[0,1]
	v_pk_add_f32 v[204:205], v[22:23], v[54:55]
	v_pk_add_f32 v[22:23], v[22:23], v[54:55] neg_lo:[0,1] neg_hi:[0,1]
	v_pk_add_f32 v[38:39], v[202:203], v[204:205]
	v_pk_add_f32 v[54:55], v[202:203], v[204:205] neg_lo:[0,1] neg_hi:[0,1]
	v_pk_add_f32 v[202:203], v[6:7], v[22:23] op_sel:[0,1] op_sel_hi:[1,0] neg_hi:[0,1]
	v_pk_add_f32 v[204:205], v[6:7], v[22:23] op_sel:[0,1] op_sel_hi:[1,0] neg_lo:[0,1]
	v_pk_mul_f32 v[6:7], v[224:225], v[202:203] op_sel:[1,1] op_sel_hi:[1,0]
	v_pk_fma_f32 v[6:7], v[224:225], v[202:203], v[6:7] op_sel_hi:[0,1,1] neg_lo:[0,0,1]
	v_pk_mul_f32 v[22:23], v[226:227], v[54:55] op_sel:[1,1] op_sel_hi:[1,0]
	v_pk_fma_f32 v[22:23], v[226:227], v[54:55], v[22:23] op_sel_hi:[0,1,1] neg_lo:[0,0,1]
	v_pk_mul_f32 v[54:55], v[230:231], v[204:205] op_sel:[1,1] op_sel_hi:[1,0]
	v_pk_fma_f32 v[54:55], v[230:231], v[204:205], v[54:55] op_sel_hi:[0,1,1] neg_lo:[0,0,1]
	v_pk_add_f32 v[202:203], v[2:3], v[34:35]
	v_pk_add_f32 v[2:3], v[2:3], v[34:35] neg_lo:[0,1] neg_hi:[0,1]
	v_pk_add_f32 v[204:205], v[18:19], v[50:51]
	v_pk_add_f32 v[18:19], v[18:19], v[50:51] neg_lo:[0,1] neg_hi:[0,1]
	v_pk_add_f32 v[34:35], v[202:203], v[204:205]
	v_pk_add_f32 v[50:51], v[202:203], v[204:205] neg_lo:[0,1] neg_hi:[0,1]
	v_pk_add_f32 v[202:203], v[2:3], v[18:19] op_sel:[0,1] op_sel_hi:[1,0] neg_hi:[0,1]
	v_pk_add_f32 v[204:205], v[2:3], v[18:19] op_sel:[0,1] op_sel_hi:[1,0] neg_lo:[0,1]
	v_pk_mul_f32 v[2:3], v[224:225], v[202:203] op_sel:[1,1] op_sel_hi:[1,0]
	v_pk_fma_f32 v[2:3], v[224:225], v[202:203], v[2:3] op_sel_hi:[0,1,1] neg_lo:[0,0,1]
	v_pk_mul_f32 v[18:19], v[226:227], v[50:51] op_sel:[1,1] op_sel_hi:[1,0]
	v_pk_fma_f32 v[18:19], v[226:227], v[50:51], v[18:19] op_sel_hi:[0,1,1] neg_lo:[0,0,1]
	v_pk_mul_f32 v[50:51], v[230:231], v[204:205] op_sel:[1,1] op_sel_hi:[1,0]
	v_pk_fma_f32 v[50:51], v[230:231], v[204:205], v[50:51] op_sel_hi:[0,1,1] neg_lo:[0,0,1]
	v_pk_add_f32 v[202:203], v[4:5], v[36:37]
	v_pk_add_f32 v[4:5], v[4:5], v[36:37] neg_lo:[0,1] neg_hi:[0,1]
	v_pk_add_f32 v[204:205], v[20:21], v[52:53]
	v_pk_add_f32 v[20:21], v[20:21], v[52:53] neg_lo:[0,1] neg_hi:[0,1]
	v_pk_add_f32 v[36:37], v[202:203], v[204:205]
	v_pk_add_f32 v[52:53], v[202:203], v[204:205] neg_lo:[0,1] neg_hi:[0,1]
	v_pk_add_f32 v[202:203], v[4:5], v[20:21] op_sel:[0,1] op_sel_hi:[1,0] neg_hi:[0,1]
	v_pk_add_f32 v[204:205], v[4:5], v[20:21] op_sel:[0,1] op_sel_hi:[1,0] neg_lo:[0,1]
	v_pk_mul_f32 v[4:5], v[224:225], v[202:203] op_sel:[1,1] op_sel_hi:[1,0]
	v_pk_fma_f32 v[4:5], v[224:225], v[202:203], v[4:5] op_sel_hi:[0,1,1] neg_lo:[0,0,1]
	v_pk_mul_f32 v[20:21], v[226:227], v[52:53] op_sel:[1,1] op_sel_hi:[1,0]
	v_pk_fma_f32 v[20:21], v[226:227], v[52:53], v[20:21] op_sel_hi:[0,1,1] neg_lo:[0,0,1]
	v_pk_mul_f32 v[52:53], v[230:231], v[204:205] op_sel:[1,1] op_sel_hi:[1,0]
	v_pk_fma_f32 v[52:53], v[230:231], v[204:205], v[52:53] op_sel_hi:[0,1,1] neg_lo:[0,0,1]
	v_pk_add_f32 v[202:203], v[8:9], v[40:41]
	v_pk_add_f32 v[8:9], v[8:9], v[40:41] neg_lo:[0,1] neg_hi:[0,1]
	v_pk_add_f32 v[204:205], v[24:25], v[56:57]
	v_pk_add_f32 v[24:25], v[24:25], v[56:57] neg_lo:[0,1] neg_hi:[0,1]
	v_pk_add_f32 v[40:41], v[202:203], v[204:205]
	v_pk_add_f32 v[56:57], v[202:203], v[204:205] neg_lo:[0,1] neg_hi:[0,1]
	v_pk_add_f32 v[202:203], v[8:9], v[24:25] op_sel:[0,1] op_sel_hi:[1,0] neg_hi:[0,1]
	v_pk_add_f32 v[204:205], v[8:9], v[24:25] op_sel:[0,1] op_sel_hi:[1,0] neg_lo:[0,1]
	v_pk_mul_f32 v[8:9], v[224:225], v[202:203] op_sel:[1,1] op_sel_hi:[1,0]
	v_pk_fma_f32 v[8:9], v[224:225], v[202:203], v[8:9] op_sel_hi:[0,1,1] neg_lo:[0,0,1]
	v_pk_mul_f32 v[24:25], v[226:227], v[56:57] op_sel:[1,1] op_sel_hi:[1,0]
	v_pk_fma_f32 v[24:25], v[226:227], v[56:57], v[24:25] op_sel_hi:[0,1,1] neg_lo:[0,0,1]
; DI f32x2 cmul(f32x2 a, f32x2 b) { return mkf2(a.x * b.x - a.y * b.y, a.x * b.y + a.y * b.x); }
; DI void fft8192(f32x2* buf, const f32x2* __restrict__ tw) {
;     ...
; #pragma unroll
;     for (int e = 0; e < 8; ++e) {
;       const int i = tid + 256 * e;
;       const int q = i & (s - 1);
;       const int ps = i - q;
;       const float rev = (float)ps * (1.f / 8192.f);
;       const f32x2 w1 = mkf2(__builtin_amdgcn_cosf(rev), -__builtin_amdgcn_sinf(rev));
;       const f32x2 w2 = cmul(w1, w1), w3 = cmul(w1, w2);
;       const f32x2 apc = mkf2(a[e].x + c[e].x, a[e].y + c[e].y), amc = mkf2(a[e].x - c[e].x, a[e].y - c[e].y);
;       const f32x2 bpd = mkf2(b[e].x + d[e].x, b[e].y + d[e].y), bmd = mkf2(b[e].x - d[e].x, b[e].y - d[e].y);
;       const int o = 4 * i - 3 * q;
;       buf[SW(o)] = mkf2(apc.x + bpd.x, apc.y + bpd.y);
;       buf[SW(o + s)] = cmul(w1, mkf2(amc.x + bmd.y, amc.y - bmd.x));
;       buf[SW(o + 2 * s)] = cmul(w2, mkf2(apc.x - bpd.x, apc.y - bpd.y));
;       buf[SW(o + 3 * s)] = cmul(w3, mkf2(amc.x - bmd.y, amc.y + bmd.x));
;     }
	v_pk_mul_f32 v[56:57], v[230:231], v[204:205] op_sel:[1,1] op_sel_hi:[1,0]
	v_pk_fma_f32 v[56:57], v[230:231], v[204:205], v[56:57] op_sel_hi:[0,1,1] neg_lo:[0,0,1]
	v_mul_f32_e32 v214, 4.0, v201
	v_add_f32_e32 v214, 0x3e000000, v214
	v_cos_f32_e32 v224, v214
	v_sin_f32_e64 v225, -v214
	s_nop 0
	v_pk_mul_f32 v[206:207], v[224:225], v[224:225] op_sel:[1,1] op_sel_hi:[1,0]
	v_pk_fma_f32 v[226:227], v[224:225], v[224:225], v[206:207] op_sel_hi:[0,1,1] neg_lo:[0,0,1]
	v_pk_mul_f32 v[206:207], v[224:225], v[226:227] op_sel:[1,1] op_sel_hi:[1,0]
	v_pk_fma_f32 v[230:231], v[224:225], v[226:227], v[206:207] op_sel_hi:[0,1,1] neg_lo:[0,0,1]
	v_pk_add_f32 v[202:203], v[14:15], v[46:47]
	v_pk_add_f32 v[14:15], v[14:15], v[46:47] neg_lo:[0,1] neg_hi:[0,1]
	v_pk_add_f32 v[204:205], v[30:31], v[62:63]
	v_pk_add_f32 v[30:31], v[30:31], v[62:63] neg_lo:[0,1] neg_hi:[0,1]
	v_pk_add_f32 v[46:47], v[202:203], v[204:205]
	v_pk_add_f32 v[62:63], v[202:203], v[204:205] neg_lo:[0,1] neg_hi:[0,1]
	v_pk_add_f32 v[202:203], v[14:15], v[30:31] op_sel:[0,1] op_sel_hi:[1,0] neg_hi:[0,1]
	v_pk_add_f32 v[204:205], v[14:15], v[30:31] op_sel:[0,1] op_sel_hi:[1,0] neg_lo:[0,1]
	v_pk_mul_f32 v[14:15], v[224:225], v[202:203] op_sel:[1,1] op_sel_hi:[1,0]
	v_pk_fma_f32 v[14:15], v[224:225], v[202:203], v[14:15] op_sel_hi:[0,1,1] neg_lo:[0,0,1]
	v_pk_mul_f32 v[30:31], v[226:227], v[62:63] op_sel:[1,1] op_sel_hi:[1,0]
	v_pk_fma_f32 v[30:31], v[226:227], v[62:63], v[30:31] op_sel_hi:[0,1,1] neg_lo:[0,0,1]
	v_pk_mul_f32 v[62:63], v[230:231], v[204:205] op_sel:[1,1] op_sel_hi:[1,0]
	v_pk_fma_f32 v[62:63], v[230:231], v[204:205], v[62:63] op_sel_hi:[0,1,1] neg_lo:[0,0,1]
	v_pk_add_f32 v[202:203], v[10:11], v[42:43]
	v_pk_add_f32 v[10:11], v[10:11], v[42:43] neg_lo:[0,1] neg_hi:[0,1]
	v_pk_add_f32 v[204:205], v[26:27], v[58:59]
	v_pk_add_f32 v[26:27], v[26:27], v[58:59] neg_lo:[0,1] neg_hi:[0,1]
	v_pk_add_f32 v[42:43], v[202:203], v[204:205]
	v_pk_add_f32 v[58:59], v[202:203], v[204:205] neg_lo:[0,1] neg_hi:[0,1]
	v_pk_add_f32 v[202:203], v[10:11], v[26:27] op_sel:[0,1] op_sel_hi:[1,0] neg_hi:[0,1]
	v_pk_add_f32 v[204:205], v[10:11], v[26:27] op_sel:[0,1] op_sel_hi:[1,0] neg_lo:[0,1]
	v_pk_mul_f32 v[10:11], v[224:225], v[202:203] op_sel:[1,1] op_sel_hi:[1,0]
	v_pk_fma_f32 v[10:11], v[224:225], v[202:203], v[10:11] op_sel_hi:[0,1,1] neg_lo:[0,0,1]
	v_pk_mul_f32 v[26:27], v[226:227], v[58:59] op_sel:[1,1] op_sel_hi:[1,0]
	v_pk_fma_f32 v[26:27], v[226:227], v[58:59], v[26:27] op_sel_hi:[0,1,1] neg_lo:[0,0,1]
	v_pk_mul_f32 v[58:59], v[230:231], v[204:205] op_sel:[1,1] op_sel_hi:[1,0]
	v_pk_fma_f32 v[58:59], v[230:231], v[204:205], v[58:59] op_sel_hi:[0,1,1] neg_lo:[0,0,1]
	v_pk_add_f32 v[202:203], v[12:13], v[44:45]
	v_pk_add_f32 v[12:13], v[12:13], v[44:45] neg_lo:[0,1] neg_hi:[0,1]
	v_pk_add_f32 v[204:205], v[28:29], v[60:61]
	v_pk_add_f32 v[28:29], v[28:29], v[60:61] neg_lo:[0,1] neg_hi:[0,1]
	v_pk_add_f32 v[44:45], v[202:203], v[204:205]
	v_pk_add_f32 v[60:61], v[202:203], v[204:205] neg_lo:[0,1] neg_hi:[0,1]
	v_pk_add_f32 v[202:203], v[12:13], v[28:29] op_sel:[0,1] op_sel_hi:[1,0] neg_hi:[0,1]
	v_pk_add_f32 v[204:205], v[12:13], v[28:29] op_sel:[0,1] op_sel_hi:[1,0] neg_lo:[0,1]
	v_pk_mul_f32 v[12:13], v[224:225], v[202:203] op_sel:[1,1] op_sel_hi:[1,0]
	v_pk_fma_f32 v[12:13], v[224:225], v[202:203], v[12:13] op_sel_hi:[0,1,1] neg_lo:[0,0,1]
	v_pk_mul_f32 v[28:29], v[226:227], v[60:61] op_sel:[1,1] op_sel_hi:[1,0]
	v_pk_fma_f32 v[28:29], v[226:227], v[60:61], v[28:29] op_sel_hi:[0,1,1] neg_lo:[0,0,1]
	v_pk_mul_f32 v[60:61], v[230:231], v[204:205] op_sel:[1,1] op_sel_hi:[1,0]
	v_pk_fma_f32 v[60:61], v[230:231], v[204:205], v[60:61] op_sel_hi:[0,1,1] neg_lo:[0,0,1]
	v_pk_add_f32 v[202:203], v[16:17], v[48:49]
	v_pk_add_f32 v[16:17], v[16:17], v[48:49] neg_lo:[0,1] neg_hi:[0,1]
	v_pk_add_f32 v[204:205], v[32:33], v[64:65]
	v_pk_add_f32 v[32:33], v[32:33], v[64:65] neg_lo:[0,1] neg_hi:[0,1]
	v_pk_add_f32 v[48:49], v[202:203], v[204:205]
	v_pk_add_f32 v[64:65], v[202:203], v[204:205] neg_lo:[0,1] neg_hi:[0,1]
	v_pk_add_f32 v[202:203], v[16:17], v[32:33] op_sel:[0,1] op_sel_hi:[1,0] neg_hi:[0,1]
	v_pk_add_f32 v[204:205], v[16:17], v[32:33] op_sel:[0,1] op_sel_hi:[1,0] neg_lo:[0,1]
	v_pk_mul_f32 v[16:17], v[224:225], v[202:203] op_sel:[1,1] op_sel_hi:[1,0]
	v_pk_fma_f32 v[16:17], v[224:225], v[202:203], v[16:17] op_sel_hi:[0,1,1] neg_lo:[0,0,1]
	v_pk_mul_f32 v[32:33], v[226:227], v[64:65] op_sel:[1,1] op_sel_hi:[1,0]
	v_pk_fma_f32 v[32:33], v[226:227], v[64:65], v[32:33] op_sel_hi:[0,1,1] neg_lo:[0,0,1]
	v_pk_mul_f32 v[64:65], v[230:231], v[204:205] op_sel:[1,1] op_sel_hi:[1,0]
	v_pk_fma_f32 v[64:65], v[230:231], v[204:205], v[64:65] op_sel_hi:[0,1,1] neg_lo:[0,0,1]
	ds_write_b64 v164, v[38:39] offset:0
	v_xor_b32_e32 v156, 0x80, v164
	ds_write_b64 v156, v[34:35] offset:0
	v_xor_b32_e32 v158, 0x128, v164
	ds_write_b64 v158, v[36:37] offset:0
	v_xor_b32_e32 v160, 0x1a8, v164
	ds_write_b64 v160, v[40:41] offset:0
	v_xor_b32_e32 v162, 0x2d0, v164
	ds_write_b64 v162, v[6:7] offset:0
	v_xor_b32_e32 v156, 0x250, v164
	ds_write_b64 v156, v[2:3] offset:0
	v_xor_b32_e32 v158, 0x3f8, v164
	ds_write_b64 v158, v[4:5] offset:0
	v_xor_b32_e32 v160, 0x378, v164
	ds_write_b64 v160, v[8:9] offset:0
	v_xor_b32_e32 v162, 0x400, v164
	ds_write_b64 v162, v[22:23] offset:0
	v_xor_b32_e32 v156, 0x480, v164
	ds_write_b64 v156, v[18:19] offset:0
	v_xor_b32_e32 v158, 0x528, v164
	ds_write_b64 v158, v[20:21] offset:0
	v_xor_b32_e32 v160, 0x5a8, v164
	ds_write_b64 v160, v[24:25] offset:0
	v_xor_b32_e32 v162, 0x6d0, v164
	ds_write_b64 v162, v[54:55] offset:0
	v_xor_b32_e32 v156, 0x650, v164
	ds_write_b64 v156, v[50:51] offset:0
	v_xor_b32_e32 v158, 0x7f8, v164
	ds_write_b64 v158, v[52:53] offset:0
	v_xor_b32_e32 v160, 0x778, v164
	ds_write_b64 v160, v[56:57] offset:0
	ds_write_b64 v164, v[46:47] offset:32768
	v_xor_b32_e32 v162, 0x80, v164
	ds_write_b64 v162, v[42:43] offset:32768
	v_xor_b32_e32 v156, 0x128, v164
	ds_write_b64 v156, v[44:45] offset:32768
	v_xor_b32_e32 v158, 0x1a8, v164
	ds_write_b64 v158, v[48:49] offset:32768
	v_xor_b32_e32 v160, 0x2d0, v164
	ds_write_b64 v160, v[14:15] offset:32768
	v_xor_b32_e32 v162, 0x250, v164
	ds_write_b64 v162, v[10:11] offset:32768
	v_xor_b32_e32 v156, 0x3f8, v164
	ds_write_b64 v156, v[12:13] offset:32768
	v_xor_b32_e32 v158, 0x378, v164
	ds_write_b64 v158, v[16:17] offset:32768
	v_xor_b32_e32 v160, 0x400, v164
	ds_write_b64 v160, v[30:31] offset:32768
	v_xor_b32_e32 v162, 0x480, v164
	ds_write_b64 v162, v[26:27] offset:32768
	v_xor_b32_e32 v156, 0x528, v164
	ds_write_b64 v156, v[28:29] offset:32768
	v_xor_b32_e32 v158, 0x5a8, v164
	ds_write_b64 v158, v[32:33] offset:32768
	v_xor_b32_e32 v160, 0x6d0, v164
	ds_write_b64 v160, v[62:63] offset:32768
	v_xor_b32_e32 v162, 0x650, v164
	ds_write_b64 v162, v[58:59] offset:32768
	v_xor_b32_e32 v156, 0x7f8, v164
	ds_write_b64 v156, v[60:61] offset:32768
	v_xor_b32_e32 v158, 0x778, v164
	ds_write_b64 v158, v[64:65] offset:32768
	s_waitcnt lgkmcnt(0)
	s_barrier
; DI f32x2 cmul(f32x2 a, f32x2 b) { return mkf2(a.x * b.x - a.y * b.y, a.x * b.y + a.y * b.x); }
; DI void fft8192(f32x2* buf, const f32x2* __restrict__ tw) {
;     ...
; #pragma unroll
;     for (int e = 0; e < 8; ++e) {
;       const int i = tid + 256 * e;
;       const int pi = SW(i);
;       a[e] = buf[pi]; b[e] = buf[pi + 2048]; c[e] = buf[pi + 4096]; d[e] = buf[pi + 6144];
;     }
;     __syncthreads();
; #pragma unroll
;     for (int e = 0; e < 8; ++e) {
;       const int i = tid + 256 * e;
;       const int q = i & (s - 1);
;       const int ps = i - q;
;       const float rev = (float)ps * (1.f / 8192.f);
;       const f32x2 w1 = mkf2(__builtin_amdgcn_cosf(rev), -__builtin_amdgcn_sinf(rev));
;       const f32x2 w2 = cmul(w1, w1), w3 = cmul(w1, w2);
;       const f32x2 apc = mkf2(a[e].x + c[e].x, a[e].y + c[e].y), amc = mkf2(a[e].x - c[e].x, a[e].y - c[e].y);
;       const f32x2 bpd = mkf2(b[e].x + d[e].x, b[e].y + d[e].y), bmd = mkf2(b[e].x - d[e].x, b[e].y - d[e].y);
;       const int o = 4 * i - 3 * q;
;       buf[SW(o)] = mkf2(apc.x + bpd.x, apc.y + bpd.y);
;       buf[SW(o + s)] = cmul(w1, mkf2(amc.x + bmd.y, amc.y - bmd.x));
;       buf[SW(o + 2 * s)] = cmul(w2, mkf2(apc.x - bpd.x, apc.y - bpd.y));
;       buf[SW(o + 3 * s)] = cmul(w3, mkf2(amc.x - bmd.y, amc.y + bmd.x));
;     }
	ds_read2st64_b64 v[2:5], v154 offset0:0 offset1:32
	ds_read2st64_b64 v[6:9], v154 offset0:64 offset1:96
	ds_read2st64_b64 v[10:13], v154 offset0:4 offset1:36
	ds_read2st64_b64 v[14:17], v154 offset0:68 offset1:100
	ds_read2st64_b64 v[18:21], v154 offset0:8 offset1:40
	ds_read2st64_b64 v[22:25], v154 offset0:72 offset1:104
	ds_read2st64_b64 v[26:29], v154 offset0:12 offset1:44
	ds_read2st64_b64 v[30:33], v154 offset0:76 offset1:108
	ds_read2st64_b64 v[34:37], v154 offset0:16 offset1:48
	ds_read2st64_b64 v[38:41], v154 offset0:80 offset1:112
	ds_read2st64_b64 v[42:45], v154 offset0:20 offset1:52
	ds_read2st64_b64 v[46:49], v154 offset0:84 offset1:116
	ds_read2st64_b64 v[50:53], v154 offset0:24 offset1:56
	ds_read2st64_b64 v[54:57], v154 offset0:88 offset1:120
	ds_read2st64_b64 v[58:61], v154 offset0:28 offset1:60
	ds_read2st64_b64 v[62:65], v154 offset0:92 offset1:124
	s_waitcnt lgkmcnt(14)
	v_pk_add_f32 v[202:203], v[2:3], v[6:7]
	v_pk_add_f32 v[2:3], v[2:3], v[6:7] neg_lo:[0,1] neg_hi:[0,1]
	v_pk_add_f32 v[204:205], v[4:5], v[8:9]
	v_pk_add_f32 v[4:5], v[4:5], v[8:9] neg_lo:[0,1] neg_hi:[0,1]
	v_pk_add_f32 v[6:7], v[202:203], v[204:205]
	v_pk_add_f32 v[8:9], v[202:203], v[204:205] neg_lo:[0,1] neg_hi:[0,1]
	v_pk_add_f32 v[202:203], v[2:3], v[4:5] op_sel:[0,1] op_sel_hi:[1,0] neg_hi:[0,1]
	v_pk_add_f32 v[4:5], v[2:3], v[4:5] op_sel:[0,1] op_sel_hi:[1,0] neg_lo:[0,1]
	v_pk_mov_b32 v[2:3], v[202:203], v[202:203] op_sel:[0,1]
	v_cos_f32_e32 v210, 0x3d000000
	v_sin_f32_e32 v211, 0xbd000000
	s_waitcnt lgkmcnt(12)
	v_pk_add_f32 v[202:203], v[10:11], v[14:15]
	v_pk_add_f32 v[10:11], v[10:11], v[14:15] neg_lo:[0,1] neg_hi:[0,1]
	v_pk_add_f32 v[204:205], v[12:13], v[16:17]
	v_pk_add_f32 v[12:13], v[12:13], v[16:17] neg_lo:[0,1] neg_hi:[0,1]
	v_pk_add_f32 v[14:15], v[202:203], v[204:205]
	v_pk_add_f32 v[16:17], v[202:203], v[204:205] neg_lo:[0,1] neg_hi:[0,1]
	v_pk_add_f32 v[202:203], v[10:11], v[12:13] op_sel:[0,1] op_sel_hi:[1,0] neg_hi:[0,1]
	v_pk_add_f32 v[204:205], v[10:11], v[12:13] op_sel:[0,1] op_sel_hi:[1,0] neg_lo:[0,1]
	v_pk_mul_f32 v[206:207], v[210:211], v[210:211] op_sel:[1,1] op_sel_hi:[1,0]
	v_pk_fma_f32 v[212:213], v[210:211], v[210:211], v[206:207] op_sel_hi:[0,1,1] neg_lo:[0,0,1]
	v_pk_mul_f32 v[206:207], v[210:211], v[212:213] op_sel:[1,1] op_sel_hi:[1,0]
	v_pk_fma_f32 v[220:221], v[210:211], v[212:213], v[206:207] op_sel_hi:[0,1,1] neg_lo:[0,0,1]
	v_pk_mul_f32 v[10:11], v[210:211], v[202:203] op_sel:[1,1] op_sel_hi:[1,0]
	v_pk_fma_f32 v[10:11], v[210:211], v[202:203], v[10:11] op_sel_hi:[0,1,1] neg_lo:[0,0,1]
	v_pk_mul_f32 v[12:13], v[212:213], v[16:17] op_sel:[1,1] op_sel_hi:[1,0]
	v_pk_fma_f32 v[12:13], v[212:213], v[16:17], v[12:13] op_sel_hi:[0,1,1] neg_lo:[0,0,1]
	v_pk_mul_f32 v[16:17], v[220:221], v[204:205] op_sel:[1,1] op_sel_hi:[1,0]
	v_pk_fma_f32 v[16:17], v[220:221], v[204:205], v[16:17] op_sel_hi:[0,1,1] neg_lo:[0,0,1]
	v_cos_f32_e32 v210, 0x3d800000
	v_sin_f32_e32 v211, 0xbd800000
	s_waitcnt lgkmcnt(10)
	v_pk_add_f32 v[202:203], v[18:19], v[22:23]
	v_pk_add_f32 v[18:19], v[18:19], v[22:23] neg_lo:[0,1] neg_hi:[0,1]
	v_pk_add_f32 v[204:205], v[20:21], v[24:25]
	v_pk_add_f32 v[20:21], v[20:21], v[24:25] neg_lo:[0,1] neg_hi:[0,1]
	v_pk_add_f32 v[22:23], v[202:203], v[204:205]
	v_pk_add_f32 v[24:25], v[202:203], v[204:205] neg_lo:[0,1] neg_hi:[0,1]
	v_pk_add_f32 v[202:203], v[18:19], v[20:21] op_sel:[0,1] op_sel_hi:[1,0] neg_hi:[0,1]
	v_pk_add_f32 v[204:205], v[18:19], v[20:21] op_sel:[0,1] op_sel_hi:[1,0] neg_lo:[0,1]
	v_pk_mul_f32 v[206:207], v[210:211], v[210:211] op_sel:[1,1] op_sel_hi:[1,0]
	v_pk_fma_f32 v[212:213], v[210:211], v[210:211], v[206:207] op_sel_hi:[0,1,1] neg_lo:[0,0,1]
	v_pk_mul_f32 v[206:207], v[210:211], v[212:213] op_sel:[1,1] op_sel_hi:[1,0]
	v_pk_fma_f32 v[220:221], v[210:211], v[212:213], v[206:207] op_sel_hi:[0,1,1] neg_lo:[0,0,1]
	v_pk_mul_f32 v[18:19], v[210:211], v[202:203] op_sel:[1,1] op_sel_hi:[1,0]
	v_pk_fma_f32 v[18:19], v[210:211], v[202:203], v[18:19] op_sel_hi:[0,1,1] neg_lo:[0,0,1]
	v_pk_mul_f32 v[20:21], v[212:213], v[24:25] op_sel:[1,1] op_sel_hi:[1,0]
	v_pk_fma_f32 v[20:21], v[212:213], v[24:25], v[20:21] op_sel_hi:[0,1,1] neg_lo:[0,0,1]
	v_pk_mul_f32 v[24:25], v[220:221], v[204:205] op_sel:[1,1] op_sel_hi:[1,0]
	v_pk_fma_f32 v[24:25], v[220:221], v[204:205], v[24:25] op_sel_hi:[0,1,1] neg_lo:[0,0,1]
	v_cos_f32_e32 v210, 0x3dc00000
	v_sin_f32_e32 v211, 0xbdc00000
	s_waitcnt lgkmcnt(8)
	v_pk_add_f32 v[202:203], v[26:27], v[30:31]
	v_pk_add_f32 v[26:27], v[26:27], v[30:31] neg_lo:[0,1] neg_hi:[0,1]
	v_pk_add_f32 v[204:205], v[28:29], v[32:33]
	v_pk_add_f32 v[28:29], v[28:29], v[32:33] neg_lo:[0,1] neg_hi:[0,1]
	v_pk_add_f32 v[30:31], v[202:203], v[204:205]
	v_pk_add_f32 v[32:33], v[202:203], v[204:205] neg_lo:[0,1] neg_hi:[0,1]
	v_pk_add_f32 v[202:203], v[26:27], v[28:29] op_sel:[0,1] op_sel_hi:[1,0] neg_hi:[0,1]
	v_pk_add_f32 v[204:205], v[26:27], v[28:29] op_sel:[0,1] op_sel_hi:[1,0] neg_lo:[0,1]
	v_pk_mul_f32 v[206:207], v[210:211], v[210:211] op_sel:[1,1] op_sel_hi:[1,0]
	v_pk_fma_f32 v[212:213], v[210:211], v[210:211], v[206:207] op_sel_hi:[0,1,1] neg_lo:[0,0,1]
	v_pk_mul_f32 v[206:207], v[210:211], v[212:213] op_sel:[1,1] op_sel_hi:[1,0]
	v_pk_fma_f32 v[220:221], v[210:211], v[212:213], v[206:207] op_sel_hi:[0,1,1] neg_lo:[0,0,1]
	v_pk_mul_f32 v[26:27], v[210:211], v[202:203] op_sel:[1,1] op_sel_hi:[1,0]
	v_pk_fma_f32 v[26:27], v[210:211], v[202:203], v[26:27] op_sel_hi:[0,1,1] neg_lo:[0,0,1]
	v_pk_mul_f32 v[28:29], v[212:213], v[32:33] op_sel:[1,1] op_sel_hi:[1,0]
	v_pk_fma_f32 v[28:29], v[212:213], v[32:33], v[28:29] op_sel_hi:[0,1,1] neg_lo:[0,0,1]
	v_pk_mul_f32 v[32:33], v[220:221], v[204:205] op_sel:[1,1] op_sel_hi:[1,0]
	v_pk_fma_f32 v[32:33], v[220:221], v[204:205], v[32:33] op_sel_hi:[0,1,1] neg_lo:[0,0,1]
	v_cos_f32_e32 v210, 0x3e000000
	v_sin_f32_e32 v211, 0xbe000000
	s_waitcnt lgkmcnt(6)
; DI f32x2 cmul(f32x2 a, f32x2 b) { return mkf2(a.x * b.x - a.y * b.y, a.x * b.y + a.y * b.x); }
; DI void fft8192(f32x2* buf, const f32x2* __restrict__ tw) {
;     ...
; #pragma unroll
;     for (int e = 0; e < 8; ++e) {
;       const int i = tid + 256 * e;
;       const int q = i & (s - 1);
;       const int ps = i - q;
;       const float rev = (float)ps * (1.f / 8192.f);
;       const f32x2 w1 = mkf2(__builtin_amdgcn_cosf(rev), -__builtin_amdgcn_sinf(rev));
;       const f32x2 w2 = cmul(w1, w1), w3 = cmul(w1, w2);
;       const f32x2 apc = mkf2(a[e].x + c[e].x, a[e].y + c[e].y), amc = mkf2(a[e].x - c[e].x, a[e].y - c[e].y);
;       const f32x2 bpd = mkf2(b[e].x + d[e].x, b[e].y + d[e].y), bmd = mkf2(b[e].x - d[e].x, b[e].y - d[e].y);
;       const int o = 4 * i - 3 * q;
;       buf[SW(o)] = mkf2(apc.x + bpd.x, apc.y + bpd.y);
;       buf[SW(o + s)] = cmul(w1, mkf2(amc.x + bmd.y, amc.y - bmd.x));
;       buf[SW(o + 2 * s)] = cmul(w2, mkf2(apc.x - bpd.x, apc.y - bpd.y));
;       buf[SW(o + 3 * s)] = cmul(w3, mkf2(amc.x - bmd.y, amc.y + bmd.x));
;     }
	v_pk_add_f32 v[202:203], v[34:35], v[38:39]
	v_pk_add_f32 v[34:35], v[34:35], v[38:39] neg_lo:[0,1] neg_hi:[0,1]
	v_pk_add_f32 v[204:205], v[36:37], v[40:41]
	v_pk_add_f32 v[36:37], v[36:37], v[40:41] neg_lo:[0,1] neg_hi:[0,1]
	v_pk_add_f32 v[38:39], v[202:203], v[204:205]
	v_pk_add_f32 v[40:41], v[202:203], v[204:205] neg_lo:[0,1] neg_hi:[0,1]
	v_pk_add_f32 v[202:203], v[34:35], v[36:37] op_sel:[0,1] op_sel_hi:[1,0] neg_hi:[0,1]
	v_pk_add_f32 v[204:205], v[34:35], v[36:37] op_sel:[0,1] op_sel_hi:[1,0] neg_lo:[0,1]
	v_pk_mul_f32 v[206:207], v[210:211], v[210:211] op_sel:[1,1] op_sel_hi:[1,0]
	v_pk_fma_f32 v[212:213], v[210:211], v[210:211], v[206:207] op_sel_hi:[0,1,1] neg_lo:[0,0,1]
	v_pk_mul_f32 v[206:207], v[210:211], v[212:213] op_sel:[1,1] op_sel_hi:[1,0]
	v_pk_fma_f32 v[220:221], v[210:211], v[212:213], v[206:207] op_sel_hi:[0,1,1] neg_lo:[0,0,1]
	v_pk_mul_f32 v[34:35], v[210:211], v[202:203] op_sel:[1,1] op_sel_hi:[1,0]
	v_pk_fma_f32 v[34:35], v[210:211], v[202:203], v[34:35] op_sel_hi:[0,1,1] neg_lo:[0,0,1]
	v_pk_mul_f32 v[36:37], v[212:213], v[40:41] op_sel:[1,1] op_sel_hi:[1,0]
	v_pk_fma_f32 v[36:37], v[212:213], v[40:41], v[36:37] op_sel_hi:[0,1,1] neg_lo:[0,0,1]
	v_pk_mul_f32 v[40:41], v[220:221], v[204:205] op_sel:[1,1] op_sel_hi:[1,0]
	v_pk_fma_f32 v[40:41], v[220:221], v[204:205], v[40:41] op_sel_hi:[0,1,1] neg_lo:[0,0,1]
	v_cos_f32_e32 v210, 0x3e200000
	v_sin_f32_e32 v211, 0xbe200000
	s_waitcnt lgkmcnt(4)
	v_pk_add_f32 v[202:203], v[42:43], v[46:47]
	v_pk_add_f32 v[42:43], v[42:43], v[46:47] neg_lo:[0,1] neg_hi:[0,1]
	v_pk_add_f32 v[204:205], v[44:45], v[48:49]
	v_pk_add_f32 v[44:45], v[44:45], v[48:49] neg_lo:[0,1] neg_hi:[0,1]
	v_pk_add_f32 v[46:47], v[202:203], v[204:205]
	v_pk_add_f32 v[48:49], v[202:203], v[204:205] neg_lo:[0,1] neg_hi:[0,1]
	v_pk_add_f32 v[202:203], v[42:43], v[44:45] op_sel:[0,1] op_sel_hi:[1,0] neg_hi:[0,1]
	v_pk_add_f32 v[204:205], v[42:43], v[44:45] op_sel:[0,1] op_sel_hi:[1,0] neg_lo:[0,1]
	v_pk_mul_f32 v[206:207], v[210:211], v[210:211] op_sel:[1,1] op_sel_hi:[1,0]
	v_pk_fma_f32 v[212:213], v[210:211], v[210:211], v[206:207] op_sel_hi:[0,1,1] neg_lo:[0,0,1]
	v_pk_mul_f32 v[206:207], v[210:211], v[212:213] op_sel:[1,1] op_sel_hi:[1,0]
	v_pk_fma_f32 v[220:221], v[210:211], v[212:213], v[206:207] op_sel_hi:[0,1,1] neg_lo:[0,0,1]
	v_pk_mul_f32 v[42:43], v[210:211], v[202:203] op_sel:[1,1] op_sel_hi:[1,0]
	v_pk_fma_f32 v[42:43], v[210:211], v[202:203], v[42:43] op_sel_hi:[0,1,1] neg_lo:[0,0,1]
	v_pk_mul_f32 v[44:45], v[212:213], v[48:49] op_sel:[1,1] op_sel_hi:[1,0]
	v_pk_fma_f32 v[44:45], v[212:213], v[48:49], v[44:45] op_sel_hi:[0,1,1] neg_lo:[0,0,1]
	v_pk_mul_f32 v[48:49], v[220:221], v[204:205] op_sel:[1,1] op_sel_hi:[1,0]
	v_pk_fma_f32 v[48:49], v[220:221], v[204:205], v[48:49] op_sel_hi:[0,1,1] neg_lo:[0,0,1]
	v_cos_f32_e32 v210, 0x3e400000
	v_sin_f32_e32 v211, 0xbe400000
	s_waitcnt lgkmcnt(2)
	v_pk_add_f32 v[202:203], v[50:51], v[54:55]
	v_pk_add_f32 v[50:51], v[50:51], v[54:55] neg_lo:[0,1] neg_hi:[0,1]
	v_pk_add_f32 v[204:205], v[52:53], v[56:57]
	v_pk_add_f32 v[52:53], v[52:53], v[56:57] neg_lo:[0,1] neg_hi:[0,1]
	v_pk_add_f32 v[54:55], v[202:203], v[204:205]
	v_pk_add_f32 v[56:57], v[202:203], v[204:205] neg_lo:[0,1] neg_hi:[0,1]
	v_pk_add_f32 v[202:203], v[50:51], v[52:53] op_sel:[0,1] op_sel_hi:[1,0] neg_hi:[0,1]
	v_pk_add_f32 v[204:205], v[50:51], v[52:53] op_sel:[0,1] op_sel_hi:[1,0] neg_lo:[0,1]
	v_pk_mul_f32 v[206:207], v[210:211], v[210:211] op_sel:[1,1] op_sel_hi:[1,0]
	v_pk_fma_f32 v[212:213], v[210:211], v[210:211], v[206:207] op_sel_hi:[0,1,1] neg_lo:[0,0,1]
	v_pk_mul_f32 v[206:207], v[210:211], v[212:213] op_sel:[1,1] op_sel_hi:[1,0]
	v_pk_fma_f32 v[220:221], v[210:211], v[212:213], v[206:207] op_sel_hi:[0,1,1] neg_lo:[0,0,1]
	v_pk_mul_f32 v[50:51], v[210:211], v[202:203] op_sel:[1,1] op_sel_hi:[1,0]
	v_pk_fma_f32 v[50:51], v[210:211], v[202:203], v[50:51] op_sel_hi:[0,1,1] neg_lo:[0,0,1]
	v_pk_mul_f32 v[52:53], v[212:213], v[56:57] op_sel:[1,1] op_sel_hi:[1,0]
	v_pk_fma_f32 v[52:53], v[212:213], v[56:57], v[52:53] op_sel_hi:[0,1,1] neg_lo:[0,0,1]
	v_pk_mul_f32 v[56:57], v[220:221], v[204:205] op_sel:[1,1] op_sel_hi:[1,0]
	v_pk_fma_f32 v[56:57], v[220:221], v[204:205], v[56:57] op_sel_hi:[0,1,1] neg_lo:[0,0,1]
	v_cos_f32_e32 v210, 0x3e600000
	v_sin_f32_e32 v211, 0xbe600000
	s_waitcnt lgkmcnt(0)
	v_pk_add_f32 v[202:203], v[58:59], v[62:63]
	v_pk_add_f32 v[58:59], v[58:59], v[62:63] neg_lo:[0,1] neg_hi:[0,1]
	v_pk_add_f32 v[204:205], v[60:61], v[64:65]
	v_pk_add_f32 v[60:61], v[60:61], v[64:65] neg_lo:[0,1] neg_hi:[0,1]
	v_pk_add_f32 v[62:63], v[202:203], v[204:205]
	v_pk_add_f32 v[64:65], v[202:203], v[204:205] neg_lo:[0,1] neg_hi:[0,1]
	v_pk_add_f32 v[202:203], v[58:59], v[60:61] op_sel:[0,1] op_sel_hi:[1,0] neg_hi:[0,1]
	v_pk_add_f32 v[204:205], v[58:59], v[60:61] op_sel:[0,1] op_sel_hi:[1,0] neg_lo:[0,1]
	v_pk_mul_f32 v[206:207], v[210:211], v[210:211] op_sel:[1,1] op_sel_hi:[1,0]
	v_pk_fma_f32 v[212:213], v[210:211], v[210:211], v[206:207] op_sel_hi:[0,1,1] neg_lo:[0,0,1]
	v_pk_mul_f32 v[206:207], v[210:211], v[212:213] op_sel:[1,1] op_sel_hi:[1,0]
	v_pk_fma_f32 v[220:221], v[210:211], v[212:213], v[206:207] op_sel_hi:[0,1,1] neg_lo:[0,0,1]
	v_pk_mul_f32 v[58:59], v[210:211], v[202:203] op_sel:[1,1] op_sel_hi:[1,0]
	v_pk_fma_f32 v[58:59], v[210:211], v[202:203], v[58:59] op_sel_hi:[0,1,1] neg_lo:[0,0,1]
	v_pk_mul_f32 v[60:61], v[212:213], v[64:65] op_sel:[1,1] op_sel_hi:[1,0]
	v_pk_fma_f32 v[60:61], v[212:213], v[64:65], v[60:61] op_sel_hi:[0,1,1] neg_lo:[0,0,1]
	v_pk_mul_f32 v[64:65], v[220:221], v[204:205] op_sel:[1,1] op_sel_hi:[1,0]
	v_pk_fma_f32 v[64:65], v[220:221], v[204:205], v[64:65] op_sel_hi:[0,1,1] neg_lo:[0,0,1]
	s_barrier
; DI f32x2 cmul(f32x2 a, f32x2 b) { return mkf2(a.x * b.x - a.y * b.y, a.x * b.y + a.y * b.x); }
; DI void fft8192(f32x2* buf, const f32x2* __restrict__ tw) {
;     ...
; #pragma unroll
;     for (int e = 0; e < 8; ++e) {
;       const int i = tid + 256 * e;
;       const int q = i & (s - 1);
;       const int ps = i - q;
;       const float rev = (float)ps * (1.f / 8192.f);
;       const f32x2 w1 = mkf2(__builtin_amdgcn_cosf(rev), -__builtin_amdgcn_sinf(rev));
;       const f32x2 w2 = cmul(w1, w1), w3 = cmul(w1, w2);
;       const f32x2 apc = mkf2(a[e].x + c[e].x, a[e].y + c[e].y), amc = mkf2(a[e].x - c[e].x, a[e].y - c[e].y);
;       const f32x2 bpd = mkf2(b[e].x + d[e].x, b[e].y + d[e].y), bmd = mkf2(b[e].x - d[e].x, b[e].y - d[e].y);
;       const int o = 4 * i - 3 * q;
;       buf[SW(o)] = mkf2(apc.x + bpd.x, apc.y + bpd.y);
;       buf[SW(o + s)] = cmul(w1, mkf2(amc.x + bmd.y, amc.y - bmd.x));
;       buf[SW(o + 2 * s)] = cmul(w2, mkf2(apc.x - bpd.x, apc.y - bpd.y));
;       buf[SW(o + 3 * s)] = cmul(w3, mkf2(amc.x - bmd.y, amc.y + bmd.x));
;     }
	v_pk_add_f32 v[202:203], v[6:7], v[38:39]
	v_pk_add_f32 v[6:7], v[6:7], v[38:39] neg_lo:[0,1] neg_hi:[0,1]
	v_pk_add_f32 v[204:205], v[22:23], v[54:55]
	v_pk_add_f32 v[22:23], v[22:23], v[54:55] neg_lo:[0,1] neg_hi:[0,1]
	v_pk_add_f32 v[38:39], v[202:203], v[204:205]
	v_pk_add_f32 v[54:55], v[202:203], v[204:205] neg_lo:[0,1] neg_hi:[0,1]
	v_pk_add_f32 v[202:203], v[6:7], v[22:23] op_sel:[0,1] op_sel_hi:[1,0] neg_hi:[0,1]
	v_pk_add_f32 v[22:23], v[6:7], v[22:23] op_sel:[0,1] op_sel_hi:[1,0] neg_lo:[0,1]
	v_pk_mov_b32 v[6:7], v[202:203], v[202:203] op_sel:[0,1]
	v_pk_add_f32 v[202:203], v[2:3], v[34:35]
	v_pk_add_f32 v[2:3], v[2:3], v[34:35] neg_lo:[0,1] neg_hi:[0,1]
	v_pk_add_f32 v[204:205], v[18:19], v[50:51]
	v_pk_add_f32 v[18:19], v[18:19], v[50:51] neg_lo:[0,1] neg_hi:[0,1]
	v_pk_add_f32 v[34:35], v[202:203], v[204:205]
	v_pk_add_f32 v[50:51], v[202:203], v[204:205] neg_lo:[0,1] neg_hi:[0,1]
	v_pk_add_f32 v[202:203], v[2:3], v[18:19] op_sel:[0,1] op_sel_hi:[1,0] neg_hi:[0,1]
	v_pk_add_f32 v[18:19], v[2:3], v[18:19] op_sel:[0,1] op_sel_hi:[1,0] neg_lo:[0,1]
	v_pk_mov_b32 v[2:3], v[202:203], v[202:203] op_sel:[0,1]
	v_pk_add_f32 v[202:203], v[8:9], v[36:37]
	v_pk_add_f32 v[8:9], v[8:9], v[36:37] neg_lo:[0,1] neg_hi:[0,1]
	v_pk_add_f32 v[204:205], v[20:21], v[52:53]
	v_pk_add_f32 v[20:21], v[20:21], v[52:53] neg_lo:[0,1] neg_hi:[0,1]
	v_pk_add_f32 v[36:37], v[202:203], v[204:205]
	v_pk_add_f32 v[52:53], v[202:203], v[204:205] neg_lo:[0,1] neg_hi:[0,1]
	v_pk_add_f32 v[202:203], v[8:9], v[20:21] op_sel:[0,1] op_sel_hi:[1,0] neg_hi:[0,1]
	v_pk_add_f32 v[20:21], v[8:9], v[20:21] op_sel:[0,1] op_sel_hi:[1,0] neg_lo:[0,1]
	v_pk_mov_b32 v[8:9], v[202:203], v[202:203] op_sel:[0,1]
	v_pk_add_f32 v[202:203], v[4:5], v[40:41]
	v_pk_add_f32 v[4:5], v[4:5], v[40:41] neg_lo:[0,1] neg_hi:[0,1]
	v_pk_add_f32 v[204:205], v[24:25], v[56:57]
	v_pk_add_f32 v[24:25], v[24:25], v[56:57] neg_lo:[0,1] neg_hi:[0,1]
	v_pk_add_f32 v[40:41], v[202:203], v[204:205]
	v_pk_add_f32 v[56:57], v[202:203], v[204:205] neg_lo:[0,1] neg_hi:[0,1]
	v_pk_add_f32 v[202:203], v[4:5], v[24:25] op_sel:[0,1] op_sel_hi:[1,0] neg_hi:[0,1]
	v_pk_add_f32 v[24:25], v[4:5], v[24:25] op_sel:[0,1] op_sel_hi:[1,0] neg_lo:[0,1]
	v_pk_mov_b32 v[4:5], v[202:203], v[202:203] op_sel:[0,1]
	v_cos_f32_e32 v224, 0x3e000000
	v_sin_f32_e32 v225, 0xbe000000
	s_nop 0
	v_pk_mul_f32 v[206:207], v[224:225], v[224:225] op_sel:[1,1] op_sel_hi:[1,0]
	v_pk_fma_f32 v[226:227], v[224:225], v[224:225], v[206:207] op_sel_hi:[0,1,1] neg_lo:[0,0,1]
	v_pk_mul_f32 v[206:207], v[224:225], v[226:227] op_sel:[1,1] op_sel_hi:[1,0]
	v_pk_fma_f32 v[230:231], v[224:225], v[226:227], v[206:207] op_sel_hi:[0,1,1] neg_lo:[0,0,1]
	v_pk_add_f32 v[202:203], v[14:15], v[46:47]
	v_pk_add_f32 v[14:15], v[14:15], v[46:47] neg_lo:[0,1] neg_hi:[0,1]
	v_pk_add_f32 v[204:205], v[30:31], v[62:63]
	v_pk_add_f32 v[30:31], v[30:31], v[62:63] neg_lo:[0,1] neg_hi:[0,1]
	v_pk_add_f32 v[46:47], v[202:203], v[204:205]
	v_pk_add_f32 v[62:63], v[202:203], v[204:205] neg_lo:[0,1] neg_hi:[0,1]
	v_pk_add_f32 v[202:203], v[14:15], v[30:31] op_sel:[0,1] op_sel_hi:[1,0] neg_hi:[0,1]
	v_pk_add_f32 v[204:205], v[14:15], v[30:31] op_sel:[0,1] op_sel_hi:[1,0] neg_lo:[0,1]
	v_pk_mul_f32 v[14:15], v[224:225], v[202:203] op_sel:[1,1] op_sel_hi:[1,0]
	v_pk_fma_f32 v[14:15], v[224:225], v[202:203], v[14:15] op_sel_hi:[0,1,1] neg_lo:[0,0,1]
	v_pk_mul_f32 v[30:31], v[226:227], v[62:63] op_sel:[1,1] op_sel_hi:[1,0]
	v_pk_fma_f32 v[30:31], v[226:227], v[62:63], v[30:31] op_sel_hi:[0,1,1] neg_lo:[0,0,1]
	v_pk_mul_f32 v[62:63], v[230:231], v[204:205] op_sel:[1,1] op_sel_hi:[1,0]
	v_pk_fma_f32 v[62:63], v[230:231], v[204:205], v[62:63] op_sel_hi:[0,1,1] neg_lo:[0,0,1]
	v_pk_add_f32 v[202:203], v[10:11], v[42:43]
	v_pk_add_f32 v[10:11], v[10:11], v[42:43] neg_lo:[0,1] neg_hi:[0,1]
	v_pk_add_f32 v[204:205], v[26:27], v[58:59]
	v_pk_add_f32 v[26:27], v[26:27], v[58:59] neg_lo:[0,1] neg_hi:[0,1]
	v_pk_add_f32 v[42:43], v[202:203], v[204:205]
	v_pk_add_f32 v[58:59], v[202:203], v[204:205] neg_lo:[0,1] neg_hi:[0,1]
	v_pk_add_f32 v[202:203], v[10:11], v[26:27] op_sel:[0,1] op_sel_hi:[1,0] neg_hi:[0,1]
	v_pk_add_f32 v[204:205], v[10:11], v[26:27] op_sel:[0,1] op_sel_hi:[1,0] neg_lo:[0,1]
	v_pk_mul_f32 v[10:11], v[224:225], v[202:203] op_sel:[1,1] op_sel_hi:[1,0]
	v_pk_fma_f32 v[10:11], v[224:225], v[202:203], v[10:11] op_sel_hi:[0,1,1] neg_lo:[0,0,1]
	v_pk_mul_f32 v[26:27], v[226:227], v[58:59] op_sel:[1,1] op_sel_hi:[1,0]
	v_pk_fma_f32 v[26:27], v[226:227], v[58:59], v[26:27] op_sel_hi:[0,1,1] neg_lo:[0,0,1]
	v_pk_mul_f32 v[58:59], v[230:231], v[204:205] op_sel:[1,1] op_sel_hi:[1,0]
	v_pk_fma_f32 v[58:59], v[230:231], v[204:205], v[58:59] op_sel_hi:[0,1,1] neg_lo:[0,0,1]
	v_pk_add_f32 v[202:203], v[12:13], v[44:45]
	v_pk_add_f32 v[12:13], v[12:13], v[44:45] neg_lo:[0,1] neg_hi:[0,1]
	v_pk_add_f32 v[204:205], v[28:29], v[60:61]
	v_pk_add_f32 v[28:29], v[28:29], v[60:61] neg_lo:[0,1] neg_hi:[0,1]
	v_pk_add_f32 v[44:45], v[202:203], v[204:205]
	v_pk_add_f32 v[60:61], v[202:203], v[204:205] neg_lo:[0,1] neg_hi:[0,1]
	v_pk_add_f32 v[202:203], v[12:13], v[28:29] op_sel:[0,1] op_sel_hi:[1,0] neg_hi:[0,1]
	v_pk_add_f32 v[204:205], v[12:13], v[28:29] op_sel:[0,1] op_sel_hi:[1,0] neg_lo:[0,1]
	v_pk_mul_f32 v[12:13], v[224:225], v[202:203] op_sel:[1,1] op_sel_hi:[1,0]
	v_pk_fma_f32 v[12:13], v[224:225], v[202:203], v[12:13] op_sel_hi:[0,1,1] neg_lo:[0,0,1]
	v_pk_mul_f32 v[28:29], v[226:227], v[60:61] op_sel:[1,1] op_sel_hi:[1,0]
	v_pk_fma_f32 v[28:29], v[226:227], v[60:61], v[28:29] op_sel_hi:[0,1,1] neg_lo:[0,0,1]
	v_pk_mul_f32 v[60:61], v[230:231], v[204:205] op_sel:[1,1] op_sel_hi:[1,0]
; DI void fft8192(f32x2* buf, const f32x2* __restrict__ tw) {
;     ...
;   {
;     f32x2 a[16], b[16];
;     __syncthreads();
; #pragma unroll
;     for (int e = 0; e < 16; ++e) { const int pi = SW(tid + 256 * e); a[e] = buf[pi]; b[e] = buf[pi + 4096]; }
;     __syncthreads();
; #pragma unroll
;     for (int e = 0; e < 16; ++e) {
;       const int pi = SW(tid + 256 * e);
;       buf[pi] = mkf2(a[e].x + b[e].x, a[e].y + b[e].y);
;       buf[pi + 4096] = mkf2(a[e].x - b[e].x, a[e].y - b[e].y);
;     }
;     __syncthreads();
;   }
; DI void hyena_unit(KP p, int l, int c, char* smem) {
;     ...
;     for (int j = 0; j < 32; ++j) KF[j] = buf[SW(tid + 256 * j)];
;     const int gcol = (o == 0 ? 512 : 1024) + c;
;     const float gw0 = cw[gcol], gw1 = cw[1536 + gcol], gw2 = cw[3072 + gcol], gb = cb[gcol];
;     const float vw0 = cw[c], vw1 = cw[1536 + c], vw2 = cw[3072 + c], vb = cb[c];
	v_pk_fma_f32 v[60:61], v[230:231], v[204:205], v[60:61] op_sel_hi:[0,1,1] neg_lo:[0,0,1]
	v_pk_add_f32 v[202:203], v[16:17], v[48:49]
	v_pk_add_f32 v[16:17], v[16:17], v[48:49] neg_lo:[0,1] neg_hi:[0,1]
	v_pk_add_f32 v[204:205], v[32:33], v[64:65]
	v_pk_add_f32 v[32:33], v[32:33], v[64:65] neg_lo:[0,1] neg_hi:[0,1]
	v_pk_add_f32 v[48:49], v[202:203], v[204:205]
	v_pk_add_f32 v[64:65], v[202:203], v[204:205] neg_lo:[0,1] neg_hi:[0,1]
	v_pk_add_f32 v[202:203], v[16:17], v[32:33] op_sel:[0,1] op_sel_hi:[1,0] neg_hi:[0,1]
	v_pk_add_f32 v[204:205], v[16:17], v[32:33] op_sel:[0,1] op_sel_hi:[1,0] neg_lo:[0,1]
	v_pk_mul_f32 v[16:17], v[224:225], v[202:203] op_sel:[1,1] op_sel_hi:[1,0]
	v_pk_fma_f32 v[16:17], v[224:225], v[202:203], v[16:17] op_sel_hi:[0,1,1] neg_lo:[0,0,1]
	v_pk_mul_f32 v[32:33], v[226:227], v[64:65] op_sel:[1,1] op_sel_hi:[1,0]
	v_pk_fma_f32 v[32:33], v[226:227], v[64:65], v[32:33] op_sel_hi:[0,1,1] neg_lo:[0,0,1]
	v_pk_mul_f32 v[64:65], v[230:231], v[204:205] op_sel:[1,1] op_sel_hi:[1,0]
	v_pk_fma_f32 v[64:65], v[230:231], v[204:205], v[64:65] op_sel_hi:[0,1,1] neg_lo:[0,0,1]
	v_pk_add_f32 v[202:203], v[38:39], v[46:47]
	v_pk_add_f32 v[46:47], v[38:39], v[46:47] neg_lo:[0,1] neg_hi:[0,1]
	v_pk_add_f32 v[204:205], v[34:35], v[42:43]
	v_pk_add_f32 v[42:43], v[34:35], v[42:43] neg_lo:[0,1] neg_hi:[0,1]
	v_pk_add_f32 v[206:207], v[36:37], v[44:45]
	v_pk_add_f32 v[44:45], v[36:37], v[44:45] neg_lo:[0,1] neg_hi:[0,1]
	v_pk_add_f32 v[208:209], v[40:41], v[48:49]
	v_pk_add_f32 v[48:49], v[40:41], v[48:49] neg_lo:[0,1] neg_hi:[0,1]
	v_pk_add_f32 v[210:211], v[6:7], v[14:15]
	v_pk_add_f32 v[14:15], v[6:7], v[14:15] neg_lo:[0,1] neg_hi:[0,1]
	v_pk_add_f32 v[212:213], v[2:3], v[10:11]
	v_pk_add_f32 v[10:11], v[2:3], v[10:11] neg_lo:[0,1] neg_hi:[0,1]
	v_pk_add_f32 v[220:221], v[8:9], v[12:13]
	v_pk_add_f32 v[12:13], v[8:9], v[12:13] neg_lo:[0,1] neg_hi:[0,1]
	v_pk_add_f32 v[224:225], v[4:5], v[16:17]
	v_pk_add_f32 v[16:17], v[4:5], v[16:17] neg_lo:[0,1] neg_hi:[0,1]
	v_pk_add_f32 v[226:227], v[54:55], v[30:31]
	v_pk_add_f32 v[30:31], v[54:55], v[30:31] neg_lo:[0,1] neg_hi:[0,1]
	v_pk_add_f32 v[230:231], v[50:51], v[26:27]
	v_pk_add_f32 v[26:27], v[50:51], v[26:27] neg_lo:[0,1] neg_hi:[0,1]
	v_pk_add_f32 v[232:233], v[52:53], v[28:29]
	v_pk_add_f32 v[28:29], v[52:53], v[28:29] neg_lo:[0,1] neg_hi:[0,1]
	v_pk_add_f32 v[236:237], v[56:57], v[32:33]
	v_pk_add_f32 v[32:33], v[56:57], v[32:33] neg_lo:[0,1] neg_hi:[0,1]
	v_pk_add_f32 v[238:239], v[22:23], v[62:63]
	v_pk_add_f32 v[62:63], v[22:23], v[62:63] neg_lo:[0,1] neg_hi:[0,1]
	v_pk_add_f32 v[240:241], v[18:19], v[58:59]
	v_pk_add_f32 v[58:59], v[18:19], v[58:59] neg_lo:[0,1] neg_hi:[0,1]
	v_pk_add_f32 v[244:245], v[20:21], v[60:61]
	v_pk_add_f32 v[60:61], v[20:21], v[60:61] neg_lo:[0,1] neg_hi:[0,1]
	v_pk_add_f32 v[246:247], v[24:25], v[64:65]
	v_pk_add_f32 v[64:65], v[24:25], v[64:65] neg_lo:[0,1] neg_hi:[0,1]
	ds_write2st64_b64 v154, v[202:203], v[46:47] offset0:0 offset1:64
	ds_write2st64_b64 v154, v[204:205], v[42:43] offset0:4 offset1:68
	ds_write2st64_b64 v154, v[206:207], v[44:45] offset0:8 offset1:72
	ds_write2st64_b64 v154, v[208:209], v[48:49] offset0:12 offset1:76
	ds_write2st64_b64 v154, v[210:211], v[14:15] offset0:16 offset1:80
	ds_write2st64_b64 v154, v[212:213], v[10:11] offset0:20 offset1:84
	ds_write2st64_b64 v154, v[220:221], v[12:13] offset0:24 offset1:88
	ds_write2st64_b64 v154, v[224:225], v[16:17] offset0:28 offset1:92
	ds_write2st64_b64 v154, v[226:227], v[30:31] offset0:32 offset1:96
	ds_write2st64_b64 v154, v[230:231], v[26:27] offset0:36 offset1:100
	ds_write2st64_b64 v154, v[232:233], v[28:29] offset0:40 offset1:104
	ds_write2st64_b64 v154, v[236:237], v[32:33] offset0:44 offset1:108
	ds_write2st64_b64 v154, v[238:239], v[62:63] offset0:48 offset1:112
	ds_write2st64_b64 v154, v[240:241], v[58:59] offset0:52 offset1:116
	ds_write2st64_b64 v154, v[244:245], v[60:61] offset0:56 offset1:120
	ds_write2st64_b64 v154, v[246:247], v[64:65] offset0:60 offset1:124
	s_and_b64 s[2:3], s[96:97], exec
	s_cselect_b32 s4, 0x200, s62
	s_add_i32 s21, s4, s86
	s_lshl_b32 s5, s4, 2
	s_add_u32 s2, s88, s5
	v_mov_b32_e32 v2, s5
	s_waitcnt lgkmcnt(0)
	s_barrier
	s_addc_u32 s3, s89, 0
	global_load_dword v74, v2, s[88:89]
	global_load_dword v195, v2, s[94:95]
	global_load_dword v196, v235, s[2:3] offset:2048
	global_load_dword v75, v229, s[2:3]
	global_load_dword v76, v199, s[88:89]
	global_load_dword v197, v199, s[90:91]
	global_load_dword v77, v199, s[92:93]
	global_load_dword v200, v199, s[94:95]
	ds_read_b64 v[78:79], v157
	ds_read_b64 v[80:81], v159
	ds_read_b64 v[82:83], v161
	ds_read_b64 v[84:85], v163
	ds_read_b64 v[86:87], v165
	ds_read_b64 v[88:89], v167
	ds_read_b64 v[90:91], v169
	ds_read_b64 v[92:93], v170
	ds_read_b64 v[94:95], v171
	ds_read_b64 v[96:97], v172
	ds_read_b64 v[98:99], v173
	ds_read_b64 v[100:101], v174
	ds_read_b64 v[102:103], v175
	ds_read_b64 v[104:105], v176
	ds_read_b64 v[106:107], v177
	ds_read_b64 v[108:109], v178
	ds_read_b64 v[110:111], v179
	ds_read_b64 v[112:113], v180
	ds_read_b64 v[114:115], v181
	ds_read_b64 v[116:117], v182
	ds_read_b64 v[118:119], v183
	ds_read_b64 v[120:121], v184
	ds_read_b64 v[122:123], v185
	ds_read_b64 v[124:125], v186
	ds_read_b64 v[126:127], v187
	ds_read_b64 v[128:129], v188
	ds_read_b64 v[130:131], v189
	ds_read_b64 v[132:133], v190
	ds_read_b64 v[134:135], v191
	ds_read_b64 v[136:137], v192
	ds_read_b64 v[138:139], v193
	ds_read_b64 v[140:141], v194
	s_waitcnt lgkmcnt(5)
	v_pk_mov_b32 v[142:143], v[130:131], v[130:131] op_sel:[1,0]
	s_waitcnt lgkmcnt(4)
	v_pk_mov_b32 v[144:145], v[132:133], v[132:133] op_sel:[1,0]
	s_waitcnt lgkmcnt(3)
	v_pk_mov_b32 v[146:147], v[134:135], v[134:135] op_sel:[1,0]
	s_waitcnt lgkmcnt(2)
	v_pk_mov_b32 v[148:149], v[136:137], v[136:137] op_sel:[1,0]
	s_waitcnt lgkmcnt(1)
	v_pk_mov_b32 v[150:151], v[138:139], v[138:139] op_sel:[1,0]
	s_waitcnt lgkmcnt(0)
	v_pk_mov_b32 v[152:153], v[140:141], v[140:141] op_sel:[1,0]
	s_add_i32 s77, s40, s4
	s_mov_b32 s83, 0
	s_mov_b64 s[6:7], -1
	s_branch .LBB0_937

; DI float bf2f(u16 v) { return __uint_as_float(((unsigned)v) << 16); }
; DI float sconv3(const u16* row, int t, int n, float w0, float w1, float w2, float bias) {
;   float xm = (t > 0) ? bf2f(row[t - 1]) : 0.f, x0 = bf2f(row[t]), xp = (t + 1 < n) ? bf2f(row[t + 1]) : 0.f;
;   return w0 * xm + w1 * x0 + w2 * xp + bias;
; DI void hyena_unit(KP p, int l, int c, char* smem) {
;     ...
;       u16* r0 = Zhy + (size_t)(b0 * 1536 + c) * 4096;
;       u16* r1 = Zhy + (size_t)(b1 * 1536 + c) * 4096;
;       u16* y0p = yct + (size_t)(b0 * 512 + c) * 4096;
;       u16* y1p = yct + (size_t)(b1 * 512 + c) * 4096;
;       __syncthreads();
; #pragma unroll 4
;       for (int jj = 0; jj < 16; ++jj) {
;         const int t = tid + 256 * jj;
;         float v0, v1;
;         if (o == 0) { v0 = sconv3(r0, t, 4096, vw0, vw1, vw2, vb); v1 = sconv3(r1, t, 4096, vw0, vw1, vw2, vb); }
;         else { v0 = bf2f(r0[t]); v1 = bf2f(r1[t]); }
;         buf[SW(t)] = mkf2(v0, v1);
;         buf[SW(t + 4096)] = mkf2(0.f, 0.f);
;       }
.LBB0_937:
	s_mul_i32 s82, s83, 0xc00
	s_add_i32 s28, s82, s86
	s_lshl_b32 s2, s83, 1
	s_ashr_i32 s29, s28, 31
	s_xor_b64 s[36:37], s[6:7], -1
	s_or_b32 s78, s2, 1
	s_lshl_b64 s[2:3], s[28:29], 13
	s_add_u32 s24, s80, s2
	s_mul_i32 s29, s78, 0x600
	s_addc_u32 s25, s76, s3
	s_add_i32 s6, s29, s86
	s_ashr_i32 s7, s6, 31
	s_lshl_b64 s[4:5], s[6:7], 13
	s_add_u32 s26, s80, s4
	s_addc_u32 s27, s76, s5
	s_add_i32 s4, s40, s82
	s_ashr_i32 s5, s4, 31
	s_lshl_b64 s[4:5], s[4:5], 13
	v_lshl_add_u64 v[2:3], v[70:71], 0, s[4:5]
	v_lshl_add_u64 v[4:5], v[70:71], 0, s[2:3]
	s_mov_b64 s[22:23], 0
	s_movk_i32 s2, 0x200
	s_barrier
	v_lshlrev_b32_e32 v6, 1, v66
	v_xor_b32_e32 v8, v66, v155
	v_add_u32_e32 v7, 0x1000, v6
	v_lshlrev_b32_e32 v8, 3, v8
	s_and_b64 vcc, exec, s[34:35]
	s_cbranch_vccnz .Lhy_inA_direct
	v_cmp_eq_u32_e64 s[8:9], 0, v66
	v_cmp_eq_u32_e32 vcc, 0xff, v66
	s_mov_b64 s[10:11], vcc
	global_load_ushort v18, v6, s[24:25] offset:-2
	global_load_ushort v16, v6, s[24:25] offset:0
	global_load_ushort v19, v6, s[24:25] offset:2
	global_load_ushort v20, v6, s[26:27] offset:-2
	global_load_ushort v17, v6, s[26:27] offset:0
	global_load_ushort v21, v6, s[26:27] offset:2
	global_load_ushort v24, v6, s[24:25] offset:510
	global_load_ushort v22, v6, s[24:25] offset:512
	global_load_ushort v25, v6, s[24:25] offset:514
	global_load_ushort v26, v6, s[26:27] offset:510
	global_load_ushort v23, v6, s[26:27] offset:512
	global_load_ushort v27, v6, s[26:27] offset:514
	global_load_ushort v30, v6, s[24:25] offset:1022
	global_load_ushort v28, v6, s[24:25] offset:1024
	global_load_ushort v31, v6, s[24:25] offset:1026
	global_load_ushort v32, v6, s[26:27] offset:1022
	global_load_ushort v29, v6, s[26:27] offset:1024
	global_load_ushort v33, v6, s[26:27] offset:1026
	global_load_ushort v36, v6, s[24:25] offset:1534
	global_load_ushort v34, v6, s[24:25] offset:1536
	global_load_ushort v37, v6, s[24:25] offset:1538
	global_load_ushort v38, v6, s[26:27] offset:1534
	global_load_ushort v35, v6, s[26:27] offset:1536
	global_load_ushort v39, v6, s[26:27] offset:1538
	global_load_ushort v42, v6, s[24:25] offset:2046
	global_load_ushort v40, v6, s[24:25] offset:2048
	global_load_ushort v43, v6, s[24:25] offset:2050
	global_load_ushort v44, v6, s[26:27] offset:2046
	global_load_ushort v41, v6, s[26:27] offset:2048
	global_load_ushort v45, v6, s[26:27] offset:2050
	global_load_ushort v48, v6, s[24:25] offset:2558
	global_load_ushort v46, v6, s[24:25] offset:2560
	global_load_ushort v49, v6, s[24:25] offset:2562
	global_load_ushort v50, v6, s[26:27] offset:2558
	global_load_ushort v47, v6, s[26:27] offset:2560
	global_load_ushort v51, v6, s[26:27] offset:2562
	global_load_ushort v54, v6, s[24:25] offset:3070
	global_load_ushort v52, v6, s[24:25] offset:3072
	global_load_ushort v55, v6, s[24:25] offset:3074
	global_load_ushort v56, v6, s[26:27] offset:3070
	global_load_ushort v53, v6, s[26:27] offset:3072
	global_load_ushort v57, v6, s[26:27] offset:3074
	global_load_ushort v60, v6, s[24:25] offset:3582
	global_load_ushort v58, v6, s[24:25] offset:3584
	global_load_ushort v61, v6, s[24:25] offset:3586
	global_load_ushort v62, v6, s[26:27] offset:3582
	global_load_ushort v59, v6, s[26:27] offset:3584
	global_load_ushort v63, v6, s[26:27] offset:3586
	s_waitcnt vmcnt(42)
	v_cndmask_b32_e64 v18, v18, 0, s[8:9]
	v_cndmask_b32_e64 v20, v20, 0, s[8:9]
	v_lshlrev_b32_e32 v16, 16, v16
	v_lshlrev_b32_e32 v17, 16, v17
	v_lshlrev_b32_e32 v18, 16, v18
	v_lshlrev_b32_e32 v19, 16, v19
	v_lshlrev_b32_e32 v20, 16, v20
	v_lshlrev_b32_e32 v21, 16, v21
	v_mul_f32_e32 v16, v197, v16
	v_mul_f32_e32 v17, v197, v17
	v_fmac_f32_e32 v16, v76, v18
	v_fmac_f32_e32 v17, v76, v20
	v_fmac_f32_e32 v16, v77, v19
	v_fmac_f32_e32 v17, v77, v21
	v_add_f32_e32 v16, v200, v16
	v_add_f32_e32 v17, v200, v17
	ds_write_b64 v8, v[16:17]
	s_waitcnt vmcnt(36)
	v_lshlrev_b32_e32 v22, 16, v22
	v_lshlrev_b32_e32 v23, 16, v23
	v_lshlrev_b32_e32 v24, 16, v24
	v_lshlrev_b32_e32 v25, 16, v25
	v_lshlrev_b32_e32 v26, 16, v26
	v_lshlrev_b32_e32 v27, 16, v27
	v_mul_f32_e32 v22, v197, v22
	v_mul_f32_e32 v23, v197, v23
	v_fmac_f32_e32 v22, v76, v24
	v_fmac_f32_e32 v23, v76, v26
	v_fmac_f32_e32 v22, v77, v25
	v_fmac_f32_e32 v23, v77, v27
	v_add_f32_e32 v22, v200, v22
	v_add_f32_e32 v23, v200, v23
	ds_write_b64 v8, v[22:23] offset:2048
	s_waitcnt vmcnt(30)
	v_lshlrev_b32_e32 v28, 16, v28
	v_lshlrev_b32_e32 v29, 16, v29
	v_lshlrev_b32_e32 v30, 16, v30
	v_lshlrev_b32_e32 v31, 16, v31
	v_lshlrev_b32_e32 v32, 16, v32
	v_lshlrev_b32_e32 v33, 16, v33
	v_mul_f32_e32 v28, v197, v28
	v_mul_f32_e32 v29, v197, v29
	v_fmac_f32_e32 v28, v76, v30
	v_fmac_f32_e32 v29, v76, v32
	v_fmac_f32_e32 v28, v77, v31
	v_fmac_f32_e32 v29, v77, v33
	v_add_f32_e32 v28, v200, v28
	v_add_f32_e32 v29, v200, v29
	ds_write_b64 v8, v[28:29] offset:4096
	s_waitcnt vmcnt(24)
	v_lshlrev_b32_e32 v34, 16, v34
	v_lshlrev_b32_e32 v35, 16, v35
	v_lshlrev_b32_e32 v36, 16, v36
	v_lshlrev_b32_e32 v37, 16, v37
	v_lshlrev_b32_e32 v38, 16, v38
	v_lshlrev_b32_e32 v39, 16, v39
	v_mul_f32_e32 v34, v197, v34
	v_mul_f32_e32 v35, v197, v35
	v_fmac_f32_e32 v34, v76, v36
	v_fmac_f32_e32 v35, v76, v38
	v_fmac_f32_e32 v34, v77, v37
	v_fmac_f32_e32 v35, v77, v39
	v_add_f32_e32 v34, v200, v34
	v_add_f32_e32 v35, v200, v35
	ds_write_b64 v8, v[34:35] offset:6144
	s_waitcnt vmcnt(18)
	v_lshlrev_b32_e32 v40, 16, v40
	v_lshlrev_b32_e32 v41, 16, v41
	v_lshlrev_b32_e32 v42, 16, v42
	v_lshlrev_b32_e32 v43, 16, v43
	v_lshlrev_b32_e32 v44, 16, v44
	v_lshlrev_b32_e32 v45, 16, v45
	v_mul_f32_e32 v40, v197, v40
	v_mul_f32_e32 v41, v197, v41
	v_fmac_f32_e32 v40, v76, v42
	v_fmac_f32_e32 v41, v76, v44
	v_fmac_f32_e32 v40, v77, v43
	v_fmac_f32_e32 v41, v77, v45
	v_add_f32_e32 v40, v200, v40
	v_add_f32_e32 v41, v200, v41
	ds_write_b64 v8, v[40:41] offset:8192
	s_waitcnt vmcnt(12)
; DI float bf2f(u16 v) { return __uint_as_float(((unsigned)v) << 16); }
; DI float sconv3(const u16* row, int t, int n, float w0, float w1, float w2, float bias) {
;   float xm = (t > 0) ? bf2f(row[t - 1]) : 0.f, x0 = bf2f(row[t]), xp = (t + 1 < n) ? bf2f(row[t + 1]) : 0.f;
;   return w0 * xm + w1 * x0 + w2 * xp + bias;
; DI void hyena_unit(KP p, int l, int c, char* smem) {
;     ...
; #pragma unroll 4
;       for (int jj = 0; jj < 16; ++jj) {
;         const int t = tid + 256 * jj;
;         float v0, v1;
;         if (o == 0) { v0 = sconv3(r0, t, 4096, vw0, vw1, vw2, vb); v1 = sconv3(r1, t, 4096, vw0, vw1, vw2, vb); }
;         else { v0 = bf2f(r0[t]); v1 = bf2f(r1[t]); }
;         buf[SW(t)] = mkf2(v0, v1);
;         buf[SW(t + 4096)] = mkf2(0.f, 0.f);
;       }
	v_lshlrev_b32_e32 v46, 16, v46
	v_lshlrev_b32_e32 v47, 16, v47
	v_lshlrev_b32_e32 v48, 16, v48
	v_lshlrev_b32_e32 v49, 16, v49
	v_lshlrev_b32_e32 v50, 16, v50
	v_lshlrev_b32_e32 v51, 16, v51
	v_mul_f32_e32 v46, v197, v46
	v_mul_f32_e32 v47, v197, v47
	v_fmac_f32_e32 v46, v76, v48
	v_fmac_f32_e32 v47, v76, v50
	v_fmac_f32_e32 v46, v77, v49
	v_fmac_f32_e32 v47, v77, v51
	v_add_f32_e32 v46, v200, v46
	v_add_f32_e32 v47, v200, v47
	ds_write_b64 v8, v[46:47] offset:10240
	s_waitcnt vmcnt(6)
	v_lshlrev_b32_e32 v52, 16, v52
	v_lshlrev_b32_e32 v53, 16, v53
	v_lshlrev_b32_e32 v54, 16, v54
	v_lshlrev_b32_e32 v55, 16, v55
	v_lshlrev_b32_e32 v56, 16, v56
	v_lshlrev_b32_e32 v57, 16, v57
	v_mul_f32_e32 v52, v197, v52
	v_mul_f32_e32 v53, v197, v53
	v_fmac_f32_e32 v52, v76, v54
	v_fmac_f32_e32 v53, v76, v56
	v_fmac_f32_e32 v52, v77, v55
	v_fmac_f32_e32 v53, v77, v57
	v_add_f32_e32 v52, v200, v52
	v_add_f32_e32 v53, v200, v53
	ds_write_b64 v8, v[52:53] offset:12288
	s_waitcnt vmcnt(0)
	v_lshlrev_b32_e32 v58, 16, v58
	v_lshlrev_b32_e32 v59, 16, v59
	v_lshlrev_b32_e32 v60, 16, v60
	v_lshlrev_b32_e32 v61, 16, v61
	v_lshlrev_b32_e32 v62, 16, v62
	v_lshlrev_b32_e32 v63, 16, v63
	v_mul_f32_e32 v58, v197, v58
	v_mul_f32_e32 v59, v197, v59
	v_fmac_f32_e32 v58, v76, v60
	v_fmac_f32_e32 v59, v76, v62
	v_fmac_f32_e32 v58, v77, v61
	v_fmac_f32_e32 v59, v77, v63
	v_add_f32_e32 v58, v200, v58
	v_add_f32_e32 v59, v200, v59
	ds_write_b64 v8, v[58:59] offset:14336
	global_load_ushort v18, v7, s[24:25] offset:-2
	global_load_ushort v16, v7, s[24:25] offset:0
	global_load_ushort v19, v7, s[24:25] offset:2
	global_load_ushort v20, v7, s[26:27] offset:-2
	global_load_ushort v17, v7, s[26:27] offset:0
	global_load_ushort v21, v7, s[26:27] offset:2
	global_load_ushort v24, v7, s[24:25] offset:510
	global_load_ushort v22, v7, s[24:25] offset:512
	global_load_ushort v25, v7, s[24:25] offset:514
	global_load_ushort v26, v7, s[26:27] offset:510
	global_load_ushort v23, v7, s[26:27] offset:512
	global_load_ushort v27, v7, s[26:27] offset:514
	global_load_ushort v30, v7, s[24:25] offset:1022
	global_load_ushort v28, v7, s[24:25] offset:1024
	global_load_ushort v31, v7, s[24:25] offset:1026
	global_load_ushort v32, v7, s[26:27] offset:1022
	global_load_ushort v29, v7, s[26:27] offset:1024
	global_load_ushort v33, v7, s[26:27] offset:1026
	global_load_ushort v36, v7, s[24:25] offset:1534
	global_load_ushort v34, v7, s[24:25] offset:1536
	global_load_ushort v37, v7, s[24:25] offset:1538
	global_load_ushort v38, v7, s[26:27] offset:1534
	global_load_ushort v35, v7, s[26:27] offset:1536
	global_load_ushort v39, v7, s[26:27] offset:1538
	global_load_ushort v42, v7, s[24:25] offset:2046
	global_load_ushort v40, v7, s[24:25] offset:2048
	global_load_ushort v43, v7, s[24:25] offset:2050
	global_load_ushort v44, v7, s[26:27] offset:2046
	global_load_ushort v41, v7, s[26:27] offset:2048
	global_load_ushort v45, v7, s[26:27] offset:2050
	global_load_ushort v48, v7, s[24:25] offset:2558
	global_load_ushort v46, v7, s[24:25] offset:2560
	global_load_ushort v49, v7, s[24:25] offset:2562
	global_load_ushort v50, v7, s[26:27] offset:2558
	global_load_ushort v47, v7, s[26:27] offset:2560
	global_load_ushort v51, v7, s[26:27] offset:2562
	global_load_ushort v54, v7, s[24:25] offset:3070
	global_load_ushort v52, v7, s[24:25] offset:3072
	global_load_ushort v55, v7, s[24:25] offset:3074
	global_load_ushort v56, v7, s[26:27] offset:3070
	global_load_ushort v53, v7, s[26:27] offset:3072
	global_load_ushort v57, v7, s[26:27] offset:3074
	global_load_ushort v60, v7, s[24:25] offset:3582
	global_load_ushort v58, v7, s[24:25] offset:3584
	global_load_ushort v61, v7, s[24:25] offset:3586
	global_load_ushort v62, v7, s[26:27] offset:3582
	global_load_ushort v59, v7, s[26:27] offset:3584
	global_load_ushort v63, v7, s[26:27] offset:3586
	s_waitcnt vmcnt(42)
	v_lshlrev_b32_e32 v16, 16, v16
	v_lshlrev_b32_e32 v17, 16, v17
	v_lshlrev_b32_e32 v18, 16, v18
	v_lshlrev_b32_e32 v19, 16, v19
	v_lshlrev_b32_e32 v20, 16, v20
	v_lshlrev_b32_e32 v21, 16, v21
	v_mul_f32_e32 v16, v197, v16
	v_mul_f32_e32 v17, v197, v17
	v_fmac_f32_e32 v16, v76, v18
	v_fmac_f32_e32 v17, v76, v20
	v_fmac_f32_e32 v16, v77, v19
	v_fmac_f32_e32 v17, v77, v21
	v_add_f32_e32 v16, v200, v16
	v_add_f32_e32 v17, v200, v17
	ds_write_b64 v8, v[16:17] offset:16384
	s_waitcnt vmcnt(36)
	v_lshlrev_b32_e32 v22, 16, v22
	v_lshlrev_b32_e32 v23, 16, v23
	v_lshlrev_b32_e32 v24, 16, v24
	v_lshlrev_b32_e32 v25, 16, v25
	v_lshlrev_b32_e32 v26, 16, v26
	v_lshlrev_b32_e32 v27, 16, v27
	v_mul_f32_e32 v22, v197, v22
	v_mul_f32_e32 v23, v197, v23
	v_fmac_f32_e32 v22, v76, v24
	v_fmac_f32_e32 v23, v76, v26
	v_fmac_f32_e32 v22, v77, v25
	v_fmac_f32_e32 v23, v77, v27
	v_add_f32_e32 v22, v200, v22
	v_add_f32_e32 v23, v200, v23
	ds_write_b64 v8, v[22:23] offset:18432
	s_waitcnt vmcnt(30)
	v_lshlrev_b32_e32 v28, 16, v28
	v_lshlrev_b32_e32 v29, 16, v29
	v_lshlrev_b32_e32 v30, 16, v30
	v_lshlrev_b32_e32 v31, 16, v31
	v_lshlrev_b32_e32 v32, 16, v32
	v_lshlrev_b32_e32 v33, 16, v33
	v_mul_f32_e32 v28, v197, v28
	v_mul_f32_e32 v29, v197, v29
	v_fmac_f32_e32 v28, v76, v30
	v_fmac_f32_e32 v29, v76, v32
	v_fmac_f32_e32 v28, v77, v31
	v_fmac_f32_e32 v29, v77, v33
	v_add_f32_e32 v28, v200, v28
	v_add_f32_e32 v29, v200, v29
	ds_write_b64 v8, v[28:29] offset:20480
	s_waitcnt vmcnt(24)
	v_lshlrev_b32_e32 v34, 16, v34
	v_lshlrev_b32_e32 v35, 16, v35
	v_lshlrev_b32_e32 v36, 16, v36
	v_lshlrev_b32_e32 v37, 16, v37
	v_lshlrev_b32_e32 v38, 16, v38
	v_lshlrev_b32_e32 v39, 16, v39
	v_mul_f32_e32 v34, v197, v34
	v_mul_f32_e32 v35, v197, v35
	v_fmac_f32_e32 v34, v76, v36
	v_fmac_f32_e32 v35, v76, v38
	v_fmac_f32_e32 v34, v77, v37
	v_fmac_f32_e32 v35, v77, v39
	v_add_f32_e32 v34, v200, v34
	v_add_f32_e32 v35, v200, v35
	ds_write_b64 v8, v[34:35] offset:22528
	s_waitcnt vmcnt(18)
; DI float bf2f(u16 v) { return __uint_as_float(((unsigned)v) << 16); }
; DI void hyena_unit(KP p, int l, int c, char* smem) {
;     ...
; #pragma unroll 4
;       for (int jj = 0; jj < 16; ++jj) {
;         const int t = tid + 256 * jj;
;         float v0, v1;
;         if (o == 0) { v0 = sconv3(r0, t, 4096, vw0, vw1, vw2, vb); v1 = sconv3(r1, t, 4096, vw0, vw1, vw2, vb); }
;         else { v0 = bf2f(r0[t]); v1 = bf2f(r1[t]); }
;         buf[SW(t)] = mkf2(v0, v1);
;         buf[SW(t + 4096)] = mkf2(0.f, 0.f);
;       }
	v_lshlrev_b32_e32 v40, 16, v40
	v_lshlrev_b32_e32 v41, 16, v41
	v_lshlrev_b32_e32 v42, 16, v42
	v_lshlrev_b32_e32 v43, 16, v43
	v_lshlrev_b32_e32 v44, 16, v44
	v_lshlrev_b32_e32 v45, 16, v45
	v_mul_f32_e32 v40, v197, v40
	v_mul_f32_e32 v41, v197, v41
	v_fmac_f32_e32 v40, v76, v42
	v_fmac_f32_e32 v41, v76, v44
	v_fmac_f32_e32 v40, v77, v43
	v_fmac_f32_e32 v41, v77, v45
	v_add_f32_e32 v40, v200, v40
	v_add_f32_e32 v41, v200, v41
	ds_write_b64 v8, v[40:41] offset:24576
	s_waitcnt vmcnt(12)
	v_lshlrev_b32_e32 v46, 16, v46
	v_lshlrev_b32_e32 v47, 16, v47
	v_lshlrev_b32_e32 v48, 16, v48
	v_lshlrev_b32_e32 v49, 16, v49
	v_lshlrev_b32_e32 v50, 16, v50
	v_lshlrev_b32_e32 v51, 16, v51
	v_mul_f32_e32 v46, v197, v46
	v_mul_f32_e32 v47, v197, v47
	v_fmac_f32_e32 v46, v76, v48
	v_fmac_f32_e32 v47, v76, v50
	v_fmac_f32_e32 v46, v77, v49
	v_fmac_f32_e32 v47, v77, v51
	v_add_f32_e32 v46, v200, v46
	v_add_f32_e32 v47, v200, v47
	ds_write_b64 v8, v[46:47] offset:26624
	s_waitcnt vmcnt(6)
	v_lshlrev_b32_e32 v52, 16, v52
	v_lshlrev_b32_e32 v53, 16, v53
	v_lshlrev_b32_e32 v54, 16, v54
	v_lshlrev_b32_e32 v55, 16, v55
	v_lshlrev_b32_e32 v56, 16, v56
	v_lshlrev_b32_e32 v57, 16, v57
	v_mul_f32_e32 v52, v197, v52
	v_mul_f32_e32 v53, v197, v53
	v_fmac_f32_e32 v52, v76, v54
	v_fmac_f32_e32 v53, v76, v56
	v_fmac_f32_e32 v52, v77, v55
	v_fmac_f32_e32 v53, v77, v57
	v_add_f32_e32 v52, v200, v52
	v_add_f32_e32 v53, v200, v53
	ds_write_b64 v8, v[52:53] offset:28672
	s_waitcnt vmcnt(0)
	v_cndmask_b32_e64 v61, v61, 0, s[10:11]
	v_cndmask_b32_e64 v63, v63, 0, s[10:11]
	v_lshlrev_b32_e32 v58, 16, v58
	v_lshlrev_b32_e32 v59, 16, v59
	v_lshlrev_b32_e32 v60, 16, v60
	v_lshlrev_b32_e32 v61, 16, v61
	v_lshlrev_b32_e32 v62, 16, v62
	v_lshlrev_b32_e32 v63, 16, v63
	v_mul_f32_e32 v58, v197, v58
	v_mul_f32_e32 v59, v197, v59
	v_fmac_f32_e32 v58, v76, v60
	v_fmac_f32_e32 v59, v76, v62
	v_fmac_f32_e32 v58, v77, v61
	v_fmac_f32_e32 v59, v77, v63
	v_add_f32_e32 v58, v200, v58
	v_add_f32_e32 v59, v200, v59
	ds_write_b64 v8, v[58:59] offset:30720
	s_branch .Lhy_inA_done
.Lhy_inA_direct:
	global_load_ushort v16, v6, s[24:25]
	global_load_ushort v17, v6, s[26:27]
	global_load_ushort v18, v6, s[24:25] offset:512
	global_load_ushort v19, v6, s[26:27] offset:512
	global_load_ushort v20, v6, s[24:25] offset:1024
	global_load_ushort v21, v6, s[26:27] offset:1024
	global_load_ushort v22, v6, s[24:25] offset:1536
	global_load_ushort v23, v6, s[26:27] offset:1536
	global_load_ushort v24, v6, s[24:25] offset:2048
	global_load_ushort v25, v6, s[26:27] offset:2048
	global_load_ushort v26, v6, s[24:25] offset:2560
	global_load_ushort v27, v6, s[26:27] offset:2560
	global_load_ushort v28, v6, s[24:25] offset:3072
	global_load_ushort v29, v6, s[26:27] offset:3072
	global_load_ushort v30, v6, s[24:25] offset:3584
	global_load_ushort v31, v6, s[26:27] offset:3584
	global_load_ushort v32, v7, s[24:25]
	global_load_ushort v33, v7, s[26:27]
	global_load_ushort v34, v7, s[24:25] offset:512
	global_load_ushort v35, v7, s[26:27] offset:512
	global_load_ushort v36, v7, s[24:25] offset:1024
	global_load_ushort v37, v7, s[26:27] offset:1024
	global_load_ushort v38, v7, s[24:25] offset:1536
	global_load_ushort v39, v7, s[26:27] offset:1536
	global_load_ushort v40, v7, s[24:25] offset:2048
	global_load_ushort v41, v7, s[26:27] offset:2048
	global_load_ushort v42, v7, s[24:25] offset:2560
	global_load_ushort v43, v7, s[26:27] offset:2560
	global_load_ushort v44, v7, s[24:25] offset:3072
	global_load_ushort v45, v7, s[26:27] offset:3072
	global_load_ushort v46, v7, s[24:25] offset:3584
	global_load_ushort v47, v7, s[26:27] offset:3584
	s_waitcnt vmcnt(30)
	v_lshlrev_b32_e32 v16, 16, v16
	v_lshlrev_b32_e32 v17, 16, v17
	ds_write_b64 v8, v[16:17]
	s_waitcnt vmcnt(28)
	v_lshlrev_b32_e32 v18, 16, v18
	v_lshlrev_b32_e32 v19, 16, v19
	ds_write_b64 v8, v[18:19] offset:2048
	s_waitcnt vmcnt(26)
	v_lshlrev_b32_e32 v20, 16, v20
	v_lshlrev_b32_e32 v21, 16, v21
	ds_write_b64 v8, v[20:21] offset:4096
	s_waitcnt vmcnt(24)
	v_lshlrev_b32_e32 v22, 16, v22
	v_lshlrev_b32_e32 v23, 16, v23
	ds_write_b64 v8, v[22:23] offset:6144
	s_waitcnt vmcnt(22)
	v_lshlrev_b32_e32 v24, 16, v24
	v_lshlrev_b32_e32 v25, 16, v25
	ds_write_b64 v8, v[24:25] offset:8192
	s_waitcnt vmcnt(20)
	v_lshlrev_b32_e32 v26, 16, v26
	v_lshlrev_b32_e32 v27, 16, v27
	ds_write_b64 v8, v[26:27] offset:10240
	s_waitcnt vmcnt(18)
	v_lshlrev_b32_e32 v28, 16, v28
	v_lshlrev_b32_e32 v29, 16, v29
	ds_write_b64 v8, v[28:29] offset:12288
	s_waitcnt vmcnt(16)
	v_lshlrev_b32_e32 v30, 16, v30
	v_lshlrev_b32_e32 v31, 16, v31
	ds_write_b64 v8, v[30:31] offset:14336
	s_waitcnt vmcnt(14)
	v_lshlrev_b32_e32 v32, 16, v32
	v_lshlrev_b32_e32 v33, 16, v33
	ds_write_b64 v8, v[32:33] offset:16384
	s_waitcnt vmcnt(12)
	v_lshlrev_b32_e32 v34, 16, v34
	v_lshlrev_b32_e32 v35, 16, v35
	ds_write_b64 v8, v[34:35] offset:18432
	s_waitcnt vmcnt(10)
	v_lshlrev_b32_e32 v36, 16, v36
	v_lshlrev_b32_e32 v37, 16, v37
	ds_write_b64 v8, v[36:37] offset:20480
	s_waitcnt vmcnt(8)
	v_lshlrev_b32_e32 v38, 16, v38
	v_lshlrev_b32_e32 v39, 16, v39
	ds_write_b64 v8, v[38:39] offset:22528
	s_waitcnt vmcnt(6)
	v_lshlrev_b32_e32 v40, 16, v40
	v_lshlrev_b32_e32 v41, 16, v41
	ds_write_b64 v8, v[40:41] offset:24576
	s_waitcnt vmcnt(4)
	v_lshlrev_b32_e32 v42, 16, v42
	v_lshlrev_b32_e32 v43, 16, v43
	ds_write_b64 v8, v[42:43] offset:26624
	s_waitcnt vmcnt(2)
	v_lshlrev_b32_e32 v44, 16, v44
	v_lshlrev_b32_e32 v45, 16, v45
	ds_write_b64 v8, v[44:45] offset:28672
	s_waitcnt vmcnt(0)
	v_lshlrev_b32_e32 v46, 16, v46
	v_lshlrev_b32_e32 v47, 16, v47
	ds_write_b64 v8, v[46:47] offset:30720
; DI f32x2 cmul(f32x2 a, f32x2 b) { return mkf2(a.x * b.x - a.y * b.y, a.x * b.y + a.y * b.x); }
; DI void fft8192(f32x2* buf, const f32x2* __restrict__ tw) {
;     ...
;   for (int ls = 0; ls < 12; ls += 2) {
;     const int s = 1 << ls;
;     f32x2 a[8], b[8], c[8], d[8];
;     __syncthreads();
; #pragma unroll
;     for (int e = 0; e < 8; ++e) {
;       const int i = tid + 256 * e;
;       const int pi = SW(i);
;       a[e] = buf[pi]; b[e] = buf[pi + 2048]; c[e] = buf[pi + 4096]; d[e] = buf[pi + 6144];
;     }
;     __syncthreads();
; #pragma unroll
;     for (int e = 0; e < 8; ++e) {
;       const int i = tid + 256 * e;
;       const int q = i & (s - 1);
;       const int ps = i - q;
;       const float rev = (float)ps * (1.f / 8192.f);
;       const f32x2 w1 = mkf2(__builtin_amdgcn_cosf(rev), -__builtin_amdgcn_sinf(rev));
;       const f32x2 w2 = cmul(w1, w1), w3 = cmul(w1, w2);
;       const f32x2 apc = mkf2(a[e].x + c[e].x, a[e].y + c[e].y), amc = mkf2(a[e].x - c[e].x, a[e].y - c[e].y);
;       const f32x2 bpd = mkf2(b[e].x + d[e].x, b[e].y + d[e].y), bmd = mkf2(b[e].x - d[e].x, b[e].y - d[e].y);
;       const int o = 4 * i - 3 * q;
;       buf[SW(o)] = mkf2(apc.x + bpd.x, apc.y + bpd.y);
;       buf[SW(o + s)] = cmul(w1, mkf2(amc.x + bmd.y, amc.y - bmd.x));
;       buf[SW(o + 2 * s)] = cmul(w2, mkf2(apc.x - bpd.x, apc.y - bpd.y));
;       buf[SW(o + 3 * s)] = cmul(w3, mkf2(amc.x - bmd.y, amc.y + bmd.x));
;     }
.Lhy_inA_done:
.LBB0_987:
	v_bfe_i32 v166, v0, 5, 1
	v_bfe_i32 v168, v0, 6, 1
	v_and_b32_e32 v166, 5, v166
	v_and_b32_e32 v168, 26, v168
	v_xor_b32_e32 v166, v166, v168
	v_xor_b32_e32 v166, v166, v0
	v_lshlrev_b32_e32 v154, 3, v166
	s_waitcnt lgkmcnt(0)
	s_barrier
	ds_read2st64_b64 v[2:5], v154 offset0:0 offset1:32
	ds_read2st64_b64 v[10:13], v154 offset0:4 offset1:36
	ds_read2st64_b64 v[18:21], v154 offset0:8 offset1:40
	ds_read2st64_b64 v[26:29], v154 offset0:12 offset1:44
	ds_read2st64_b64 v[34:37], v154 offset0:16 offset1:48
	ds_read2st64_b64 v[42:45], v154 offset0:20 offset1:52
	ds_read2st64_b64 v[50:53], v154 offset0:24 offset1:56
	ds_read2st64_b64 v[58:61], v154 offset0:28 offset1:60
	v_cvt_f32_u32_e32 v201, v0
	v_lshlrev_b32_e32 v164, 4, v0
	v_bfe_i32 v166, v164, 5, 1
	v_bfe_i32 v168, v164, 6, 1
	v_and_b32_e32 v166, 5, v166
	v_and_b32_e32 v168, 26, v168
	v_xor_b32_e32 v166, v166, v168
	v_xor_b32_e32 v166, v166, v164
	v_lshlrev_b32_e32 v164, 3, v166
	v_mul_f32_e32 v201, 0x39000000, v201
	v_cos_f32_e32 v210, v201
	v_sin_f32_e64 v211, -v201
	s_waitcnt lgkmcnt(7)
	v_pk_add_f32 v[6:7], v[2:3], v[4:5]
	v_pk_add_f32 v[8:9], v[2:3], v[4:5] neg_lo:[0,1] neg_hi:[0,1]
	v_pk_add_f32 v[202:203], v[2:3], v[4:5] op_sel:[0,1] op_sel_hi:[1,0] neg_hi:[0,1]
	v_pk_add_f32 v[204:205], v[2:3], v[4:5] op_sel:[0,1] op_sel_hi:[1,0] neg_lo:[0,1]
	v_pk_mul_f32 v[206:207], v[210:211], v[210:211] op_sel:[1,1] op_sel_hi:[1,0]
	v_pk_fma_f32 v[212:213], v[210:211], v[210:211], v[206:207] op_sel_hi:[0,1,1] neg_lo:[0,0,1]
	v_pk_mul_f32 v[206:207], v[210:211], v[212:213] op_sel:[1,1] op_sel_hi:[1,0]
	v_pk_fma_f32 v[220:221], v[210:211], v[212:213], v[206:207] op_sel_hi:[0,1,1] neg_lo:[0,0,1]
	v_pk_mul_f32 v[2:3], v[210:211], v[202:203] op_sel:[1,1] op_sel_hi:[1,0]
	v_pk_fma_f32 v[2:3], v[210:211], v[202:203], v[2:3] op_sel_hi:[0,1,1] neg_lo:[0,0,1]
	v_pk_mul_f32 v[4:5], v[212:213], v[8:9] op_sel:[1,1] op_sel_hi:[1,0]
	v_pk_fma_f32 v[4:5], v[212:213], v[8:9], v[4:5] op_sel_hi:[0,1,1] neg_lo:[0,0,1]
	v_pk_mul_f32 v[8:9], v[220:221], v[204:205] op_sel:[1,1] op_sel_hi:[1,0]
	v_pk_fma_f32 v[8:9], v[220:221], v[204:205], v[8:9] op_sel_hi:[0,1,1] neg_lo:[0,0,1]
	v_add_f32_e32 v214, 0x3d000000, v201
	v_cos_f32_e32 v210, v214
	v_sin_f32_e64 v211, -v214
	s_waitcnt lgkmcnt(6)
	v_pk_add_f32 v[14:15], v[10:11], v[12:13]
	v_pk_add_f32 v[16:17], v[10:11], v[12:13] neg_lo:[0,1] neg_hi:[0,1]
	v_pk_add_f32 v[202:203], v[10:11], v[12:13] op_sel:[0,1] op_sel_hi:[1,0] neg_hi:[0,1]
	v_pk_add_f32 v[204:205], v[10:11], v[12:13] op_sel:[0,1] op_sel_hi:[1,0] neg_lo:[0,1]
	v_pk_mul_f32 v[206:207], v[210:211], v[210:211] op_sel:[1,1] op_sel_hi:[1,0]
	v_pk_fma_f32 v[212:213], v[210:211], v[210:211], v[206:207] op_sel_hi:[0,1,1] neg_lo:[0,0,1]
	v_pk_mul_f32 v[206:207], v[210:211], v[212:213] op_sel:[1,1] op_sel_hi:[1,0]
	v_pk_fma_f32 v[220:221], v[210:211], v[212:213], v[206:207] op_sel_hi:[0,1,1] neg_lo:[0,0,1]
	v_pk_mul_f32 v[10:11], v[210:211], v[202:203] op_sel:[1,1] op_sel_hi:[1,0]
	v_pk_fma_f32 v[10:11], v[210:211], v[202:203], v[10:11] op_sel_hi:[0,1,1] neg_lo:[0,0,1]
	v_pk_mul_f32 v[12:13], v[212:213], v[16:17] op_sel:[1,1] op_sel_hi:[1,0]
	v_pk_fma_f32 v[12:13], v[212:213], v[16:17], v[12:13] op_sel_hi:[0,1,1] neg_lo:[0,0,1]
	v_pk_mul_f32 v[16:17], v[220:221], v[204:205] op_sel:[1,1] op_sel_hi:[1,0]
	v_pk_fma_f32 v[16:17], v[220:221], v[204:205], v[16:17] op_sel_hi:[0,1,1] neg_lo:[0,0,1]
	v_add_f32_e32 v214, 0x3d800000, v201
	v_cos_f32_e32 v210, v214
	v_sin_f32_e64 v211, -v214
	s_waitcnt lgkmcnt(5)
	v_pk_add_f32 v[22:23], v[18:19], v[20:21]
	v_pk_add_f32 v[24:25], v[18:19], v[20:21] neg_lo:[0,1] neg_hi:[0,1]
	v_pk_add_f32 v[202:203], v[18:19], v[20:21] op_sel:[0,1] op_sel_hi:[1,0] neg_hi:[0,1]
	v_pk_add_f32 v[204:205], v[18:19], v[20:21] op_sel:[0,1] op_sel_hi:[1,0] neg_lo:[0,1]
	v_pk_mul_f32 v[206:207], v[210:211], v[210:211] op_sel:[1,1] op_sel_hi:[1,0]
	v_pk_fma_f32 v[212:213], v[210:211], v[210:211], v[206:207] op_sel_hi:[0,1,1] neg_lo:[0,0,1]
	v_pk_mul_f32 v[206:207], v[210:211], v[212:213] op_sel:[1,1] op_sel_hi:[1,0]
	v_pk_fma_f32 v[220:221], v[210:211], v[212:213], v[206:207] op_sel_hi:[0,1,1] neg_lo:[0,0,1]
	v_pk_mul_f32 v[18:19], v[210:211], v[202:203] op_sel:[1,1] op_sel_hi:[1,0]
	v_pk_fma_f32 v[18:19], v[210:211], v[202:203], v[18:19] op_sel_hi:[0,1,1] neg_lo:[0,0,1]
	v_pk_mul_f32 v[20:21], v[212:213], v[24:25] op_sel:[1,1] op_sel_hi:[1,0]
	v_pk_fma_f32 v[20:21], v[212:213], v[24:25], v[20:21] op_sel_hi:[0,1,1] neg_lo:[0,0,1]
	v_pk_mul_f32 v[24:25], v[220:221], v[204:205] op_sel:[1,1] op_sel_hi:[1,0]
	v_pk_fma_f32 v[24:25], v[220:221], v[204:205], v[24:25] op_sel_hi:[0,1,1] neg_lo:[0,0,1]
	v_add_f32_e32 v214, 0x3dc00000, v201
	v_cos_f32_e32 v210, v214
	v_sin_f32_e64 v211, -v214
	s_waitcnt lgkmcnt(4)
	v_pk_add_f32 v[30:31], v[26:27], v[28:29]
	v_pk_add_f32 v[32:33], v[26:27], v[28:29] neg_lo:[0,1] neg_hi:[0,1]
	v_pk_add_f32 v[202:203], v[26:27], v[28:29] op_sel:[0,1] op_sel_hi:[1,0] neg_hi:[0,1]
	v_pk_add_f32 v[204:205], v[26:27], v[28:29] op_sel:[0,1] op_sel_hi:[1,0] neg_lo:[0,1]
	v_pk_mul_f32 v[206:207], v[210:211], v[210:211] op_sel:[1,1] op_sel_hi:[1,0]
	v_pk_fma_f32 v[212:213], v[210:211], v[210:211], v[206:207] op_sel_hi:[0,1,1] neg_lo:[0,0,1]
	v_pk_mul_f32 v[206:207], v[210:211], v[212:213] op_sel:[1,1] op_sel_hi:[1,0]
	v_pk_fma_f32 v[220:221], v[210:211], v[212:213], v[206:207] op_sel_hi:[0,1,1] neg_lo:[0,0,1]
	v_pk_mul_f32 v[26:27], v[210:211], v[202:203] op_sel:[1,1] op_sel_hi:[1,0]
	v_pk_fma_f32 v[26:27], v[210:211], v[202:203], v[26:27] op_sel_hi:[0,1,1] neg_lo:[0,0,1]
	v_pk_mul_f32 v[28:29], v[212:213], v[32:33] op_sel:[1,1] op_sel_hi:[1,0]
	v_pk_fma_f32 v[28:29], v[212:213], v[32:33], v[28:29] op_sel_hi:[0,1,1] neg_lo:[0,0,1]
	v_pk_mul_f32 v[32:33], v[220:221], v[204:205] op_sel:[1,1] op_sel_hi:[1,0]
	v_pk_fma_f32 v[32:33], v[220:221], v[204:205], v[32:33] op_sel_hi:[0,1,1] neg_lo:[0,0,1]
	v_add_f32_e32 v214, 0x3e000000, v201
	v_cos_f32_e32 v210, v214
	v_sin_f32_e64 v211, -v214
	s_waitcnt lgkmcnt(3)
; DI f32x2 cmul(f32x2 a, f32x2 b) { return mkf2(a.x * b.x - a.y * b.y, a.x * b.y + a.y * b.x); }
; DI void fft8192(f32x2* buf, const f32x2* __restrict__ tw) {
;     ...
; #pragma unroll
;     for (int e = 0; e < 8; ++e) {
;       const int i = tid + 256 * e;
;       const int q = i & (s - 1);
;       const int ps = i - q;
;       const float rev = (float)ps * (1.f / 8192.f);
;       const f32x2 w1 = mkf2(__builtin_amdgcn_cosf(rev), -__builtin_amdgcn_sinf(rev));
;       const f32x2 w2 = cmul(w1, w1), w3 = cmul(w1, w2);
;       const f32x2 apc = mkf2(a[e].x + c[e].x, a[e].y + c[e].y), amc = mkf2(a[e].x - c[e].x, a[e].y - c[e].y);
;       const f32x2 bpd = mkf2(b[e].x + d[e].x, b[e].y + d[e].y), bmd = mkf2(b[e].x - d[e].x, b[e].y - d[e].y);
;       const int o = 4 * i - 3 * q;
;       buf[SW(o)] = mkf2(apc.x + bpd.x, apc.y + bpd.y);
;       buf[SW(o + s)] = cmul(w1, mkf2(amc.x + bmd.y, amc.y - bmd.x));
;       buf[SW(o + 2 * s)] = cmul(w2, mkf2(apc.x - bpd.x, apc.y - bpd.y));
;       buf[SW(o + 3 * s)] = cmul(w3, mkf2(amc.x - bmd.y, amc.y + bmd.x));
;     }
	v_pk_add_f32 v[38:39], v[34:35], v[36:37]
	v_pk_add_f32 v[40:41], v[34:35], v[36:37] neg_lo:[0,1] neg_hi:[0,1]
	v_pk_add_f32 v[202:203], v[34:35], v[36:37] op_sel:[0,1] op_sel_hi:[1,0] neg_hi:[0,1]
	v_pk_add_f32 v[204:205], v[34:35], v[36:37] op_sel:[0,1] op_sel_hi:[1,0] neg_lo:[0,1]
	v_pk_mul_f32 v[206:207], v[210:211], v[210:211] op_sel:[1,1] op_sel_hi:[1,0]
	v_pk_fma_f32 v[212:213], v[210:211], v[210:211], v[206:207] op_sel_hi:[0,1,1] neg_lo:[0,0,1]
	v_pk_mul_f32 v[206:207], v[210:211], v[212:213] op_sel:[1,1] op_sel_hi:[1,0]
	v_pk_fma_f32 v[220:221], v[210:211], v[212:213], v[206:207] op_sel_hi:[0,1,1] neg_lo:[0,0,1]
	v_pk_mul_f32 v[34:35], v[210:211], v[202:203] op_sel:[1,1] op_sel_hi:[1,0]
	v_pk_fma_f32 v[34:35], v[210:211], v[202:203], v[34:35] op_sel_hi:[0,1,1] neg_lo:[0,0,1]
	v_pk_mul_f32 v[36:37], v[212:213], v[40:41] op_sel:[1,1] op_sel_hi:[1,0]
	v_pk_fma_f32 v[36:37], v[212:213], v[40:41], v[36:37] op_sel_hi:[0,1,1] neg_lo:[0,0,1]
	v_pk_mul_f32 v[40:41], v[220:221], v[204:205] op_sel:[1,1] op_sel_hi:[1,0]
	v_pk_fma_f32 v[40:41], v[220:221], v[204:205], v[40:41] op_sel_hi:[0,1,1] neg_lo:[0,0,1]
	v_add_f32_e32 v214, 0x3e200000, v201
	v_cos_f32_e32 v210, v214
	v_sin_f32_e64 v211, -v214
	s_waitcnt lgkmcnt(2)
	v_pk_add_f32 v[46:47], v[42:43], v[44:45]
	v_pk_add_f32 v[48:49], v[42:43], v[44:45] neg_lo:[0,1] neg_hi:[0,1]
	v_pk_add_f32 v[202:203], v[42:43], v[44:45] op_sel:[0,1] op_sel_hi:[1,0] neg_hi:[0,1]
	v_pk_add_f32 v[204:205], v[42:43], v[44:45] op_sel:[0,1] op_sel_hi:[1,0] neg_lo:[0,1]
	v_pk_mul_f32 v[206:207], v[210:211], v[210:211] op_sel:[1,1] op_sel_hi:[1,0]
	v_pk_fma_f32 v[212:213], v[210:211], v[210:211], v[206:207] op_sel_hi:[0,1,1] neg_lo:[0,0,1]
	v_pk_mul_f32 v[206:207], v[210:211], v[212:213] op_sel:[1,1] op_sel_hi:[1,0]
	v_pk_fma_f32 v[220:221], v[210:211], v[212:213], v[206:207] op_sel_hi:[0,1,1] neg_lo:[0,0,1]
	v_pk_mul_f32 v[42:43], v[210:211], v[202:203] op_sel:[1,1] op_sel_hi:[1,0]
	v_pk_fma_f32 v[42:43], v[210:211], v[202:203], v[42:43] op_sel_hi:[0,1,1] neg_lo:[0,0,1]
	v_pk_mul_f32 v[44:45], v[212:213], v[48:49] op_sel:[1,1] op_sel_hi:[1,0]
	v_pk_fma_f32 v[44:45], v[212:213], v[48:49], v[44:45] op_sel_hi:[0,1,1] neg_lo:[0,0,1]
	v_pk_mul_f32 v[48:49], v[220:221], v[204:205] op_sel:[1,1] op_sel_hi:[1,0]
	v_pk_fma_f32 v[48:49], v[220:221], v[204:205], v[48:49] op_sel_hi:[0,1,1] neg_lo:[0,0,1]
	v_add_f32_e32 v214, 0x3e400000, v201
	v_cos_f32_e32 v210, v214
	v_sin_f32_e64 v211, -v214
	s_waitcnt lgkmcnt(1)
	v_pk_add_f32 v[54:55], v[50:51], v[52:53]
	v_pk_add_f32 v[56:57], v[50:51], v[52:53] neg_lo:[0,1] neg_hi:[0,1]
	v_pk_add_f32 v[202:203], v[50:51], v[52:53] op_sel:[0,1] op_sel_hi:[1,0] neg_hi:[0,1]
	v_pk_add_f32 v[204:205], v[50:51], v[52:53] op_sel:[0,1] op_sel_hi:[1,0] neg_lo:[0,1]
	v_pk_mul_f32 v[206:207], v[210:211], v[210:211] op_sel:[1,1] op_sel_hi:[1,0]
	v_pk_fma_f32 v[212:213], v[210:211], v[210:211], v[206:207] op_sel_hi:[0,1,1] neg_lo:[0,0,1]
	v_pk_mul_f32 v[206:207], v[210:211], v[212:213] op_sel:[1,1] op_sel_hi:[1,0]
	v_pk_fma_f32 v[220:221], v[210:211], v[212:213], v[206:207] op_sel_hi:[0,1,1] neg_lo:[0,0,1]
	v_pk_mul_f32 v[50:51], v[210:211], v[202:203] op_sel:[1,1] op_sel_hi:[1,0]
	v_pk_fma_f32 v[50:51], v[210:211], v[202:203], v[50:51] op_sel_hi:[0,1,1] neg_lo:[0,0,1]
	v_pk_mul_f32 v[52:53], v[212:213], v[56:57] op_sel:[1,1] op_sel_hi:[1,0]
	v_pk_fma_f32 v[52:53], v[212:213], v[56:57], v[52:53] op_sel_hi:[0,1,1] neg_lo:[0,0,1]
	v_pk_mul_f32 v[56:57], v[220:221], v[204:205] op_sel:[1,1] op_sel_hi:[1,0]
	v_pk_fma_f32 v[56:57], v[220:221], v[204:205], v[56:57] op_sel_hi:[0,1,1] neg_lo:[0,0,1]
	v_add_f32_e32 v214, 0x3e600000, v201
	v_cos_f32_e32 v210, v214
	v_sin_f32_e64 v211, -v214
	s_waitcnt lgkmcnt(0)
	v_pk_add_f32 v[62:63], v[58:59], v[60:61]
	v_pk_add_f32 v[64:65], v[58:59], v[60:61] neg_lo:[0,1] neg_hi:[0,1]
	v_pk_add_f32 v[202:203], v[58:59], v[60:61] op_sel:[0,1] op_sel_hi:[1,0] neg_hi:[0,1]
	v_pk_add_f32 v[204:205], v[58:59], v[60:61] op_sel:[0,1] op_sel_hi:[1,0] neg_lo:[0,1]
	v_pk_mul_f32 v[206:207], v[210:211], v[210:211] op_sel:[1,1] op_sel_hi:[1,0]
	v_pk_fma_f32 v[212:213], v[210:211], v[210:211], v[206:207] op_sel_hi:[0,1,1] neg_lo:[0,0,1]
	v_pk_mul_f32 v[206:207], v[210:211], v[212:213] op_sel:[1,1] op_sel_hi:[1,0]
	v_pk_fma_f32 v[220:221], v[210:211], v[212:213], v[206:207] op_sel_hi:[0,1,1] neg_lo:[0,0,1]
	v_pk_mul_f32 v[58:59], v[210:211], v[202:203] op_sel:[1,1] op_sel_hi:[1,0]
	v_pk_fma_f32 v[58:59], v[210:211], v[202:203], v[58:59] op_sel_hi:[0,1,1] neg_lo:[0,0,1]
	v_pk_mul_f32 v[60:61], v[212:213], v[64:65] op_sel:[1,1] op_sel_hi:[1,0]
	v_pk_fma_f32 v[60:61], v[212:213], v[64:65], v[60:61] op_sel_hi:[0,1,1] neg_lo:[0,0,1]
	v_pk_mul_f32 v[64:65], v[220:221], v[204:205] op_sel:[1,1] op_sel_hi:[1,0]
	v_pk_fma_f32 v[64:65], v[220:221], v[204:205], v[64:65] op_sel_hi:[0,1,1] neg_lo:[0,0,1]
	s_barrier
; DI f32x2 cmul(f32x2 a, f32x2 b) { return mkf2(a.x * b.x - a.y * b.y, a.x * b.y + a.y * b.x); }
; DI void fft8192(f32x2* buf, const f32x2* __restrict__ tw) {
;     ...
; #pragma unroll
;     for (int e = 0; e < 8; ++e) {
;       const int i = tid + 256 * e;
;       const int q = i & (s - 1);
;       const int ps = i - q;
;       const float rev = (float)ps * (1.f / 8192.f);
;       const f32x2 w1 = mkf2(__builtin_amdgcn_cosf(rev), -__builtin_amdgcn_sinf(rev));
;       const f32x2 w2 = cmul(w1, w1), w3 = cmul(w1, w2);
;       const f32x2 apc = mkf2(a[e].x + c[e].x, a[e].y + c[e].y), amc = mkf2(a[e].x - c[e].x, a[e].y - c[e].y);
;       const f32x2 bpd = mkf2(b[e].x + d[e].x, b[e].y + d[e].y), bmd = mkf2(b[e].x - d[e].x, b[e].y - d[e].y);
;       const int o = 4 * i - 3 * q;
;       buf[SW(o)] = mkf2(apc.x + bpd.x, apc.y + bpd.y);
;       buf[SW(o + s)] = cmul(w1, mkf2(amc.x + bmd.y, amc.y - bmd.x));
;       buf[SW(o + 2 * s)] = cmul(w2, mkf2(apc.x - bpd.x, apc.y - bpd.y));
;       buf[SW(o + 3 * s)] = cmul(w3, mkf2(amc.x - bmd.y, amc.y + bmd.x));
;     }
	v_mul_f32_e32 v214, 4.0, v201
	v_cos_f32_e32 v224, v214
	v_sin_f32_e64 v225, -v214
	s_nop 0
	v_pk_mul_f32 v[206:207], v[224:225], v[224:225] op_sel:[1,1] op_sel_hi:[1,0]
	v_pk_fma_f32 v[226:227], v[224:225], v[224:225], v[206:207] op_sel_hi:[0,1,1] neg_lo:[0,0,1]
	v_pk_mul_f32 v[206:207], v[224:225], v[226:227] op_sel:[1,1] op_sel_hi:[1,0]
	v_pk_fma_f32 v[230:231], v[224:225], v[226:227], v[206:207] op_sel_hi:[0,1,1] neg_lo:[0,0,1]
	v_pk_add_f32 v[202:203], v[6:7], v[38:39]
	v_pk_add_f32 v[6:7], v[6:7], v[38:39] neg_lo:[0,1] neg_hi:[0,1]
	v_pk_add_f32 v[204:205], v[22:23], v[54:55]
	v_pk_add_f32 v[22:23], v[22:23], v[54:55] neg_lo:[0,1] neg_hi:[0,1]
	v_pk_add_f32 v[38:39], v[202:203], v[204:205]
	v_pk_add_f32 v[54:55], v[202:203], v[204:205] neg_lo:[0,1] neg_hi:[0,1]
	v_pk_add_f32 v[202:203], v[6:7], v[22:23] op_sel:[0,1] op_sel_hi:[1,0] neg_hi:[0,1]
	v_pk_add_f32 v[204:205], v[6:7], v[22:23] op_sel:[0,1] op_sel_hi:[1,0] neg_lo:[0,1]
	v_pk_mul_f32 v[6:7], v[224:225], v[202:203] op_sel:[1,1] op_sel_hi:[1,0]
	v_pk_fma_f32 v[6:7], v[224:225], v[202:203], v[6:7] op_sel_hi:[0,1,1] neg_lo:[0,0,1]
	v_pk_mul_f32 v[22:23], v[226:227], v[54:55] op_sel:[1,1] op_sel_hi:[1,0]
	v_pk_fma_f32 v[22:23], v[226:227], v[54:55], v[22:23] op_sel_hi:[0,1,1] neg_lo:[0,0,1]
	v_pk_mul_f32 v[54:55], v[230:231], v[204:205] op_sel:[1,1] op_sel_hi:[1,0]
	v_pk_fma_f32 v[54:55], v[230:231], v[204:205], v[54:55] op_sel_hi:[0,1,1] neg_lo:[0,0,1]
	v_pk_add_f32 v[202:203], v[2:3], v[34:35]
	v_pk_add_f32 v[2:3], v[2:3], v[34:35] neg_lo:[0,1] neg_hi:[0,1]
	v_pk_add_f32 v[204:205], v[18:19], v[50:51]
	v_pk_add_f32 v[18:19], v[18:19], v[50:51] neg_lo:[0,1] neg_hi:[0,1]
	v_pk_add_f32 v[34:35], v[202:203], v[204:205]
	v_pk_add_f32 v[50:51], v[202:203], v[204:205] neg_lo:[0,1] neg_hi:[0,1]
	v_pk_add_f32 v[202:203], v[2:3], v[18:19] op_sel:[0,1] op_sel_hi:[1,0] neg_hi:[0,1]
	v_pk_add_f32 v[204:205], v[2:3], v[18:19] op_sel:[0,1] op_sel_hi:[1,0] neg_lo:[0,1]
	v_pk_mul_f32 v[2:3], v[224:225], v[202:203] op_sel:[1,1] op_sel_hi:[1,0]
	v_pk_fma_f32 v[2:3], v[224:225], v[202:203], v[2:3] op_sel_hi:[0,1,1] neg_lo:[0,0,1]
	v_pk_mul_f32 v[18:19], v[226:227], v[50:51] op_sel:[1,1] op_sel_hi:[1,0]
	v_pk_fma_f32 v[18:19], v[226:227], v[50:51], v[18:19] op_sel_hi:[0,1,1] neg_lo:[0,0,1]
	v_pk_mul_f32 v[50:51], v[230:231], v[204:205] op_sel:[1,1] op_sel_hi:[1,0]
	v_pk_fma_f32 v[50:51], v[230:231], v[204:205], v[50:51] op_sel_hi:[0,1,1] neg_lo:[0,0,1]
	v_pk_add_f32 v[202:203], v[4:5], v[36:37]
	v_pk_add_f32 v[4:5], v[4:5], v[36:37] neg_lo:[0,1] neg_hi:[0,1]
	v_pk_add_f32 v[204:205], v[20:21], v[52:53]
	v_pk_add_f32 v[20:21], v[20:21], v[52:53] neg_lo:[0,1] neg_hi:[0,1]
	v_pk_add_f32 v[36:37], v[202:203], v[204:205]
	v_pk_add_f32 v[52:53], v[202:203], v[204:205] neg_lo:[0,1] neg_hi:[0,1]
	v_pk_add_f32 v[202:203], v[4:5], v[20:21] op_sel:[0,1] op_sel_hi:[1,0] neg_hi:[0,1]
	v_pk_add_f32 v[204:205], v[4:5], v[20:21] op_sel:[0,1] op_sel_hi:[1,0] neg_lo:[0,1]
	v_pk_mul_f32 v[4:5], v[224:225], v[202:203] op_sel:[1,1] op_sel_hi:[1,0]
	v_pk_fma_f32 v[4:5], v[224:225], v[202:203], v[4:5] op_sel_hi:[0,1,1] neg_lo:[0,0,1]
	v_pk_mul_f32 v[20:21], v[226:227], v[52:53] op_sel:[1,1] op_sel_hi:[1,0]
	v_pk_fma_f32 v[20:21], v[226:227], v[52:53], v[20:21] op_sel_hi:[0,1,1] neg_lo:[0,0,1]
	v_pk_mul_f32 v[52:53], v[230:231], v[204:205] op_sel:[1,1] op_sel_hi:[1,0]
	v_pk_fma_f32 v[52:53], v[230:231], v[204:205], v[52:53] op_sel_hi:[0,1,1] neg_lo:[0,0,1]
	v_pk_add_f32 v[202:203], v[8:9], v[40:41]
	v_pk_add_f32 v[8:9], v[8:9], v[40:41] neg_lo:[0,1] neg_hi:[0,1]
	v_pk_add_f32 v[204:205], v[24:25], v[56:57]
	v_pk_add_f32 v[24:25], v[24:25], v[56:57] neg_lo:[0,1] neg_hi:[0,1]
	v_pk_add_f32 v[40:41], v[202:203], v[204:205]
	v_pk_add_f32 v[56:57], v[202:203], v[204:205] neg_lo:[0,1] neg_hi:[0,1]
	v_pk_add_f32 v[202:203], v[8:9], v[24:25] op_sel:[0,1] op_sel_hi:[1,0] neg_hi:[0,1]
	v_pk_add_f32 v[204:205], v[8:9], v[24:25] op_sel:[0,1] op_sel_hi:[1,0] neg_lo:[0,1]
	v_pk_mul_f32 v[8:9], v[224:225], v[202:203] op_sel:[1,1] op_sel_hi:[1,0]
	v_pk_fma_f32 v[8:9], v[224:225], v[202:203], v[8:9] op_sel_hi:[0,1,1] neg_lo:[0,0,1]
	v_pk_mul_f32 v[24:25], v[226:227], v[56:57] op_sel:[1,1] op_sel_hi:[1,0]
	v_pk_fma_f32 v[24:25], v[226:227], v[56:57], v[24:25] op_sel_hi:[0,1,1] neg_lo:[0,0,1]
	v_pk_mul_f32 v[56:57], v[230:231], v[204:205] op_sel:[1,1] op_sel_hi:[1,0]
	v_pk_fma_f32 v[56:57], v[230:231], v[204:205], v[56:57] op_sel_hi:[0,1,1] neg_lo:[0,0,1]
	v_mul_f32_e32 v214, 4.0, v201
	v_add_f32_e32 v214, 0x3e000000, v214
	v_cos_f32_e32 v224, v214
	v_sin_f32_e64 v225, -v214
	s_nop 0
	v_pk_mul_f32 v[206:207], v[224:225], v[224:225] op_sel:[1,1] op_sel_hi:[1,0]
	v_pk_fma_f32 v[226:227], v[224:225], v[224:225], v[206:207] op_sel_hi:[0,1,1] neg_lo:[0,0,1]
	v_pk_mul_f32 v[206:207], v[224:225], v[226:227] op_sel:[1,1] op_sel_hi:[1,0]
	v_pk_fma_f32 v[230:231], v[224:225], v[226:227], v[206:207] op_sel_hi:[0,1,1] neg_lo:[0,0,1]
	v_pk_add_f32 v[202:203], v[14:15], v[46:47]
	v_pk_add_f32 v[14:15], v[14:15], v[46:47] neg_lo:[0,1] neg_hi:[0,1]
	v_pk_add_f32 v[204:205], v[30:31], v[62:63]
	v_pk_add_f32 v[30:31], v[30:31], v[62:63] neg_lo:[0,1] neg_hi:[0,1]
	v_pk_add_f32 v[46:47], v[202:203], v[204:205]
	v_pk_add_f32 v[62:63], v[202:203], v[204:205] neg_lo:[0,1] neg_hi:[0,1]
	v_pk_add_f32 v[202:203], v[14:15], v[30:31] op_sel:[0,1] op_sel_hi:[1,0] neg_hi:[0,1]
	v_pk_add_f32 v[204:205], v[14:15], v[30:31] op_sel:[0,1] op_sel_hi:[1,0] neg_lo:[0,1]
	v_pk_mul_f32 v[14:15], v[224:225], v[202:203] op_sel:[1,1] op_sel_hi:[1,0]
	v_pk_fma_f32 v[14:15], v[224:225], v[202:203], v[14:15] op_sel_hi:[0,1,1] neg_lo:[0,0,1]
	v_pk_mul_f32 v[30:31], v[226:227], v[62:63] op_sel:[1,1] op_sel_hi:[1,0]
; DI f32x2 cmul(f32x2 a, f32x2 b) { return mkf2(a.x * b.x - a.y * b.y, a.x * b.y + a.y * b.x); }
; DI void fft8192(f32x2* buf, const f32x2* __restrict__ tw) {
;     ...
; #pragma unroll
;     for (int e = 0; e < 8; ++e) {
;       const int i = tid + 256 * e;
;       const int q = i & (s - 1);
;       const int ps = i - q;
;       const float rev = (float)ps * (1.f / 8192.f);
;       const f32x2 w1 = mkf2(__builtin_amdgcn_cosf(rev), -__builtin_amdgcn_sinf(rev));
;       const f32x2 w2 = cmul(w1, w1), w3 = cmul(w1, w2);
;       const f32x2 apc = mkf2(a[e].x + c[e].x, a[e].y + c[e].y), amc = mkf2(a[e].x - c[e].x, a[e].y - c[e].y);
;       const f32x2 bpd = mkf2(b[e].x + d[e].x, b[e].y + d[e].y), bmd = mkf2(b[e].x - d[e].x, b[e].y - d[e].y);
;       const int o = 4 * i - 3 * q;
;       buf[SW(o)] = mkf2(apc.x + bpd.x, apc.y + bpd.y);
;       buf[SW(o + s)] = cmul(w1, mkf2(amc.x + bmd.y, amc.y - bmd.x));
;       buf[SW(o + 2 * s)] = cmul(w2, mkf2(apc.x - bpd.x, apc.y - bpd.y));
;       buf[SW(o + 3 * s)] = cmul(w3, mkf2(amc.x - bmd.y, amc.y + bmd.x));
;     }
	v_pk_fma_f32 v[30:31], v[226:227], v[62:63], v[30:31] op_sel_hi:[0,1,1] neg_lo:[0,0,1]
	v_pk_mul_f32 v[62:63], v[230:231], v[204:205] op_sel:[1,1] op_sel_hi:[1,0]
	v_pk_fma_f32 v[62:63], v[230:231], v[204:205], v[62:63] op_sel_hi:[0,1,1] neg_lo:[0,0,1]
	v_pk_add_f32 v[202:203], v[10:11], v[42:43]
	v_pk_add_f32 v[10:11], v[10:11], v[42:43] neg_lo:[0,1] neg_hi:[0,1]
	v_pk_add_f32 v[204:205], v[26:27], v[58:59]
	v_pk_add_f32 v[26:27], v[26:27], v[58:59] neg_lo:[0,1] neg_hi:[0,1]
	v_pk_add_f32 v[42:43], v[202:203], v[204:205]
	v_pk_add_f32 v[58:59], v[202:203], v[204:205] neg_lo:[0,1] neg_hi:[0,1]
	v_pk_add_f32 v[202:203], v[10:11], v[26:27] op_sel:[0,1] op_sel_hi:[1,0] neg_hi:[0,1]
	v_pk_add_f32 v[204:205], v[10:11], v[26:27] op_sel:[0,1] op_sel_hi:[1,0] neg_lo:[0,1]
	v_pk_mul_f32 v[10:11], v[224:225], v[202:203] op_sel:[1,1] op_sel_hi:[1,0]
	v_pk_fma_f32 v[10:11], v[224:225], v[202:203], v[10:11] op_sel_hi:[0,1,1] neg_lo:[0,0,1]
	v_pk_mul_f32 v[26:27], v[226:227], v[58:59] op_sel:[1,1] op_sel_hi:[1,0]
	v_pk_fma_f32 v[26:27], v[226:227], v[58:59], v[26:27] op_sel_hi:[0,1,1] neg_lo:[0,0,1]
	v_pk_mul_f32 v[58:59], v[230:231], v[204:205] op_sel:[1,1] op_sel_hi:[1,0]
	v_pk_fma_f32 v[58:59], v[230:231], v[204:205], v[58:59] op_sel_hi:[0,1,1] neg_lo:[0,0,1]
	v_pk_add_f32 v[202:203], v[12:13], v[44:45]
	v_pk_add_f32 v[12:13], v[12:13], v[44:45] neg_lo:[0,1] neg_hi:[0,1]
	v_pk_add_f32 v[204:205], v[28:29], v[60:61]
	v_pk_add_f32 v[28:29], v[28:29], v[60:61] neg_lo:[0,1] neg_hi:[0,1]
	v_pk_add_f32 v[44:45], v[202:203], v[204:205]
	v_pk_add_f32 v[60:61], v[202:203], v[204:205] neg_lo:[0,1] neg_hi:[0,1]
	v_pk_add_f32 v[202:203], v[12:13], v[28:29] op_sel:[0,1] op_sel_hi:[1,0] neg_hi:[0,1]
	v_pk_add_f32 v[204:205], v[12:13], v[28:29] op_sel:[0,1] op_sel_hi:[1,0] neg_lo:[0,1]
	v_pk_mul_f32 v[12:13], v[224:225], v[202:203] op_sel:[1,1] op_sel_hi:[1,0]
	v_pk_fma_f32 v[12:13], v[224:225], v[202:203], v[12:13] op_sel_hi:[0,1,1] neg_lo:[0,0,1]
	v_pk_mul_f32 v[28:29], v[226:227], v[60:61] op_sel:[1,1] op_sel_hi:[1,0]
	v_pk_fma_f32 v[28:29], v[226:227], v[60:61], v[28:29] op_sel_hi:[0,1,1] neg_lo:[0,0,1]
	v_pk_mul_f32 v[60:61], v[230:231], v[204:205] op_sel:[1,1] op_sel_hi:[1,0]
	v_pk_fma_f32 v[60:61], v[230:231], v[204:205], v[60:61] op_sel_hi:[0,1,1] neg_lo:[0,0,1]
	v_pk_add_f32 v[202:203], v[16:17], v[48:49]
	v_pk_add_f32 v[16:17], v[16:17], v[48:49] neg_lo:[0,1] neg_hi:[0,1]
	v_pk_add_f32 v[204:205], v[32:33], v[64:65]
	v_pk_add_f32 v[32:33], v[32:33], v[64:65] neg_lo:[0,1] neg_hi:[0,1]
	v_pk_add_f32 v[48:49], v[202:203], v[204:205]
	v_pk_add_f32 v[64:65], v[202:203], v[204:205] neg_lo:[0,1] neg_hi:[0,1]
	v_pk_add_f32 v[202:203], v[16:17], v[32:33] op_sel:[0,1] op_sel_hi:[1,0] neg_hi:[0,1]
	v_pk_add_f32 v[204:205], v[16:17], v[32:33] op_sel:[0,1] op_sel_hi:[1,0] neg_lo:[0,1]
	v_pk_mul_f32 v[16:17], v[224:225], v[202:203] op_sel:[1,1] op_sel_hi:[1,0]
	v_pk_fma_f32 v[16:17], v[224:225], v[202:203], v[16:17] op_sel_hi:[0,1,1] neg_lo:[0,0,1]
	v_pk_mul_f32 v[32:33], v[226:227], v[64:65] op_sel:[1,1] op_sel_hi:[1,0]
	v_pk_fma_f32 v[32:33], v[226:227], v[64:65], v[32:33] op_sel_hi:[0,1,1] neg_lo:[0,0,1]
	v_pk_mul_f32 v[64:65], v[230:231], v[204:205] op_sel:[1,1] op_sel_hi:[1,0]
	v_pk_fma_f32 v[64:65], v[230:231], v[204:205], v[64:65] op_sel_hi:[0,1,1] neg_lo:[0,0,1]
	ds_write_b64 v164, v[38:39] offset:0
	v_xor_b32_e32 v156, 8, v164
	ds_write_b64 v156, v[34:35] offset:0
	v_xor_b32_e32 v158, 16, v164
	ds_write_b64 v158, v[36:37] offset:0
	v_xor_b32_e32 v160, 24, v164
	ds_write_b64 v160, v[40:41] offset:0
	v_xor_b32_e32 v162, 32, v164
	ds_write_b64 v162, v[6:7] offset:0
	v_xor_b32_e32 v156, 40, v164
	ds_write_b64 v156, v[2:3] offset:0
	v_xor_b32_e32 v158, 48, v164
	ds_write_b64 v158, v[4:5] offset:0
	v_xor_b32_e32 v160, 56, v164
	ds_write_b64 v160, v[8:9] offset:0
	v_xor_b32_e32 v162, 64, v164
	ds_write_b64 v162, v[22:23] offset:0
	v_xor_b32_e32 v156, 0x48, v164
	ds_write_b64 v156, v[18:19] offset:0
	v_xor_b32_e32 v158, 0x50, v164
	ds_write_b64 v158, v[20:21] offset:0
	v_xor_b32_e32 v160, 0x58, v164
	ds_write_b64 v160, v[24:25] offset:0
	v_xor_b32_e32 v162, 0x60, v164
	ds_write_b64 v162, v[54:55] offset:0
	v_xor_b32_e32 v156, 0x68, v164
	ds_write_b64 v156, v[50:51] offset:0
	v_xor_b32_e32 v158, 0x70, v164
	ds_write_b64 v158, v[52:53] offset:0
	v_xor_b32_e32 v160, 0x78, v164
	ds_write_b64 v160, v[56:57] offset:0
	ds_write_b64 v164, v[46:47] offset:32768
	v_xor_b32_e32 v162, 8, v164
	ds_write_b64 v162, v[42:43] offset:32768
	v_xor_b32_e32 v156, 16, v164
	ds_write_b64 v156, v[44:45] offset:32768
	v_xor_b32_e32 v158, 24, v164
	ds_write_b64 v158, v[48:49] offset:32768
	v_xor_b32_e32 v160, 32, v164
	ds_write_b64 v160, v[14:15] offset:32768
	v_xor_b32_e32 v162, 40, v164
	ds_write_b64 v162, v[10:11] offset:32768
	v_xor_b32_e32 v156, 48, v164
	ds_write_b64 v156, v[12:13] offset:32768
	v_xor_b32_e32 v158, 56, v164
	ds_write_b64 v158, v[16:17] offset:32768
	v_xor_b32_e32 v160, 64, v164
	ds_write_b64 v160, v[30:31] offset:32768
	v_xor_b32_e32 v162, 0x48, v164
	ds_write_b64 v162, v[26:27] offset:32768
	v_xor_b32_e32 v156, 0x50, v164
	ds_write_b64 v156, v[28:29] offset:32768
	v_xor_b32_e32 v158, 0x58, v164
	ds_write_b64 v158, v[32:33] offset:32768
	v_xor_b32_e32 v160, 0x60, v164
	ds_write_b64 v160, v[62:63] offset:32768
	v_xor_b32_e32 v162, 0x68, v164
	ds_write_b64 v162, v[58:59] offset:32768
	v_xor_b32_e32 v156, 0x70, v164
	ds_write_b64 v156, v[60:61] offset:32768
	v_xor_b32_e32 v158, 0x78, v164
	ds_write_b64 v158, v[64:65] offset:32768
	s_waitcnt lgkmcnt(0)
	s_barrier
; DI f32x2 cmul(f32x2 a, f32x2 b) { return mkf2(a.x * b.x - a.y * b.y, a.x * b.y + a.y * b.x); }
; DI void fft8192(f32x2* buf, const f32x2* __restrict__ tw) {
;     ...
;   for (int ls = 0; ls < 12; ls += 2) {
;     const int s = 1 << ls;
;     f32x2 a[8], b[8], c[8], d[8];
;     __syncthreads();
; #pragma unroll
;     for (int e = 0; e < 8; ++e) {
;       const int i = tid + 256 * e;
;       const int pi = SW(i);
;       a[e] = buf[pi]; b[e] = buf[pi + 2048]; c[e] = buf[pi + 4096]; d[e] = buf[pi + 6144];
;     }
;     __syncthreads();
; #pragma unroll
;     for (int e = 0; e < 8; ++e) {
;       const int i = tid + 256 * e;
;       const int q = i & (s - 1);
;       const int ps = i - q;
;       const float rev = (float)ps * (1.f / 8192.f);
;       const f32x2 w1 = mkf2(__builtin_amdgcn_cosf(rev), -__builtin_amdgcn_sinf(rev));
;       const f32x2 w2 = cmul(w1, w1), w3 = cmul(w1, w2);
;       const f32x2 apc = mkf2(a[e].x + c[e].x, a[e].y + c[e].y), amc = mkf2(a[e].x - c[e].x, a[e].y - c[e].y);
;       const f32x2 bpd = mkf2(b[e].x + d[e].x, b[e].y + d[e].y), bmd = mkf2(b[e].x - d[e].x, b[e].y - d[e].y);
;       const int o = 4 * i - 3 * q;
;       buf[SW(o)] = mkf2(apc.x + bpd.x, apc.y + bpd.y);
;       buf[SW(o + s)] = cmul(w1, mkf2(amc.x + bmd.y, amc.y - bmd.x));
;       buf[SW(o + 2 * s)] = cmul(w2, mkf2(apc.x - bpd.x, apc.y - bpd.y));
;       buf[SW(o + 3 * s)] = cmul(w3, mkf2(amc.x - bmd.y, amc.y + bmd.x));
;     }
	ds_read2st64_b64 v[2:5], v154 offset0:0 offset1:32
	ds_read2st64_b64 v[6:9], v154 offset0:64 offset1:96
	ds_read2st64_b64 v[10:13], v154 offset0:4 offset1:36
	ds_read2st64_b64 v[14:17], v154 offset0:68 offset1:100
	ds_read2st64_b64 v[18:21], v154 offset0:8 offset1:40
	ds_read2st64_b64 v[22:25], v154 offset0:72 offset1:104
	ds_read2st64_b64 v[26:29], v154 offset0:12 offset1:44
	ds_read2st64_b64 v[30:33], v154 offset0:76 offset1:108
	ds_read2st64_b64 v[34:37], v154 offset0:16 offset1:48
	ds_read2st64_b64 v[38:41], v154 offset0:80 offset1:112
	ds_read2st64_b64 v[42:45], v154 offset0:20 offset1:52
	ds_read2st64_b64 v[46:49], v154 offset0:84 offset1:116
	ds_read2st64_b64 v[50:53], v154 offset0:24 offset1:56
	ds_read2st64_b64 v[54:57], v154 offset0:88 offset1:120
	ds_read2st64_b64 v[58:61], v154 offset0:28 offset1:60
	ds_read2st64_b64 v[62:65], v154 offset0:92 offset1:124
	v_and_b32_e32 v166, 15, v0
	v_sub_u32_e32 v168, v0, v166
	v_cvt_f32_u32_e32 v201, v168
	v_lshl_add_u32 v164, v168, 4, v166
	v_lshlrev_b32_e32 v164, 3, v164
	v_mul_f32_e32 v201, 0x39000000, v201
	v_cos_f32_e32 v210, v201
	v_sin_f32_e64 v211, -v201
	s_waitcnt lgkmcnt(14)
	v_pk_add_f32 v[202:203], v[2:3], v[6:7]
	v_pk_add_f32 v[2:3], v[2:3], v[6:7] neg_lo:[0,1] neg_hi:[0,1]
	v_pk_add_f32 v[204:205], v[4:5], v[8:9]
	v_pk_add_f32 v[4:5], v[4:5], v[8:9] neg_lo:[0,1] neg_hi:[0,1]
	v_pk_add_f32 v[6:7], v[202:203], v[204:205]
	v_pk_add_f32 v[8:9], v[202:203], v[204:205] neg_lo:[0,1] neg_hi:[0,1]
	v_pk_add_f32 v[202:203], v[2:3], v[4:5] op_sel:[0,1] op_sel_hi:[1,0] neg_hi:[0,1]
	v_pk_add_f32 v[204:205], v[2:3], v[4:5] op_sel:[0,1] op_sel_hi:[1,0] neg_lo:[0,1]
	v_pk_mul_f32 v[206:207], v[210:211], v[210:211] op_sel:[1,1] op_sel_hi:[1,0]
	v_pk_fma_f32 v[212:213], v[210:211], v[210:211], v[206:207] op_sel_hi:[0,1,1] neg_lo:[0,0,1]
	v_pk_mul_f32 v[206:207], v[210:211], v[212:213] op_sel:[1,1] op_sel_hi:[1,0]
	v_pk_fma_f32 v[220:221], v[210:211], v[212:213], v[206:207] op_sel_hi:[0,1,1] neg_lo:[0,0,1]
	v_pk_mul_f32 v[2:3], v[210:211], v[202:203] op_sel:[1,1] op_sel_hi:[1,0]
	v_pk_fma_f32 v[2:3], v[210:211], v[202:203], v[2:3] op_sel_hi:[0,1,1] neg_lo:[0,0,1]
	v_pk_mul_f32 v[4:5], v[212:213], v[8:9] op_sel:[1,1] op_sel_hi:[1,0]
	v_pk_fma_f32 v[4:5], v[212:213], v[8:9], v[4:5] op_sel_hi:[0,1,1] neg_lo:[0,0,1]
	v_pk_mul_f32 v[8:9], v[220:221], v[204:205] op_sel:[1,1] op_sel_hi:[1,0]
	v_pk_fma_f32 v[8:9], v[220:221], v[204:205], v[8:9] op_sel_hi:[0,1,1] neg_lo:[0,0,1]
	v_add_f32_e32 v214, 0x3d000000, v201
	v_cos_f32_e32 v210, v214
	v_sin_f32_e64 v211, -v214
	s_waitcnt lgkmcnt(12)
	v_pk_add_f32 v[202:203], v[10:11], v[14:15]
	v_pk_add_f32 v[10:11], v[10:11], v[14:15] neg_lo:[0,1] neg_hi:[0,1]
	v_pk_add_f32 v[204:205], v[12:13], v[16:17]
	v_pk_add_f32 v[12:13], v[12:13], v[16:17] neg_lo:[0,1] neg_hi:[0,1]
	v_pk_add_f32 v[14:15], v[202:203], v[204:205]
	v_pk_add_f32 v[16:17], v[202:203], v[204:205] neg_lo:[0,1] neg_hi:[0,1]
	v_pk_add_f32 v[202:203], v[10:11], v[12:13] op_sel:[0,1] op_sel_hi:[1,0] neg_hi:[0,1]
	v_pk_add_f32 v[204:205], v[10:11], v[12:13] op_sel:[0,1] op_sel_hi:[1,0] neg_lo:[0,1]
	v_pk_mul_f32 v[206:207], v[210:211], v[210:211] op_sel:[1,1] op_sel_hi:[1,0]
	v_pk_fma_f32 v[212:213], v[210:211], v[210:211], v[206:207] op_sel_hi:[0,1,1] neg_lo:[0,0,1]
	v_pk_mul_f32 v[206:207], v[210:211], v[212:213] op_sel:[1,1] op_sel_hi:[1,0]
	v_pk_fma_f32 v[220:221], v[210:211], v[212:213], v[206:207] op_sel_hi:[0,1,1] neg_lo:[0,0,1]
	v_pk_mul_f32 v[10:11], v[210:211], v[202:203] op_sel:[1,1] op_sel_hi:[1,0]
	v_pk_fma_f32 v[10:11], v[210:211], v[202:203], v[10:11] op_sel_hi:[0,1,1] neg_lo:[0,0,1]
	v_pk_mul_f32 v[12:13], v[212:213], v[16:17] op_sel:[1,1] op_sel_hi:[1,0]
	v_pk_fma_f32 v[12:13], v[212:213], v[16:17], v[12:13] op_sel_hi:[0,1,1] neg_lo:[0,0,1]
	v_pk_mul_f32 v[16:17], v[220:221], v[204:205] op_sel:[1,1] op_sel_hi:[1,0]
	v_pk_fma_f32 v[16:17], v[220:221], v[204:205], v[16:17] op_sel_hi:[0,1,1] neg_lo:[0,0,1]
	v_add_f32_e32 v214, 0x3d800000, v201
	v_cos_f32_e32 v210, v214
	v_sin_f32_e64 v211, -v214
	s_waitcnt lgkmcnt(10)
	v_pk_add_f32 v[202:203], v[18:19], v[22:23]
	v_pk_add_f32 v[18:19], v[18:19], v[22:23] neg_lo:[0,1] neg_hi:[0,1]
	v_pk_add_f32 v[204:205], v[20:21], v[24:25]
	v_pk_add_f32 v[20:21], v[20:21], v[24:25] neg_lo:[0,1] neg_hi:[0,1]
	v_pk_add_f32 v[22:23], v[202:203], v[204:205]
	v_pk_add_f32 v[24:25], v[202:203], v[204:205] neg_lo:[0,1] neg_hi:[0,1]
	v_pk_add_f32 v[202:203], v[18:19], v[20:21] op_sel:[0,1] op_sel_hi:[1,0] neg_hi:[0,1]
	v_pk_add_f32 v[204:205], v[18:19], v[20:21] op_sel:[0,1] op_sel_hi:[1,0] neg_lo:[0,1]
	v_pk_mul_f32 v[206:207], v[210:211], v[210:211] op_sel:[1,1] op_sel_hi:[1,0]
	v_pk_fma_f32 v[212:213], v[210:211], v[210:211], v[206:207] op_sel_hi:[0,1,1] neg_lo:[0,0,1]
	v_pk_mul_f32 v[206:207], v[210:211], v[212:213] op_sel:[1,1] op_sel_hi:[1,0]
	v_pk_fma_f32 v[220:221], v[210:211], v[212:213], v[206:207] op_sel_hi:[0,1,1] neg_lo:[0,0,1]
	v_pk_mul_f32 v[18:19], v[210:211], v[202:203] op_sel:[1,1] op_sel_hi:[1,0]
	v_pk_fma_f32 v[18:19], v[210:211], v[202:203], v[18:19] op_sel_hi:[0,1,1] neg_lo:[0,0,1]
	v_pk_mul_f32 v[20:21], v[212:213], v[24:25] op_sel:[1,1] op_sel_hi:[1,0]
	v_pk_fma_f32 v[20:21], v[212:213], v[24:25], v[20:21] op_sel_hi:[0,1,1] neg_lo:[0,0,1]
	v_pk_mul_f32 v[24:25], v[220:221], v[204:205] op_sel:[1,1] op_sel_hi:[1,0]
	v_pk_fma_f32 v[24:25], v[220:221], v[204:205], v[24:25] op_sel_hi:[0,1,1] neg_lo:[0,0,1]
	v_add_f32_e32 v214, 0x3dc00000, v201
	v_cos_f32_e32 v210, v214
	v_sin_f32_e64 v211, -v214
	s_waitcnt lgkmcnt(8)
; DI f32x2 cmul(f32x2 a, f32x2 b) { return mkf2(a.x * b.x - a.y * b.y, a.x * b.y + a.y * b.x); }
; DI void fft8192(f32x2* buf, const f32x2* __restrict__ tw) {
;     ...
; #pragma unroll
;     for (int e = 0; e < 8; ++e) {
;       const int i = tid + 256 * e;
;       const int q = i & (s - 1);
;       const int ps = i - q;
;       const float rev = (float)ps * (1.f / 8192.f);
;       const f32x2 w1 = mkf2(__builtin_amdgcn_cosf(rev), -__builtin_amdgcn_sinf(rev));
;       const f32x2 w2 = cmul(w1, w1), w3 = cmul(w1, w2);
;       const f32x2 apc = mkf2(a[e].x + c[e].x, a[e].y + c[e].y), amc = mkf2(a[e].x - c[e].x, a[e].y - c[e].y);
;       const f32x2 bpd = mkf2(b[e].x + d[e].x, b[e].y + d[e].y), bmd = mkf2(b[e].x - d[e].x, b[e].y - d[e].y);
;       const int o = 4 * i - 3 * q;
;       buf[SW(o)] = mkf2(apc.x + bpd.x, apc.y + bpd.y);
;       buf[SW(o + s)] = cmul(w1, mkf2(amc.x + bmd.y, amc.y - bmd.x));
;       buf[SW(o + 2 * s)] = cmul(w2, mkf2(apc.x - bpd.x, apc.y - bpd.y));
;       buf[SW(o + 3 * s)] = cmul(w3, mkf2(amc.x - bmd.y, amc.y + bmd.x));
;     }
	v_pk_add_f32 v[202:203], v[26:27], v[30:31]
	v_pk_add_f32 v[26:27], v[26:27], v[30:31] neg_lo:[0,1] neg_hi:[0,1]
	v_pk_add_f32 v[204:205], v[28:29], v[32:33]
	v_pk_add_f32 v[28:29], v[28:29], v[32:33] neg_lo:[0,1] neg_hi:[0,1]
	v_pk_add_f32 v[30:31], v[202:203], v[204:205]
	v_pk_add_f32 v[32:33], v[202:203], v[204:205] neg_lo:[0,1] neg_hi:[0,1]
	v_pk_add_f32 v[202:203], v[26:27], v[28:29] op_sel:[0,1] op_sel_hi:[1,0] neg_hi:[0,1]
	v_pk_add_f32 v[204:205], v[26:27], v[28:29] op_sel:[0,1] op_sel_hi:[1,0] neg_lo:[0,1]
	v_pk_mul_f32 v[206:207], v[210:211], v[210:211] op_sel:[1,1] op_sel_hi:[1,0]
	v_pk_fma_f32 v[212:213], v[210:211], v[210:211], v[206:207] op_sel_hi:[0,1,1] neg_lo:[0,0,1]
	v_pk_mul_f32 v[206:207], v[210:211], v[212:213] op_sel:[1,1] op_sel_hi:[1,0]
	v_pk_fma_f32 v[220:221], v[210:211], v[212:213], v[206:207] op_sel_hi:[0,1,1] neg_lo:[0,0,1]
	v_pk_mul_f32 v[26:27], v[210:211], v[202:203] op_sel:[1,1] op_sel_hi:[1,0]
	v_pk_fma_f32 v[26:27], v[210:211], v[202:203], v[26:27] op_sel_hi:[0,1,1] neg_lo:[0,0,1]
	v_pk_mul_f32 v[28:29], v[212:213], v[32:33] op_sel:[1,1] op_sel_hi:[1,0]
	v_pk_fma_f32 v[28:29], v[212:213], v[32:33], v[28:29] op_sel_hi:[0,1,1] neg_lo:[0,0,1]
	v_pk_mul_f32 v[32:33], v[220:221], v[204:205] op_sel:[1,1] op_sel_hi:[1,0]
	v_pk_fma_f32 v[32:33], v[220:221], v[204:205], v[32:33] op_sel_hi:[0,1,1] neg_lo:[0,0,1]
	v_add_f32_e32 v214, 0x3e000000, v201
	v_cos_f32_e32 v210, v214
	v_sin_f32_e64 v211, -v214
	s_waitcnt lgkmcnt(6)
	v_pk_add_f32 v[202:203], v[34:35], v[38:39]
	v_pk_add_f32 v[34:35], v[34:35], v[38:39] neg_lo:[0,1] neg_hi:[0,1]
	v_pk_add_f32 v[204:205], v[36:37], v[40:41]
	v_pk_add_f32 v[36:37], v[36:37], v[40:41] neg_lo:[0,1] neg_hi:[0,1]
	v_pk_add_f32 v[38:39], v[202:203], v[204:205]
	v_pk_add_f32 v[40:41], v[202:203], v[204:205] neg_lo:[0,1] neg_hi:[0,1]
	v_pk_add_f32 v[202:203], v[34:35], v[36:37] op_sel:[0,1] op_sel_hi:[1,0] neg_hi:[0,1]
	v_pk_add_f32 v[204:205], v[34:35], v[36:37] op_sel:[0,1] op_sel_hi:[1,0] neg_lo:[0,1]
	v_pk_mul_f32 v[206:207], v[210:211], v[210:211] op_sel:[1,1] op_sel_hi:[1,0]
	v_pk_fma_f32 v[212:213], v[210:211], v[210:211], v[206:207] op_sel_hi:[0,1,1] neg_lo:[0,0,1]
	v_pk_mul_f32 v[206:207], v[210:211], v[212:213] op_sel:[1,1] op_sel_hi:[1,0]
	v_pk_fma_f32 v[220:221], v[210:211], v[212:213], v[206:207] op_sel_hi:[0,1,1] neg_lo:[0,0,1]
	v_pk_mul_f32 v[34:35], v[210:211], v[202:203] op_sel:[1,1] op_sel_hi:[1,0]
	v_pk_fma_f32 v[34:35], v[210:211], v[202:203], v[34:35] op_sel_hi:[0,1,1] neg_lo:[0,0,1]
	v_pk_mul_f32 v[36:37], v[212:213], v[40:41] op_sel:[1,1] op_sel_hi:[1,0]
	v_pk_fma_f32 v[36:37], v[212:213], v[40:41], v[36:37] op_sel_hi:[0,1,1] neg_lo:[0,0,1]
	v_pk_mul_f32 v[40:41], v[220:221], v[204:205] op_sel:[1,1] op_sel_hi:[1,0]
	v_pk_fma_f32 v[40:41], v[220:221], v[204:205], v[40:41] op_sel_hi:[0,1,1] neg_lo:[0,0,1]
	v_add_f32_e32 v214, 0x3e200000, v201
	v_cos_f32_e32 v210, v214
	v_sin_f32_e64 v211, -v214
	s_waitcnt lgkmcnt(4)
	v_pk_add_f32 v[202:203], v[42:43], v[46:47]
	v_pk_add_f32 v[42:43], v[42:43], v[46:47] neg_lo:[0,1] neg_hi:[0,1]
	v_pk_add_f32 v[204:205], v[44:45], v[48:49]
	v_pk_add_f32 v[44:45], v[44:45], v[48:49] neg_lo:[0,1] neg_hi:[0,1]
	v_pk_add_f32 v[46:47], v[202:203], v[204:205]
	v_pk_add_f32 v[48:49], v[202:203], v[204:205] neg_lo:[0,1] neg_hi:[0,1]
	v_pk_add_f32 v[202:203], v[42:43], v[44:45] op_sel:[0,1] op_sel_hi:[1,0] neg_hi:[0,1]
	v_pk_add_f32 v[204:205], v[42:43], v[44:45] op_sel:[0,1] op_sel_hi:[1,0] neg_lo:[0,1]
	v_pk_mul_f32 v[206:207], v[210:211], v[210:211] op_sel:[1,1] op_sel_hi:[1,0]
	v_pk_fma_f32 v[212:213], v[210:211], v[210:211], v[206:207] op_sel_hi:[0,1,1] neg_lo:[0,0,1]
	v_pk_mul_f32 v[206:207], v[210:211], v[212:213] op_sel:[1,1] op_sel_hi:[1,0]
	v_pk_fma_f32 v[220:221], v[210:211], v[212:213], v[206:207] op_sel_hi:[0,1,1] neg_lo:[0,0,1]
	v_pk_mul_f32 v[42:43], v[210:211], v[202:203] op_sel:[1,1] op_sel_hi:[1,0]
	v_pk_fma_f32 v[42:43], v[210:211], v[202:203], v[42:43] op_sel_hi:[0,1,1] neg_lo:[0,0,1]
	v_pk_mul_f32 v[44:45], v[212:213], v[48:49] op_sel:[1,1] op_sel_hi:[1,0]
	v_pk_fma_f32 v[44:45], v[212:213], v[48:49], v[44:45] op_sel_hi:[0,1,1] neg_lo:[0,0,1]
	v_pk_mul_f32 v[48:49], v[220:221], v[204:205] op_sel:[1,1] op_sel_hi:[1,0]
	v_pk_fma_f32 v[48:49], v[220:221], v[204:205], v[48:49] op_sel_hi:[0,1,1] neg_lo:[0,0,1]
	v_add_f32_e32 v214, 0x3e400000, v201
	v_cos_f32_e32 v210, v214
	v_sin_f32_e64 v211, -v214
	s_waitcnt lgkmcnt(2)
	v_pk_add_f32 v[202:203], v[50:51], v[54:55]
	v_pk_add_f32 v[50:51], v[50:51], v[54:55] neg_lo:[0,1] neg_hi:[0,1]
	v_pk_add_f32 v[204:205], v[52:53], v[56:57]
	v_pk_add_f32 v[52:53], v[52:53], v[56:57] neg_lo:[0,1] neg_hi:[0,1]
	v_pk_add_f32 v[54:55], v[202:203], v[204:205]
	v_pk_add_f32 v[56:57], v[202:203], v[204:205] neg_lo:[0,1] neg_hi:[0,1]
	v_pk_add_f32 v[202:203], v[50:51], v[52:53] op_sel:[0,1] op_sel_hi:[1,0] neg_hi:[0,1]
	v_pk_add_f32 v[204:205], v[50:51], v[52:53] op_sel:[0,1] op_sel_hi:[1,0] neg_lo:[0,1]
	v_pk_mul_f32 v[206:207], v[210:211], v[210:211] op_sel:[1,1] op_sel_hi:[1,0]
	v_pk_fma_f32 v[212:213], v[210:211], v[210:211], v[206:207] op_sel_hi:[0,1,1] neg_lo:[0,0,1]
	v_pk_mul_f32 v[206:207], v[210:211], v[212:213] op_sel:[1,1] op_sel_hi:[1,0]
	v_pk_fma_f32 v[220:221], v[210:211], v[212:213], v[206:207] op_sel_hi:[0,1,1] neg_lo:[0,0,1]
	v_pk_mul_f32 v[50:51], v[210:211], v[202:203] op_sel:[1,1] op_sel_hi:[1,0]
	v_pk_fma_f32 v[50:51], v[210:211], v[202:203], v[50:51] op_sel_hi:[0,1,1] neg_lo:[0,0,1]
	v_pk_mul_f32 v[52:53], v[212:213], v[56:57] op_sel:[1,1] op_sel_hi:[1,0]
	v_pk_fma_f32 v[52:53], v[212:213], v[56:57], v[52:53] op_sel_hi:[0,1,1] neg_lo:[0,0,1]
	v_pk_mul_f32 v[56:57], v[220:221], v[204:205] op_sel:[1,1] op_sel_hi:[1,0]
	v_pk_fma_f32 v[56:57], v[220:221], v[204:205], v[56:57] op_sel_hi:[0,1,1] neg_lo:[0,0,1]
	v_add_f32_e32 v214, 0x3e600000, v201
	v_cos_f32_e32 v210, v214
	v_sin_f32_e64 v211, -v214
	s_waitcnt lgkmcnt(0)
; DI f32x2 cmul(f32x2 a, f32x2 b) { return mkf2(a.x * b.x - a.y * b.y, a.x * b.y + a.y * b.x); }
; DI void fft8192(f32x2* buf, const f32x2* __restrict__ tw) {
;     ...
; #pragma unroll
;     for (int e = 0; e < 8; ++e) {
;       const int i = tid + 256 * e;
;       const int q = i & (s - 1);
;       const int ps = i - q;
;       const float rev = (float)ps * (1.f / 8192.f);
;       const f32x2 w1 = mkf2(__builtin_amdgcn_cosf(rev), -__builtin_amdgcn_sinf(rev));
;       const f32x2 w2 = cmul(w1, w1), w3 = cmul(w1, w2);
;       const f32x2 apc = mkf2(a[e].x + c[e].x, a[e].y + c[e].y), amc = mkf2(a[e].x - c[e].x, a[e].y - c[e].y);
;       const f32x2 bpd = mkf2(b[e].x + d[e].x, b[e].y + d[e].y), bmd = mkf2(b[e].x - d[e].x, b[e].y - d[e].y);
;       const int o = 4 * i - 3 * q;
;       buf[SW(o)] = mkf2(apc.x + bpd.x, apc.y + bpd.y);
;       buf[SW(o + s)] = cmul(w1, mkf2(amc.x + bmd.y, amc.y - bmd.x));
;       buf[SW(o + 2 * s)] = cmul(w2, mkf2(apc.x - bpd.x, apc.y - bpd.y));
;       buf[SW(o + 3 * s)] = cmul(w3, mkf2(amc.x - bmd.y, amc.y + bmd.x));
;     }
	v_pk_add_f32 v[202:203], v[58:59], v[62:63]
	v_pk_add_f32 v[58:59], v[58:59], v[62:63] neg_lo:[0,1] neg_hi:[0,1]
	v_pk_add_f32 v[204:205], v[60:61], v[64:65]
	v_pk_add_f32 v[60:61], v[60:61], v[64:65] neg_lo:[0,1] neg_hi:[0,1]
	v_pk_add_f32 v[62:63], v[202:203], v[204:205]
	v_pk_add_f32 v[64:65], v[202:203], v[204:205] neg_lo:[0,1] neg_hi:[0,1]
	v_pk_add_f32 v[202:203], v[58:59], v[60:61] op_sel:[0,1] op_sel_hi:[1,0] neg_hi:[0,1]
	v_pk_add_f32 v[204:205], v[58:59], v[60:61] op_sel:[0,1] op_sel_hi:[1,0] neg_lo:[0,1]
	v_pk_mul_f32 v[206:207], v[210:211], v[210:211] op_sel:[1,1] op_sel_hi:[1,0]
	v_pk_fma_f32 v[212:213], v[210:211], v[210:211], v[206:207] op_sel_hi:[0,1,1] neg_lo:[0,0,1]
	v_pk_mul_f32 v[206:207], v[210:211], v[212:213] op_sel:[1,1] op_sel_hi:[1,0]
	v_pk_fma_f32 v[220:221], v[210:211], v[212:213], v[206:207] op_sel_hi:[0,1,1] neg_lo:[0,0,1]
	v_pk_mul_f32 v[58:59], v[210:211], v[202:203] op_sel:[1,1] op_sel_hi:[1,0]
	v_pk_fma_f32 v[58:59], v[210:211], v[202:203], v[58:59] op_sel_hi:[0,1,1] neg_lo:[0,0,1]
	v_pk_mul_f32 v[60:61], v[212:213], v[64:65] op_sel:[1,1] op_sel_hi:[1,0]
	v_pk_fma_f32 v[60:61], v[212:213], v[64:65], v[60:61] op_sel_hi:[0,1,1] neg_lo:[0,0,1]
	v_pk_mul_f32 v[64:65], v[220:221], v[204:205] op_sel:[1,1] op_sel_hi:[1,0]
	v_pk_fma_f32 v[64:65], v[220:221], v[204:205], v[64:65] op_sel_hi:[0,1,1] neg_lo:[0,0,1]
	s_barrier
	v_mul_f32_e32 v214, 4.0, v201
	v_cos_f32_e32 v224, v214
	v_sin_f32_e64 v225, -v214
	s_nop 0
	v_pk_mul_f32 v[206:207], v[224:225], v[224:225] op_sel:[1,1] op_sel_hi:[1,0]
	v_pk_fma_f32 v[226:227], v[224:225], v[224:225], v[206:207] op_sel_hi:[0,1,1] neg_lo:[0,0,1]
	v_pk_mul_f32 v[206:207], v[224:225], v[226:227] op_sel:[1,1] op_sel_hi:[1,0]
	v_pk_fma_f32 v[230:231], v[224:225], v[226:227], v[206:207] op_sel_hi:[0,1,1] neg_lo:[0,0,1]
	v_pk_add_f32 v[202:203], v[6:7], v[38:39]
	v_pk_add_f32 v[6:7], v[6:7], v[38:39] neg_lo:[0,1] neg_hi:[0,1]
	v_pk_add_f32 v[204:205], v[22:23], v[54:55]
	v_pk_add_f32 v[22:23], v[22:23], v[54:55] neg_lo:[0,1] neg_hi:[0,1]
	v_pk_add_f32 v[38:39], v[202:203], v[204:205]
	v_pk_add_f32 v[54:55], v[202:203], v[204:205] neg_lo:[0,1] neg_hi:[0,1]
	v_pk_add_f32 v[202:203], v[6:7], v[22:23] op_sel:[0,1] op_sel_hi:[1,0] neg_hi:[0,1]
	v_pk_add_f32 v[204:205], v[6:7], v[22:23] op_sel:[0,1] op_sel_hi:[1,0] neg_lo:[0,1]
	v_pk_mul_f32 v[6:7], v[224:225], v[202:203] op_sel:[1,1] op_sel_hi:[1,0]
	v_pk_fma_f32 v[6:7], v[224:225], v[202:203], v[6:7] op_sel_hi:[0,1,1] neg_lo:[0,0,1]
	v_pk_mul_f32 v[22:23], v[226:227], v[54:55] op_sel:[1,1] op_sel_hi:[1,0]
	v_pk_fma_f32 v[22:23], v[226:227], v[54:55], v[22:23] op_sel_hi:[0,1,1] neg_lo:[0,0,1]
	v_pk_mul_f32 v[54:55], v[230:231], v[204:205] op_sel:[1,1] op_sel_hi:[1,0]
	v_pk_fma_f32 v[54:55], v[230:231], v[204:205], v[54:55] op_sel_hi:[0,1,1] neg_lo:[0,0,1]
	v_pk_add_f32 v[202:203], v[2:3], v[34:35]
	v_pk_add_f32 v[2:3], v[2:3], v[34:35] neg_lo:[0,1] neg_hi:[0,1]
	v_pk_add_f32 v[204:205], v[18:19], v[50:51]
	v_pk_add_f32 v[18:19], v[18:19], v[50:51] neg_lo:[0,1] neg_hi:[0,1]
	v_pk_add_f32 v[34:35], v[202:203], v[204:205]
	v_pk_add_f32 v[50:51], v[202:203], v[204:205] neg_lo:[0,1] neg_hi:[0,1]
	v_pk_add_f32 v[202:203], v[2:3], v[18:19] op_sel:[0,1] op_sel_hi:[1,0] neg_hi:[0,1]
	v_pk_add_f32 v[204:205], v[2:3], v[18:19] op_sel:[0,1] op_sel_hi:[1,0] neg_lo:[0,1]
	v_pk_mul_f32 v[2:3], v[224:225], v[202:203] op_sel:[1,1] op_sel_hi:[1,0]
	v_pk_fma_f32 v[2:3], v[224:225], v[202:203], v[2:3] op_sel_hi:[0,1,1] neg_lo:[0,0,1]
	v_pk_mul_f32 v[18:19], v[226:227], v[50:51] op_sel:[1,1] op_sel_hi:[1,0]
	v_pk_fma_f32 v[18:19], v[226:227], v[50:51], v[18:19] op_sel_hi:[0,1,1] neg_lo:[0,0,1]
	v_pk_mul_f32 v[50:51], v[230:231], v[204:205] op_sel:[1,1] op_sel_hi:[1,0]
	v_pk_fma_f32 v[50:51], v[230:231], v[204:205], v[50:51] op_sel_hi:[0,1,1] neg_lo:[0,0,1]
	v_pk_add_f32 v[202:203], v[4:5], v[36:37]
	v_pk_add_f32 v[4:5], v[4:5], v[36:37] neg_lo:[0,1] neg_hi:[0,1]
	v_pk_add_f32 v[204:205], v[20:21], v[52:53]
	v_pk_add_f32 v[20:21], v[20:21], v[52:53] neg_lo:[0,1] neg_hi:[0,1]
	v_pk_add_f32 v[36:37], v[202:203], v[204:205]
	v_pk_add_f32 v[52:53], v[202:203], v[204:205] neg_lo:[0,1] neg_hi:[0,1]
	v_pk_add_f32 v[202:203], v[4:5], v[20:21] op_sel:[0,1] op_sel_hi:[1,0] neg_hi:[0,1]
	v_pk_add_f32 v[204:205], v[4:5], v[20:21] op_sel:[0,1] op_sel_hi:[1,0] neg_lo:[0,1]
	v_pk_mul_f32 v[4:5], v[224:225], v[202:203] op_sel:[1,1] op_sel_hi:[1,0]
	v_pk_fma_f32 v[4:5], v[224:225], v[202:203], v[4:5] op_sel_hi:[0,1,1] neg_lo:[0,0,1]
	v_pk_mul_f32 v[20:21], v[226:227], v[52:53] op_sel:[1,1] op_sel_hi:[1,0]
	v_pk_fma_f32 v[20:21], v[226:227], v[52:53], v[20:21] op_sel_hi:[0,1,1] neg_lo:[0,0,1]
	v_pk_mul_f32 v[52:53], v[230:231], v[204:205] op_sel:[1,1] op_sel_hi:[1,0]
	v_pk_fma_f32 v[52:53], v[230:231], v[204:205], v[52:53] op_sel_hi:[0,1,1] neg_lo:[0,0,1]
	v_pk_add_f32 v[202:203], v[8:9], v[40:41]
	v_pk_add_f32 v[8:9], v[8:9], v[40:41] neg_lo:[0,1] neg_hi:[0,1]
	v_pk_add_f32 v[204:205], v[24:25], v[56:57]
	v_pk_add_f32 v[24:25], v[24:25], v[56:57] neg_lo:[0,1] neg_hi:[0,1]
	v_pk_add_f32 v[40:41], v[202:203], v[204:205]
	v_pk_add_f32 v[56:57], v[202:203], v[204:205] neg_lo:[0,1] neg_hi:[0,1]
	v_pk_add_f32 v[202:203], v[8:9], v[24:25] op_sel:[0,1] op_sel_hi:[1,0] neg_hi:[0,1]
	v_pk_add_f32 v[204:205], v[8:9], v[24:25] op_sel:[0,1] op_sel_hi:[1,0] neg_lo:[0,1]
	v_pk_mul_f32 v[8:9], v[224:225], v[202:203] op_sel:[1,1] op_sel_hi:[1,0]
	v_pk_fma_f32 v[8:9], v[224:225], v[202:203], v[8:9] op_sel_hi:[0,1,1] neg_lo:[0,0,1]
	v_pk_mul_f32 v[24:25], v[226:227], v[56:57] op_sel:[1,1] op_sel_hi:[1,0]
	v_pk_fma_f32 v[24:25], v[226:227], v[56:57], v[24:25] op_sel_hi:[0,1,1] neg_lo:[0,0,1]
; DI f32x2 cmul(f32x2 a, f32x2 b) { return mkf2(a.x * b.x - a.y * b.y, a.x * b.y + a.y * b.x); }
; DI void fft8192(f32x2* buf, const f32x2* __restrict__ tw) {
;     ...
; #pragma unroll
;     for (int e = 0; e < 8; ++e) {
;       const int i = tid + 256 * e;
;       const int q = i & (s - 1);
;       const int ps = i - q;
;       const float rev = (float)ps * (1.f / 8192.f);
;       const f32x2 w1 = mkf2(__builtin_amdgcn_cosf(rev), -__builtin_amdgcn_sinf(rev));
;       const f32x2 w2 = cmul(w1, w1), w3 = cmul(w1, w2);
;       const f32x2 apc = mkf2(a[e].x + c[e].x, a[e].y + c[e].y), amc = mkf2(a[e].x - c[e].x, a[e].y - c[e].y);
;       const f32x2 bpd = mkf2(b[e].x + d[e].x, b[e].y + d[e].y), bmd = mkf2(b[e].x - d[e].x, b[e].y - d[e].y);
;       const int o = 4 * i - 3 * q;
;       buf[SW(o)] = mkf2(apc.x + bpd.x, apc.y + bpd.y);
;       buf[SW(o + s)] = cmul(w1, mkf2(amc.x + bmd.y, amc.y - bmd.x));
;       buf[SW(o + 2 * s)] = cmul(w2, mkf2(apc.x - bpd.x, apc.y - bpd.y));
;       buf[SW(o + 3 * s)] = cmul(w3, mkf2(amc.x - bmd.y, amc.y + bmd.x));
;     }
	v_pk_mul_f32 v[56:57], v[230:231], v[204:205] op_sel:[1,1] op_sel_hi:[1,0]
	v_pk_fma_f32 v[56:57], v[230:231], v[204:205], v[56:57] op_sel_hi:[0,1,1] neg_lo:[0,0,1]
	v_mul_f32_e32 v214, 4.0, v201
	v_add_f32_e32 v214, 0x3e000000, v214
	v_cos_f32_e32 v224, v214
	v_sin_f32_e64 v225, -v214
	s_nop 0
	v_pk_mul_f32 v[206:207], v[224:225], v[224:225] op_sel:[1,1] op_sel_hi:[1,0]
	v_pk_fma_f32 v[226:227], v[224:225], v[224:225], v[206:207] op_sel_hi:[0,1,1] neg_lo:[0,0,1]
	v_pk_mul_f32 v[206:207], v[224:225], v[226:227] op_sel:[1,1] op_sel_hi:[1,0]
	v_pk_fma_f32 v[230:231], v[224:225], v[226:227], v[206:207] op_sel_hi:[0,1,1] neg_lo:[0,0,1]
	v_pk_add_f32 v[202:203], v[14:15], v[46:47]
	v_pk_add_f32 v[14:15], v[14:15], v[46:47] neg_lo:[0,1] neg_hi:[0,1]
	v_pk_add_f32 v[204:205], v[30:31], v[62:63]
	v_pk_add_f32 v[30:31], v[30:31], v[62:63] neg_lo:[0,1] neg_hi:[0,1]
	v_pk_add_f32 v[46:47], v[202:203], v[204:205]
	v_pk_add_f32 v[62:63], v[202:203], v[204:205] neg_lo:[0,1] neg_hi:[0,1]
	v_pk_add_f32 v[202:203], v[14:15], v[30:31] op_sel:[0,1] op_sel_hi:[1,0] neg_hi:[0,1]
	v_pk_add_f32 v[204:205], v[14:15], v[30:31] op_sel:[0,1] op_sel_hi:[1,0] neg_lo:[0,1]
	v_pk_mul_f32 v[14:15], v[224:225], v[202:203] op_sel:[1,1] op_sel_hi:[1,0]
	v_pk_fma_f32 v[14:15], v[224:225], v[202:203], v[14:15] op_sel_hi:[0,1,1] neg_lo:[0,0,1]
	v_pk_mul_f32 v[30:31], v[226:227], v[62:63] op_sel:[1,1] op_sel_hi:[1,0]
	v_pk_fma_f32 v[30:31], v[226:227], v[62:63], v[30:31] op_sel_hi:[0,1,1] neg_lo:[0,0,1]
	v_pk_mul_f32 v[62:63], v[230:231], v[204:205] op_sel:[1,1] op_sel_hi:[1,0]
	v_pk_fma_f32 v[62:63], v[230:231], v[204:205], v[62:63] op_sel_hi:[0,1,1] neg_lo:[0,0,1]
	v_pk_add_f32 v[202:203], v[10:11], v[42:43]
	v_pk_add_f32 v[10:11], v[10:11], v[42:43] neg_lo:[0,1] neg_hi:[0,1]
	v_pk_add_f32 v[204:205], v[26:27], v[58:59]
	v_pk_add_f32 v[26:27], v[26:27], v[58:59] neg_lo:[0,1] neg_hi:[0,1]
	v_pk_add_f32 v[42:43], v[202:203], v[204:205]
	v_pk_add_f32 v[58:59], v[202:203], v[204:205] neg_lo:[0,1] neg_hi:[0,1]
	v_pk_add_f32 v[202:203], v[10:11], v[26:27] op_sel:[0,1] op_sel_hi:[1,0] neg_hi:[0,1]
	v_pk_add_f32 v[204:205], v[10:11], v[26:27] op_sel:[0,1] op_sel_hi:[1,0] neg_lo:[0,1]
	v_pk_mul_f32 v[10:11], v[224:225], v[202:203] op_sel:[1,1] op_sel_hi:[1,0]
	v_pk_fma_f32 v[10:11], v[224:225], v[202:203], v[10:11] op_sel_hi:[0,1,1] neg_lo:[0,0,1]
	v_pk_mul_f32 v[26:27], v[226:227], v[58:59] op_sel:[1,1] op_sel_hi:[1,0]
	v_pk_fma_f32 v[26:27], v[226:227], v[58:59], v[26:27] op_sel_hi:[0,1,1] neg_lo:[0,0,1]
	v_pk_mul_f32 v[58:59], v[230:231], v[204:205] op_sel:[1,1] op_sel_hi:[1,0]
	v_pk_fma_f32 v[58:59], v[230:231], v[204:205], v[58:59] op_sel_hi:[0,1,1] neg_lo:[0,0,1]
	v_pk_add_f32 v[202:203], v[12:13], v[44:45]
	v_pk_add_f32 v[12:13], v[12:13], v[44:45] neg_lo:[0,1] neg_hi:[0,1]
	v_pk_add_f32 v[204:205], v[28:29], v[60:61]
	v_pk_add_f32 v[28:29], v[28:29], v[60:61] neg_lo:[0,1] neg_hi:[0,1]
	v_pk_add_f32 v[44:45], v[202:203], v[204:205]
	v_pk_add_f32 v[60:61], v[202:203], v[204:205] neg_lo:[0,1] neg_hi:[0,1]
	v_pk_add_f32 v[202:203], v[12:13], v[28:29] op_sel:[0,1] op_sel_hi:[1,0] neg_hi:[0,1]
	v_pk_add_f32 v[204:205], v[12:13], v[28:29] op_sel:[0,1] op_sel_hi:[1,0] neg_lo:[0,1]
	v_pk_mul_f32 v[12:13], v[224:225], v[202:203] op_sel:[1,1] op_sel_hi:[1,0]
	v_pk_fma_f32 v[12:13], v[224:225], v[202:203], v[12:13] op_sel_hi:[0,1,1] neg_lo:[0,0,1]
	v_pk_mul_f32 v[28:29], v[226:227], v[60:61] op_sel:[1,1] op_sel_hi:[1,0]
	v_pk_fma_f32 v[28:29], v[226:227], v[60:61], v[28:29] op_sel_hi:[0,1,1] neg_lo:[0,0,1]
	v_pk_mul_f32 v[60:61], v[230:231], v[204:205] op_sel:[1,1] op_sel_hi:[1,0]
	v_pk_fma_f32 v[60:61], v[230:231], v[204:205], v[60:61] op_sel_hi:[0,1,1] neg_lo:[0,0,1]
	v_pk_add_f32 v[202:203], v[16:17], v[48:49]
	v_pk_add_f32 v[16:17], v[16:17], v[48:49] neg_lo:[0,1] neg_hi:[0,1]
	v_pk_add_f32 v[204:205], v[32:33], v[64:65]
	v_pk_add_f32 v[32:33], v[32:33], v[64:65] neg_lo:[0,1] neg_hi:[0,1]
	v_pk_add_f32 v[48:49], v[202:203], v[204:205]
	v_pk_add_f32 v[64:65], v[202:203], v[204:205] neg_lo:[0,1] neg_hi:[0,1]
	v_pk_add_f32 v[202:203], v[16:17], v[32:33] op_sel:[0,1] op_sel_hi:[1,0] neg_hi:[0,1]
	v_pk_add_f32 v[204:205], v[16:17], v[32:33] op_sel:[0,1] op_sel_hi:[1,0] neg_lo:[0,1]
	v_pk_mul_f32 v[16:17], v[224:225], v[202:203] op_sel:[1,1] op_sel_hi:[1,0]
	v_pk_fma_f32 v[16:17], v[224:225], v[202:203], v[16:17] op_sel_hi:[0,1,1] neg_lo:[0,0,1]
	v_pk_mul_f32 v[32:33], v[226:227], v[64:65] op_sel:[1,1] op_sel_hi:[1,0]
	v_pk_fma_f32 v[32:33], v[226:227], v[64:65], v[32:33] op_sel_hi:[0,1,1] neg_lo:[0,0,1]
	v_pk_mul_f32 v[64:65], v[230:231], v[204:205] op_sel:[1,1] op_sel_hi:[1,0]
	v_pk_fma_f32 v[64:65], v[230:231], v[204:205], v[64:65] op_sel_hi:[0,1,1] neg_lo:[0,0,1]
	ds_write_b64 v164, v[38:39] offset:0
	v_xor_b32_e32 v156, 0x80, v164
	ds_write_b64 v156, v[34:35] offset:0
	v_xor_b32_e32 v158, 0x128, v164
	ds_write_b64 v158, v[36:37] offset:0
	v_xor_b32_e32 v160, 0x1a8, v164
	ds_write_b64 v160, v[40:41] offset:0
	v_xor_b32_e32 v162, 0x2d0, v164
	ds_write_b64 v162, v[6:7] offset:0
	v_xor_b32_e32 v156, 0x250, v164
	ds_write_b64 v156, v[2:3] offset:0
	v_xor_b32_e32 v158, 0x3f8, v164
	ds_write_b64 v158, v[4:5] offset:0
	v_xor_b32_e32 v160, 0x378, v164
	ds_write_b64 v160, v[8:9] offset:0
	v_xor_b32_e32 v162, 0x400, v164
	ds_write_b64 v162, v[22:23] offset:0
	v_xor_b32_e32 v156, 0x480, v164
	ds_write_b64 v156, v[18:19] offset:0
	v_xor_b32_e32 v158, 0x528, v164
	ds_write_b64 v158, v[20:21] offset:0
	v_xor_b32_e32 v160, 0x5a8, v164
	ds_write_b64 v160, v[24:25] offset:0
	v_xor_b32_e32 v162, 0x6d0, v164
	ds_write_b64 v162, v[54:55] offset:0
	v_xor_b32_e32 v156, 0x650, v164
	ds_write_b64 v156, v[50:51] offset:0
	v_xor_b32_e32 v158, 0x7f8, v164
	ds_write_b64 v158, v[52:53] offset:0
	v_xor_b32_e32 v160, 0x778, v164
	ds_write_b64 v160, v[56:57] offset:0
	ds_write_b64 v164, v[46:47] offset:32768
	v_xor_b32_e32 v162, 0x80, v164
	ds_write_b64 v162, v[42:43] offset:32768
	v_xor_b32_e32 v156, 0x128, v164
	ds_write_b64 v156, v[44:45] offset:32768
	v_xor_b32_e32 v158, 0x1a8, v164
	ds_write_b64 v158, v[48:49] offset:32768
	v_xor_b32_e32 v160, 0x2d0, v164
	ds_write_b64 v160, v[14:15] offset:32768
	v_xor_b32_e32 v162, 0x250, v164
	ds_write_b64 v162, v[10:11] offset:32768
	v_xor_b32_e32 v156, 0x3f8, v164
	ds_write_b64 v156, v[12:13] offset:32768
	v_xor_b32_e32 v158, 0x378, v164
	ds_write_b64 v158, v[16:17] offset:32768
	v_xor_b32_e32 v160, 0x400, v164
	ds_write_b64 v160, v[30:31] offset:32768
	v_xor_b32_e32 v162, 0x480, v164
	ds_write_b64 v162, v[26:27] offset:32768
	v_xor_b32_e32 v156, 0x528, v164
	ds_write_b64 v156, v[28:29] offset:32768
	v_xor_b32_e32 v158, 0x5a8, v164
	ds_write_b64 v158, v[32:33] offset:32768
	v_xor_b32_e32 v160, 0x6d0, v164
	ds_write_b64 v160, v[62:63] offset:32768
	v_xor_b32_e32 v162, 0x650, v164
	ds_write_b64 v162, v[58:59] offset:32768
	v_xor_b32_e32 v156, 0x7f8, v164
	ds_write_b64 v156, v[60:61] offset:32768
	v_xor_b32_e32 v158, 0x778, v164
	ds_write_b64 v158, v[64:65] offset:32768
	s_waitcnt lgkmcnt(0)
	s_barrier
; DI f32x2 cmul(f32x2 a, f32x2 b) { return mkf2(a.x * b.x - a.y * b.y, a.x * b.y + a.y * b.x); }
; DI void fft8192(f32x2* buf, const f32x2* __restrict__ tw) {
;     ...
;   for (int ls = 0; ls < 12; ls += 2) {
;     const int s = 1 << ls;
;     f32x2 a[8], b[8], c[8], d[8];
;     __syncthreads();
; #pragma unroll
;     for (int e = 0; e < 8; ++e) {
;       const int i = tid + 256 * e;
;       const int pi = SW(i);
;       a[e] = buf[pi]; b[e] = buf[pi + 2048]; c[e] = buf[pi + 4096]; d[e] = buf[pi + 6144];
;     }
;     __syncthreads();
; #pragma unroll
;     for (int e = 0; e < 8; ++e) {
;       const int i = tid + 256 * e;
;       const int q = i & (s - 1);
;       const int ps = i - q;
;       const float rev = (float)ps * (1.f / 8192.f);
;       const f32x2 w1 = mkf2(__builtin_amdgcn_cosf(rev), -__builtin_amdgcn_sinf(rev));
;       const f32x2 w2 = cmul(w1, w1), w3 = cmul(w1, w2);
;       const f32x2 apc = mkf2(a[e].x + c[e].x, a[e].y + c[e].y), amc = mkf2(a[e].x - c[e].x, a[e].y - c[e].y);
;       const f32x2 bpd = mkf2(b[e].x + d[e].x, b[e].y + d[e].y), bmd = mkf2(b[e].x - d[e].x, b[e].y - d[e].y);
;       const int o = 4 * i - 3 * q;
;       buf[SW(o)] = mkf2(apc.x + bpd.x, apc.y + bpd.y);
;       buf[SW(o + s)] = cmul(w1, mkf2(amc.x + bmd.y, amc.y - bmd.x));
;       buf[SW(o + 2 * s)] = cmul(w2, mkf2(apc.x - bpd.x, apc.y - bpd.y));
;       buf[SW(o + 3 * s)] = cmul(w3, mkf2(amc.x - bmd.y, amc.y + bmd.x));
;     }
	ds_read2st64_b64 v[2:5], v154 offset0:0 offset1:32
	ds_read2st64_b64 v[6:9], v154 offset0:64 offset1:96
	ds_read2st64_b64 v[10:13], v154 offset0:4 offset1:36
	ds_read2st64_b64 v[14:17], v154 offset0:68 offset1:100
	ds_read2st64_b64 v[18:21], v154 offset0:8 offset1:40
	ds_read2st64_b64 v[22:25], v154 offset0:72 offset1:104
	ds_read2st64_b64 v[26:29], v154 offset0:12 offset1:44
	ds_read2st64_b64 v[30:33], v154 offset0:76 offset1:108
	ds_read2st64_b64 v[34:37], v154 offset0:16 offset1:48
	ds_read2st64_b64 v[38:41], v154 offset0:80 offset1:112
	ds_read2st64_b64 v[42:45], v154 offset0:20 offset1:52
	ds_read2st64_b64 v[46:49], v154 offset0:84 offset1:116
	ds_read2st64_b64 v[50:53], v154 offset0:24 offset1:56
	ds_read2st64_b64 v[54:57], v154 offset0:88 offset1:120
	ds_read2st64_b64 v[58:61], v154 offset0:28 offset1:60
	ds_read2st64_b64 v[62:65], v154 offset0:92 offset1:124
	s_waitcnt lgkmcnt(14)
	v_pk_add_f32 v[202:203], v[2:3], v[6:7]
	v_pk_add_f32 v[2:3], v[2:3], v[6:7] neg_lo:[0,1] neg_hi:[0,1]
	v_pk_add_f32 v[204:205], v[4:5], v[8:9]
	v_pk_add_f32 v[4:5], v[4:5], v[8:9] neg_lo:[0,1] neg_hi:[0,1]
	v_pk_add_f32 v[6:7], v[202:203], v[204:205]
	v_pk_add_f32 v[8:9], v[202:203], v[204:205] neg_lo:[0,1] neg_hi:[0,1]
	v_pk_add_f32 v[202:203], v[2:3], v[4:5] op_sel:[0,1] op_sel_hi:[1,0] neg_hi:[0,1]
	v_pk_add_f32 v[4:5], v[2:3], v[4:5] op_sel:[0,1] op_sel_hi:[1,0] neg_lo:[0,1]
	v_pk_mov_b32 v[2:3], v[202:203], v[202:203] op_sel:[0,1]
	v_cos_f32_e32 v210, 0x3d000000
	v_sin_f32_e32 v211, 0xbd000000
	s_waitcnt lgkmcnt(12)
	v_pk_add_f32 v[202:203], v[10:11], v[14:15]
	v_pk_add_f32 v[10:11], v[10:11], v[14:15] neg_lo:[0,1] neg_hi:[0,1]
	v_pk_add_f32 v[204:205], v[12:13], v[16:17]
	v_pk_add_f32 v[12:13], v[12:13], v[16:17] neg_lo:[0,1] neg_hi:[0,1]
	v_pk_add_f32 v[14:15], v[202:203], v[204:205]
	v_pk_add_f32 v[16:17], v[202:203], v[204:205] neg_lo:[0,1] neg_hi:[0,1]
	v_pk_add_f32 v[202:203], v[10:11], v[12:13] op_sel:[0,1] op_sel_hi:[1,0] neg_hi:[0,1]
	v_pk_add_f32 v[204:205], v[10:11], v[12:13] op_sel:[0,1] op_sel_hi:[1,0] neg_lo:[0,1]
	v_pk_mul_f32 v[206:207], v[210:211], v[210:211] op_sel:[1,1] op_sel_hi:[1,0]
	v_pk_fma_f32 v[212:213], v[210:211], v[210:211], v[206:207] op_sel_hi:[0,1,1] neg_lo:[0,0,1]
	v_pk_mul_f32 v[206:207], v[210:211], v[212:213] op_sel:[1,1] op_sel_hi:[1,0]
	v_pk_fma_f32 v[220:221], v[210:211], v[212:213], v[206:207] op_sel_hi:[0,1,1] neg_lo:[0,0,1]
	v_pk_mul_f32 v[10:11], v[210:211], v[202:203] op_sel:[1,1] op_sel_hi:[1,0]
	v_pk_fma_f32 v[10:11], v[210:211], v[202:203], v[10:11] op_sel_hi:[0,1,1] neg_lo:[0,0,1]
	v_pk_mul_f32 v[12:13], v[212:213], v[16:17] op_sel:[1,1] op_sel_hi:[1,0]
	v_pk_fma_f32 v[12:13], v[212:213], v[16:17], v[12:13] op_sel_hi:[0,1,1] neg_lo:[0,0,1]
	v_pk_mul_f32 v[16:17], v[220:221], v[204:205] op_sel:[1,1] op_sel_hi:[1,0]
	v_pk_fma_f32 v[16:17], v[220:221], v[204:205], v[16:17] op_sel_hi:[0,1,1] neg_lo:[0,0,1]
	v_cos_f32_e32 v210, 0x3d800000
	v_sin_f32_e32 v211, 0xbd800000
	s_waitcnt lgkmcnt(10)
	v_pk_add_f32 v[202:203], v[18:19], v[22:23]
	v_pk_add_f32 v[18:19], v[18:19], v[22:23] neg_lo:[0,1] neg_hi:[0,1]
	v_pk_add_f32 v[204:205], v[20:21], v[24:25]
	v_pk_add_f32 v[20:21], v[20:21], v[24:25] neg_lo:[0,1] neg_hi:[0,1]
	v_pk_add_f32 v[22:23], v[202:203], v[204:205]
	v_pk_add_f32 v[24:25], v[202:203], v[204:205] neg_lo:[0,1] neg_hi:[0,1]
	v_pk_add_f32 v[202:203], v[18:19], v[20:21] op_sel:[0,1] op_sel_hi:[1,0] neg_hi:[0,1]
	v_pk_add_f32 v[204:205], v[18:19], v[20:21] op_sel:[0,1] op_sel_hi:[1,0] neg_lo:[0,1]
	v_pk_mul_f32 v[206:207], v[210:211], v[210:211] op_sel:[1,1] op_sel_hi:[1,0]
	v_pk_fma_f32 v[212:213], v[210:211], v[210:211], v[206:207] op_sel_hi:[0,1,1] neg_lo:[0,0,1]
	v_pk_mul_f32 v[206:207], v[210:211], v[212:213] op_sel:[1,1] op_sel_hi:[1,0]
	v_pk_fma_f32 v[220:221], v[210:211], v[212:213], v[206:207] op_sel_hi:[0,1,1] neg_lo:[0,0,1]
	v_pk_mul_f32 v[18:19], v[210:211], v[202:203] op_sel:[1,1] op_sel_hi:[1,0]
	v_pk_fma_f32 v[18:19], v[210:211], v[202:203], v[18:19] op_sel_hi:[0,1,1] neg_lo:[0,0,1]
	v_pk_mul_f32 v[20:21], v[212:213], v[24:25] op_sel:[1,1] op_sel_hi:[1,0]
	v_pk_fma_f32 v[20:21], v[212:213], v[24:25], v[20:21] op_sel_hi:[0,1,1] neg_lo:[0,0,1]
	v_pk_mul_f32 v[24:25], v[220:221], v[204:205] op_sel:[1,1] op_sel_hi:[1,0]
	v_pk_fma_f32 v[24:25], v[220:221], v[204:205], v[24:25] op_sel_hi:[0,1,1] neg_lo:[0,0,1]
	v_cos_f32_e32 v210, 0x3dc00000
	v_sin_f32_e32 v211, 0xbdc00000
	s_waitcnt lgkmcnt(8)
	v_pk_add_f32 v[202:203], v[26:27], v[30:31]
	v_pk_add_f32 v[26:27], v[26:27], v[30:31] neg_lo:[0,1] neg_hi:[0,1]
	v_pk_add_f32 v[204:205], v[28:29], v[32:33]
	v_pk_add_f32 v[28:29], v[28:29], v[32:33] neg_lo:[0,1] neg_hi:[0,1]
	v_pk_add_f32 v[30:31], v[202:203], v[204:205]
	v_pk_add_f32 v[32:33], v[202:203], v[204:205] neg_lo:[0,1] neg_hi:[0,1]
	v_pk_add_f32 v[202:203], v[26:27], v[28:29] op_sel:[0,1] op_sel_hi:[1,0] neg_hi:[0,1]
	v_pk_add_f32 v[204:205], v[26:27], v[28:29] op_sel:[0,1] op_sel_hi:[1,0] neg_lo:[0,1]
	v_pk_mul_f32 v[206:207], v[210:211], v[210:211] op_sel:[1,1] op_sel_hi:[1,0]
	v_pk_fma_f32 v[212:213], v[210:211], v[210:211], v[206:207] op_sel_hi:[0,1,1] neg_lo:[0,0,1]
	v_pk_mul_f32 v[206:207], v[210:211], v[212:213] op_sel:[1,1] op_sel_hi:[1,0]
	v_pk_fma_f32 v[220:221], v[210:211], v[212:213], v[206:207] op_sel_hi:[0,1,1] neg_lo:[0,0,1]
	v_pk_mul_f32 v[26:27], v[210:211], v[202:203] op_sel:[1,1] op_sel_hi:[1,0]
	v_pk_fma_f32 v[26:27], v[210:211], v[202:203], v[26:27] op_sel_hi:[0,1,1] neg_lo:[0,0,1]
	v_pk_mul_f32 v[28:29], v[212:213], v[32:33] op_sel:[1,1] op_sel_hi:[1,0]
	v_pk_fma_f32 v[28:29], v[212:213], v[32:33], v[28:29] op_sel_hi:[0,1,1] neg_lo:[0,0,1]
	v_pk_mul_f32 v[32:33], v[220:221], v[204:205] op_sel:[1,1] op_sel_hi:[1,0]
	v_pk_fma_f32 v[32:33], v[220:221], v[204:205], v[32:33] op_sel_hi:[0,1,1] neg_lo:[0,0,1]
	v_cos_f32_e32 v210, 0x3e000000
	v_sin_f32_e32 v211, 0xbe000000
	s_waitcnt lgkmcnt(6)
; DI f32x2 cmul(f32x2 a, f32x2 b) { return mkf2(a.x * b.x - a.y * b.y, a.x * b.y + a.y * b.x); }
; DI void fft8192(f32x2* buf, const f32x2* __restrict__ tw) {
;     ...
; #pragma unroll
;     for (int e = 0; e < 8; ++e) {
;       const int i = tid + 256 * e;
;       const int q = i & (s - 1);
;       const int ps = i - q;
;       const float rev = (float)ps * (1.f / 8192.f);
;       const f32x2 w1 = mkf2(__builtin_amdgcn_cosf(rev), -__builtin_amdgcn_sinf(rev));
;       const f32x2 w2 = cmul(w1, w1), w3 = cmul(w1, w2);
;       const f32x2 apc = mkf2(a[e].x + c[e].x, a[e].y + c[e].y), amc = mkf2(a[e].x - c[e].x, a[e].y - c[e].y);
;       const f32x2 bpd = mkf2(b[e].x + d[e].x, b[e].y + d[e].y), bmd = mkf2(b[e].x - d[e].x, b[e].y - d[e].y);
;       const int o = 4 * i - 3 * q;
;       buf[SW(o)] = mkf2(apc.x + bpd.x, apc.y + bpd.y);
;       buf[SW(o + s)] = cmul(w1, mkf2(amc.x + bmd.y, amc.y - bmd.x));
;       buf[SW(o + 2 * s)] = cmul(w2, mkf2(apc.x - bpd.x, apc.y - bpd.y));
;       buf[SW(o + 3 * s)] = cmul(w3, mkf2(amc.x - bmd.y, amc.y + bmd.x));
;     }
	v_pk_add_f32 v[202:203], v[34:35], v[38:39]
	v_pk_add_f32 v[34:35], v[34:35], v[38:39] neg_lo:[0,1] neg_hi:[0,1]
	v_pk_add_f32 v[204:205], v[36:37], v[40:41]
	v_pk_add_f32 v[36:37], v[36:37], v[40:41] neg_lo:[0,1] neg_hi:[0,1]
	v_pk_add_f32 v[38:39], v[202:203], v[204:205]
	v_pk_add_f32 v[40:41], v[202:203], v[204:205] neg_lo:[0,1] neg_hi:[0,1]
	v_pk_add_f32 v[202:203], v[34:35], v[36:37] op_sel:[0,1] op_sel_hi:[1,0] neg_hi:[0,1]
	v_pk_add_f32 v[204:205], v[34:35], v[36:37] op_sel:[0,1] op_sel_hi:[1,0] neg_lo:[0,1]
	v_pk_mul_f32 v[206:207], v[210:211], v[210:211] op_sel:[1,1] op_sel_hi:[1,0]
	v_pk_fma_f32 v[212:213], v[210:211], v[210:211], v[206:207] op_sel_hi:[0,1,1] neg_lo:[0,0,1]
	v_pk_mul_f32 v[206:207], v[210:211], v[212:213] op_sel:[1,1] op_sel_hi:[1,0]
	v_pk_fma_f32 v[220:221], v[210:211], v[212:213], v[206:207] op_sel_hi:[0,1,1] neg_lo:[0,0,1]
	v_pk_mul_f32 v[34:35], v[210:211], v[202:203] op_sel:[1,1] op_sel_hi:[1,0]
	v_pk_fma_f32 v[34:35], v[210:211], v[202:203], v[34:35] op_sel_hi:[0,1,1] neg_lo:[0,0,1]
	v_pk_mul_f32 v[36:37], v[212:213], v[40:41] op_sel:[1,1] op_sel_hi:[1,0]
	v_pk_fma_f32 v[36:37], v[212:213], v[40:41], v[36:37] op_sel_hi:[0,1,1] neg_lo:[0,0,1]
	v_pk_mul_f32 v[40:41], v[220:221], v[204:205] op_sel:[1,1] op_sel_hi:[1,0]
	v_pk_fma_f32 v[40:41], v[220:221], v[204:205], v[40:41] op_sel_hi:[0,1,1] neg_lo:[0,0,1]
	v_cos_f32_e32 v210, 0x3e200000
	v_sin_f32_e32 v211, 0xbe200000
	s_waitcnt lgkmcnt(4)
	v_pk_add_f32 v[202:203], v[42:43], v[46:47]
	v_pk_add_f32 v[42:43], v[42:43], v[46:47] neg_lo:[0,1] neg_hi:[0,1]
	v_pk_add_f32 v[204:205], v[44:45], v[48:49]
	v_pk_add_f32 v[44:45], v[44:45], v[48:49] neg_lo:[0,1] neg_hi:[0,1]
	v_pk_add_f32 v[46:47], v[202:203], v[204:205]
	v_pk_add_f32 v[48:49], v[202:203], v[204:205] neg_lo:[0,1] neg_hi:[0,1]
	v_pk_add_f32 v[202:203], v[42:43], v[44:45] op_sel:[0,1] op_sel_hi:[1,0] neg_hi:[0,1]
	v_pk_add_f32 v[204:205], v[42:43], v[44:45] op_sel:[0,1] op_sel_hi:[1,0] neg_lo:[0,1]
	v_pk_mul_f32 v[206:207], v[210:211], v[210:211] op_sel:[1,1] op_sel_hi:[1,0]
	v_pk_fma_f32 v[212:213], v[210:211], v[210:211], v[206:207] op_sel_hi:[0,1,1] neg_lo:[0,0,1]
	v_pk_mul_f32 v[206:207], v[210:211], v[212:213] op_sel:[1,1] op_sel_hi:[1,0]
	v_pk_fma_f32 v[220:221], v[210:211], v[212:213], v[206:207] op_sel_hi:[0,1,1] neg_lo:[0,0,1]
	v_pk_mul_f32 v[42:43], v[210:211], v[202:203] op_sel:[1,1] op_sel_hi:[1,0]
	v_pk_fma_f32 v[42:43], v[210:211], v[202:203], v[42:43] op_sel_hi:[0,1,1] neg_lo:[0,0,1]
	v_pk_mul_f32 v[44:45], v[212:213], v[48:49] op_sel:[1,1] op_sel_hi:[1,0]
	v_pk_fma_f32 v[44:45], v[212:213], v[48:49], v[44:45] op_sel_hi:[0,1,1] neg_lo:[0,0,1]
	v_pk_mul_f32 v[48:49], v[220:221], v[204:205] op_sel:[1,1] op_sel_hi:[1,0]
	v_pk_fma_f32 v[48:49], v[220:221], v[204:205], v[48:49] op_sel_hi:[0,1,1] neg_lo:[0,0,1]
	v_cos_f32_e32 v210, 0x3e400000
	v_sin_f32_e32 v211, 0xbe400000
	s_waitcnt lgkmcnt(2)
	v_pk_add_f32 v[202:203], v[50:51], v[54:55]
	v_pk_add_f32 v[50:51], v[50:51], v[54:55] neg_lo:[0,1] neg_hi:[0,1]
	v_pk_add_f32 v[204:205], v[52:53], v[56:57]
	v_pk_add_f32 v[52:53], v[52:53], v[56:57] neg_lo:[0,1] neg_hi:[0,1]
	v_pk_add_f32 v[54:55], v[202:203], v[204:205]
	v_pk_add_f32 v[56:57], v[202:203], v[204:205] neg_lo:[0,1] neg_hi:[0,1]
	v_pk_add_f32 v[202:203], v[50:51], v[52:53] op_sel:[0,1] op_sel_hi:[1,0] neg_hi:[0,1]
	v_pk_add_f32 v[204:205], v[50:51], v[52:53] op_sel:[0,1] op_sel_hi:[1,0] neg_lo:[0,1]
	v_pk_mul_f32 v[206:207], v[210:211], v[210:211] op_sel:[1,1] op_sel_hi:[1,0]
	v_pk_fma_f32 v[212:213], v[210:211], v[210:211], v[206:207] op_sel_hi:[0,1,1] neg_lo:[0,0,1]
	v_pk_mul_f32 v[206:207], v[210:211], v[212:213] op_sel:[1,1] op_sel_hi:[1,0]
	v_pk_fma_f32 v[220:221], v[210:211], v[212:213], v[206:207] op_sel_hi:[0,1,1] neg_lo:[0,0,1]
	v_pk_mul_f32 v[50:51], v[210:211], v[202:203] op_sel:[1,1] op_sel_hi:[1,0]
	v_pk_fma_f32 v[50:51], v[210:211], v[202:203], v[50:51] op_sel_hi:[0,1,1] neg_lo:[0,0,1]
	v_pk_mul_f32 v[52:53], v[212:213], v[56:57] op_sel:[1,1] op_sel_hi:[1,0]
	v_pk_fma_f32 v[52:53], v[212:213], v[56:57], v[52:53] op_sel_hi:[0,1,1] neg_lo:[0,0,1]
	v_pk_mul_f32 v[56:57], v[220:221], v[204:205] op_sel:[1,1] op_sel_hi:[1,0]
	v_pk_fma_f32 v[56:57], v[220:221], v[204:205], v[56:57] op_sel_hi:[0,1,1] neg_lo:[0,0,1]
	v_cos_f32_e32 v210, 0x3e600000
	v_sin_f32_e32 v211, 0xbe600000
	s_waitcnt lgkmcnt(0)
	v_pk_add_f32 v[202:203], v[58:59], v[62:63]
	v_pk_add_f32 v[58:59], v[58:59], v[62:63] neg_lo:[0,1] neg_hi:[0,1]
	v_pk_add_f32 v[204:205], v[60:61], v[64:65]
	v_pk_add_f32 v[60:61], v[60:61], v[64:65] neg_lo:[0,1] neg_hi:[0,1]
	v_pk_add_f32 v[62:63], v[202:203], v[204:205]
	v_pk_add_f32 v[64:65], v[202:203], v[204:205] neg_lo:[0,1] neg_hi:[0,1]
	v_pk_add_f32 v[202:203], v[58:59], v[60:61] op_sel:[0,1] op_sel_hi:[1,0] neg_hi:[0,1]
	v_pk_add_f32 v[204:205], v[58:59], v[60:61] op_sel:[0,1] op_sel_hi:[1,0] neg_lo:[0,1]
	v_pk_mul_f32 v[206:207], v[210:211], v[210:211] op_sel:[1,1] op_sel_hi:[1,0]
	v_pk_fma_f32 v[212:213], v[210:211], v[210:211], v[206:207] op_sel_hi:[0,1,1] neg_lo:[0,0,1]
	v_pk_mul_f32 v[206:207], v[210:211], v[212:213] op_sel:[1,1] op_sel_hi:[1,0]
	v_pk_fma_f32 v[220:221], v[210:211], v[212:213], v[206:207] op_sel_hi:[0,1,1] neg_lo:[0,0,1]
	v_pk_mul_f32 v[58:59], v[210:211], v[202:203] op_sel:[1,1] op_sel_hi:[1,0]
	v_pk_fma_f32 v[58:59], v[210:211], v[202:203], v[58:59] op_sel_hi:[0,1,1] neg_lo:[0,0,1]
	v_pk_mul_f32 v[60:61], v[212:213], v[64:65] op_sel:[1,1] op_sel_hi:[1,0]
	v_pk_fma_f32 v[60:61], v[212:213], v[64:65], v[60:61] op_sel_hi:[0,1,1] neg_lo:[0,0,1]
	v_pk_mul_f32 v[64:65], v[220:221], v[204:205] op_sel:[1,1] op_sel_hi:[1,0]
	v_pk_fma_f32 v[64:65], v[220:221], v[204:205], v[64:65] op_sel_hi:[0,1,1] neg_lo:[0,0,1]
	s_barrier
; DI f32x2 cmul(f32x2 a, f32x2 b) { return mkf2(a.x * b.x - a.y * b.y, a.x * b.y + a.y * b.x); }
; DI void fft8192(f32x2* buf, const f32x2* __restrict__ tw) {
;     ...
; #pragma unroll
;     for (int e = 0; e < 8; ++e) {
;       const int i = tid + 256 * e;
;       const int q = i & (s - 1);
;       const int ps = i - q;
;       const float rev = (float)ps * (1.f / 8192.f);
;       const f32x2 w1 = mkf2(__builtin_amdgcn_cosf(rev), -__builtin_amdgcn_sinf(rev));
;       const f32x2 w2 = cmul(w1, w1), w3 = cmul(w1, w2);
;       const f32x2 apc = mkf2(a[e].x + c[e].x, a[e].y + c[e].y), amc = mkf2(a[e].x - c[e].x, a[e].y - c[e].y);
;       const f32x2 bpd = mkf2(b[e].x + d[e].x, b[e].y + d[e].y), bmd = mkf2(b[e].x - d[e].x, b[e].y - d[e].y);
;       const int o = 4 * i - 3 * q;
;       buf[SW(o)] = mkf2(apc.x + bpd.x, apc.y + bpd.y);
;       buf[SW(o + s)] = cmul(w1, mkf2(amc.x + bmd.y, amc.y - bmd.x));
;       buf[SW(o + 2 * s)] = cmul(w2, mkf2(apc.x - bpd.x, apc.y - bpd.y));
;       buf[SW(o + 3 * s)] = cmul(w3, mkf2(amc.x - bmd.y, amc.y + bmd.x));
;     }
	v_pk_add_f32 v[202:203], v[6:7], v[38:39]
	v_pk_add_f32 v[6:7], v[6:7], v[38:39] neg_lo:[0,1] neg_hi:[0,1]
	v_pk_add_f32 v[204:205], v[22:23], v[54:55]
	v_pk_add_f32 v[22:23], v[22:23], v[54:55] neg_lo:[0,1] neg_hi:[0,1]
	v_pk_add_f32 v[38:39], v[202:203], v[204:205]
	v_pk_add_f32 v[54:55], v[202:203], v[204:205] neg_lo:[0,1] neg_hi:[0,1]
	v_pk_add_f32 v[202:203], v[6:7], v[22:23] op_sel:[0,1] op_sel_hi:[1,0] neg_hi:[0,1]
	v_pk_add_f32 v[22:23], v[6:7], v[22:23] op_sel:[0,1] op_sel_hi:[1,0] neg_lo:[0,1]
	v_pk_mov_b32 v[6:7], v[202:203], v[202:203] op_sel:[0,1]
	v_pk_add_f32 v[202:203], v[2:3], v[34:35]
	v_pk_add_f32 v[2:3], v[2:3], v[34:35] neg_lo:[0,1] neg_hi:[0,1]
	v_pk_add_f32 v[204:205], v[18:19], v[50:51]
	v_pk_add_f32 v[18:19], v[18:19], v[50:51] neg_lo:[0,1] neg_hi:[0,1]
	v_pk_add_f32 v[34:35], v[202:203], v[204:205]
	v_pk_add_f32 v[50:51], v[202:203], v[204:205] neg_lo:[0,1] neg_hi:[0,1]
	v_pk_add_f32 v[202:203], v[2:3], v[18:19] op_sel:[0,1] op_sel_hi:[1,0] neg_hi:[0,1]
	v_pk_add_f32 v[18:19], v[2:3], v[18:19] op_sel:[0,1] op_sel_hi:[1,0] neg_lo:[0,1]
	v_pk_mov_b32 v[2:3], v[202:203], v[202:203] op_sel:[0,1]
	v_pk_add_f32 v[202:203], v[8:9], v[36:37]
	v_pk_add_f32 v[8:9], v[8:9], v[36:37] neg_lo:[0,1] neg_hi:[0,1]
	v_pk_add_f32 v[204:205], v[20:21], v[52:53]
	v_pk_add_f32 v[20:21], v[20:21], v[52:53] neg_lo:[0,1] neg_hi:[0,1]
	v_pk_add_f32 v[36:37], v[202:203], v[204:205]
	v_pk_add_f32 v[52:53], v[202:203], v[204:205] neg_lo:[0,1] neg_hi:[0,1]
	v_pk_add_f32 v[202:203], v[8:9], v[20:21] op_sel:[0,1] op_sel_hi:[1,0] neg_hi:[0,1]
	v_pk_add_f32 v[20:21], v[8:9], v[20:21] op_sel:[0,1] op_sel_hi:[1,0] neg_lo:[0,1]
	v_pk_mov_b32 v[8:9], v[202:203], v[202:203] op_sel:[0,1]
	v_pk_add_f32 v[202:203], v[4:5], v[40:41]
	v_pk_add_f32 v[4:5], v[4:5], v[40:41] neg_lo:[0,1] neg_hi:[0,1]
	v_pk_add_f32 v[204:205], v[24:25], v[56:57]
	v_pk_add_f32 v[24:25], v[24:25], v[56:57] neg_lo:[0,1] neg_hi:[0,1]
	v_pk_add_f32 v[40:41], v[202:203], v[204:205]
	v_pk_add_f32 v[56:57], v[202:203], v[204:205] neg_lo:[0,1] neg_hi:[0,1]
	v_pk_add_f32 v[202:203], v[4:5], v[24:25] op_sel:[0,1] op_sel_hi:[1,0] neg_hi:[0,1]
	v_pk_add_f32 v[24:25], v[4:5], v[24:25] op_sel:[0,1] op_sel_hi:[1,0] neg_lo:[0,1]
	v_pk_mov_b32 v[4:5], v[202:203], v[202:203] op_sel:[0,1]
	v_cos_f32_e32 v224, 0x3e000000
	v_sin_f32_e32 v225, 0xbe000000
	s_nop 0
	v_pk_mul_f32 v[206:207], v[224:225], v[224:225] op_sel:[1,1] op_sel_hi:[1,0]
	v_pk_fma_f32 v[226:227], v[224:225], v[224:225], v[206:207] op_sel_hi:[0,1,1] neg_lo:[0,0,1]
	v_pk_mul_f32 v[206:207], v[224:225], v[226:227] op_sel:[1,1] op_sel_hi:[1,0]
	v_pk_fma_f32 v[230:231], v[224:225], v[226:227], v[206:207] op_sel_hi:[0,1,1] neg_lo:[0,0,1]
	v_pk_add_f32 v[202:203], v[14:15], v[46:47]
	v_pk_add_f32 v[14:15], v[14:15], v[46:47] neg_lo:[0,1] neg_hi:[0,1]
	v_pk_add_f32 v[204:205], v[30:31], v[62:63]
	v_pk_add_f32 v[30:31], v[30:31], v[62:63] neg_lo:[0,1] neg_hi:[0,1]
	v_pk_add_f32 v[46:47], v[202:203], v[204:205]
	v_pk_add_f32 v[62:63], v[202:203], v[204:205] neg_lo:[0,1] neg_hi:[0,1]
	v_pk_add_f32 v[202:203], v[14:15], v[30:31] op_sel:[0,1] op_sel_hi:[1,0] neg_hi:[0,1]
	v_pk_add_f32 v[204:205], v[14:15], v[30:31] op_sel:[0,1] op_sel_hi:[1,0] neg_lo:[0,1]
	v_pk_mul_f32 v[14:15], v[224:225], v[202:203] op_sel:[1,1] op_sel_hi:[1,0]
	v_pk_fma_f32 v[14:15], v[224:225], v[202:203], v[14:15] op_sel_hi:[0,1,1] neg_lo:[0,0,1]
	v_pk_mul_f32 v[30:31], v[226:227], v[62:63] op_sel:[1,1] op_sel_hi:[1,0]
	v_pk_fma_f32 v[30:31], v[226:227], v[62:63], v[30:31] op_sel_hi:[0,1,1] neg_lo:[0,0,1]
	v_pk_mul_f32 v[62:63], v[230:231], v[204:205] op_sel:[1,1] op_sel_hi:[1,0]
	v_pk_fma_f32 v[62:63], v[230:231], v[204:205], v[62:63] op_sel_hi:[0,1,1] neg_lo:[0,0,1]
	v_pk_add_f32 v[202:203], v[10:11], v[42:43]
	v_pk_add_f32 v[10:11], v[10:11], v[42:43] neg_lo:[0,1] neg_hi:[0,1]
	v_pk_add_f32 v[204:205], v[26:27], v[58:59]
	v_pk_add_f32 v[26:27], v[26:27], v[58:59] neg_lo:[0,1] neg_hi:[0,1]
	v_pk_add_f32 v[42:43], v[202:203], v[204:205]
	v_pk_add_f32 v[58:59], v[202:203], v[204:205] neg_lo:[0,1] neg_hi:[0,1]
	v_pk_add_f32 v[202:203], v[10:11], v[26:27] op_sel:[0,1] op_sel_hi:[1,0] neg_hi:[0,1]
	v_pk_add_f32 v[204:205], v[10:11], v[26:27] op_sel:[0,1] op_sel_hi:[1,0] neg_lo:[0,1]
	v_pk_mul_f32 v[10:11], v[224:225], v[202:203] op_sel:[1,1] op_sel_hi:[1,0]
	v_pk_fma_f32 v[10:11], v[224:225], v[202:203], v[10:11] op_sel_hi:[0,1,1] neg_lo:[0,0,1]
	v_pk_mul_f32 v[26:27], v[226:227], v[58:59] op_sel:[1,1] op_sel_hi:[1,0]
	v_pk_fma_f32 v[26:27], v[226:227], v[58:59], v[26:27] op_sel_hi:[0,1,1] neg_lo:[0,0,1]
	v_pk_mul_f32 v[58:59], v[230:231], v[204:205] op_sel:[1,1] op_sel_hi:[1,0]
	v_pk_fma_f32 v[58:59], v[230:231], v[204:205], v[58:59] op_sel_hi:[0,1,1] neg_lo:[0,0,1]
	v_pk_add_f32 v[202:203], v[12:13], v[44:45]
	v_pk_add_f32 v[12:13], v[12:13], v[44:45] neg_lo:[0,1] neg_hi:[0,1]
	v_pk_add_f32 v[204:205], v[28:29], v[60:61]
	v_pk_add_f32 v[28:29], v[28:29], v[60:61] neg_lo:[0,1] neg_hi:[0,1]
	v_pk_add_f32 v[44:45], v[202:203], v[204:205]
	v_pk_add_f32 v[60:61], v[202:203], v[204:205] neg_lo:[0,1] neg_hi:[0,1]
	v_pk_add_f32 v[202:203], v[12:13], v[28:29] op_sel:[0,1] op_sel_hi:[1,0] neg_hi:[0,1]
	v_pk_add_f32 v[204:205], v[12:13], v[28:29] op_sel:[0,1] op_sel_hi:[1,0] neg_lo:[0,1]
	v_pk_mul_f32 v[12:13], v[224:225], v[202:203] op_sel:[1,1] op_sel_hi:[1,0]
	v_pk_fma_f32 v[12:13], v[224:225], v[202:203], v[12:13] op_sel_hi:[0,1,1] neg_lo:[0,0,1]
	v_pk_mul_f32 v[28:29], v[226:227], v[60:61] op_sel:[1,1] op_sel_hi:[1,0]
	v_pk_fma_f32 v[28:29], v[226:227], v[60:61], v[28:29] op_sel_hi:[0,1,1] neg_lo:[0,0,1]
	v_pk_mul_f32 v[60:61], v[230:231], v[204:205] op_sel:[1,1] op_sel_hi:[1,0]
; DI f32x2 cmul(f32x2 a, f32x2 b) { return mkf2(a.x * b.x - a.y * b.y, a.x * b.y + a.y * b.x); }
; DI void fft8192(f32x2* buf, const f32x2* __restrict__ tw) {
;     ...
; #pragma unroll
;     for (int e = 0; e < 8; ++e) {
;       const int i = tid + 256 * e;
;       const int q = i & (s - 1);
;       const int ps = i - q;
;       const float rev = (float)ps * (1.f / 8192.f);
;       const f32x2 w1 = mkf2(__builtin_amdgcn_cosf(rev), -__builtin_amdgcn_sinf(rev));
;       const f32x2 w2 = cmul(w1, w1), w3 = cmul(w1, w2);
;       const f32x2 apc = mkf2(a[e].x + c[e].x, a[e].y + c[e].y), amc = mkf2(a[e].x - c[e].x, a[e].y - c[e].y);
;       const f32x2 bpd = mkf2(b[e].x + d[e].x, b[e].y + d[e].y), bmd = mkf2(b[e].x - d[e].x, b[e].y - d[e].y);
;       const int o = 4 * i - 3 * q;
;       buf[SW(o)] = mkf2(apc.x + bpd.x, apc.y + bpd.y);
;       buf[SW(o + s)] = cmul(w1, mkf2(amc.x + bmd.y, amc.y - bmd.x));
;       buf[SW(o + 2 * s)] = cmul(w2, mkf2(apc.x - bpd.x, apc.y - bpd.y));
;       buf[SW(o + 3 * s)] = cmul(w3, mkf2(amc.x - bmd.y, amc.y + bmd.x));
;     }
; DI void hyena_unit(KP p, int l, int c, char* smem) {
;     ...
;       for (int j = 0; j < 32; ++j) {
;         const int f = tid + 256 * j;
;         f32x2 z = cmul(buf[SW(f)], KF[j]);
;         buf[SW(f)] = mkf2(z.x, -z.y);
;       }
	v_pk_fma_f32 v[60:61], v[230:231], v[204:205], v[60:61] op_sel_hi:[0,1,1] neg_lo:[0,0,1]
	v_pk_add_f32 v[202:203], v[16:17], v[48:49]
	v_pk_add_f32 v[16:17], v[16:17], v[48:49] neg_lo:[0,1] neg_hi:[0,1]
	v_pk_add_f32 v[204:205], v[32:33], v[64:65]
	v_pk_add_f32 v[32:33], v[32:33], v[64:65] neg_lo:[0,1] neg_hi:[0,1]
	v_pk_add_f32 v[48:49], v[202:203], v[204:205]
	v_pk_add_f32 v[64:65], v[202:203], v[204:205] neg_lo:[0,1] neg_hi:[0,1]
	v_pk_add_f32 v[202:203], v[16:17], v[32:33] op_sel:[0,1] op_sel_hi:[1,0] neg_hi:[0,1]
	v_pk_add_f32 v[204:205], v[16:17], v[32:33] op_sel:[0,1] op_sel_hi:[1,0] neg_lo:[0,1]
	v_pk_mul_f32 v[16:17], v[224:225], v[202:203] op_sel:[1,1] op_sel_hi:[1,0]
	v_pk_fma_f32 v[16:17], v[224:225], v[202:203], v[16:17] op_sel_hi:[0,1,1] neg_lo:[0,0,1]
	v_pk_mul_f32 v[32:33], v[226:227], v[64:65] op_sel:[1,1] op_sel_hi:[1,0]
	v_pk_fma_f32 v[32:33], v[226:227], v[64:65], v[32:33] op_sel_hi:[0,1,1] neg_lo:[0,0,1]
	v_pk_mul_f32 v[64:65], v[230:231], v[204:205] op_sel:[1,1] op_sel_hi:[1,0]
	v_pk_fma_f32 v[64:65], v[230:231], v[204:205], v[64:65] op_sel_hi:[0,1,1] neg_lo:[0,0,1]
	v_pk_add_f32 v[202:203], v[38:39], v[46:47]
	v_pk_add_f32 v[46:47], v[38:39], v[46:47] neg_lo:[0,1] neg_hi:[0,1]
	v_pk_mul_f32 v[38:39], v[78:79], v[202:203] op_sel:[1,1] op_sel_hi:[1,0]
	v_pk_fma_f32 v[202:203], v[78:79], v[202:203], v[38:39] op_sel_hi:[0,1,1] neg_lo:[0,0,1] neg_hi:[1,0,1]
	v_pk_mul_f32 v[38:39], v[110:111], v[46:47] op_sel:[1,1] op_sel_hi:[1,0]
	v_pk_fma_f32 v[46:47], v[110:111], v[46:47], v[38:39] op_sel_hi:[0,1,1] neg_lo:[0,0,1] neg_hi:[1,0,1]
	v_pk_add_f32 v[204:205], v[34:35], v[42:43]
	v_pk_add_f32 v[42:43], v[34:35], v[42:43] neg_lo:[0,1] neg_hi:[0,1]
	v_pk_mul_f32 v[34:35], v[80:81], v[204:205] op_sel:[1,1] op_sel_hi:[1,0]
	v_pk_fma_f32 v[204:205], v[80:81], v[204:205], v[34:35] op_sel_hi:[0,1,1] neg_lo:[0,0,1] neg_hi:[1,0,1]
	v_pk_mul_f32 v[34:35], v[112:113], v[42:43] op_sel:[1,1] op_sel_hi:[1,0]
	v_pk_fma_f32 v[42:43], v[112:113], v[42:43], v[34:35] op_sel_hi:[0,1,1] neg_lo:[0,0,1] neg_hi:[1,0,1]
	v_pk_add_f32 v[206:207], v[36:37], v[44:45]
	v_pk_add_f32 v[44:45], v[36:37], v[44:45] neg_lo:[0,1] neg_hi:[0,1]
	v_pk_mul_f32 v[36:37], v[82:83], v[206:207] op_sel:[1,1] op_sel_hi:[1,0]
	v_pk_fma_f32 v[206:207], v[82:83], v[206:207], v[36:37] op_sel_hi:[0,1,1] neg_lo:[0,0,1] neg_hi:[1,0,1]
	v_pk_mul_f32 v[36:37], v[114:115], v[44:45] op_sel:[1,1] op_sel_hi:[1,0]
	v_pk_fma_f32 v[44:45], v[114:115], v[44:45], v[36:37] op_sel_hi:[0,1,1] neg_lo:[0,0,1] neg_hi:[1,0,1]
	v_pk_add_f32 v[208:209], v[40:41], v[48:49]
	v_pk_add_f32 v[48:49], v[40:41], v[48:49] neg_lo:[0,1] neg_hi:[0,1]
	v_pk_mul_f32 v[40:41], v[84:85], v[208:209] op_sel:[1,1] op_sel_hi:[1,0]
	v_pk_fma_f32 v[208:209], v[84:85], v[208:209], v[40:41] op_sel_hi:[0,1,1] neg_lo:[0,0,1] neg_hi:[1,0,1]
	v_pk_mul_f32 v[40:41], v[116:117], v[48:49] op_sel:[1,1] op_sel_hi:[1,0]
	v_pk_fma_f32 v[48:49], v[116:117], v[48:49], v[40:41] op_sel_hi:[0,1,1] neg_lo:[0,0,1] neg_hi:[1,0,1]
	v_pk_add_f32 v[210:211], v[6:7], v[14:15]
	v_pk_add_f32 v[14:15], v[6:7], v[14:15] neg_lo:[0,1] neg_hi:[0,1]
	v_pk_mul_f32 v[6:7], v[86:87], v[210:211] op_sel:[1,1] op_sel_hi:[1,0]
	v_pk_fma_f32 v[210:211], v[86:87], v[210:211], v[6:7] op_sel_hi:[0,1,1] neg_lo:[0,0,1] neg_hi:[1,0,1]
	v_pk_mul_f32 v[6:7], v[118:119], v[14:15] op_sel:[1,1] op_sel_hi:[1,0]
	v_pk_fma_f32 v[14:15], v[118:119], v[14:15], v[6:7] op_sel_hi:[0,1,1] neg_lo:[0,0,1] neg_hi:[1,0,1]
	v_pk_add_f32 v[212:213], v[2:3], v[10:11]
	v_pk_add_f32 v[10:11], v[2:3], v[10:11] neg_lo:[0,1] neg_hi:[0,1]
	v_pk_mul_f32 v[2:3], v[88:89], v[212:213] op_sel:[1,1] op_sel_hi:[1,0]
	v_pk_fma_f32 v[212:213], v[88:89], v[212:213], v[2:3] op_sel_hi:[0,1,1] neg_lo:[0,0,1] neg_hi:[1,0,1]
	v_pk_mul_f32 v[2:3], v[120:121], v[10:11] op_sel:[1,1] op_sel_hi:[1,0]
	v_pk_fma_f32 v[10:11], v[120:121], v[10:11], v[2:3] op_sel_hi:[0,1,1] neg_lo:[0,0,1] neg_hi:[1,0,1]
	v_pk_add_f32 v[220:221], v[8:9], v[12:13]
	v_pk_add_f32 v[12:13], v[8:9], v[12:13] neg_lo:[0,1] neg_hi:[0,1]
	v_pk_mul_f32 v[8:9], v[90:91], v[220:221] op_sel:[1,1] op_sel_hi:[1,0]
	v_pk_fma_f32 v[220:221], v[90:91], v[220:221], v[8:9] op_sel_hi:[0,1,1] neg_lo:[0,0,1] neg_hi:[1,0,1]
	v_pk_mul_f32 v[8:9], v[122:123], v[12:13] op_sel:[1,1] op_sel_hi:[1,0]
	v_pk_fma_f32 v[12:13], v[122:123], v[12:13], v[8:9] op_sel_hi:[0,1,1] neg_lo:[0,0,1] neg_hi:[1,0,1]
	v_pk_add_f32 v[224:225], v[4:5], v[16:17]
	v_pk_add_f32 v[16:17], v[4:5], v[16:17] neg_lo:[0,1] neg_hi:[0,1]
	v_pk_mul_f32 v[4:5], v[92:93], v[224:225] op_sel:[1,1] op_sel_hi:[1,0]
	v_pk_fma_f32 v[224:225], v[92:93], v[224:225], v[4:5] op_sel_hi:[0,1,1] neg_lo:[0,0,1] neg_hi:[1,0,1]
	v_pk_mul_f32 v[4:5], v[124:125], v[16:17] op_sel:[1,1] op_sel_hi:[1,0]
	v_pk_fma_f32 v[16:17], v[124:125], v[16:17], v[4:5] op_sel_hi:[0,1,1] neg_lo:[0,0,1] neg_hi:[1,0,1]
	v_pk_add_f32 v[226:227], v[54:55], v[30:31]
	v_pk_add_f32 v[30:31], v[54:55], v[30:31] neg_lo:[0,1] neg_hi:[0,1]
	v_pk_mul_f32 v[54:55], v[94:95], v[226:227] op_sel:[1,1] op_sel_hi:[1,0]
	v_pk_fma_f32 v[226:227], v[94:95], v[226:227], v[54:55] op_sel_hi:[0,1,1] neg_lo:[0,0,1] neg_hi:[1,0,1]
	v_pk_mul_f32 v[54:55], v[126:127], v[30:31] op_sel:[1,1] op_sel_hi:[1,0]
	v_pk_fma_f32 v[30:31], v[126:127], v[30:31], v[54:55] op_sel_hi:[0,1,1] neg_lo:[0,0,1] neg_hi:[1,0,1]
	v_pk_add_f32 v[230:231], v[50:51], v[26:27]
	v_pk_add_f32 v[26:27], v[50:51], v[26:27] neg_lo:[0,1] neg_hi:[0,1]
	v_pk_mul_f32 v[50:51], v[96:97], v[230:231] op_sel:[1,1] op_sel_hi:[1,0]
	v_pk_fma_f32 v[230:231], v[96:97], v[230:231], v[50:51] op_sel_hi:[0,1,1] neg_lo:[0,0,1] neg_hi:[1,0,1]
	v_pk_mul_f32 v[50:51], v[128:129], v[26:27] op_sel:[1,1] op_sel_hi:[1,0]
; DI f32x2 cmul(f32x2 a, f32x2 b) { return mkf2(a.x * b.x - a.y * b.y, a.x * b.y + a.y * b.x); }
; DI void hyena_unit(KP p, int l, int c, char* smem) {
;     ...
;       for (int j = 0; j < 32; ++j) {
;         const int f = tid + 256 * j;
;         f32x2 z = cmul(buf[SW(f)], KF[j]);
;         buf[SW(f)] = mkf2(z.x, -z.y);
;       }
	v_pk_fma_f32 v[26:27], v[128:129], v[26:27], v[50:51] op_sel_hi:[0,1,1] neg_lo:[0,0,1] neg_hi:[1,0,1]
	v_pk_add_f32 v[232:233], v[52:53], v[28:29]
	v_pk_add_f32 v[28:29], v[52:53], v[28:29] neg_lo:[0,1] neg_hi:[0,1]
	v_pk_mul_f32 v[52:53], v[98:99], v[232:233] op_sel:[1,1] op_sel_hi:[1,0]
	v_pk_fma_f32 v[232:233], v[98:99], v[232:233], v[52:53] op_sel_hi:[0,1,1] neg_lo:[0,0,1] neg_hi:[1,0,1]
	v_pk_mul_f32 v[52:53], v[130:131], v[28:29] op_sel:[1,1] op_sel_hi:[1,0]
	v_pk_fma_f32 v[28:29], v[130:131], v[28:29], v[52:53] op_sel_hi:[0,1,1] neg_lo:[0,0,1] neg_hi:[1,0,1]
	v_pk_add_f32 v[236:237], v[56:57], v[32:33]
	v_pk_add_f32 v[32:33], v[56:57], v[32:33] neg_lo:[0,1] neg_hi:[0,1]
	v_pk_mul_f32 v[56:57], v[100:101], v[236:237] op_sel:[1,1] op_sel_hi:[1,0]
	v_pk_fma_f32 v[236:237], v[100:101], v[236:237], v[56:57] op_sel_hi:[0,1,1] neg_lo:[0,0,1] neg_hi:[1,0,1]
	v_pk_mul_f32 v[56:57], v[132:133], v[32:33] op_sel:[1,1] op_sel_hi:[1,0]
	v_pk_fma_f32 v[32:33], v[132:133], v[32:33], v[56:57] op_sel_hi:[0,1,1] neg_lo:[0,0,1] neg_hi:[1,0,1]
	v_pk_add_f32 v[238:239], v[22:23], v[62:63]
	v_pk_add_f32 v[62:63], v[22:23], v[62:63] neg_lo:[0,1] neg_hi:[0,1]
	v_pk_mul_f32 v[22:23], v[102:103], v[238:239] op_sel:[1,1] op_sel_hi:[1,0]
	v_pk_fma_f32 v[238:239], v[102:103], v[238:239], v[22:23] op_sel_hi:[0,1,1] neg_lo:[0,0,1] neg_hi:[1,0,1]
	v_pk_mul_f32 v[22:23], v[134:135], v[62:63] op_sel:[1,1] op_sel_hi:[1,0]
	v_pk_fma_f32 v[62:63], v[134:135], v[62:63], v[22:23] op_sel_hi:[0,1,1] neg_lo:[0,0,1] neg_hi:[1,0,1]
	v_pk_add_f32 v[240:241], v[18:19], v[58:59]
	v_pk_add_f32 v[58:59], v[18:19], v[58:59] neg_lo:[0,1] neg_hi:[0,1]
	v_pk_mul_f32 v[18:19], v[104:105], v[240:241] op_sel:[1,1] op_sel_hi:[1,0]
	v_pk_fma_f32 v[240:241], v[104:105], v[240:241], v[18:19] op_sel_hi:[0,1,1] neg_lo:[0,0,1] neg_hi:[1,0,1]
	v_pk_mul_f32 v[18:19], v[136:137], v[58:59] op_sel:[1,1] op_sel_hi:[1,0]
	v_pk_fma_f32 v[58:59], v[136:137], v[58:59], v[18:19] op_sel_hi:[0,1,1] neg_lo:[0,0,1] neg_hi:[1,0,1]
	v_pk_add_f32 v[244:245], v[20:21], v[60:61]
	v_pk_add_f32 v[60:61], v[20:21], v[60:61] neg_lo:[0,1] neg_hi:[0,1]
	v_pk_mul_f32 v[20:21], v[106:107], v[244:245] op_sel:[1,1] op_sel_hi:[1,0]
	v_pk_fma_f32 v[244:245], v[106:107], v[244:245], v[20:21] op_sel_hi:[0,1,1] neg_lo:[0,0,1] neg_hi:[1,0,1]
	v_pk_mul_f32 v[20:21], v[138:139], v[60:61] op_sel:[1,1] op_sel_hi:[1,0]
	v_pk_fma_f32 v[60:61], v[138:139], v[60:61], v[20:21] op_sel_hi:[0,1,1] neg_lo:[0,0,1] neg_hi:[1,0,1]
	v_pk_add_f32 v[246:247], v[24:25], v[64:65]
	v_pk_add_f32 v[64:65], v[24:25], v[64:65] neg_lo:[0,1] neg_hi:[0,1]
	v_pk_mul_f32 v[24:25], v[108:109], v[246:247] op_sel:[1,1] op_sel_hi:[1,0]
	v_pk_fma_f32 v[246:247], v[108:109], v[246:247], v[24:25] op_sel_hi:[0,1,1] neg_lo:[0,0,1] neg_hi:[1,0,1]
	v_pk_mul_f32 v[24:25], v[140:141], v[64:65] op_sel:[1,1] op_sel_hi:[1,0]
	v_pk_fma_f32 v[64:65], v[140:141], v[64:65], v[24:25] op_sel_hi:[0,1,1] neg_lo:[0,0,1] neg_hi:[1,0,1]
	ds_write2st64_b64 v154, v[202:203], v[46:47] offset0:0 offset1:64
	ds_write2st64_b64 v154, v[204:205], v[42:43] offset0:4 offset1:68
	ds_write2st64_b64 v154, v[206:207], v[44:45] offset0:8 offset1:72
	ds_write2st64_b64 v154, v[208:209], v[48:49] offset0:12 offset1:76
	ds_write2st64_b64 v154, v[210:211], v[14:15] offset0:16 offset1:80
	ds_write2st64_b64 v154, v[212:213], v[10:11] offset0:20 offset1:84
	ds_write2st64_b64 v154, v[220:221], v[12:13] offset0:24 offset1:88
	ds_write2st64_b64 v154, v[224:225], v[16:17] offset0:28 offset1:92
	ds_write2st64_b64 v154, v[226:227], v[30:31] offset0:32 offset1:96
	ds_write2st64_b64 v154, v[230:231], v[26:27] offset0:36 offset1:100
	ds_write2st64_b64 v154, v[232:233], v[28:29] offset0:40 offset1:104
	ds_write2st64_b64 v154, v[236:237], v[32:33] offset0:44 offset1:108
	ds_write2st64_b64 v154, v[238:239], v[62:63] offset0:48 offset1:112
	ds_write2st64_b64 v154, v[240:241], v[58:59] offset0:52 offset1:116
	ds_write2st64_b64 v154, v[244:245], v[60:61] offset0:56 offset1:120
	ds_write2st64_b64 v154, v[246:247], v[64:65] offset0:60 offset1:124
	v_bfe_i32 v166, v0, 5, 1
	v_bfe_i32 v168, v0, 6, 1
	v_and_b32_e32 v166, 5, v166
	v_and_b32_e32 v168, 26, v168
	v_xor_b32_e32 v166, v166, v168
	v_xor_b32_e32 v166, v166, v0
	v_lshlrev_b32_e32 v154, 3, v166
	s_waitcnt lgkmcnt(0)
	s_barrier
; DI f32x2 cmul(f32x2 a, f32x2 b) { return mkf2(a.x * b.x - a.y * b.y, a.x * b.y + a.y * b.x); }
; DI void fft8192(f32x2* buf, const f32x2* __restrict__ tw) {
;     ...
;     __syncthreads();
; #pragma unroll
;     for (int e = 0; e < 8; ++e) {
;       const int i = tid + 256 * e;
;       const int pi = SW(i);
;       a[e] = buf[pi]; b[e] = buf[pi + 2048]; c[e] = buf[pi + 4096]; d[e] = buf[pi + 6144];
;     }
;     __syncthreads();
; #pragma unroll
;     for (int e = 0; e < 8; ++e) {
;       const int i = tid + 256 * e;
;       const int q = i & (s - 1);
;       const int ps = i - q;
;       const float rev = (float)ps * (1.f / 8192.f);
;       const f32x2 w1 = mkf2(__builtin_amdgcn_cosf(rev), -__builtin_amdgcn_sinf(rev));
;       const f32x2 w2 = cmul(w1, w1), w3 = cmul(w1, w2);
;       const f32x2 apc = mkf2(a[e].x + c[e].x, a[e].y + c[e].y), amc = mkf2(a[e].x - c[e].x, a[e].y - c[e].y);
;       const f32x2 bpd = mkf2(b[e].x + d[e].x, b[e].y + d[e].y), bmd = mkf2(b[e].x - d[e].x, b[e].y - d[e].y);
;       const int o = 4 * i - 3 * q;
;       buf[SW(o)] = mkf2(apc.x + bpd.x, apc.y + bpd.y);
;       buf[SW(o + s)] = cmul(w1, mkf2(amc.x + bmd.y, amc.y - bmd.x));
;       buf[SW(o + 2 * s)] = cmul(w2, mkf2(apc.x - bpd.x, apc.y - bpd.y));
;       buf[SW(o + 3 * s)] = cmul(w3, mkf2(amc.x - bmd.y, amc.y + bmd.x));
;     }
	ds_read2st64_b64 v[2:5], v154 offset0:0 offset1:32
	ds_read2st64_b64 v[6:9], v154 offset0:64 offset1:96
	ds_read2st64_b64 v[10:13], v154 offset0:4 offset1:36
	ds_read2st64_b64 v[14:17], v154 offset0:68 offset1:100
	ds_read2st64_b64 v[18:21], v154 offset0:8 offset1:40
	ds_read2st64_b64 v[22:25], v154 offset0:72 offset1:104
	ds_read2st64_b64 v[26:29], v154 offset0:12 offset1:44
	ds_read2st64_b64 v[30:33], v154 offset0:76 offset1:108
	ds_read2st64_b64 v[34:37], v154 offset0:16 offset1:48
	ds_read2st64_b64 v[38:41], v154 offset0:80 offset1:112
	ds_read2st64_b64 v[42:45], v154 offset0:20 offset1:52
	ds_read2st64_b64 v[46:49], v154 offset0:84 offset1:116
	ds_read2st64_b64 v[50:53], v154 offset0:24 offset1:56
	ds_read2st64_b64 v[54:57], v154 offset0:88 offset1:120
	ds_read2st64_b64 v[58:61], v154 offset0:28 offset1:60
	ds_read2st64_b64 v[62:65], v154 offset0:92 offset1:124
	v_cvt_f32_u32_e32 v201, v0
	v_lshlrev_b32_e32 v164, 4, v0
	v_bfe_i32 v166, v164, 5, 1
	v_bfe_i32 v168, v164, 6, 1
	v_and_b32_e32 v166, 5, v166
	v_and_b32_e32 v168, 26, v168
	v_xor_b32_e32 v166, v166, v168
	v_xor_b32_e32 v166, v166, v164
	v_lshlrev_b32_e32 v164, 3, v166
	v_mul_f32_e32 v201, 0x39000000, v201
	v_cos_f32_e32 v210, v201
	v_sin_f32_e64 v211, -v201
	s_waitcnt lgkmcnt(14)
	v_pk_add_f32 v[202:203], v[2:3], v[6:7]
	v_pk_add_f32 v[2:3], v[2:3], v[6:7] neg_lo:[0,1] neg_hi:[0,1]
	v_pk_add_f32 v[204:205], v[4:5], v[8:9]
	v_pk_add_f32 v[4:5], v[4:5], v[8:9] neg_lo:[0,1] neg_hi:[0,1]
	v_pk_add_f32 v[6:7], v[202:203], v[204:205]
	v_pk_add_f32 v[8:9], v[202:203], v[204:205] neg_lo:[0,1] neg_hi:[0,1]
	v_pk_add_f32 v[202:203], v[2:3], v[4:5] op_sel:[0,1] op_sel_hi:[1,0] neg_hi:[0,1]
	v_pk_add_f32 v[204:205], v[2:3], v[4:5] op_sel:[0,1] op_sel_hi:[1,0] neg_lo:[0,1]
	v_pk_mul_f32 v[206:207], v[210:211], v[210:211] op_sel:[1,1] op_sel_hi:[1,0]
	v_pk_fma_f32 v[212:213], v[210:211], v[210:211], v[206:207] op_sel_hi:[0,1,1] neg_lo:[0,0,1]
	v_pk_mul_f32 v[206:207], v[210:211], v[212:213] op_sel:[1,1] op_sel_hi:[1,0]
	v_pk_fma_f32 v[220:221], v[210:211], v[212:213], v[206:207] op_sel_hi:[0,1,1] neg_lo:[0,0,1]
	v_pk_mul_f32 v[2:3], v[210:211], v[202:203] op_sel:[1,1] op_sel_hi:[1,0]
	v_pk_fma_f32 v[2:3], v[210:211], v[202:203], v[2:3] op_sel_hi:[0,1,1] neg_lo:[0,0,1]
	v_pk_mul_f32 v[4:5], v[212:213], v[8:9] op_sel:[1,1] op_sel_hi:[1,0]
	v_pk_fma_f32 v[4:5], v[212:213], v[8:9], v[4:5] op_sel_hi:[0,1,1] neg_lo:[0,0,1]
	v_pk_mul_f32 v[8:9], v[220:221], v[204:205] op_sel:[1,1] op_sel_hi:[1,0]
	v_pk_fma_f32 v[8:9], v[220:221], v[204:205], v[8:9] op_sel_hi:[0,1,1] neg_lo:[0,0,1]
	v_add_f32_e32 v214, 0x3d000000, v201
	v_cos_f32_e32 v210, v214
	v_sin_f32_e64 v211, -v214
	s_waitcnt lgkmcnt(12)
	v_pk_add_f32 v[202:203], v[10:11], v[14:15]
	v_pk_add_f32 v[10:11], v[10:11], v[14:15] neg_lo:[0,1] neg_hi:[0,1]
	v_pk_add_f32 v[204:205], v[12:13], v[16:17]
	v_pk_add_f32 v[12:13], v[12:13], v[16:17] neg_lo:[0,1] neg_hi:[0,1]
	v_pk_add_f32 v[14:15], v[202:203], v[204:205]
	v_pk_add_f32 v[16:17], v[202:203], v[204:205] neg_lo:[0,1] neg_hi:[0,1]
	v_pk_add_f32 v[202:203], v[10:11], v[12:13] op_sel:[0,1] op_sel_hi:[1,0] neg_hi:[0,1]
	v_pk_add_f32 v[204:205], v[10:11], v[12:13] op_sel:[0,1] op_sel_hi:[1,0] neg_lo:[0,1]
	v_pk_mul_f32 v[206:207], v[210:211], v[210:211] op_sel:[1,1] op_sel_hi:[1,0]
	v_pk_fma_f32 v[212:213], v[210:211], v[210:211], v[206:207] op_sel_hi:[0,1,1] neg_lo:[0,0,1]
	v_pk_mul_f32 v[206:207], v[210:211], v[212:213] op_sel:[1,1] op_sel_hi:[1,0]
	v_pk_fma_f32 v[220:221], v[210:211], v[212:213], v[206:207] op_sel_hi:[0,1,1] neg_lo:[0,0,1]
	v_pk_mul_f32 v[10:11], v[210:211], v[202:203] op_sel:[1,1] op_sel_hi:[1,0]
	v_pk_fma_f32 v[10:11], v[210:211], v[202:203], v[10:11] op_sel_hi:[0,1,1] neg_lo:[0,0,1]
	v_pk_mul_f32 v[12:13], v[212:213], v[16:17] op_sel:[1,1] op_sel_hi:[1,0]
	v_pk_fma_f32 v[12:13], v[212:213], v[16:17], v[12:13] op_sel_hi:[0,1,1] neg_lo:[0,0,1]
	v_pk_mul_f32 v[16:17], v[220:221], v[204:205] op_sel:[1,1] op_sel_hi:[1,0]
	v_pk_fma_f32 v[16:17], v[220:221], v[204:205], v[16:17] op_sel_hi:[0,1,1] neg_lo:[0,0,1]
	v_add_f32_e32 v214, 0x3d800000, v201
	v_cos_f32_e32 v210, v214
	v_sin_f32_e64 v211, -v214
	s_waitcnt lgkmcnt(10)
	v_pk_add_f32 v[202:203], v[18:19], v[22:23]
	v_pk_add_f32 v[18:19], v[18:19], v[22:23] neg_lo:[0,1] neg_hi:[0,1]
	v_pk_add_f32 v[204:205], v[20:21], v[24:25]
	v_pk_add_f32 v[20:21], v[20:21], v[24:25] neg_lo:[0,1] neg_hi:[0,1]
	v_pk_add_f32 v[22:23], v[202:203], v[204:205]
	v_pk_add_f32 v[24:25], v[202:203], v[204:205] neg_lo:[0,1] neg_hi:[0,1]
	v_pk_add_f32 v[202:203], v[18:19], v[20:21] op_sel:[0,1] op_sel_hi:[1,0] neg_hi:[0,1]
	v_pk_add_f32 v[204:205], v[18:19], v[20:21] op_sel:[0,1] op_sel_hi:[1,0] neg_lo:[0,1]
	v_pk_mul_f32 v[206:207], v[210:211], v[210:211] op_sel:[1,1] op_sel_hi:[1,0]
	v_pk_fma_f32 v[212:213], v[210:211], v[210:211], v[206:207] op_sel_hi:[0,1,1] neg_lo:[0,0,1]
	v_pk_mul_f32 v[206:207], v[210:211], v[212:213] op_sel:[1,1] op_sel_hi:[1,0]
	v_pk_fma_f32 v[220:221], v[210:211], v[212:213], v[206:207] op_sel_hi:[0,1,1] neg_lo:[0,0,1]
	v_pk_mul_f32 v[18:19], v[210:211], v[202:203] op_sel:[1,1] op_sel_hi:[1,0]
	v_pk_fma_f32 v[18:19], v[210:211], v[202:203], v[18:19] op_sel_hi:[0,1,1] neg_lo:[0,0,1]
	v_pk_mul_f32 v[20:21], v[212:213], v[24:25] op_sel:[1,1] op_sel_hi:[1,0]
	v_pk_fma_f32 v[20:21], v[212:213], v[24:25], v[20:21] op_sel_hi:[0,1,1] neg_lo:[0,0,1]
	v_pk_mul_f32 v[24:25], v[220:221], v[204:205] op_sel:[1,1] op_sel_hi:[1,0]
	v_pk_fma_f32 v[24:25], v[220:221], v[204:205], v[24:25] op_sel_hi:[0,1,1] neg_lo:[0,0,1]
	v_add_f32_e32 v214, 0x3dc00000, v201
	v_cos_f32_e32 v210, v214
	v_sin_f32_e64 v211, -v214
	s_waitcnt lgkmcnt(8)
; DI f32x2 cmul(f32x2 a, f32x2 b) { return mkf2(a.x * b.x - a.y * b.y, a.x * b.y + a.y * b.x); }
; DI void fft8192(f32x2* buf, const f32x2* __restrict__ tw) {
;     ...
; #pragma unroll
;     for (int e = 0; e < 8; ++e) {
;       const int i = tid + 256 * e;
;       const int q = i & (s - 1);
;       const int ps = i - q;
;       const float rev = (float)ps * (1.f / 8192.f);
;       const f32x2 w1 = mkf2(__builtin_amdgcn_cosf(rev), -__builtin_amdgcn_sinf(rev));
;       const f32x2 w2 = cmul(w1, w1), w3 = cmul(w1, w2);
;       const f32x2 apc = mkf2(a[e].x + c[e].x, a[e].y + c[e].y), amc = mkf2(a[e].x - c[e].x, a[e].y - c[e].y);
;       const f32x2 bpd = mkf2(b[e].x + d[e].x, b[e].y + d[e].y), bmd = mkf2(b[e].x - d[e].x, b[e].y - d[e].y);
;       const int o = 4 * i - 3 * q;
;       buf[SW(o)] = mkf2(apc.x + bpd.x, apc.y + bpd.y);
;       buf[SW(o + s)] = cmul(w1, mkf2(amc.x + bmd.y, amc.y - bmd.x));
;       buf[SW(o + 2 * s)] = cmul(w2, mkf2(apc.x - bpd.x, apc.y - bpd.y));
;       buf[SW(o + 3 * s)] = cmul(w3, mkf2(amc.x - bmd.y, amc.y + bmd.x));
;     }
	v_pk_add_f32 v[202:203], v[26:27], v[30:31]
	v_pk_add_f32 v[26:27], v[26:27], v[30:31] neg_lo:[0,1] neg_hi:[0,1]
	v_pk_add_f32 v[204:205], v[28:29], v[32:33]
	v_pk_add_f32 v[28:29], v[28:29], v[32:33] neg_lo:[0,1] neg_hi:[0,1]
	v_pk_add_f32 v[30:31], v[202:203], v[204:205]
	v_pk_add_f32 v[32:33], v[202:203], v[204:205] neg_lo:[0,1] neg_hi:[0,1]
	v_pk_add_f32 v[202:203], v[26:27], v[28:29] op_sel:[0,1] op_sel_hi:[1,0] neg_hi:[0,1]
	v_pk_add_f32 v[204:205], v[26:27], v[28:29] op_sel:[0,1] op_sel_hi:[1,0] neg_lo:[0,1]
	v_pk_mul_f32 v[206:207], v[210:211], v[210:211] op_sel:[1,1] op_sel_hi:[1,0]
	v_pk_fma_f32 v[212:213], v[210:211], v[210:211], v[206:207] op_sel_hi:[0,1,1] neg_lo:[0,0,1]
	v_pk_mul_f32 v[206:207], v[210:211], v[212:213] op_sel:[1,1] op_sel_hi:[1,0]
	v_pk_fma_f32 v[220:221], v[210:211], v[212:213], v[206:207] op_sel_hi:[0,1,1] neg_lo:[0,0,1]
	v_pk_mul_f32 v[26:27], v[210:211], v[202:203] op_sel:[1,1] op_sel_hi:[1,0]
	v_pk_fma_f32 v[26:27], v[210:211], v[202:203], v[26:27] op_sel_hi:[0,1,1] neg_lo:[0,0,1]
	v_pk_mul_f32 v[28:29], v[212:213], v[32:33] op_sel:[1,1] op_sel_hi:[1,0]
	v_pk_fma_f32 v[28:29], v[212:213], v[32:33], v[28:29] op_sel_hi:[0,1,1] neg_lo:[0,0,1]
	v_pk_mul_f32 v[32:33], v[220:221], v[204:205] op_sel:[1,1] op_sel_hi:[1,0]
	v_pk_fma_f32 v[32:33], v[220:221], v[204:205], v[32:33] op_sel_hi:[0,1,1] neg_lo:[0,0,1]
	v_add_f32_e32 v214, 0x3e000000, v201
	v_cos_f32_e32 v210, v214
	v_sin_f32_e64 v211, -v214
	s_waitcnt lgkmcnt(6)
	v_pk_add_f32 v[202:203], v[34:35], v[38:39]
	v_pk_add_f32 v[34:35], v[34:35], v[38:39] neg_lo:[0,1] neg_hi:[0,1]
	v_pk_add_f32 v[204:205], v[36:37], v[40:41]
	v_pk_add_f32 v[36:37], v[36:37], v[40:41] neg_lo:[0,1] neg_hi:[0,1]
	v_pk_add_f32 v[38:39], v[202:203], v[204:205]
	v_pk_add_f32 v[40:41], v[202:203], v[204:205] neg_lo:[0,1] neg_hi:[0,1]
	v_pk_add_f32 v[202:203], v[34:35], v[36:37] op_sel:[0,1] op_sel_hi:[1,0] neg_hi:[0,1]
	v_pk_add_f32 v[204:205], v[34:35], v[36:37] op_sel:[0,1] op_sel_hi:[1,0] neg_lo:[0,1]
	v_pk_mul_f32 v[206:207], v[210:211], v[210:211] op_sel:[1,1] op_sel_hi:[1,0]
	v_pk_fma_f32 v[212:213], v[210:211], v[210:211], v[206:207] op_sel_hi:[0,1,1] neg_lo:[0,0,1]
	v_pk_mul_f32 v[206:207], v[210:211], v[212:213] op_sel:[1,1] op_sel_hi:[1,0]
	v_pk_fma_f32 v[220:221], v[210:211], v[212:213], v[206:207] op_sel_hi:[0,1,1] neg_lo:[0,0,1]
	v_pk_mul_f32 v[34:35], v[210:211], v[202:203] op_sel:[1,1] op_sel_hi:[1,0]
	v_pk_fma_f32 v[34:35], v[210:211], v[202:203], v[34:35] op_sel_hi:[0,1,1] neg_lo:[0,0,1]
	v_pk_mul_f32 v[36:37], v[212:213], v[40:41] op_sel:[1,1] op_sel_hi:[1,0]
	v_pk_fma_f32 v[36:37], v[212:213], v[40:41], v[36:37] op_sel_hi:[0,1,1] neg_lo:[0,0,1]
	v_pk_mul_f32 v[40:41], v[220:221], v[204:205] op_sel:[1,1] op_sel_hi:[1,0]
	v_pk_fma_f32 v[40:41], v[220:221], v[204:205], v[40:41] op_sel_hi:[0,1,1] neg_lo:[0,0,1]
	v_add_f32_e32 v214, 0x3e200000, v201
	v_cos_f32_e32 v210, v214
	v_sin_f32_e64 v211, -v214
	s_waitcnt lgkmcnt(4)
	v_pk_add_f32 v[202:203], v[42:43], v[46:47]
	v_pk_add_f32 v[42:43], v[42:43], v[46:47] neg_lo:[0,1] neg_hi:[0,1]
	v_pk_add_f32 v[204:205], v[44:45], v[48:49]
	v_pk_add_f32 v[44:45], v[44:45], v[48:49] neg_lo:[0,1] neg_hi:[0,1]
	v_pk_add_f32 v[46:47], v[202:203], v[204:205]
	v_pk_add_f32 v[48:49], v[202:203], v[204:205] neg_lo:[0,1] neg_hi:[0,1]
	v_pk_add_f32 v[202:203], v[42:43], v[44:45] op_sel:[0,1] op_sel_hi:[1,0] neg_hi:[0,1]
	v_pk_add_f32 v[204:205], v[42:43], v[44:45] op_sel:[0,1] op_sel_hi:[1,0] neg_lo:[0,1]
	v_pk_mul_f32 v[206:207], v[210:211], v[210:211] op_sel:[1,1] op_sel_hi:[1,0]
	v_pk_fma_f32 v[212:213], v[210:211], v[210:211], v[206:207] op_sel_hi:[0,1,1] neg_lo:[0,0,1]
	v_pk_mul_f32 v[206:207], v[210:211], v[212:213] op_sel:[1,1] op_sel_hi:[1,0]
	v_pk_fma_f32 v[220:221], v[210:211], v[212:213], v[206:207] op_sel_hi:[0,1,1] neg_lo:[0,0,1]
	v_pk_mul_f32 v[42:43], v[210:211], v[202:203] op_sel:[1,1] op_sel_hi:[1,0]
	v_pk_fma_f32 v[42:43], v[210:211], v[202:203], v[42:43] op_sel_hi:[0,1,1] neg_lo:[0,0,1]
	v_pk_mul_f32 v[44:45], v[212:213], v[48:49] op_sel:[1,1] op_sel_hi:[1,0]
	v_pk_fma_f32 v[44:45], v[212:213], v[48:49], v[44:45] op_sel_hi:[0,1,1] neg_lo:[0,0,1]
	v_pk_mul_f32 v[48:49], v[220:221], v[204:205] op_sel:[1,1] op_sel_hi:[1,0]
	v_pk_fma_f32 v[48:49], v[220:221], v[204:205], v[48:49] op_sel_hi:[0,1,1] neg_lo:[0,0,1]
	v_add_f32_e32 v214, 0x3e400000, v201
	v_cos_f32_e32 v210, v214
	v_sin_f32_e64 v211, -v214
	s_waitcnt lgkmcnt(2)
	v_pk_add_f32 v[202:203], v[50:51], v[54:55]
	v_pk_add_f32 v[50:51], v[50:51], v[54:55] neg_lo:[0,1] neg_hi:[0,1]
	v_pk_add_f32 v[204:205], v[52:53], v[56:57]
	v_pk_add_f32 v[52:53], v[52:53], v[56:57] neg_lo:[0,1] neg_hi:[0,1]
	v_pk_add_f32 v[54:55], v[202:203], v[204:205]
	v_pk_add_f32 v[56:57], v[202:203], v[204:205] neg_lo:[0,1] neg_hi:[0,1]
	v_pk_add_f32 v[202:203], v[50:51], v[52:53] op_sel:[0,1] op_sel_hi:[1,0] neg_hi:[0,1]
	v_pk_add_f32 v[204:205], v[50:51], v[52:53] op_sel:[0,1] op_sel_hi:[1,0] neg_lo:[0,1]
	v_pk_mul_f32 v[206:207], v[210:211], v[210:211] op_sel:[1,1] op_sel_hi:[1,0]
	v_pk_fma_f32 v[212:213], v[210:211], v[210:211], v[206:207] op_sel_hi:[0,1,1] neg_lo:[0,0,1]
	v_pk_mul_f32 v[206:207], v[210:211], v[212:213] op_sel:[1,1] op_sel_hi:[1,0]
	v_pk_fma_f32 v[220:221], v[210:211], v[212:213], v[206:207] op_sel_hi:[0,1,1] neg_lo:[0,0,1]
	v_pk_mul_f32 v[50:51], v[210:211], v[202:203] op_sel:[1,1] op_sel_hi:[1,0]
	v_pk_fma_f32 v[50:51], v[210:211], v[202:203], v[50:51] op_sel_hi:[0,1,1] neg_lo:[0,0,1]
	v_pk_mul_f32 v[52:53], v[212:213], v[56:57] op_sel:[1,1] op_sel_hi:[1,0]
	v_pk_fma_f32 v[52:53], v[212:213], v[56:57], v[52:53] op_sel_hi:[0,1,1] neg_lo:[0,0,1]
	v_pk_mul_f32 v[56:57], v[220:221], v[204:205] op_sel:[1,1] op_sel_hi:[1,0]
	v_pk_fma_f32 v[56:57], v[220:221], v[204:205], v[56:57] op_sel_hi:[0,1,1] neg_lo:[0,0,1]
	v_add_f32_e32 v214, 0x3e600000, v201
	v_cos_f32_e32 v210, v214
	v_sin_f32_e64 v211, -v214
	s_waitcnt lgkmcnt(0)
; DI f32x2 cmul(f32x2 a, f32x2 b) { return mkf2(a.x * b.x - a.y * b.y, a.x * b.y + a.y * b.x); }
; DI void fft8192(f32x2* buf, const f32x2* __restrict__ tw) {
;     ...
; #pragma unroll
;     for (int e = 0; e < 8; ++e) {
;       const int i = tid + 256 * e;
;       const int q = i & (s - 1);
;       const int ps = i - q;
;       const float rev = (float)ps * (1.f / 8192.f);
;       const f32x2 w1 = mkf2(__builtin_amdgcn_cosf(rev), -__builtin_amdgcn_sinf(rev));
;       const f32x2 w2 = cmul(w1, w1), w3 = cmul(w1, w2);
;       const f32x2 apc = mkf2(a[e].x + c[e].x, a[e].y + c[e].y), amc = mkf2(a[e].x - c[e].x, a[e].y - c[e].y);
;       const f32x2 bpd = mkf2(b[e].x + d[e].x, b[e].y + d[e].y), bmd = mkf2(b[e].x - d[e].x, b[e].y - d[e].y);
;       const int o = 4 * i - 3 * q;
;       buf[SW(o)] = mkf2(apc.x + bpd.x, apc.y + bpd.y);
;       buf[SW(o + s)] = cmul(w1, mkf2(amc.x + bmd.y, amc.y - bmd.x));
;       buf[SW(o + 2 * s)] = cmul(w2, mkf2(apc.x - bpd.x, apc.y - bpd.y));
;       buf[SW(o + 3 * s)] = cmul(w3, mkf2(amc.x - bmd.y, amc.y + bmd.x));
;     }
	v_pk_add_f32 v[202:203], v[58:59], v[62:63]
	v_pk_add_f32 v[58:59], v[58:59], v[62:63] neg_lo:[0,1] neg_hi:[0,1]
	v_pk_add_f32 v[204:205], v[60:61], v[64:65]
	v_pk_add_f32 v[60:61], v[60:61], v[64:65] neg_lo:[0,1] neg_hi:[0,1]
	v_pk_add_f32 v[62:63], v[202:203], v[204:205]
	v_pk_add_f32 v[64:65], v[202:203], v[204:205] neg_lo:[0,1] neg_hi:[0,1]
	v_pk_add_f32 v[202:203], v[58:59], v[60:61] op_sel:[0,1] op_sel_hi:[1,0] neg_hi:[0,1]
	v_pk_add_f32 v[204:205], v[58:59], v[60:61] op_sel:[0,1] op_sel_hi:[1,0] neg_lo:[0,1]
	v_pk_mul_f32 v[206:207], v[210:211], v[210:211] op_sel:[1,1] op_sel_hi:[1,0]
	v_pk_fma_f32 v[212:213], v[210:211], v[210:211], v[206:207] op_sel_hi:[0,1,1] neg_lo:[0,0,1]
	v_pk_mul_f32 v[206:207], v[210:211], v[212:213] op_sel:[1,1] op_sel_hi:[1,0]
	v_pk_fma_f32 v[220:221], v[210:211], v[212:213], v[206:207] op_sel_hi:[0,1,1] neg_lo:[0,0,1]
	v_pk_mul_f32 v[58:59], v[210:211], v[202:203] op_sel:[1,1] op_sel_hi:[1,0]
	v_pk_fma_f32 v[58:59], v[210:211], v[202:203], v[58:59] op_sel_hi:[0,1,1] neg_lo:[0,0,1]
	v_pk_mul_f32 v[60:61], v[212:213], v[64:65] op_sel:[1,1] op_sel_hi:[1,0]
	v_pk_fma_f32 v[60:61], v[212:213], v[64:65], v[60:61] op_sel_hi:[0,1,1] neg_lo:[0,0,1]
	v_pk_mul_f32 v[64:65], v[220:221], v[204:205] op_sel:[1,1] op_sel_hi:[1,0]
	v_pk_fma_f32 v[64:65], v[220:221], v[204:205], v[64:65] op_sel_hi:[0,1,1] neg_lo:[0,0,1]
	s_barrier
	v_mul_f32_e32 v214, 4.0, v201
	v_cos_f32_e32 v224, v214
	v_sin_f32_e64 v225, -v214
	s_nop 0
	v_pk_mul_f32 v[206:207], v[224:225], v[224:225] op_sel:[1,1] op_sel_hi:[1,0]
	v_pk_fma_f32 v[226:227], v[224:225], v[224:225], v[206:207] op_sel_hi:[0,1,1] neg_lo:[0,0,1]
	v_pk_mul_f32 v[206:207], v[224:225], v[226:227] op_sel:[1,1] op_sel_hi:[1,0]
	v_pk_fma_f32 v[230:231], v[224:225], v[226:227], v[206:207] op_sel_hi:[0,1,1] neg_lo:[0,0,1]
	v_pk_add_f32 v[202:203], v[6:7], v[38:39]
	v_pk_add_f32 v[6:7], v[6:7], v[38:39] neg_lo:[0,1] neg_hi:[0,1]
	v_pk_add_f32 v[204:205], v[22:23], v[54:55]
	v_pk_add_f32 v[22:23], v[22:23], v[54:55] neg_lo:[0,1] neg_hi:[0,1]
	v_pk_add_f32 v[38:39], v[202:203], v[204:205]
	v_pk_add_f32 v[54:55], v[202:203], v[204:205] neg_lo:[0,1] neg_hi:[0,1]
	v_pk_add_f32 v[202:203], v[6:7], v[22:23] op_sel:[0,1] op_sel_hi:[1,0] neg_hi:[0,1]
	v_pk_add_f32 v[204:205], v[6:7], v[22:23] op_sel:[0,1] op_sel_hi:[1,0] neg_lo:[0,1]
	v_pk_mul_f32 v[6:7], v[224:225], v[202:203] op_sel:[1,1] op_sel_hi:[1,0]
	v_pk_fma_f32 v[6:7], v[224:225], v[202:203], v[6:7] op_sel_hi:[0,1,1] neg_lo:[0,0,1]
	v_pk_mul_f32 v[22:23], v[226:227], v[54:55] op_sel:[1,1] op_sel_hi:[1,0]
	v_pk_fma_f32 v[22:23], v[226:227], v[54:55], v[22:23] op_sel_hi:[0,1,1] neg_lo:[0,0,1]
	v_pk_mul_f32 v[54:55], v[230:231], v[204:205] op_sel:[1,1] op_sel_hi:[1,0]
	v_pk_fma_f32 v[54:55], v[230:231], v[204:205], v[54:55] op_sel_hi:[0,1,1] neg_lo:[0,0,1]
	v_pk_add_f32 v[202:203], v[2:3], v[34:35]
	v_pk_add_f32 v[2:3], v[2:3], v[34:35] neg_lo:[0,1] neg_hi:[0,1]
	v_pk_add_f32 v[204:205], v[18:19], v[50:51]
	v_pk_add_f32 v[18:19], v[18:19], v[50:51] neg_lo:[0,1] neg_hi:[0,1]
	v_pk_add_f32 v[34:35], v[202:203], v[204:205]
	v_pk_add_f32 v[50:51], v[202:203], v[204:205] neg_lo:[0,1] neg_hi:[0,1]
	v_pk_add_f32 v[202:203], v[2:3], v[18:19] op_sel:[0,1] op_sel_hi:[1,0] neg_hi:[0,1]
	v_pk_add_f32 v[204:205], v[2:3], v[18:19] op_sel:[0,1] op_sel_hi:[1,0] neg_lo:[0,1]
	v_pk_mul_f32 v[2:3], v[224:225], v[202:203] op_sel:[1,1] op_sel_hi:[1,0]
	v_pk_fma_f32 v[2:3], v[224:225], v[202:203], v[2:3] op_sel_hi:[0,1,1] neg_lo:[0,0,1]
	v_pk_mul_f32 v[18:19], v[226:227], v[50:51] op_sel:[1,1] op_sel_hi:[1,0]
	v_pk_fma_f32 v[18:19], v[226:227], v[50:51], v[18:19] op_sel_hi:[0,1,1] neg_lo:[0,0,1]
	v_pk_mul_f32 v[50:51], v[230:231], v[204:205] op_sel:[1,1] op_sel_hi:[1,0]
	v_pk_fma_f32 v[50:51], v[230:231], v[204:205], v[50:51] op_sel_hi:[0,1,1] neg_lo:[0,0,1]
	v_pk_add_f32 v[202:203], v[4:5], v[36:37]
	v_pk_add_f32 v[4:5], v[4:5], v[36:37] neg_lo:[0,1] neg_hi:[0,1]
	v_pk_add_f32 v[204:205], v[20:21], v[52:53]
	v_pk_add_f32 v[20:21], v[20:21], v[52:53] neg_lo:[0,1] neg_hi:[0,1]
	v_pk_add_f32 v[36:37], v[202:203], v[204:205]
	v_pk_add_f32 v[52:53], v[202:203], v[204:205] neg_lo:[0,1] neg_hi:[0,1]
	v_pk_add_f32 v[202:203], v[4:5], v[20:21] op_sel:[0,1] op_sel_hi:[1,0] neg_hi:[0,1]
	v_pk_add_f32 v[204:205], v[4:5], v[20:21] op_sel:[0,1] op_sel_hi:[1,0] neg_lo:[0,1]
	v_pk_mul_f32 v[4:5], v[224:225], v[202:203] op_sel:[1,1] op_sel_hi:[1,0]
	v_pk_fma_f32 v[4:5], v[224:225], v[202:203], v[4:5] op_sel_hi:[0,1,1] neg_lo:[0,0,1]
	v_pk_mul_f32 v[20:21], v[226:227], v[52:53] op_sel:[1,1] op_sel_hi:[1,0]
	v_pk_fma_f32 v[20:21], v[226:227], v[52:53], v[20:21] op_sel_hi:[0,1,1] neg_lo:[0,0,1]
	v_pk_mul_f32 v[52:53], v[230:231], v[204:205] op_sel:[1,1] op_sel_hi:[1,0]
	v_pk_fma_f32 v[52:53], v[230:231], v[204:205], v[52:53] op_sel_hi:[0,1,1] neg_lo:[0,0,1]
	v_pk_add_f32 v[202:203], v[8:9], v[40:41]
	v_pk_add_f32 v[8:9], v[8:9], v[40:41] neg_lo:[0,1] neg_hi:[0,1]
	v_pk_add_f32 v[204:205], v[24:25], v[56:57]
	v_pk_add_f32 v[24:25], v[24:25], v[56:57] neg_lo:[0,1] neg_hi:[0,1]
	v_pk_add_f32 v[40:41], v[202:203], v[204:205]
	v_pk_add_f32 v[56:57], v[202:203], v[204:205] neg_lo:[0,1] neg_hi:[0,1]
	v_pk_add_f32 v[202:203], v[8:9], v[24:25] op_sel:[0,1] op_sel_hi:[1,0] neg_hi:[0,1]
	v_pk_add_f32 v[204:205], v[8:9], v[24:25] op_sel:[0,1] op_sel_hi:[1,0] neg_lo:[0,1]
	v_pk_mul_f32 v[8:9], v[224:225], v[202:203] op_sel:[1,1] op_sel_hi:[1,0]
	v_pk_fma_f32 v[8:9], v[224:225], v[202:203], v[8:9] op_sel_hi:[0,1,1] neg_lo:[0,0,1]
	v_pk_mul_f32 v[24:25], v[226:227], v[56:57] op_sel:[1,1] op_sel_hi:[1,0]
	v_pk_fma_f32 v[24:25], v[226:227], v[56:57], v[24:25] op_sel_hi:[0,1,1] neg_lo:[0,0,1]
; DI f32x2 cmul(f32x2 a, f32x2 b) { return mkf2(a.x * b.x - a.y * b.y, a.x * b.y + a.y * b.x); }
; DI void fft8192(f32x2* buf, const f32x2* __restrict__ tw) {
;     ...
; #pragma unroll
;     for (int e = 0; e < 8; ++e) {
;       const int i = tid + 256 * e;
;       const int q = i & (s - 1);
;       const int ps = i - q;
;       const float rev = (float)ps * (1.f / 8192.f);
;       const f32x2 w1 = mkf2(__builtin_amdgcn_cosf(rev), -__builtin_amdgcn_sinf(rev));
;       const f32x2 w2 = cmul(w1, w1), w3 = cmul(w1, w2);
;       const f32x2 apc = mkf2(a[e].x + c[e].x, a[e].y + c[e].y), amc = mkf2(a[e].x - c[e].x, a[e].y - c[e].y);
;       const f32x2 bpd = mkf2(b[e].x + d[e].x, b[e].y + d[e].y), bmd = mkf2(b[e].x - d[e].x, b[e].y - d[e].y);
;       const int o = 4 * i - 3 * q;
;       buf[SW(o)] = mkf2(apc.x + bpd.x, apc.y + bpd.y);
;       buf[SW(o + s)] = cmul(w1, mkf2(amc.x + bmd.y, amc.y - bmd.x));
;       buf[SW(o + 2 * s)] = cmul(w2, mkf2(apc.x - bpd.x, apc.y - bpd.y));
;       buf[SW(o + 3 * s)] = cmul(w3, mkf2(amc.x - bmd.y, amc.y + bmd.x));
;     }
	v_pk_mul_f32 v[56:57], v[230:231], v[204:205] op_sel:[1,1] op_sel_hi:[1,0]
	v_pk_fma_f32 v[56:57], v[230:231], v[204:205], v[56:57] op_sel_hi:[0,1,1] neg_lo:[0,0,1]
	v_mul_f32_e32 v214, 4.0, v201
	v_add_f32_e32 v214, 0x3e000000, v214
	v_cos_f32_e32 v224, v214
	v_sin_f32_e64 v225, -v214
	s_nop 0
	v_pk_mul_f32 v[206:207], v[224:225], v[224:225] op_sel:[1,1] op_sel_hi:[1,0]
	v_pk_fma_f32 v[226:227], v[224:225], v[224:225], v[206:207] op_sel_hi:[0,1,1] neg_lo:[0,0,1]
	v_pk_mul_f32 v[206:207], v[224:225], v[226:227] op_sel:[1,1] op_sel_hi:[1,0]
	v_pk_fma_f32 v[230:231], v[224:225], v[226:227], v[206:207] op_sel_hi:[0,1,1] neg_lo:[0,0,1]
	v_pk_add_f32 v[202:203], v[14:15], v[46:47]
	v_pk_add_f32 v[14:15], v[14:15], v[46:47] neg_lo:[0,1] neg_hi:[0,1]
	v_pk_add_f32 v[204:205], v[30:31], v[62:63]
	v_pk_add_f32 v[30:31], v[30:31], v[62:63] neg_lo:[0,1] neg_hi:[0,1]
	v_pk_add_f32 v[46:47], v[202:203], v[204:205]
	v_pk_add_f32 v[62:63], v[202:203], v[204:205] neg_lo:[0,1] neg_hi:[0,1]
	v_pk_add_f32 v[202:203], v[14:15], v[30:31] op_sel:[0,1] op_sel_hi:[1,0] neg_hi:[0,1]
	v_pk_add_f32 v[204:205], v[14:15], v[30:31] op_sel:[0,1] op_sel_hi:[1,0] neg_lo:[0,1]
	v_pk_mul_f32 v[14:15], v[224:225], v[202:203] op_sel:[1,1] op_sel_hi:[1,0]
	v_pk_fma_f32 v[14:15], v[224:225], v[202:203], v[14:15] op_sel_hi:[0,1,1] neg_lo:[0,0,1]
	v_pk_mul_f32 v[30:31], v[226:227], v[62:63] op_sel:[1,1] op_sel_hi:[1,0]
	v_pk_fma_f32 v[30:31], v[226:227], v[62:63], v[30:31] op_sel_hi:[0,1,1] neg_lo:[0,0,1]
	v_pk_mul_f32 v[62:63], v[230:231], v[204:205] op_sel:[1,1] op_sel_hi:[1,0]
	v_pk_fma_f32 v[62:63], v[230:231], v[204:205], v[62:63] op_sel_hi:[0,1,1] neg_lo:[0,0,1]
	v_pk_add_f32 v[202:203], v[10:11], v[42:43]
	v_pk_add_f32 v[10:11], v[10:11], v[42:43] neg_lo:[0,1] neg_hi:[0,1]
	v_pk_add_f32 v[204:205], v[26:27], v[58:59]
	v_pk_add_f32 v[26:27], v[26:27], v[58:59] neg_lo:[0,1] neg_hi:[0,1]
	v_pk_add_f32 v[42:43], v[202:203], v[204:205]
	v_pk_add_f32 v[58:59], v[202:203], v[204:205] neg_lo:[0,1] neg_hi:[0,1]
	v_pk_add_f32 v[202:203], v[10:11], v[26:27] op_sel:[0,1] op_sel_hi:[1,0] neg_hi:[0,1]
	v_pk_add_f32 v[204:205], v[10:11], v[26:27] op_sel:[0,1] op_sel_hi:[1,0] neg_lo:[0,1]
	v_pk_mul_f32 v[10:11], v[224:225], v[202:203] op_sel:[1,1] op_sel_hi:[1,0]
	v_pk_fma_f32 v[10:11], v[224:225], v[202:203], v[10:11] op_sel_hi:[0,1,1] neg_lo:[0,0,1]
	v_pk_mul_f32 v[26:27], v[226:227], v[58:59] op_sel:[1,1] op_sel_hi:[1,0]
	v_pk_fma_f32 v[26:27], v[226:227], v[58:59], v[26:27] op_sel_hi:[0,1,1] neg_lo:[0,0,1]
	v_pk_mul_f32 v[58:59], v[230:231], v[204:205] op_sel:[1,1] op_sel_hi:[1,0]
	v_pk_fma_f32 v[58:59], v[230:231], v[204:205], v[58:59] op_sel_hi:[0,1,1] neg_lo:[0,0,1]
	v_pk_add_f32 v[202:203], v[12:13], v[44:45]
	v_pk_add_f32 v[12:13], v[12:13], v[44:45] neg_lo:[0,1] neg_hi:[0,1]
	v_pk_add_f32 v[204:205], v[28:29], v[60:61]
	v_pk_add_f32 v[28:29], v[28:29], v[60:61] neg_lo:[0,1] neg_hi:[0,1]
	v_pk_add_f32 v[44:45], v[202:203], v[204:205]
	v_pk_add_f32 v[60:61], v[202:203], v[204:205] neg_lo:[0,1] neg_hi:[0,1]
	v_pk_add_f32 v[202:203], v[12:13], v[28:29] op_sel:[0,1] op_sel_hi:[1,0] neg_hi:[0,1]
	v_pk_add_f32 v[204:205], v[12:13], v[28:29] op_sel:[0,1] op_sel_hi:[1,0] neg_lo:[0,1]
	v_pk_mul_f32 v[12:13], v[224:225], v[202:203] op_sel:[1,1] op_sel_hi:[1,0]
	v_pk_fma_f32 v[12:13], v[224:225], v[202:203], v[12:13] op_sel_hi:[0,1,1] neg_lo:[0,0,1]
	v_pk_mul_f32 v[28:29], v[226:227], v[60:61] op_sel:[1,1] op_sel_hi:[1,0]
	v_pk_fma_f32 v[28:29], v[226:227], v[60:61], v[28:29] op_sel_hi:[0,1,1] neg_lo:[0,0,1]
	v_pk_mul_f32 v[60:61], v[230:231], v[204:205] op_sel:[1,1] op_sel_hi:[1,0]
	v_pk_fma_f32 v[60:61], v[230:231], v[204:205], v[60:61] op_sel_hi:[0,1,1] neg_lo:[0,0,1]
	v_pk_add_f32 v[202:203], v[16:17], v[48:49]
	v_pk_add_f32 v[16:17], v[16:17], v[48:49] neg_lo:[0,1] neg_hi:[0,1]
	v_pk_add_f32 v[204:205], v[32:33], v[64:65]
	v_pk_add_f32 v[32:33], v[32:33], v[64:65] neg_lo:[0,1] neg_hi:[0,1]
	v_pk_add_f32 v[48:49], v[202:203], v[204:205]
	v_pk_add_f32 v[64:65], v[202:203], v[204:205] neg_lo:[0,1] neg_hi:[0,1]
	v_pk_add_f32 v[202:203], v[16:17], v[32:33] op_sel:[0,1] op_sel_hi:[1,0] neg_hi:[0,1]
	v_pk_add_f32 v[204:205], v[16:17], v[32:33] op_sel:[0,1] op_sel_hi:[1,0] neg_lo:[0,1]
	v_pk_mul_f32 v[16:17], v[224:225], v[202:203] op_sel:[1,1] op_sel_hi:[1,0]
	v_pk_fma_f32 v[16:17], v[224:225], v[202:203], v[16:17] op_sel_hi:[0,1,1] neg_lo:[0,0,1]
	v_pk_mul_f32 v[32:33], v[226:227], v[64:65] op_sel:[1,1] op_sel_hi:[1,0]
	v_pk_fma_f32 v[32:33], v[226:227], v[64:65], v[32:33] op_sel_hi:[0,1,1] neg_lo:[0,0,1]
	v_pk_mul_f32 v[64:65], v[230:231], v[204:205] op_sel:[1,1] op_sel_hi:[1,0]
	v_pk_fma_f32 v[64:65], v[230:231], v[204:205], v[64:65] op_sel_hi:[0,1,1] neg_lo:[0,0,1]
	ds_write_b64 v164, v[38:39] offset:0
	v_xor_b32_e32 v156, 8, v164
	ds_write_b64 v156, v[34:35] offset:0
	v_xor_b32_e32 v158, 16, v164
	ds_write_b64 v158, v[36:37] offset:0
	v_xor_b32_e32 v160, 24, v164
	ds_write_b64 v160, v[40:41] offset:0
	v_xor_b32_e32 v162, 32, v164
	ds_write_b64 v162, v[6:7] offset:0
	v_xor_b32_e32 v156, 40, v164
	ds_write_b64 v156, v[2:3] offset:0
	v_xor_b32_e32 v158, 48, v164
	ds_write_b64 v158, v[4:5] offset:0
	v_xor_b32_e32 v160, 56, v164
	ds_write_b64 v160, v[8:9] offset:0
	v_xor_b32_e32 v162, 64, v164
	ds_write_b64 v162, v[22:23] offset:0
	v_xor_b32_e32 v156, 0x48, v164
	ds_write_b64 v156, v[18:19] offset:0
	v_xor_b32_e32 v158, 0x50, v164
	ds_write_b64 v158, v[20:21] offset:0
	v_xor_b32_e32 v160, 0x58, v164
	ds_write_b64 v160, v[24:25] offset:0
	v_xor_b32_e32 v162, 0x60, v164
	ds_write_b64 v162, v[54:55] offset:0
	v_xor_b32_e32 v156, 0x68, v164
	ds_write_b64 v156, v[50:51] offset:0
	v_xor_b32_e32 v158, 0x70, v164
	ds_write_b64 v158, v[52:53] offset:0
	v_xor_b32_e32 v160, 0x78, v164
	ds_write_b64 v160, v[56:57] offset:0
	ds_write_b64 v164, v[46:47] offset:32768
	v_xor_b32_e32 v162, 8, v164
	ds_write_b64 v162, v[42:43] offset:32768
	v_xor_b32_e32 v156, 16, v164
	ds_write_b64 v156, v[44:45] offset:32768
	v_xor_b32_e32 v158, 24, v164
	ds_write_b64 v158, v[48:49] offset:32768
	v_xor_b32_e32 v160, 32, v164
	ds_write_b64 v160, v[14:15] offset:32768
	v_xor_b32_e32 v162, 40, v164
	ds_write_b64 v162, v[10:11] offset:32768
	v_xor_b32_e32 v156, 48, v164
	ds_write_b64 v156, v[12:13] offset:32768
	v_xor_b32_e32 v158, 56, v164
	ds_write_b64 v158, v[16:17] offset:32768
	v_xor_b32_e32 v160, 64, v164
	ds_write_b64 v160, v[30:31] offset:32768
	v_xor_b32_e32 v162, 0x48, v164
	ds_write_b64 v162, v[26:27] offset:32768
	v_xor_b32_e32 v156, 0x50, v164
	ds_write_b64 v156, v[28:29] offset:32768
	v_xor_b32_e32 v158, 0x58, v164
	ds_write_b64 v158, v[32:33] offset:32768
	v_xor_b32_e32 v160, 0x60, v164
	ds_write_b64 v160, v[62:63] offset:32768
	v_xor_b32_e32 v162, 0x68, v164
	ds_write_b64 v162, v[58:59] offset:32768
	v_xor_b32_e32 v156, 0x70, v164
	ds_write_b64 v156, v[60:61] offset:32768
	v_xor_b32_e32 v158, 0x78, v164
	ds_write_b64 v158, v[64:65] offset:32768
	s_waitcnt lgkmcnt(0)
	s_barrier
; DI f32x2 cmul(f32x2 a, f32x2 b) { return mkf2(a.x * b.x - a.y * b.y, a.x * b.y + a.y * b.x); }
; DI void fft8192(f32x2* buf, const f32x2* __restrict__ tw) {
;     ...
;     __syncthreads();
; #pragma unroll
;     for (int e = 0; e < 8; ++e) {
;       const int i = tid + 256 * e;
;       const int pi = SW(i);
;       a[e] = buf[pi]; b[e] = buf[pi + 2048]; c[e] = buf[pi + 4096]; d[e] = buf[pi + 6144];
;     }
;     __syncthreads();
; #pragma unroll
;     for (int e = 0; e < 8; ++e) {
;       const int i = tid + 256 * e;
;       const int q = i & (s - 1);
;       const int ps = i - q;
;       const float rev = (float)ps * (1.f / 8192.f);
;       const f32x2 w1 = mkf2(__builtin_amdgcn_cosf(rev), -__builtin_amdgcn_sinf(rev));
;       const f32x2 w2 = cmul(w1, w1), w3 = cmul(w1, w2);
;       const f32x2 apc = mkf2(a[e].x + c[e].x, a[e].y + c[e].y), amc = mkf2(a[e].x - c[e].x, a[e].y - c[e].y);
;       const f32x2 bpd = mkf2(b[e].x + d[e].x, b[e].y + d[e].y), bmd = mkf2(b[e].x - d[e].x, b[e].y - d[e].y);
;       const int o = 4 * i - 3 * q;
;       buf[SW(o)] = mkf2(apc.x + bpd.x, apc.y + bpd.y);
;       buf[SW(o + s)] = cmul(w1, mkf2(amc.x + bmd.y, amc.y - bmd.x));
;       buf[SW(o + 2 * s)] = cmul(w2, mkf2(apc.x - bpd.x, apc.y - bpd.y));
;       buf[SW(o + 3 * s)] = cmul(w3, mkf2(amc.x - bmd.y, amc.y + bmd.x));
;     }
	ds_read2st64_b64 v[2:5], v154 offset0:0 offset1:32
	ds_read2st64_b64 v[6:9], v154 offset0:64 offset1:96
	ds_read2st64_b64 v[10:13], v154 offset0:4 offset1:36
	ds_read2st64_b64 v[14:17], v154 offset0:68 offset1:100
	ds_read2st64_b64 v[18:21], v154 offset0:8 offset1:40
	ds_read2st64_b64 v[22:25], v154 offset0:72 offset1:104
	ds_read2st64_b64 v[26:29], v154 offset0:12 offset1:44
	ds_read2st64_b64 v[30:33], v154 offset0:76 offset1:108
	ds_read2st64_b64 v[34:37], v154 offset0:16 offset1:48
	ds_read2st64_b64 v[38:41], v154 offset0:80 offset1:112
	ds_read2st64_b64 v[42:45], v154 offset0:20 offset1:52
	ds_read2st64_b64 v[46:49], v154 offset0:84 offset1:116
	ds_read2st64_b64 v[50:53], v154 offset0:24 offset1:56
	ds_read2st64_b64 v[54:57], v154 offset0:88 offset1:120
	ds_read2st64_b64 v[58:61], v154 offset0:28 offset1:60
	ds_read2st64_b64 v[62:65], v154 offset0:92 offset1:124
	v_and_b32_e32 v166, 15, v0
	v_sub_u32_e32 v168, v0, v166
	v_cvt_f32_u32_e32 v201, v168
	v_lshl_add_u32 v164, v168, 4, v166
	v_lshlrev_b32_e32 v164, 3, v164
	v_mul_f32_e32 v201, 0x39000000, v201
	v_cos_f32_e32 v210, v201
	v_sin_f32_e64 v211, -v201
	s_waitcnt lgkmcnt(14)
	v_pk_add_f32 v[202:203], v[2:3], v[6:7]
	v_pk_add_f32 v[2:3], v[2:3], v[6:7] neg_lo:[0,1] neg_hi:[0,1]
	v_pk_add_f32 v[204:205], v[4:5], v[8:9]
	v_pk_add_f32 v[4:5], v[4:5], v[8:9] neg_lo:[0,1] neg_hi:[0,1]
	v_pk_add_f32 v[6:7], v[202:203], v[204:205]
	v_pk_add_f32 v[8:9], v[202:203], v[204:205] neg_lo:[0,1] neg_hi:[0,1]
	v_pk_add_f32 v[202:203], v[2:3], v[4:5] op_sel:[0,1] op_sel_hi:[1,0] neg_hi:[0,1]
	v_pk_add_f32 v[204:205], v[2:3], v[4:5] op_sel:[0,1] op_sel_hi:[1,0] neg_lo:[0,1]
	v_pk_mul_f32 v[206:207], v[210:211], v[210:211] op_sel:[1,1] op_sel_hi:[1,0]
	v_pk_fma_f32 v[212:213], v[210:211], v[210:211], v[206:207] op_sel_hi:[0,1,1] neg_lo:[0,0,1]
	v_pk_mul_f32 v[206:207], v[210:211], v[212:213] op_sel:[1,1] op_sel_hi:[1,0]
	v_pk_fma_f32 v[220:221], v[210:211], v[212:213], v[206:207] op_sel_hi:[0,1,1] neg_lo:[0,0,1]
	v_pk_mul_f32 v[2:3], v[210:211], v[202:203] op_sel:[1,1] op_sel_hi:[1,0]
	v_pk_fma_f32 v[2:3], v[210:211], v[202:203], v[2:3] op_sel_hi:[0,1,1] neg_lo:[0,0,1]
	v_pk_mul_f32 v[4:5], v[212:213], v[8:9] op_sel:[1,1] op_sel_hi:[1,0]
	v_pk_fma_f32 v[4:5], v[212:213], v[8:9], v[4:5] op_sel_hi:[0,1,1] neg_lo:[0,0,1]
	v_pk_mul_f32 v[8:9], v[220:221], v[204:205] op_sel:[1,1] op_sel_hi:[1,0]
	v_pk_fma_f32 v[8:9], v[220:221], v[204:205], v[8:9] op_sel_hi:[0,1,1] neg_lo:[0,0,1]
	v_add_f32_e32 v214, 0x3d000000, v201
	v_cos_f32_e32 v210, v214
	v_sin_f32_e64 v211, -v214
	s_waitcnt lgkmcnt(12)
	v_pk_add_f32 v[202:203], v[10:11], v[14:15]
	v_pk_add_f32 v[10:11], v[10:11], v[14:15] neg_lo:[0,1] neg_hi:[0,1]
	v_pk_add_f32 v[204:205], v[12:13], v[16:17]
	v_pk_add_f32 v[12:13], v[12:13], v[16:17] neg_lo:[0,1] neg_hi:[0,1]
	v_pk_add_f32 v[14:15], v[202:203], v[204:205]
	v_pk_add_f32 v[16:17], v[202:203], v[204:205] neg_lo:[0,1] neg_hi:[0,1]
	v_pk_add_f32 v[202:203], v[10:11], v[12:13] op_sel:[0,1] op_sel_hi:[1,0] neg_hi:[0,1]
	v_pk_add_f32 v[204:205], v[10:11], v[12:13] op_sel:[0,1] op_sel_hi:[1,0] neg_lo:[0,1]
	v_pk_mul_f32 v[206:207], v[210:211], v[210:211] op_sel:[1,1] op_sel_hi:[1,0]
	v_pk_fma_f32 v[212:213], v[210:211], v[210:211], v[206:207] op_sel_hi:[0,1,1] neg_lo:[0,0,1]
	v_pk_mul_f32 v[206:207], v[210:211], v[212:213] op_sel:[1,1] op_sel_hi:[1,0]
	v_pk_fma_f32 v[220:221], v[210:211], v[212:213], v[206:207] op_sel_hi:[0,1,1] neg_lo:[0,0,1]
	v_pk_mul_f32 v[10:11], v[210:211], v[202:203] op_sel:[1,1] op_sel_hi:[1,0]
	v_pk_fma_f32 v[10:11], v[210:211], v[202:203], v[10:11] op_sel_hi:[0,1,1] neg_lo:[0,0,1]
	v_pk_mul_f32 v[12:13], v[212:213], v[16:17] op_sel:[1,1] op_sel_hi:[1,0]
	v_pk_fma_f32 v[12:13], v[212:213], v[16:17], v[12:13] op_sel_hi:[0,1,1] neg_lo:[0,0,1]
	v_pk_mul_f32 v[16:17], v[220:221], v[204:205] op_sel:[1,1] op_sel_hi:[1,0]
	v_pk_fma_f32 v[16:17], v[220:221], v[204:205], v[16:17] op_sel_hi:[0,1,1] neg_lo:[0,0,1]
	v_add_f32_e32 v214, 0x3d800000, v201
	v_cos_f32_e32 v210, v214
	v_sin_f32_e64 v211, -v214
	s_waitcnt lgkmcnt(10)
	v_pk_add_f32 v[202:203], v[18:19], v[22:23]
	v_pk_add_f32 v[18:19], v[18:19], v[22:23] neg_lo:[0,1] neg_hi:[0,1]
	v_pk_add_f32 v[204:205], v[20:21], v[24:25]
	v_pk_add_f32 v[20:21], v[20:21], v[24:25] neg_lo:[0,1] neg_hi:[0,1]
	v_pk_add_f32 v[22:23], v[202:203], v[204:205]
	v_pk_add_f32 v[24:25], v[202:203], v[204:205] neg_lo:[0,1] neg_hi:[0,1]
	v_pk_add_f32 v[202:203], v[18:19], v[20:21] op_sel:[0,1] op_sel_hi:[1,0] neg_hi:[0,1]
	v_pk_add_f32 v[204:205], v[18:19], v[20:21] op_sel:[0,1] op_sel_hi:[1,0] neg_lo:[0,1]
	v_pk_mul_f32 v[206:207], v[210:211], v[210:211] op_sel:[1,1] op_sel_hi:[1,0]
	v_pk_fma_f32 v[212:213], v[210:211], v[210:211], v[206:207] op_sel_hi:[0,1,1] neg_lo:[0,0,1]
	v_pk_mul_f32 v[206:207], v[210:211], v[212:213] op_sel:[1,1] op_sel_hi:[1,0]
	v_pk_fma_f32 v[220:221], v[210:211], v[212:213], v[206:207] op_sel_hi:[0,1,1] neg_lo:[0,0,1]
	v_pk_mul_f32 v[18:19], v[210:211], v[202:203] op_sel:[1,1] op_sel_hi:[1,0]
	v_pk_fma_f32 v[18:19], v[210:211], v[202:203], v[18:19] op_sel_hi:[0,1,1] neg_lo:[0,0,1]
	v_pk_mul_f32 v[20:21], v[212:213], v[24:25] op_sel:[1,1] op_sel_hi:[1,0]
	v_pk_fma_f32 v[20:21], v[212:213], v[24:25], v[20:21] op_sel_hi:[0,1,1] neg_lo:[0,0,1]
	v_pk_mul_f32 v[24:25], v[220:221], v[204:205] op_sel:[1,1] op_sel_hi:[1,0]
	v_pk_fma_f32 v[24:25], v[220:221], v[204:205], v[24:25] op_sel_hi:[0,1,1] neg_lo:[0,0,1]
	v_add_f32_e32 v214, 0x3dc00000, v201
	v_cos_f32_e32 v210, v214
	v_sin_f32_e64 v211, -v214
	s_waitcnt lgkmcnt(8)
; DI f32x2 cmul(f32x2 a, f32x2 b) { return mkf2(a.x * b.x - a.y * b.y, a.x * b.y + a.y * b.x); }
; DI void fft8192(f32x2* buf, const f32x2* __restrict__ tw) {
;     ...
; #pragma unroll
;     for (int e = 0; e < 8; ++e) {
;       const int i = tid + 256 * e;
;       const int q = i & (s - 1);
;       const int ps = i - q;
;       const float rev = (float)ps * (1.f / 8192.f);
;       const f32x2 w1 = mkf2(__builtin_amdgcn_cosf(rev), -__builtin_amdgcn_sinf(rev));
;       const f32x2 w2 = cmul(w1, w1), w3 = cmul(w1, w2);
;       const f32x2 apc = mkf2(a[e].x + c[e].x, a[e].y + c[e].y), amc = mkf2(a[e].x - c[e].x, a[e].y - c[e].y);
;       const f32x2 bpd = mkf2(b[e].x + d[e].x, b[e].y + d[e].y), bmd = mkf2(b[e].x - d[e].x, b[e].y - d[e].y);
;       const int o = 4 * i - 3 * q;
;       buf[SW(o)] = mkf2(apc.x + bpd.x, apc.y + bpd.y);
;       buf[SW(o + s)] = cmul(w1, mkf2(amc.x + bmd.y, amc.y - bmd.x));
;       buf[SW(o + 2 * s)] = cmul(w2, mkf2(apc.x - bpd.x, apc.y - bpd.y));
;       buf[SW(o + 3 * s)] = cmul(w3, mkf2(amc.x - bmd.y, amc.y + bmd.x));
;     }
	v_pk_add_f32 v[202:203], v[26:27], v[30:31]
	v_pk_add_f32 v[26:27], v[26:27], v[30:31] neg_lo:[0,1] neg_hi:[0,1]
	v_pk_add_f32 v[204:205], v[28:29], v[32:33]
	v_pk_add_f32 v[28:29], v[28:29], v[32:33] neg_lo:[0,1] neg_hi:[0,1]
	v_pk_add_f32 v[30:31], v[202:203], v[204:205]
	v_pk_add_f32 v[32:33], v[202:203], v[204:205] neg_lo:[0,1] neg_hi:[0,1]
	v_pk_add_f32 v[202:203], v[26:27], v[28:29] op_sel:[0,1] op_sel_hi:[1,0] neg_hi:[0,1]
	v_pk_add_f32 v[204:205], v[26:27], v[28:29] op_sel:[0,1] op_sel_hi:[1,0] neg_lo:[0,1]
	v_pk_mul_f32 v[206:207], v[210:211], v[210:211] op_sel:[1,1] op_sel_hi:[1,0]
	v_pk_fma_f32 v[212:213], v[210:211], v[210:211], v[206:207] op_sel_hi:[0,1,1] neg_lo:[0,0,1]
	v_pk_mul_f32 v[206:207], v[210:211], v[212:213] op_sel:[1,1] op_sel_hi:[1,0]
	v_pk_fma_f32 v[220:221], v[210:211], v[212:213], v[206:207] op_sel_hi:[0,1,1] neg_lo:[0,0,1]
	v_pk_mul_f32 v[26:27], v[210:211], v[202:203] op_sel:[1,1] op_sel_hi:[1,0]
	v_pk_fma_f32 v[26:27], v[210:211], v[202:203], v[26:27] op_sel_hi:[0,1,1] neg_lo:[0,0,1]
	v_pk_mul_f32 v[28:29], v[212:213], v[32:33] op_sel:[1,1] op_sel_hi:[1,0]
	v_pk_fma_f32 v[28:29], v[212:213], v[32:33], v[28:29] op_sel_hi:[0,1,1] neg_lo:[0,0,1]
	v_pk_mul_f32 v[32:33], v[220:221], v[204:205] op_sel:[1,1] op_sel_hi:[1,0]
	v_pk_fma_f32 v[32:33], v[220:221], v[204:205], v[32:33] op_sel_hi:[0,1,1] neg_lo:[0,0,1]
	v_add_f32_e32 v214, 0x3e000000, v201
	v_cos_f32_e32 v210, v214
	v_sin_f32_e64 v211, -v214
	s_waitcnt lgkmcnt(6)
	v_pk_add_f32 v[202:203], v[34:35], v[38:39]
	v_pk_add_f32 v[34:35], v[34:35], v[38:39] neg_lo:[0,1] neg_hi:[0,1]
	v_pk_add_f32 v[204:205], v[36:37], v[40:41]
	v_pk_add_f32 v[36:37], v[36:37], v[40:41] neg_lo:[0,1] neg_hi:[0,1]
	v_pk_add_f32 v[38:39], v[202:203], v[204:205]
	v_pk_add_f32 v[40:41], v[202:203], v[204:205] neg_lo:[0,1] neg_hi:[0,1]
	v_pk_add_f32 v[202:203], v[34:35], v[36:37] op_sel:[0,1] op_sel_hi:[1,0] neg_hi:[0,1]
	v_pk_add_f32 v[204:205], v[34:35], v[36:37] op_sel:[0,1] op_sel_hi:[1,0] neg_lo:[0,1]
	v_pk_mul_f32 v[206:207], v[210:211], v[210:211] op_sel:[1,1] op_sel_hi:[1,0]
	v_pk_fma_f32 v[212:213], v[210:211], v[210:211], v[206:207] op_sel_hi:[0,1,1] neg_lo:[0,0,1]
	v_pk_mul_f32 v[206:207], v[210:211], v[212:213] op_sel:[1,1] op_sel_hi:[1,0]
	v_pk_fma_f32 v[220:221], v[210:211], v[212:213], v[206:207] op_sel_hi:[0,1,1] neg_lo:[0,0,1]
	v_pk_mul_f32 v[34:35], v[210:211], v[202:203] op_sel:[1,1] op_sel_hi:[1,0]
	v_pk_fma_f32 v[34:35], v[210:211], v[202:203], v[34:35] op_sel_hi:[0,1,1] neg_lo:[0,0,1]
	v_pk_mul_f32 v[36:37], v[212:213], v[40:41] op_sel:[1,1] op_sel_hi:[1,0]
	v_pk_fma_f32 v[36:37], v[212:213], v[40:41], v[36:37] op_sel_hi:[0,1,1] neg_lo:[0,0,1]
	v_pk_mul_f32 v[40:41], v[220:221], v[204:205] op_sel:[1,1] op_sel_hi:[1,0]
	v_pk_fma_f32 v[40:41], v[220:221], v[204:205], v[40:41] op_sel_hi:[0,1,1] neg_lo:[0,0,1]
	v_add_f32_e32 v214, 0x3e200000, v201
	v_cos_f32_e32 v210, v214
	v_sin_f32_e64 v211, -v214
	s_waitcnt lgkmcnt(4)
	v_pk_add_f32 v[202:203], v[42:43], v[46:47]
	v_pk_add_f32 v[42:43], v[42:43], v[46:47] neg_lo:[0,1] neg_hi:[0,1]
	v_pk_add_f32 v[204:205], v[44:45], v[48:49]
	v_pk_add_f32 v[44:45], v[44:45], v[48:49] neg_lo:[0,1] neg_hi:[0,1]
	v_pk_add_f32 v[46:47], v[202:203], v[204:205]
	v_pk_add_f32 v[48:49], v[202:203], v[204:205] neg_lo:[0,1] neg_hi:[0,1]
	v_pk_add_f32 v[202:203], v[42:43], v[44:45] op_sel:[0,1] op_sel_hi:[1,0] neg_hi:[0,1]
	v_pk_add_f32 v[204:205], v[42:43], v[44:45] op_sel:[0,1] op_sel_hi:[1,0] neg_lo:[0,1]
	v_pk_mul_f32 v[206:207], v[210:211], v[210:211] op_sel:[1,1] op_sel_hi:[1,0]
	v_pk_fma_f32 v[212:213], v[210:211], v[210:211], v[206:207] op_sel_hi:[0,1,1] neg_lo:[0,0,1]
	v_pk_mul_f32 v[206:207], v[210:211], v[212:213] op_sel:[1,1] op_sel_hi:[1,0]
	v_pk_fma_f32 v[220:221], v[210:211], v[212:213], v[206:207] op_sel_hi:[0,1,1] neg_lo:[0,0,1]
	v_pk_mul_f32 v[42:43], v[210:211], v[202:203] op_sel:[1,1] op_sel_hi:[1,0]
	v_pk_fma_f32 v[42:43], v[210:211], v[202:203], v[42:43] op_sel_hi:[0,1,1] neg_lo:[0,0,1]
	v_pk_mul_f32 v[44:45], v[212:213], v[48:49] op_sel:[1,1] op_sel_hi:[1,0]
	v_pk_fma_f32 v[44:45], v[212:213], v[48:49], v[44:45] op_sel_hi:[0,1,1] neg_lo:[0,0,1]
	v_pk_mul_f32 v[48:49], v[220:221], v[204:205] op_sel:[1,1] op_sel_hi:[1,0]
	v_pk_fma_f32 v[48:49], v[220:221], v[204:205], v[48:49] op_sel_hi:[0,1,1] neg_lo:[0,0,1]
	v_add_f32_e32 v214, 0x3e400000, v201
	v_cos_f32_e32 v210, v214
	v_sin_f32_e64 v211, -v214
	s_waitcnt lgkmcnt(2)
	v_pk_add_f32 v[202:203], v[50:51], v[54:55]
	v_pk_add_f32 v[50:51], v[50:51], v[54:55] neg_lo:[0,1] neg_hi:[0,1]
	v_pk_add_f32 v[204:205], v[52:53], v[56:57]
	v_pk_add_f32 v[52:53], v[52:53], v[56:57] neg_lo:[0,1] neg_hi:[0,1]
	v_pk_add_f32 v[54:55], v[202:203], v[204:205]
	v_pk_add_f32 v[56:57], v[202:203], v[204:205] neg_lo:[0,1] neg_hi:[0,1]
	v_pk_add_f32 v[202:203], v[50:51], v[52:53] op_sel:[0,1] op_sel_hi:[1,0] neg_hi:[0,1]
	v_pk_add_f32 v[204:205], v[50:51], v[52:53] op_sel:[0,1] op_sel_hi:[1,0] neg_lo:[0,1]
	v_pk_mul_f32 v[206:207], v[210:211], v[210:211] op_sel:[1,1] op_sel_hi:[1,0]
	v_pk_fma_f32 v[212:213], v[210:211], v[210:211], v[206:207] op_sel_hi:[0,1,1] neg_lo:[0,0,1]
	v_pk_mul_f32 v[206:207], v[210:211], v[212:213] op_sel:[1,1] op_sel_hi:[1,0]
	v_pk_fma_f32 v[220:221], v[210:211], v[212:213], v[206:207] op_sel_hi:[0,1,1] neg_lo:[0,0,1]
	v_pk_mul_f32 v[50:51], v[210:211], v[202:203] op_sel:[1,1] op_sel_hi:[1,0]
	v_pk_fma_f32 v[50:51], v[210:211], v[202:203], v[50:51] op_sel_hi:[0,1,1] neg_lo:[0,0,1]
	v_pk_mul_f32 v[52:53], v[212:213], v[56:57] op_sel:[1,1] op_sel_hi:[1,0]
	v_pk_fma_f32 v[52:53], v[212:213], v[56:57], v[52:53] op_sel_hi:[0,1,1] neg_lo:[0,0,1]
	v_pk_mul_f32 v[56:57], v[220:221], v[204:205] op_sel:[1,1] op_sel_hi:[1,0]
	v_pk_fma_f32 v[56:57], v[220:221], v[204:205], v[56:57] op_sel_hi:[0,1,1] neg_lo:[0,0,1]
	v_add_f32_e32 v214, 0x3e600000, v201
	v_cos_f32_e32 v210, v214
	v_sin_f32_e64 v211, -v214
	s_waitcnt lgkmcnt(0)
; DI f32x2 cmul(f32x2 a, f32x2 b) { return mkf2(a.x * b.x - a.y * b.y, a.x * b.y + a.y * b.x); }
; DI void fft8192(f32x2* buf, const f32x2* __restrict__ tw) {
;     ...
; #pragma unroll
;     for (int e = 0; e < 8; ++e) {
;       const int i = tid + 256 * e;
;       const int q = i & (s - 1);
;       const int ps = i - q;
;       const float rev = (float)ps * (1.f / 8192.f);
;       const f32x2 w1 = mkf2(__builtin_amdgcn_cosf(rev), -__builtin_amdgcn_sinf(rev));
;       const f32x2 w2 = cmul(w1, w1), w3 = cmul(w1, w2);
;       const f32x2 apc = mkf2(a[e].x + c[e].x, a[e].y + c[e].y), amc = mkf2(a[e].x - c[e].x, a[e].y - c[e].y);
;       const f32x2 bpd = mkf2(b[e].x + d[e].x, b[e].y + d[e].y), bmd = mkf2(b[e].x - d[e].x, b[e].y - d[e].y);
;       const int o = 4 * i - 3 * q;
;       buf[SW(o)] = mkf2(apc.x + bpd.x, apc.y + bpd.y);
;       buf[SW(o + s)] = cmul(w1, mkf2(amc.x + bmd.y, amc.y - bmd.x));
;       buf[SW(o + 2 * s)] = cmul(w2, mkf2(apc.x - bpd.x, apc.y - bpd.y));
;       buf[SW(o + 3 * s)] = cmul(w3, mkf2(amc.x - bmd.y, amc.y + bmd.x));
;     }
	v_pk_add_f32 v[202:203], v[58:59], v[62:63]
	v_pk_add_f32 v[58:59], v[58:59], v[62:63] neg_lo:[0,1] neg_hi:[0,1]
	v_pk_add_f32 v[204:205], v[60:61], v[64:65]
	v_pk_add_f32 v[60:61], v[60:61], v[64:65] neg_lo:[0,1] neg_hi:[0,1]
	v_pk_add_f32 v[62:63], v[202:203], v[204:205]
	v_pk_add_f32 v[64:65], v[202:203], v[204:205] neg_lo:[0,1] neg_hi:[0,1]
	v_pk_add_f32 v[202:203], v[58:59], v[60:61] op_sel:[0,1] op_sel_hi:[1,0] neg_hi:[0,1]
	v_pk_add_f32 v[204:205], v[58:59], v[60:61] op_sel:[0,1] op_sel_hi:[1,0] neg_lo:[0,1]
	v_pk_mul_f32 v[206:207], v[210:211], v[210:211] op_sel:[1,1] op_sel_hi:[1,0]
	v_pk_fma_f32 v[212:213], v[210:211], v[210:211], v[206:207] op_sel_hi:[0,1,1] neg_lo:[0,0,1]
	v_pk_mul_f32 v[206:207], v[210:211], v[212:213] op_sel:[1,1] op_sel_hi:[1,0]
	v_pk_fma_f32 v[220:221], v[210:211], v[212:213], v[206:207] op_sel_hi:[0,1,1] neg_lo:[0,0,1]
	v_pk_mul_f32 v[58:59], v[210:211], v[202:203] op_sel:[1,1] op_sel_hi:[1,0]
	v_pk_fma_f32 v[58:59], v[210:211], v[202:203], v[58:59] op_sel_hi:[0,1,1] neg_lo:[0,0,1]
	v_pk_mul_f32 v[60:61], v[212:213], v[64:65] op_sel:[1,1] op_sel_hi:[1,0]
	v_pk_fma_f32 v[60:61], v[212:213], v[64:65], v[60:61] op_sel_hi:[0,1,1] neg_lo:[0,0,1]
	v_pk_mul_f32 v[64:65], v[220:221], v[204:205] op_sel:[1,1] op_sel_hi:[1,0]
	v_pk_fma_f32 v[64:65], v[220:221], v[204:205], v[64:65] op_sel_hi:[0,1,1] neg_lo:[0,0,1]
	s_barrier
	v_mul_f32_e32 v214, 4.0, v201
	v_cos_f32_e32 v224, v214
	v_sin_f32_e64 v225, -v214
	s_nop 0
	v_pk_mul_f32 v[206:207], v[224:225], v[224:225] op_sel:[1,1] op_sel_hi:[1,0]
	v_pk_fma_f32 v[226:227], v[224:225], v[224:225], v[206:207] op_sel_hi:[0,1,1] neg_lo:[0,0,1]
	v_pk_mul_f32 v[206:207], v[224:225], v[226:227] op_sel:[1,1] op_sel_hi:[1,0]
	v_pk_fma_f32 v[230:231], v[224:225], v[226:227], v[206:207] op_sel_hi:[0,1,1] neg_lo:[0,0,1]
	v_pk_add_f32 v[202:203], v[6:7], v[38:39]
	v_pk_add_f32 v[6:7], v[6:7], v[38:39] neg_lo:[0,1] neg_hi:[0,1]
	v_pk_add_f32 v[204:205], v[22:23], v[54:55]
	v_pk_add_f32 v[22:23], v[22:23], v[54:55] neg_lo:[0,1] neg_hi:[0,1]
	v_pk_add_f32 v[38:39], v[202:203], v[204:205]
	v_pk_add_f32 v[54:55], v[202:203], v[204:205] neg_lo:[0,1] neg_hi:[0,1]
	v_pk_add_f32 v[202:203], v[6:7], v[22:23] op_sel:[0,1] op_sel_hi:[1,0] neg_hi:[0,1]
	v_pk_add_f32 v[204:205], v[6:7], v[22:23] op_sel:[0,1] op_sel_hi:[1,0] neg_lo:[0,1]
	v_pk_mul_f32 v[6:7], v[224:225], v[202:203] op_sel:[1,1] op_sel_hi:[1,0]
	v_pk_fma_f32 v[6:7], v[224:225], v[202:203], v[6:7] op_sel_hi:[0,1,1] neg_lo:[0,0,1]
	v_pk_mul_f32 v[22:23], v[226:227], v[54:55] op_sel:[1,1] op_sel_hi:[1,0]
	v_pk_fma_f32 v[22:23], v[226:227], v[54:55], v[22:23] op_sel_hi:[0,1,1] neg_lo:[0,0,1]
	v_pk_mul_f32 v[54:55], v[230:231], v[204:205] op_sel:[1,1] op_sel_hi:[1,0]
	v_pk_fma_f32 v[54:55], v[230:231], v[204:205], v[54:55] op_sel_hi:[0,1,1] neg_lo:[0,0,1]
	v_pk_add_f32 v[202:203], v[2:3], v[34:35]
	v_pk_add_f32 v[2:3], v[2:3], v[34:35] neg_lo:[0,1] neg_hi:[0,1]
	v_pk_add_f32 v[204:205], v[18:19], v[50:51]
	v_pk_add_f32 v[18:19], v[18:19], v[50:51] neg_lo:[0,1] neg_hi:[0,1]
	v_pk_add_f32 v[34:35], v[202:203], v[204:205]
	v_pk_add_f32 v[50:51], v[202:203], v[204:205] neg_lo:[0,1] neg_hi:[0,1]
	v_pk_add_f32 v[202:203], v[2:3], v[18:19] op_sel:[0,1] op_sel_hi:[1,0] neg_hi:[0,1]
	v_pk_add_f32 v[204:205], v[2:3], v[18:19] op_sel:[0,1] op_sel_hi:[1,0] neg_lo:[0,1]
	v_pk_mul_f32 v[2:3], v[224:225], v[202:203] op_sel:[1,1] op_sel_hi:[1,0]
	v_pk_fma_f32 v[2:3], v[224:225], v[202:203], v[2:3] op_sel_hi:[0,1,1] neg_lo:[0,0,1]
	v_pk_mul_f32 v[18:19], v[226:227], v[50:51] op_sel:[1,1] op_sel_hi:[1,0]
	v_pk_fma_f32 v[18:19], v[226:227], v[50:51], v[18:19] op_sel_hi:[0,1,1] neg_lo:[0,0,1]
	v_pk_mul_f32 v[50:51], v[230:231], v[204:205] op_sel:[1,1] op_sel_hi:[1,0]
	v_pk_fma_f32 v[50:51], v[230:231], v[204:205], v[50:51] op_sel_hi:[0,1,1] neg_lo:[0,0,1]
	v_pk_add_f32 v[202:203], v[4:5], v[36:37]
	v_pk_add_f32 v[4:5], v[4:5], v[36:37] neg_lo:[0,1] neg_hi:[0,1]
	v_pk_add_f32 v[204:205], v[20:21], v[52:53]
	v_pk_add_f32 v[20:21], v[20:21], v[52:53] neg_lo:[0,1] neg_hi:[0,1]
	v_pk_add_f32 v[36:37], v[202:203], v[204:205]
	v_pk_add_f32 v[52:53], v[202:203], v[204:205] neg_lo:[0,1] neg_hi:[0,1]
	v_pk_add_f32 v[202:203], v[4:5], v[20:21] op_sel:[0,1] op_sel_hi:[1,0] neg_hi:[0,1]
	v_pk_add_f32 v[204:205], v[4:5], v[20:21] op_sel:[0,1] op_sel_hi:[1,0] neg_lo:[0,1]
	v_pk_mul_f32 v[4:5], v[224:225], v[202:203] op_sel:[1,1] op_sel_hi:[1,0]
	v_pk_fma_f32 v[4:5], v[224:225], v[202:203], v[4:5] op_sel_hi:[0,1,1] neg_lo:[0,0,1]
	v_pk_mul_f32 v[20:21], v[226:227], v[52:53] op_sel:[1,1] op_sel_hi:[1,0]
	v_pk_fma_f32 v[20:21], v[226:227], v[52:53], v[20:21] op_sel_hi:[0,1,1] neg_lo:[0,0,1]
	v_pk_mul_f32 v[52:53], v[230:231], v[204:205] op_sel:[1,1] op_sel_hi:[1,0]
	v_pk_fma_f32 v[52:53], v[230:231], v[204:205], v[52:53] op_sel_hi:[0,1,1] neg_lo:[0,0,1]
	v_pk_add_f32 v[202:203], v[8:9], v[40:41]
	v_pk_add_f32 v[8:9], v[8:9], v[40:41] neg_lo:[0,1] neg_hi:[0,1]
	v_pk_add_f32 v[204:205], v[24:25], v[56:57]
	v_pk_add_f32 v[24:25], v[24:25], v[56:57] neg_lo:[0,1] neg_hi:[0,1]
	v_pk_add_f32 v[40:41], v[202:203], v[204:205]
	v_pk_add_f32 v[56:57], v[202:203], v[204:205] neg_lo:[0,1] neg_hi:[0,1]
	v_pk_add_f32 v[202:203], v[8:9], v[24:25] op_sel:[0,1] op_sel_hi:[1,0] neg_hi:[0,1]
	v_pk_add_f32 v[204:205], v[8:9], v[24:25] op_sel:[0,1] op_sel_hi:[1,0] neg_lo:[0,1]
	v_pk_mul_f32 v[8:9], v[224:225], v[202:203] op_sel:[1,1] op_sel_hi:[1,0]
	v_pk_fma_f32 v[8:9], v[224:225], v[202:203], v[8:9] op_sel_hi:[0,1,1] neg_lo:[0,0,1]
	v_pk_mul_f32 v[24:25], v[226:227], v[56:57] op_sel:[1,1] op_sel_hi:[1,0]
	v_pk_fma_f32 v[24:25], v[226:227], v[56:57], v[24:25] op_sel_hi:[0,1,1] neg_lo:[0,0,1]
; DI f32x2 cmul(f32x2 a, f32x2 b) { return mkf2(a.x * b.x - a.y * b.y, a.x * b.y + a.y * b.x); }
; DI void fft8192(f32x2* buf, const f32x2* __restrict__ tw) {
;     ...
; #pragma unroll
;     for (int e = 0; e < 8; ++e) {
;       const int i = tid + 256 * e;
;       const int q = i & (s - 1);
;       const int ps = i - q;
;       const float rev = (float)ps * (1.f / 8192.f);
;       const f32x2 w1 = mkf2(__builtin_amdgcn_cosf(rev), -__builtin_amdgcn_sinf(rev));
;       const f32x2 w2 = cmul(w1, w1), w3 = cmul(w1, w2);
;       const f32x2 apc = mkf2(a[e].x + c[e].x, a[e].y + c[e].y), amc = mkf2(a[e].x - c[e].x, a[e].y - c[e].y);
;       const f32x2 bpd = mkf2(b[e].x + d[e].x, b[e].y + d[e].y), bmd = mkf2(b[e].x - d[e].x, b[e].y - d[e].y);
;       const int o = 4 * i - 3 * q;
;       buf[SW(o)] = mkf2(apc.x + bpd.x, apc.y + bpd.y);
;       buf[SW(o + s)] = cmul(w1, mkf2(amc.x + bmd.y, amc.y - bmd.x));
;       buf[SW(o + 2 * s)] = cmul(w2, mkf2(apc.x - bpd.x, apc.y - bpd.y));
;       buf[SW(o + 3 * s)] = cmul(w3, mkf2(amc.x - bmd.y, amc.y + bmd.x));
;     }
	v_pk_mul_f32 v[56:57], v[230:231], v[204:205] op_sel:[1,1] op_sel_hi:[1,0]
	v_pk_fma_f32 v[56:57], v[230:231], v[204:205], v[56:57] op_sel_hi:[0,1,1] neg_lo:[0,0,1]
	v_mul_f32_e32 v214, 4.0, v201
	v_add_f32_e32 v214, 0x3e000000, v214
	v_cos_f32_e32 v224, v214
	v_sin_f32_e64 v225, -v214
	s_nop 0
	v_pk_mul_f32 v[206:207], v[224:225], v[224:225] op_sel:[1,1] op_sel_hi:[1,0]
	v_pk_fma_f32 v[226:227], v[224:225], v[224:225], v[206:207] op_sel_hi:[0,1,1] neg_lo:[0,0,1]
	v_pk_mul_f32 v[206:207], v[224:225], v[226:227] op_sel:[1,1] op_sel_hi:[1,0]
	v_pk_fma_f32 v[230:231], v[224:225], v[226:227], v[206:207] op_sel_hi:[0,1,1] neg_lo:[0,0,1]
	v_pk_add_f32 v[202:203], v[14:15], v[46:47]
	v_pk_add_f32 v[14:15], v[14:15], v[46:47] neg_lo:[0,1] neg_hi:[0,1]
	v_pk_add_f32 v[204:205], v[30:31], v[62:63]
	v_pk_add_f32 v[30:31], v[30:31], v[62:63] neg_lo:[0,1] neg_hi:[0,1]
	v_pk_add_f32 v[46:47], v[202:203], v[204:205]
	v_pk_add_f32 v[62:63], v[202:203], v[204:205] neg_lo:[0,1] neg_hi:[0,1]
	v_pk_add_f32 v[202:203], v[14:15], v[30:31] op_sel:[0,1] op_sel_hi:[1,0] neg_hi:[0,1]
	v_pk_add_f32 v[204:205], v[14:15], v[30:31] op_sel:[0,1] op_sel_hi:[1,0] neg_lo:[0,1]
	v_pk_mul_f32 v[14:15], v[224:225], v[202:203] op_sel:[1,1] op_sel_hi:[1,0]
	v_pk_fma_f32 v[14:15], v[224:225], v[202:203], v[14:15] op_sel_hi:[0,1,1] neg_lo:[0,0,1]
	v_pk_mul_f32 v[30:31], v[226:227], v[62:63] op_sel:[1,1] op_sel_hi:[1,0]
	v_pk_fma_f32 v[30:31], v[226:227], v[62:63], v[30:31] op_sel_hi:[0,1,1] neg_lo:[0,0,1]
	v_pk_mul_f32 v[62:63], v[230:231], v[204:205] op_sel:[1,1] op_sel_hi:[1,0]
	v_pk_fma_f32 v[62:63], v[230:231], v[204:205], v[62:63] op_sel_hi:[0,1,1] neg_lo:[0,0,1]
	v_pk_add_f32 v[202:203], v[10:11], v[42:43]
	v_pk_add_f32 v[10:11], v[10:11], v[42:43] neg_lo:[0,1] neg_hi:[0,1]
	v_pk_add_f32 v[204:205], v[26:27], v[58:59]
	v_pk_add_f32 v[26:27], v[26:27], v[58:59] neg_lo:[0,1] neg_hi:[0,1]
	v_pk_add_f32 v[42:43], v[202:203], v[204:205]
	v_pk_add_f32 v[58:59], v[202:203], v[204:205] neg_lo:[0,1] neg_hi:[0,1]
	v_pk_add_f32 v[202:203], v[10:11], v[26:27] op_sel:[0,1] op_sel_hi:[1,0] neg_hi:[0,1]
	v_pk_add_f32 v[204:205], v[10:11], v[26:27] op_sel:[0,1] op_sel_hi:[1,0] neg_lo:[0,1]
	v_pk_mul_f32 v[10:11], v[224:225], v[202:203] op_sel:[1,1] op_sel_hi:[1,0]
	v_pk_fma_f32 v[10:11], v[224:225], v[202:203], v[10:11] op_sel_hi:[0,1,1] neg_lo:[0,0,1]
	v_pk_mul_f32 v[26:27], v[226:227], v[58:59] op_sel:[1,1] op_sel_hi:[1,0]
	v_pk_fma_f32 v[26:27], v[226:227], v[58:59], v[26:27] op_sel_hi:[0,1,1] neg_lo:[0,0,1]
	v_pk_mul_f32 v[58:59], v[230:231], v[204:205] op_sel:[1,1] op_sel_hi:[1,0]
	v_pk_fma_f32 v[58:59], v[230:231], v[204:205], v[58:59] op_sel_hi:[0,1,1] neg_lo:[0,0,1]
	v_pk_add_f32 v[202:203], v[12:13], v[44:45]
	v_pk_add_f32 v[12:13], v[12:13], v[44:45] neg_lo:[0,1] neg_hi:[0,1]
	v_pk_add_f32 v[204:205], v[28:29], v[60:61]
	v_pk_add_f32 v[28:29], v[28:29], v[60:61] neg_lo:[0,1] neg_hi:[0,1]
	v_pk_add_f32 v[44:45], v[202:203], v[204:205]
	v_pk_add_f32 v[60:61], v[202:203], v[204:205] neg_lo:[0,1] neg_hi:[0,1]
	v_pk_add_f32 v[202:203], v[12:13], v[28:29] op_sel:[0,1] op_sel_hi:[1,0] neg_hi:[0,1]
	v_pk_add_f32 v[204:205], v[12:13], v[28:29] op_sel:[0,1] op_sel_hi:[1,0] neg_lo:[0,1]
	v_pk_mul_f32 v[12:13], v[224:225], v[202:203] op_sel:[1,1] op_sel_hi:[1,0]
	v_pk_fma_f32 v[12:13], v[224:225], v[202:203], v[12:13] op_sel_hi:[0,1,1] neg_lo:[0,0,1]
	v_pk_mul_f32 v[28:29], v[226:227], v[60:61] op_sel:[1,1] op_sel_hi:[1,0]
	v_pk_fma_f32 v[28:29], v[226:227], v[60:61], v[28:29] op_sel_hi:[0,1,1] neg_lo:[0,0,1]
	v_pk_mul_f32 v[60:61], v[230:231], v[204:205] op_sel:[1,1] op_sel_hi:[1,0]
	v_pk_fma_f32 v[60:61], v[230:231], v[204:205], v[60:61] op_sel_hi:[0,1,1] neg_lo:[0,0,1]
	v_pk_add_f32 v[202:203], v[16:17], v[48:49]
	v_pk_add_f32 v[16:17], v[16:17], v[48:49] neg_lo:[0,1] neg_hi:[0,1]
	v_pk_add_f32 v[204:205], v[32:33], v[64:65]
	v_pk_add_f32 v[32:33], v[32:33], v[64:65] neg_lo:[0,1] neg_hi:[0,1]
	v_pk_add_f32 v[48:49], v[202:203], v[204:205]
	v_pk_add_f32 v[64:65], v[202:203], v[204:205] neg_lo:[0,1] neg_hi:[0,1]
	v_pk_add_f32 v[202:203], v[16:17], v[32:33] op_sel:[0,1] op_sel_hi:[1,0] neg_hi:[0,1]
	v_pk_add_f32 v[204:205], v[16:17], v[32:33] op_sel:[0,1] op_sel_hi:[1,0] neg_lo:[0,1]
	v_pk_mul_f32 v[16:17], v[224:225], v[202:203] op_sel:[1,1] op_sel_hi:[1,0]
	v_pk_fma_f32 v[16:17], v[224:225], v[202:203], v[16:17] op_sel_hi:[0,1,1] neg_lo:[0,0,1]
	v_pk_mul_f32 v[32:33], v[226:227], v[64:65] op_sel:[1,1] op_sel_hi:[1,0]
	v_pk_fma_f32 v[32:33], v[226:227], v[64:65], v[32:33] op_sel_hi:[0,1,1] neg_lo:[0,0,1]
	v_pk_mul_f32 v[64:65], v[230:231], v[204:205] op_sel:[1,1] op_sel_hi:[1,0]
	v_pk_fma_f32 v[64:65], v[230:231], v[204:205], v[64:65] op_sel_hi:[0,1,1] neg_lo:[0,0,1]
	ds_write_b64 v164, v[38:39] offset:0
	v_xor_b32_e32 v156, 0x80, v164
	ds_write_b64 v156, v[34:35] offset:0
	v_xor_b32_e32 v158, 0x128, v164
	ds_write_b64 v158, v[36:37] offset:0
	v_xor_b32_e32 v160, 0x1a8, v164
	ds_write_b64 v160, v[40:41] offset:0
	v_xor_b32_e32 v162, 0x2d0, v164
	ds_write_b64 v162, v[6:7] offset:0
	v_xor_b32_e32 v156, 0x250, v164
	ds_write_b64 v156, v[2:3] offset:0
	v_xor_b32_e32 v158, 0x3f8, v164
	ds_write_b64 v158, v[4:5] offset:0
	v_xor_b32_e32 v160, 0x378, v164
	ds_write_b64 v160, v[8:9] offset:0
	v_xor_b32_e32 v162, 0x400, v164
	ds_write_b64 v162, v[22:23] offset:0
	v_xor_b32_e32 v156, 0x480, v164
	ds_write_b64 v156, v[18:19] offset:0
	v_xor_b32_e32 v158, 0x528, v164
	ds_write_b64 v158, v[20:21] offset:0
	v_xor_b32_e32 v160, 0x5a8, v164
	ds_write_b64 v160, v[24:25] offset:0
	v_xor_b32_e32 v162, 0x6d0, v164
	ds_write_b64 v162, v[54:55] offset:0
	v_xor_b32_e32 v156, 0x650, v164
	ds_write_b64 v156, v[50:51] offset:0
	v_xor_b32_e32 v158, 0x7f8, v164
	ds_write_b64 v158, v[52:53] offset:0
	v_xor_b32_e32 v160, 0x778, v164
	ds_write_b64 v160, v[56:57] offset:0
	ds_write_b64 v164, v[46:47] offset:32768
	v_xor_b32_e32 v162, 0x80, v164
	ds_write_b64 v162, v[42:43] offset:32768
	v_xor_b32_e32 v156, 0x128, v164
	ds_write_b64 v156, v[44:45] offset:32768
	v_xor_b32_e32 v158, 0x1a8, v164
	ds_write_b64 v158, v[48:49] offset:32768
	v_xor_b32_e32 v160, 0x2d0, v164
	ds_write_b64 v160, v[14:15] offset:32768
	v_xor_b32_e32 v162, 0x250, v164
	ds_write_b64 v162, v[10:11] offset:32768
	v_xor_b32_e32 v156, 0x3f8, v164
	ds_write_b64 v156, v[12:13] offset:32768
	v_xor_b32_e32 v158, 0x378, v164
	ds_write_b64 v158, v[16:17] offset:32768
	v_xor_b32_e32 v160, 0x400, v164
	ds_write_b64 v160, v[30:31] offset:32768
	v_xor_b32_e32 v162, 0x480, v164
	ds_write_b64 v162, v[26:27] offset:32768
	v_xor_b32_e32 v156, 0x528, v164
	ds_write_b64 v156, v[28:29] offset:32768
	v_xor_b32_e32 v158, 0x5a8, v164
	ds_write_b64 v158, v[32:33] offset:32768
	v_xor_b32_e32 v160, 0x6d0, v164
	ds_write_b64 v160, v[62:63] offset:32768
	v_xor_b32_e32 v162, 0x650, v164
	ds_write_b64 v162, v[58:59] offset:32768
	v_xor_b32_e32 v156, 0x7f8, v164
	ds_write_b64 v156, v[60:61] offset:32768
	v_xor_b32_e32 v158, 0x778, v164
	ds_write_b64 v158, v[64:65] offset:32768
	s_waitcnt lgkmcnt(0)
	s_barrier
; DI f32x2 cmul(f32x2 a, f32x2 b) { return mkf2(a.x * b.x - a.y * b.y, a.x * b.y + a.y * b.x); }
; DI void fft8192(f32x2* buf, const f32x2* __restrict__ tw) {
;     ...
;     __syncthreads();
; #pragma unroll
;     for (int e = 0; e < 8; ++e) {
;       const int i = tid + 256 * e;
;       const int pi = SW(i);
;       a[e] = buf[pi]; b[e] = buf[pi + 2048]; c[e] = buf[pi + 4096]; d[e] = buf[pi + 6144];
;     }
;     __syncthreads();
; #pragma unroll
;     for (int e = 0; e < 8; ++e) {
;       const int i = tid + 256 * e;
;       const int q = i & (s - 1);
;       const int ps = i - q;
;       const float rev = (float)ps * (1.f / 8192.f);
;       const f32x2 w1 = mkf2(__builtin_amdgcn_cosf(rev), -__builtin_amdgcn_sinf(rev));
;       const f32x2 w2 = cmul(w1, w1), w3 = cmul(w1, w2);
;       const f32x2 apc = mkf2(a[e].x + c[e].x, a[e].y + c[e].y), amc = mkf2(a[e].x - c[e].x, a[e].y - c[e].y);
;       const f32x2 bpd = mkf2(b[e].x + d[e].x, b[e].y + d[e].y), bmd = mkf2(b[e].x - d[e].x, b[e].y - d[e].y);
;       const int o = 4 * i - 3 * q;
;       buf[SW(o)] = mkf2(apc.x + bpd.x, apc.y + bpd.y);
;       buf[SW(o + s)] = cmul(w1, mkf2(amc.x + bmd.y, amc.y - bmd.x));
;       buf[SW(o + 2 * s)] = cmul(w2, mkf2(apc.x - bpd.x, apc.y - bpd.y));
;       buf[SW(o + 3 * s)] = cmul(w3, mkf2(amc.x - bmd.y, amc.y + bmd.x));
;     }
	ds_read2st64_b64 v[2:5], v154 offset0:0 offset1:32
	ds_read2st64_b64 v[6:9], v154 offset0:64 offset1:96
	ds_read2st64_b64 v[10:13], v154 offset0:4 offset1:36
	ds_read2st64_b64 v[14:17], v154 offset0:68 offset1:100
	ds_read2st64_b64 v[18:21], v154 offset0:8 offset1:40
	ds_read2st64_b64 v[22:25], v154 offset0:72 offset1:104
	ds_read2st64_b64 v[26:29], v154 offset0:12 offset1:44
	ds_read2st64_b64 v[30:33], v154 offset0:76 offset1:108
	ds_read2st64_b64 v[34:37], v154 offset0:16 offset1:48
	ds_read2st64_b64 v[38:41], v154 offset0:80 offset1:112
	ds_read2st64_b64 v[42:45], v154 offset0:20 offset1:52
	ds_read2st64_b64 v[46:49], v154 offset0:84 offset1:116
	ds_read2st64_b64 v[50:53], v154 offset0:24 offset1:56
	ds_read2st64_b64 v[54:57], v154 offset0:88 offset1:120
	ds_read2st64_b64 v[58:61], v154 offset0:28 offset1:60
	ds_read2st64_b64 v[62:65], v154 offset0:92 offset1:124
	s_waitcnt lgkmcnt(14)
	v_pk_add_f32 v[202:203], v[2:3], v[6:7]
	v_pk_add_f32 v[2:3], v[2:3], v[6:7] neg_lo:[0,1] neg_hi:[0,1]
	v_pk_add_f32 v[204:205], v[4:5], v[8:9]
	v_pk_add_f32 v[4:5], v[4:5], v[8:9] neg_lo:[0,1] neg_hi:[0,1]
	v_pk_add_f32 v[6:7], v[202:203], v[204:205]
	v_pk_add_f32 v[8:9], v[202:203], v[204:205] neg_lo:[0,1] neg_hi:[0,1]
	v_pk_add_f32 v[202:203], v[2:3], v[4:5] op_sel:[0,1] op_sel_hi:[1,0] neg_hi:[0,1]
	v_pk_add_f32 v[4:5], v[2:3], v[4:5] op_sel:[0,1] op_sel_hi:[1,0] neg_lo:[0,1]
	v_pk_mov_b32 v[2:3], v[202:203], v[202:203] op_sel:[0,1]
	v_cos_f32_e32 v210, 0x3d000000
	v_sin_f32_e32 v211, 0xbd000000
	s_waitcnt lgkmcnt(12)
	v_pk_add_f32 v[202:203], v[10:11], v[14:15]
	v_pk_add_f32 v[10:11], v[10:11], v[14:15] neg_lo:[0,1] neg_hi:[0,1]
	v_pk_add_f32 v[204:205], v[12:13], v[16:17]
	v_pk_add_f32 v[12:13], v[12:13], v[16:17] neg_lo:[0,1] neg_hi:[0,1]
	v_pk_add_f32 v[14:15], v[202:203], v[204:205]
	v_pk_add_f32 v[16:17], v[202:203], v[204:205] neg_lo:[0,1] neg_hi:[0,1]
	v_pk_add_f32 v[202:203], v[10:11], v[12:13] op_sel:[0,1] op_sel_hi:[1,0] neg_hi:[0,1]
	v_pk_add_f32 v[204:205], v[10:11], v[12:13] op_sel:[0,1] op_sel_hi:[1,0] neg_lo:[0,1]
	v_pk_mul_f32 v[206:207], v[210:211], v[210:211] op_sel:[1,1] op_sel_hi:[1,0]
	v_pk_fma_f32 v[212:213], v[210:211], v[210:211], v[206:207] op_sel_hi:[0,1,1] neg_lo:[0,0,1]
	v_pk_mul_f32 v[206:207], v[210:211], v[212:213] op_sel:[1,1] op_sel_hi:[1,0]
	v_pk_fma_f32 v[220:221], v[210:211], v[212:213], v[206:207] op_sel_hi:[0,1,1] neg_lo:[0,0,1]
	v_pk_mul_f32 v[10:11], v[210:211], v[202:203] op_sel:[1,1] op_sel_hi:[1,0]
	v_pk_fma_f32 v[10:11], v[210:211], v[202:203], v[10:11] op_sel_hi:[0,1,1] neg_lo:[0,0,1]
	v_pk_mul_f32 v[12:13], v[212:213], v[16:17] op_sel:[1,1] op_sel_hi:[1,0]
	v_pk_fma_f32 v[12:13], v[212:213], v[16:17], v[12:13] op_sel_hi:[0,1,1] neg_lo:[0,0,1]
	v_pk_mul_f32 v[16:17], v[220:221], v[204:205] op_sel:[1,1] op_sel_hi:[1,0]
	v_pk_fma_f32 v[16:17], v[220:221], v[204:205], v[16:17] op_sel_hi:[0,1,1] neg_lo:[0,0,1]
	v_cos_f32_e32 v210, 0x3d800000
	v_sin_f32_e32 v211, 0xbd800000
	s_waitcnt lgkmcnt(10)
	v_pk_add_f32 v[202:203], v[18:19], v[22:23]
	v_pk_add_f32 v[18:19], v[18:19], v[22:23] neg_lo:[0,1] neg_hi:[0,1]
	v_pk_add_f32 v[204:205], v[20:21], v[24:25]
	v_pk_add_f32 v[20:21], v[20:21], v[24:25] neg_lo:[0,1] neg_hi:[0,1]
	v_pk_add_f32 v[22:23], v[202:203], v[204:205]
	v_pk_add_f32 v[24:25], v[202:203], v[204:205] neg_lo:[0,1] neg_hi:[0,1]
	v_pk_add_f32 v[202:203], v[18:19], v[20:21] op_sel:[0,1] op_sel_hi:[1,0] neg_hi:[0,1]
	v_pk_add_f32 v[204:205], v[18:19], v[20:21] op_sel:[0,1] op_sel_hi:[1,0] neg_lo:[0,1]
	v_pk_mul_f32 v[206:207], v[210:211], v[210:211] op_sel:[1,1] op_sel_hi:[1,0]
	v_pk_fma_f32 v[212:213], v[210:211], v[210:211], v[206:207] op_sel_hi:[0,1,1] neg_lo:[0,0,1]
	v_pk_mul_f32 v[206:207], v[210:211], v[212:213] op_sel:[1,1] op_sel_hi:[1,0]
	v_pk_fma_f32 v[220:221], v[210:211], v[212:213], v[206:207] op_sel_hi:[0,1,1] neg_lo:[0,0,1]
	v_pk_mul_f32 v[18:19], v[210:211], v[202:203] op_sel:[1,1] op_sel_hi:[1,0]
	v_pk_fma_f32 v[18:19], v[210:211], v[202:203], v[18:19] op_sel_hi:[0,1,1] neg_lo:[0,0,1]
	v_pk_mul_f32 v[20:21], v[212:213], v[24:25] op_sel:[1,1] op_sel_hi:[1,0]
	v_pk_fma_f32 v[20:21], v[212:213], v[24:25], v[20:21] op_sel_hi:[0,1,1] neg_lo:[0,0,1]
	v_pk_mul_f32 v[24:25], v[220:221], v[204:205] op_sel:[1,1] op_sel_hi:[1,0]
	v_pk_fma_f32 v[24:25], v[220:221], v[204:205], v[24:25] op_sel_hi:[0,1,1] neg_lo:[0,0,1]
	v_cos_f32_e32 v210, 0x3dc00000
	v_sin_f32_e32 v211, 0xbdc00000
	s_waitcnt lgkmcnt(8)
	v_pk_add_f32 v[202:203], v[26:27], v[30:31]
	v_pk_add_f32 v[26:27], v[26:27], v[30:31] neg_lo:[0,1] neg_hi:[0,1]
	v_pk_add_f32 v[204:205], v[28:29], v[32:33]
	v_pk_add_f32 v[28:29], v[28:29], v[32:33] neg_lo:[0,1] neg_hi:[0,1]
	v_pk_add_f32 v[30:31], v[202:203], v[204:205]
	v_pk_add_f32 v[32:33], v[202:203], v[204:205] neg_lo:[0,1] neg_hi:[0,1]
	v_pk_add_f32 v[202:203], v[26:27], v[28:29] op_sel:[0,1] op_sel_hi:[1,0] neg_hi:[0,1]
	v_pk_add_f32 v[204:205], v[26:27], v[28:29] op_sel:[0,1] op_sel_hi:[1,0] neg_lo:[0,1]
	v_pk_mul_f32 v[206:207], v[210:211], v[210:211] op_sel:[1,1] op_sel_hi:[1,0]
	v_pk_fma_f32 v[212:213], v[210:211], v[210:211], v[206:207] op_sel_hi:[0,1,1] neg_lo:[0,0,1]
	v_pk_mul_f32 v[206:207], v[210:211], v[212:213] op_sel:[1,1] op_sel_hi:[1,0]
	v_pk_fma_f32 v[220:221], v[210:211], v[212:213], v[206:207] op_sel_hi:[0,1,1] neg_lo:[0,0,1]
	v_pk_mul_f32 v[26:27], v[210:211], v[202:203] op_sel:[1,1] op_sel_hi:[1,0]
	v_pk_fma_f32 v[26:27], v[210:211], v[202:203], v[26:27] op_sel_hi:[0,1,1] neg_lo:[0,0,1]
	v_pk_mul_f32 v[28:29], v[212:213], v[32:33] op_sel:[1,1] op_sel_hi:[1,0]
	v_pk_fma_f32 v[28:29], v[212:213], v[32:33], v[28:29] op_sel_hi:[0,1,1] neg_lo:[0,0,1]
	v_pk_mul_f32 v[32:33], v[220:221], v[204:205] op_sel:[1,1] op_sel_hi:[1,0]
	v_pk_fma_f32 v[32:33], v[220:221], v[204:205], v[32:33] op_sel_hi:[0,1,1] neg_lo:[0,0,1]
	v_cos_f32_e32 v210, 0x3e000000
	v_sin_f32_e32 v211, 0xbe000000
	s_waitcnt lgkmcnt(6)
; DI f32x2 cmul(f32x2 a, f32x2 b) { return mkf2(a.x * b.x - a.y * b.y, a.x * b.y + a.y * b.x); }
; DI void fft8192(f32x2* buf, const f32x2* __restrict__ tw) {
;     ...
; #pragma unroll
;     for (int e = 0; e < 8; ++e) {
;       const int i = tid + 256 * e;
;       const int q = i & (s - 1);
;       const int ps = i - q;
;       const float rev = (float)ps * (1.f / 8192.f);
;       const f32x2 w1 = mkf2(__builtin_amdgcn_cosf(rev), -__builtin_amdgcn_sinf(rev));
;       const f32x2 w2 = cmul(w1, w1), w3 = cmul(w1, w2);
;       const f32x2 apc = mkf2(a[e].x + c[e].x, a[e].y + c[e].y), amc = mkf2(a[e].x - c[e].x, a[e].y - c[e].y);
;       const f32x2 bpd = mkf2(b[e].x + d[e].x, b[e].y + d[e].y), bmd = mkf2(b[e].x - d[e].x, b[e].y - d[e].y);
;       const int o = 4 * i - 3 * q;
;       buf[SW(o)] = mkf2(apc.x + bpd.x, apc.y + bpd.y);
;       buf[SW(o + s)] = cmul(w1, mkf2(amc.x + bmd.y, amc.y - bmd.x));
;       buf[SW(o + 2 * s)] = cmul(w2, mkf2(apc.x - bpd.x, apc.y - bpd.y));
;       buf[SW(o + 3 * s)] = cmul(w3, mkf2(amc.x - bmd.y, amc.y + bmd.x));
;     }
	v_pk_add_f32 v[202:203], v[34:35], v[38:39]
	v_pk_add_f32 v[34:35], v[34:35], v[38:39] neg_lo:[0,1] neg_hi:[0,1]
	v_pk_add_f32 v[204:205], v[36:37], v[40:41]
	v_pk_add_f32 v[36:37], v[36:37], v[40:41] neg_lo:[0,1] neg_hi:[0,1]
	v_pk_add_f32 v[38:39], v[202:203], v[204:205]
	v_pk_add_f32 v[40:41], v[202:203], v[204:205] neg_lo:[0,1] neg_hi:[0,1]
	v_pk_add_f32 v[202:203], v[34:35], v[36:37] op_sel:[0,1] op_sel_hi:[1,0] neg_hi:[0,1]
	v_pk_add_f32 v[204:205], v[34:35], v[36:37] op_sel:[0,1] op_sel_hi:[1,0] neg_lo:[0,1]
	v_pk_mul_f32 v[206:207], v[210:211], v[210:211] op_sel:[1,1] op_sel_hi:[1,0]
	v_pk_fma_f32 v[212:213], v[210:211], v[210:211], v[206:207] op_sel_hi:[0,1,1] neg_lo:[0,0,1]
	v_pk_mul_f32 v[206:207], v[210:211], v[212:213] op_sel:[1,1] op_sel_hi:[1,0]
	v_pk_fma_f32 v[220:221], v[210:211], v[212:213], v[206:207] op_sel_hi:[0,1,1] neg_lo:[0,0,1]
	v_pk_mul_f32 v[34:35], v[210:211], v[202:203] op_sel:[1,1] op_sel_hi:[1,0]
	v_pk_fma_f32 v[34:35], v[210:211], v[202:203], v[34:35] op_sel_hi:[0,1,1] neg_lo:[0,0,1]
	v_pk_mul_f32 v[36:37], v[212:213], v[40:41] op_sel:[1,1] op_sel_hi:[1,0]
	v_pk_fma_f32 v[36:37], v[212:213], v[40:41], v[36:37] op_sel_hi:[0,1,1] neg_lo:[0,0,1]
	v_pk_mul_f32 v[40:41], v[220:221], v[204:205] op_sel:[1,1] op_sel_hi:[1,0]
	v_pk_fma_f32 v[40:41], v[220:221], v[204:205], v[40:41] op_sel_hi:[0,1,1] neg_lo:[0,0,1]
	v_cos_f32_e32 v210, 0x3e200000
	v_sin_f32_e32 v211, 0xbe200000
	s_waitcnt lgkmcnt(4)
	v_pk_add_f32 v[202:203], v[42:43], v[46:47]
	v_pk_add_f32 v[42:43], v[42:43], v[46:47] neg_lo:[0,1] neg_hi:[0,1]
	v_pk_add_f32 v[204:205], v[44:45], v[48:49]
	v_pk_add_f32 v[44:45], v[44:45], v[48:49] neg_lo:[0,1] neg_hi:[0,1]
	v_pk_add_f32 v[46:47], v[202:203], v[204:205]
	v_pk_add_f32 v[48:49], v[202:203], v[204:205] neg_lo:[0,1] neg_hi:[0,1]
	v_pk_add_f32 v[202:203], v[42:43], v[44:45] op_sel:[0,1] op_sel_hi:[1,0] neg_hi:[0,1]
	v_pk_add_f32 v[204:205], v[42:43], v[44:45] op_sel:[0,1] op_sel_hi:[1,0] neg_lo:[0,1]
	v_pk_mul_f32 v[206:207], v[210:211], v[210:211] op_sel:[1,1] op_sel_hi:[1,0]
	v_pk_fma_f32 v[212:213], v[210:211], v[210:211], v[206:207] op_sel_hi:[0,1,1] neg_lo:[0,0,1]
	v_pk_mul_f32 v[206:207], v[210:211], v[212:213] op_sel:[1,1] op_sel_hi:[1,0]
	v_pk_fma_f32 v[220:221], v[210:211], v[212:213], v[206:207] op_sel_hi:[0,1,1] neg_lo:[0,0,1]
	v_pk_mul_f32 v[42:43], v[210:211], v[202:203] op_sel:[1,1] op_sel_hi:[1,0]
	v_pk_fma_f32 v[42:43], v[210:211], v[202:203], v[42:43] op_sel_hi:[0,1,1] neg_lo:[0,0,1]
	v_pk_mul_f32 v[44:45], v[212:213], v[48:49] op_sel:[1,1] op_sel_hi:[1,0]
	v_pk_fma_f32 v[44:45], v[212:213], v[48:49], v[44:45] op_sel_hi:[0,1,1] neg_lo:[0,0,1]
	v_pk_mul_f32 v[48:49], v[220:221], v[204:205] op_sel:[1,1] op_sel_hi:[1,0]
	v_pk_fma_f32 v[48:49], v[220:221], v[204:205], v[48:49] op_sel_hi:[0,1,1] neg_lo:[0,0,1]
	v_cos_f32_e32 v210, 0x3e400000
	v_sin_f32_e32 v211, 0xbe400000
	s_waitcnt lgkmcnt(2)
	v_pk_add_f32 v[202:203], v[50:51], v[54:55]
	v_pk_add_f32 v[50:51], v[50:51], v[54:55] neg_lo:[0,1] neg_hi:[0,1]
	v_pk_add_f32 v[204:205], v[52:53], v[56:57]
	v_pk_add_f32 v[52:53], v[52:53], v[56:57] neg_lo:[0,1] neg_hi:[0,1]
	v_pk_add_f32 v[54:55], v[202:203], v[204:205]
	v_pk_add_f32 v[56:57], v[202:203], v[204:205] neg_lo:[0,1] neg_hi:[0,1]
	v_pk_add_f32 v[202:203], v[50:51], v[52:53] op_sel:[0,1] op_sel_hi:[1,0] neg_hi:[0,1]
	v_pk_add_f32 v[204:205], v[50:51], v[52:53] op_sel:[0,1] op_sel_hi:[1,0] neg_lo:[0,1]
	v_pk_mul_f32 v[206:207], v[210:211], v[210:211] op_sel:[1,1] op_sel_hi:[1,0]
	v_pk_fma_f32 v[212:213], v[210:211], v[210:211], v[206:207] op_sel_hi:[0,1,1] neg_lo:[0,0,1]
	v_pk_mul_f32 v[206:207], v[210:211], v[212:213] op_sel:[1,1] op_sel_hi:[1,0]
	v_pk_fma_f32 v[220:221], v[210:211], v[212:213], v[206:207] op_sel_hi:[0,1,1] neg_lo:[0,0,1]
	v_pk_mul_f32 v[50:51], v[210:211], v[202:203] op_sel:[1,1] op_sel_hi:[1,0]
	v_pk_fma_f32 v[50:51], v[210:211], v[202:203], v[50:51] op_sel_hi:[0,1,1] neg_lo:[0,0,1]
	v_pk_mul_f32 v[52:53], v[212:213], v[56:57] op_sel:[1,1] op_sel_hi:[1,0]
	v_pk_fma_f32 v[52:53], v[212:213], v[56:57], v[52:53] op_sel_hi:[0,1,1] neg_lo:[0,0,1]
	v_pk_mul_f32 v[56:57], v[220:221], v[204:205] op_sel:[1,1] op_sel_hi:[1,0]
	v_pk_fma_f32 v[56:57], v[220:221], v[204:205], v[56:57] op_sel_hi:[0,1,1] neg_lo:[0,0,1]
	v_cos_f32_e32 v210, 0x3e600000
	v_sin_f32_e32 v211, 0xbe600000
	s_waitcnt lgkmcnt(0)
	v_pk_add_f32 v[202:203], v[58:59], v[62:63]
	v_pk_add_f32 v[58:59], v[58:59], v[62:63] neg_lo:[0,1] neg_hi:[0,1]
	v_pk_add_f32 v[204:205], v[60:61], v[64:65]
	v_pk_add_f32 v[60:61], v[60:61], v[64:65] neg_lo:[0,1] neg_hi:[0,1]
	v_pk_add_f32 v[62:63], v[202:203], v[204:205]
	v_pk_add_f32 v[64:65], v[202:203], v[204:205] neg_lo:[0,1] neg_hi:[0,1]
	v_pk_add_f32 v[202:203], v[58:59], v[60:61] op_sel:[0,1] op_sel_hi:[1,0] neg_hi:[0,1]
	v_pk_add_f32 v[204:205], v[58:59], v[60:61] op_sel:[0,1] op_sel_hi:[1,0] neg_lo:[0,1]
	v_pk_mul_f32 v[206:207], v[210:211], v[210:211] op_sel:[1,1] op_sel_hi:[1,0]
	v_pk_fma_f32 v[212:213], v[210:211], v[210:211], v[206:207] op_sel_hi:[0,1,1] neg_lo:[0,0,1]
	v_pk_mul_f32 v[206:207], v[210:211], v[212:213] op_sel:[1,1] op_sel_hi:[1,0]
	v_pk_fma_f32 v[220:221], v[210:211], v[212:213], v[206:207] op_sel_hi:[0,1,1] neg_lo:[0,0,1]
	v_pk_mul_f32 v[58:59], v[210:211], v[202:203] op_sel:[1,1] op_sel_hi:[1,0]
	v_pk_fma_f32 v[58:59], v[210:211], v[202:203], v[58:59] op_sel_hi:[0,1,1] neg_lo:[0,0,1]
	v_pk_mul_f32 v[60:61], v[212:213], v[64:65] op_sel:[1,1] op_sel_hi:[1,0]
	v_pk_fma_f32 v[60:61], v[212:213], v[64:65], v[60:61] op_sel_hi:[0,1,1] neg_lo:[0,0,1]
	v_pk_mul_f32 v[64:65], v[220:221], v[204:205] op_sel:[1,1] op_sel_hi:[1,0]
	v_pk_fma_f32 v[64:65], v[220:221], v[204:205], v[64:65] op_sel_hi:[0,1,1] neg_lo:[0,0,1]
	s_barrier
; DI f32x2 cmul(f32x2 a, f32x2 b) { return mkf2(a.x * b.x - a.y * b.y, a.x * b.y + a.y * b.x); }
; DI void fft8192(f32x2* buf, const f32x2* __restrict__ tw) {
;     ...
; #pragma unroll
;     for (int e = 0; e < 8; ++e) {
;       const int i = tid + 256 * e;
;       const int q = i & (s - 1);
;       const int ps = i - q;
;       const float rev = (float)ps * (1.f / 8192.f);
;       const f32x2 w1 = mkf2(__builtin_amdgcn_cosf(rev), -__builtin_amdgcn_sinf(rev));
;       const f32x2 w2 = cmul(w1, w1), w3 = cmul(w1, w2);
;       const f32x2 apc = mkf2(a[e].x + c[e].x, a[e].y + c[e].y), amc = mkf2(a[e].x - c[e].x, a[e].y - c[e].y);
;       const f32x2 bpd = mkf2(b[e].x + d[e].x, b[e].y + d[e].y), bmd = mkf2(b[e].x - d[e].x, b[e].y - d[e].y);
;       const int o = 4 * i - 3 * q;
;       buf[SW(o)] = mkf2(apc.x + bpd.x, apc.y + bpd.y);
;       buf[SW(o + s)] = cmul(w1, mkf2(amc.x + bmd.y, amc.y - bmd.x));
;       buf[SW(o + 2 * s)] = cmul(w2, mkf2(apc.x - bpd.x, apc.y - bpd.y));
;       buf[SW(o + 3 * s)] = cmul(w3, mkf2(amc.x - bmd.y, amc.y + bmd.x));
;     }
;     ...
;   {
;     f32x2 a[16], b[16];
;     __syncthreads();
; #pragma unroll
;     for (int e = 0; e < 16; ++e) { const int pi = SW(tid + 256 * e); a[e] = buf[pi]; b[e] = buf[pi + 4096]; }
;     __syncthreads();
; #pragma unroll
;     for (int e = 0; e < 16; ++e) {
;       const int pi = SW(tid + 256 * e);
;       buf[pi] = mkf2(a[e].x + b[e].x, a[e].y + b[e].y);
;       buf[pi + 4096] = mkf2(a[e].x - b[e].x, a[e].y - b[e].y);
;     }
;     __syncthreads();
;   }
	v_pk_add_f32 v[202:203], v[6:7], v[38:39]
	v_pk_add_f32 v[6:7], v[6:7], v[38:39] neg_lo:[0,1] neg_hi:[0,1]
	v_pk_add_f32 v[204:205], v[22:23], v[54:55]
	v_pk_add_f32 v[22:23], v[22:23], v[54:55] neg_lo:[0,1] neg_hi:[0,1]
	v_pk_add_f32 v[38:39], v[202:203], v[204:205]
	v_pk_add_f32 v[54:55], v[202:203], v[204:205] neg_lo:[0,1] neg_hi:[0,1]
	v_pk_add_f32 v[202:203], v[6:7], v[22:23] op_sel:[0,1] op_sel_hi:[1,0] neg_hi:[0,1]
	v_pk_add_f32 v[22:23], v[6:7], v[22:23] op_sel:[0,1] op_sel_hi:[1,0] neg_lo:[0,1]
	v_pk_mov_b32 v[6:7], v[202:203], v[202:203] op_sel:[0,1]
	v_pk_add_f32 v[202:203], v[2:3], v[34:35]
	v_pk_add_f32 v[2:3], v[2:3], v[34:35] neg_lo:[0,1] neg_hi:[0,1]
	v_pk_add_f32 v[204:205], v[18:19], v[50:51]
	v_pk_add_f32 v[18:19], v[18:19], v[50:51] neg_lo:[0,1] neg_hi:[0,1]
	v_pk_add_f32 v[34:35], v[202:203], v[204:205]
	v_pk_add_f32 v[50:51], v[202:203], v[204:205] neg_lo:[0,1] neg_hi:[0,1]
	v_pk_add_f32 v[202:203], v[2:3], v[18:19] op_sel:[0,1] op_sel_hi:[1,0] neg_hi:[0,1]
	v_pk_add_f32 v[18:19], v[2:3], v[18:19] op_sel:[0,1] op_sel_hi:[1,0] neg_lo:[0,1]
	v_pk_mov_b32 v[2:3], v[202:203], v[202:203] op_sel:[0,1]
	v_pk_add_f32 v[202:203], v[8:9], v[36:37]
	v_pk_add_f32 v[8:9], v[8:9], v[36:37] neg_lo:[0,1] neg_hi:[0,1]
	v_pk_add_f32 v[204:205], v[20:21], v[52:53]
	v_pk_add_f32 v[20:21], v[20:21], v[52:53] neg_lo:[0,1] neg_hi:[0,1]
	v_pk_add_f32 v[36:37], v[202:203], v[204:205]
	v_pk_add_f32 v[52:53], v[202:203], v[204:205] neg_lo:[0,1] neg_hi:[0,1]
	v_pk_add_f32 v[202:203], v[8:9], v[20:21] op_sel:[0,1] op_sel_hi:[1,0] neg_hi:[0,1]
	v_pk_add_f32 v[20:21], v[8:9], v[20:21] op_sel:[0,1] op_sel_hi:[1,0] neg_lo:[0,1]
	v_pk_mov_b32 v[8:9], v[202:203], v[202:203] op_sel:[0,1]
	v_pk_add_f32 v[202:203], v[4:5], v[40:41]
	v_pk_add_f32 v[4:5], v[4:5], v[40:41] neg_lo:[0,1] neg_hi:[0,1]
	v_pk_add_f32 v[204:205], v[24:25], v[56:57]
	v_pk_add_f32 v[24:25], v[24:25], v[56:57] neg_lo:[0,1] neg_hi:[0,1]
	v_pk_add_f32 v[40:41], v[202:203], v[204:205]
	v_pk_add_f32 v[56:57], v[202:203], v[204:205] neg_lo:[0,1] neg_hi:[0,1]
	v_pk_add_f32 v[202:203], v[4:5], v[24:25] op_sel:[0,1] op_sel_hi:[1,0] neg_hi:[0,1]
	v_pk_add_f32 v[24:25], v[4:5], v[24:25] op_sel:[0,1] op_sel_hi:[1,0] neg_lo:[0,1]
	v_pk_mov_b32 v[4:5], v[202:203], v[202:203] op_sel:[0,1]
	v_cos_f32_e32 v224, 0x3e000000
	v_sin_f32_e32 v225, 0xbe000000
	s_nop 0
	v_pk_mul_f32 v[206:207], v[224:225], v[224:225] op_sel:[1,1] op_sel_hi:[1,0]
	v_pk_fma_f32 v[226:227], v[224:225], v[224:225], v[206:207] op_sel_hi:[0,1,1] neg_lo:[0,0,1]
	v_pk_mul_f32 v[206:207], v[224:225], v[226:227] op_sel:[1,1] op_sel_hi:[1,0]
	v_pk_fma_f32 v[230:231], v[224:225], v[226:227], v[206:207] op_sel_hi:[0,1,1] neg_lo:[0,0,1]
	v_pk_add_f32 v[202:203], v[14:15], v[46:47]
	v_pk_add_f32 v[14:15], v[14:15], v[46:47] neg_lo:[0,1] neg_hi:[0,1]
	v_pk_add_f32 v[204:205], v[30:31], v[62:63]
	v_pk_add_f32 v[30:31], v[30:31], v[62:63] neg_lo:[0,1] neg_hi:[0,1]
	v_pk_add_f32 v[46:47], v[202:203], v[204:205]
	v_pk_add_f32 v[62:63], v[202:203], v[204:205] neg_lo:[0,1] neg_hi:[0,1]
	v_pk_add_f32 v[202:203], v[14:15], v[30:31] op_sel:[0,1] op_sel_hi:[1,0] neg_hi:[0,1]
	v_pk_add_f32 v[204:205], v[14:15], v[30:31] op_sel:[0,1] op_sel_hi:[1,0] neg_lo:[0,1]
	v_pk_mul_f32 v[14:15], v[224:225], v[202:203] op_sel:[1,1] op_sel_hi:[1,0]
	v_pk_fma_f32 v[14:15], v[224:225], v[202:203], v[14:15] op_sel_hi:[0,1,1] neg_lo:[0,0,1]
	v_pk_mul_f32 v[30:31], v[226:227], v[62:63] op_sel:[1,1] op_sel_hi:[1,0]
	v_pk_fma_f32 v[30:31], v[226:227], v[62:63], v[30:31] op_sel_hi:[0,1,1] neg_lo:[0,0,1]
	v_pk_mul_f32 v[62:63], v[230:231], v[204:205] op_sel:[1,1] op_sel_hi:[1,0]
	v_pk_fma_f32 v[62:63], v[230:231], v[204:205], v[62:63] op_sel_hi:[0,1,1] neg_lo:[0,0,1]
	v_pk_add_f32 v[202:203], v[10:11], v[42:43]
	v_pk_add_f32 v[10:11], v[10:11], v[42:43] neg_lo:[0,1] neg_hi:[0,1]
	v_pk_add_f32 v[204:205], v[26:27], v[58:59]
	v_pk_add_f32 v[26:27], v[26:27], v[58:59] neg_lo:[0,1] neg_hi:[0,1]
	v_pk_add_f32 v[42:43], v[202:203], v[204:205]
	v_pk_add_f32 v[58:59], v[202:203], v[204:205] neg_lo:[0,1] neg_hi:[0,1]
	v_pk_add_f32 v[202:203], v[10:11], v[26:27] op_sel:[0,1] op_sel_hi:[1,0] neg_hi:[0,1]
	v_pk_add_f32 v[204:205], v[10:11], v[26:27] op_sel:[0,1] op_sel_hi:[1,0] neg_lo:[0,1]
	v_pk_mul_f32 v[10:11], v[224:225], v[202:203] op_sel:[1,1] op_sel_hi:[1,0]
	v_pk_fma_f32 v[10:11], v[224:225], v[202:203], v[10:11] op_sel_hi:[0,1,1] neg_lo:[0,0,1]
	v_pk_mul_f32 v[26:27], v[226:227], v[58:59] op_sel:[1,1] op_sel_hi:[1,0]
	v_pk_fma_f32 v[26:27], v[226:227], v[58:59], v[26:27] op_sel_hi:[0,1,1] neg_lo:[0,0,1]
	v_pk_mul_f32 v[58:59], v[230:231], v[204:205] op_sel:[1,1] op_sel_hi:[1,0]
	v_pk_fma_f32 v[58:59], v[230:231], v[204:205], v[58:59] op_sel_hi:[0,1,1] neg_lo:[0,0,1]
	v_pk_add_f32 v[202:203], v[12:13], v[44:45]
	v_pk_add_f32 v[12:13], v[12:13], v[44:45] neg_lo:[0,1] neg_hi:[0,1]
	v_pk_add_f32 v[204:205], v[28:29], v[60:61]
	v_pk_add_f32 v[28:29], v[28:29], v[60:61] neg_lo:[0,1] neg_hi:[0,1]
	v_pk_add_f32 v[44:45], v[202:203], v[204:205]
	v_pk_add_f32 v[60:61], v[202:203], v[204:205] neg_lo:[0,1] neg_hi:[0,1]
	v_pk_add_f32 v[202:203], v[12:13], v[28:29] op_sel:[0,1] op_sel_hi:[1,0] neg_hi:[0,1]
	v_pk_add_f32 v[204:205], v[12:13], v[28:29] op_sel:[0,1] op_sel_hi:[1,0] neg_lo:[0,1]
	v_pk_mul_f32 v[12:13], v[224:225], v[202:203] op_sel:[1,1] op_sel_hi:[1,0]
	v_pk_fma_f32 v[12:13], v[224:225], v[202:203], v[12:13] op_sel_hi:[0,1,1] neg_lo:[0,0,1]
	v_pk_mul_f32 v[28:29], v[226:227], v[60:61] op_sel:[1,1] op_sel_hi:[1,0]
	v_pk_fma_f32 v[28:29], v[226:227], v[60:61], v[28:29] op_sel_hi:[0,1,1] neg_lo:[0,0,1]
	v_pk_mul_f32 v[60:61], v[230:231], v[204:205] op_sel:[1,1] op_sel_hi:[1,0]
; DI void fft8192(f32x2* buf, const f32x2* __restrict__ tw) {
;     ...
; #pragma unroll
;     for (int e = 0; e < 16; ++e) {
;       const int pi = SW(tid + 256 * e);
;       buf[pi] = mkf2(a[e].x + b[e].x, a[e].y + b[e].y);
;       buf[pi + 4096] = mkf2(a[e].x - b[e].x, a[e].y - b[e].y);
;     }
;     __syncthreads();
;   }
; DI void hyena_unit(KP p, int l, int c, char* smem) {
;     ...
;       const u16* g0 = Zhy + (size_t)(b0 * 1536 + gcol) * 4096;
;       const u16* g1 = Zhy + (size_t)(b1 * 1536 + gcol) * 4096;
; #pragma unroll 4
;       for (int jj = 0; jj < 16; ++jj) {
;         const int t = tid + 256 * jj;
;         const f32x2 r = buf[SW(t)];
;         const float y0 = r.x * (1.f / 8192.f), y1 = -r.y * (1.f / 8192.f);
;         const float x0 = sconv3(g0, t, 4096, gw0, gw1, gw2, gb), x1 = sconv3(g1, t, 4096, gw0, gw1, gw2, gb);
;         if (o == 0) { r0[t] = f2bf(x0 * y0); r1[t] = f2bf(x1 * y1); }
;         else { y0p[t] = f2bf(x0 * y0); y1p[t] = f2bf(x1 * y1); }
;       }
	v_pk_fma_f32 v[60:61], v[230:231], v[204:205], v[60:61] op_sel_hi:[0,1,1] neg_lo:[0,0,1]
	v_pk_add_f32 v[202:203], v[16:17], v[48:49]
	v_pk_add_f32 v[16:17], v[16:17], v[48:49] neg_lo:[0,1] neg_hi:[0,1]
	v_pk_add_f32 v[204:205], v[32:33], v[64:65]
	v_pk_add_f32 v[32:33], v[32:33], v[64:65] neg_lo:[0,1] neg_hi:[0,1]
	v_pk_add_f32 v[48:49], v[202:203], v[204:205]
	v_pk_add_f32 v[64:65], v[202:203], v[204:205] neg_lo:[0,1] neg_hi:[0,1]
	v_pk_add_f32 v[202:203], v[16:17], v[32:33] op_sel:[0,1] op_sel_hi:[1,0] neg_hi:[0,1]
	v_pk_add_f32 v[204:205], v[16:17], v[32:33] op_sel:[0,1] op_sel_hi:[1,0] neg_lo:[0,1]
	v_pk_mul_f32 v[16:17], v[224:225], v[202:203] op_sel:[1,1] op_sel_hi:[1,0]
	v_pk_fma_f32 v[16:17], v[224:225], v[202:203], v[16:17] op_sel_hi:[0,1,1] neg_lo:[0,0,1]
	v_pk_mul_f32 v[32:33], v[226:227], v[64:65] op_sel:[1,1] op_sel_hi:[1,0]
	v_pk_fma_f32 v[32:33], v[226:227], v[64:65], v[32:33] op_sel_hi:[0,1,1] neg_lo:[0,0,1]
	v_pk_mul_f32 v[64:65], v[230:231], v[204:205] op_sel:[1,1] op_sel_hi:[1,0]
	v_pk_fma_f32 v[64:65], v[230:231], v[204:205], v[64:65] op_sel_hi:[0,1,1] neg_lo:[0,0,1]
	v_pk_add_f32 v[202:203], v[38:39], v[46:47]
	v_pk_add_f32 v[204:205], v[34:35], v[42:43]
	v_pk_add_f32 v[206:207], v[36:37], v[44:45]
	v_pk_add_f32 v[208:209], v[40:41], v[48:49]
	v_pk_add_f32 v[210:211], v[6:7], v[14:15]
	v_pk_add_f32 v[212:213], v[2:3], v[10:11]
	v_pk_add_f32 v[220:221], v[8:9], v[12:13]
	v_pk_add_f32 v[224:225], v[4:5], v[16:17]
	v_pk_add_f32 v[226:227], v[54:55], v[30:31]
	v_pk_add_f32 v[230:231], v[50:51], v[26:27]
	v_pk_add_f32 v[232:233], v[52:53], v[28:29]
	v_pk_add_f32 v[236:237], v[56:57], v[32:33]
	v_pk_add_f32 v[238:239], v[22:23], v[62:63]
	v_pk_add_f32 v[240:241], v[18:19], v[58:59]
	v_pk_add_f32 v[244:245], v[20:21], v[60:61]
	v_pk_add_f32 v[246:247], v[24:25], v[64:65]
	ds_write_b64 v154, v[202:203] offset:0
	ds_write_b64 v154, v[204:205] offset:2048
	ds_write_b64 v154, v[206:207] offset:4096
	ds_write_b64 v154, v[208:209] offset:6144
	ds_write_b64 v154, v[210:211] offset:8192
	ds_write_b64 v154, v[212:213] offset:10240
	ds_write_b64 v154, v[220:221] offset:12288
	ds_write_b64 v154, v[224:225] offset:14336
	ds_write_b64 v154, v[226:227] offset:16384
	ds_write_b64 v154, v[230:231] offset:18432
	ds_write_b64 v154, v[232:233] offset:20480
	ds_write_b64 v154, v[236:237] offset:22528
	ds_write_b64 v154, v[238:239] offset:24576
	ds_write_b64 v154, v[240:241] offset:26624
	ds_write_b64 v154, v[244:245] offset:28672
	ds_write_b64 v154, v[246:247] offset:30720
	s_lshl_b32 s2, s83, 11
	s_lshl_b32 s4, s78, 10
	s_sub_i32 s2, s28, s2
	s_sub_i32 s4, s6, s4
	s_ashr_i32 s3, s2, 31
	s_ashr_i32 s5, s4, 31
	s_lshl_b64 s[2:3], s[2:3], 13
	s_lshl_b64 s[4:5], s[4:5], 13
	s_add_u32 s8, s55, s2
	s_addc_u32 s9, s81, s3
	s_add_u32 s10, s55, s4
	s_addc_u32 s11, s81, s5
	s_add_i32 s2, s82, s21
	s_ashr_i32 s3, s2, 31
	s_lshl_b64 s[2:3], s[2:3], 13
	s_add_u32 s6, s80, s2
	s_addc_u32 s7, s76, s3
	s_add_i32 s4, s29, s21
	s_ashr_i32 s5, s4, 31
	s_lshl_b64 s[4:5], s[4:5], 13
	s_add_u32 s12, s80, s4
	s_addc_u32 s13, s76, s5
	s_and_b64 s[4:5], s[96:97], exec
	s_cselect_b32 s5, s25, s9
	s_cselect_b32 s4, s24, s8
	s_cselect_b32 s9, s27, s11
	s_cselect_b32 s8, s26, s10
	v_lshl_add_u64 v[4:5], s[4:5], 0, v[68:69]
	s_add_i32 s4, s77, s82
	s_ashr_i32 s5, s4, 31
	s_lshl_b64 s[4:5], s[4:5], 13
	v_lshl_add_u64 v[2:3], s[8:9], 0, v[68:69]
	v_lshl_add_u64 v[6:7], v[70:71], 0, s[4:5]
	v_lshl_add_u64 v[8:9], v[70:71], 0, s[2:3]
	s_mov_b64 s[22:23], 0
	v_mov_b32_e32 v198, v66
	s_waitcnt lgkmcnt(0)
	s_barrier
	v_lshlrev_b32_e32 v201, 1, v66
	v_xor_b32_e32 v203, v66, v155
	v_add_u32_e32 v202, 0x1000, v201
	v_lshlrev_b32_e32 v203, 3, v203
	s_mov_b64 s[8:9], 0x1000
	v_lshl_add_u64 v[204:205], v[4:5], 0, s[8:9]
	v_lshl_add_u64 v[206:207], v[2:3], 0, s[8:9]
	v_cmp_eq_u32_e64 s[8:9], 0, v66
	v_cmp_eq_u32_e32 vcc, 0xff, v66
	s_mov_b64 s[10:11], vcc
	ds_read_b64 v[224:225], v203
	ds_read_b64 v[226:227], v203 offset:2048
	ds_read_b64 v[230:231], v203 offset:4096
	ds_read_b64 v[232:233], v203 offset:6144
	ds_read_b64 v[236:237], v203 offset:8192
	ds_read_b64 v[238:239], v203 offset:10240
	ds_read_b64 v[240:241], v203 offset:12288
	ds_read_b64 v[244:245], v203 offset:14336
	global_load_ushort v10, v201, s[6:7] offset:-2
	global_load_ushort v11, v201, s[6:7] offset:0
	global_load_ushort v12, v201, s[6:7] offset:2
	global_load_ushort v13, v201, s[12:13] offset:-2
	global_load_ushort v14, v201, s[12:13] offset:0
	global_load_ushort v15, v201, s[12:13] offset:2
	global_load_ushort v16, v201, s[6:7] offset:510
	global_load_ushort v17, v201, s[6:7] offset:512
	global_load_ushort v18, v201, s[6:7] offset:514
	global_load_ushort v19, v201, s[12:13] offset:510
	global_load_ushort v20, v201, s[12:13] offset:512
	global_load_ushort v21, v201, s[12:13] offset:514
	global_load_ushort v22, v201, s[6:7] offset:1022
	global_load_ushort v23, v201, s[6:7] offset:1024
	global_load_ushort v24, v201, s[6:7] offset:1026
	global_load_ushort v25, v201, s[12:13] offset:1022
	global_load_ushort v26, v201, s[12:13] offset:1024
	global_load_ushort v27, v201, s[12:13] offset:1026
	global_load_ushort v28, v201, s[6:7] offset:1534
	global_load_ushort v29, v201, s[6:7] offset:1536
	global_load_ushort v30, v201, s[6:7] offset:1538
	global_load_ushort v31, v201, s[12:13] offset:1534
	global_load_ushort v32, v201, s[12:13] offset:1536
	global_load_ushort v34, v201, s[12:13] offset:1538
	global_load_ushort v35, v201, s[6:7] offset:2046
	global_load_ushort v36, v201, s[6:7] offset:2048
	global_load_ushort v37, v201, s[6:7] offset:2050
	global_load_ushort v38, v201, s[12:13] offset:2046
	global_load_ushort v39, v201, s[12:13] offset:2048
	global_load_ushort v40, v201, s[12:13] offset:2050
	global_load_ushort v41, v201, s[6:7] offset:2558
	global_load_ushort v42, v201, s[6:7] offset:2560
	global_load_ushort v43, v201, s[6:7] offset:2562
	global_load_ushort v44, v201, s[12:13] offset:2558
	global_load_ushort v45, v201, s[12:13] offset:2560
	global_load_ushort v46, v201, s[12:13] offset:2562
	global_load_ushort v47, v201, s[6:7] offset:3070
	global_load_ushort v48, v201, s[6:7] offset:3072
	global_load_ushort v49, v201, s[6:7] offset:3074
	global_load_ushort v50, v201, s[12:13] offset:3070
	global_load_ushort v51, v201, s[12:13] offset:3072
	global_load_ushort v52, v201, s[12:13] offset:3074
	global_load_ushort v53, v201, s[6:7] offset:3582
	global_load_ushort v54, v201, s[6:7] offset:3584
	global_load_ushort v55, v201, s[6:7] offset:3586
	global_load_ushort v56, v201, s[12:13] offset:3582
	global_load_ushort v57, v201, s[12:13] offset:3584
	global_load_ushort v58, v201, s[12:13] offset:3586
	s_waitcnt vmcnt(42)
; DI float bf2f(u16 v) { return __uint_as_float(((unsigned)v) << 16); }
; DI float sconv3(const u16* row, int t, int n, float w0, float w1, float w2, float bias) {
;   float xm = (t > 0) ? bf2f(row[t - 1]) : 0.f, x0 = bf2f(row[t]), xp = (t + 1 < n) ? bf2f(row[t + 1]) : 0.f;
;   return w0 * xm + w1 * x0 + w2 * xp + bias;
; DI void hyena_unit(KP p, int l, int c, char* smem) {
;     ...
; #pragma unroll 4
;       for (int jj = 0; jj < 16; ++jj) {
;         const int t = tid + 256 * jj;
;         const f32x2 r = buf[SW(t)];
;         const float y0 = r.x * (1.f / 8192.f), y1 = -r.y * (1.f / 8192.f);
;         const float x0 = sconv3(g0, t, 4096, gw0, gw1, gw2, gb), x1 = sconv3(g1, t, 4096, gw0, gw1, gw2, gb);
;         if (o == 0) { r0[t] = f2bf(x0 * y0); r1[t] = f2bf(x1 * y1); }
;         else { y0p[t] = f2bf(x0 * y0); y1p[t] = f2bf(x1 * y1); }
;       }
	s_waitcnt lgkmcnt(0)
	v_cndmask_b32_e64 v10, v10, 0, s[8:9]
	v_cndmask_b32_e64 v13, v13, 0, s[8:9]
	v_lshlrev_b32_e32 v10, 16, v10
	v_lshlrev_b32_e32 v11, 16, v11
	v_lshlrev_b32_e32 v12, 16, v12
	v_lshlrev_b32_e32 v13, 16, v13
	v_lshlrev_b32_e32 v14, 16, v14
	v_lshlrev_b32_e32 v15, 16, v15
	v_mul_f32_e32 v11, v196, v11
	v_mul_f32_e32 v14, v196, v14
	v_fmac_f32_e32 v11, v74, v10
	v_fmac_f32_e32 v14, v74, v13
	v_fmac_f32_e32 v11, v75, v12
	v_fmac_f32_e32 v14, v75, v15
	v_mul_f32_e32 v10, 0x39000000, v224
	v_mul_f32_e32 v13, 0xb9000000, v225
	v_add_f32_e32 v11, v195, v11
	v_add_f32_e32 v14, v195, v14
	v_mul_f32_e32 v10, v10, v11
	v_mul_f32_e32 v13, v13, v14
	v_cvt_pk_bf16_f32 v10, v10, v10
	v_cvt_pk_bf16_f32 v13, v13, v13
	global_store_short v[4:5], v10, off
	global_store_short v[2:3], v13, off
	s_waitcnt vmcnt(38)
	v_lshlrev_b32_e32 v16, 16, v16
	v_lshlrev_b32_e32 v17, 16, v17
	v_lshlrev_b32_e32 v18, 16, v18
	v_lshlrev_b32_e32 v19, 16, v19
	v_lshlrev_b32_e32 v20, 16, v20
	v_lshlrev_b32_e32 v21, 16, v21
	v_mul_f32_e32 v17, v196, v17
	v_mul_f32_e32 v20, v196, v20
	v_fmac_f32_e32 v17, v74, v16
	v_fmac_f32_e32 v20, v74, v19
	v_fmac_f32_e32 v17, v75, v18
	v_fmac_f32_e32 v20, v75, v21
	v_mul_f32_e32 v16, 0x39000000, v226
	v_mul_f32_e32 v19, 0xb9000000, v227
	v_add_f32_e32 v17, v195, v17
	v_add_f32_e32 v20, v195, v20
	v_mul_f32_e32 v16, v16, v17
	v_mul_f32_e32 v19, v19, v20
	v_cvt_pk_bf16_f32 v16, v16, v16
	v_cvt_pk_bf16_f32 v19, v19, v19
	global_store_short v[4:5], v16, off offset:512
	global_store_short v[2:3], v19, off offset:512
	s_waitcnt vmcnt(34)
	v_lshlrev_b32_e32 v22, 16, v22
	v_lshlrev_b32_e32 v23, 16, v23
	v_lshlrev_b32_e32 v24, 16, v24
	v_lshlrev_b32_e32 v25, 16, v25
	v_lshlrev_b32_e32 v26, 16, v26
	v_lshlrev_b32_e32 v27, 16, v27
	v_mul_f32_e32 v23, v196, v23
	v_mul_f32_e32 v26, v196, v26
	v_fmac_f32_e32 v23, v74, v22
	v_fmac_f32_e32 v26, v74, v25
	v_fmac_f32_e32 v23, v75, v24
	v_fmac_f32_e32 v26, v75, v27
	v_mul_f32_e32 v22, 0x39000000, v230
	v_mul_f32_e32 v25, 0xb9000000, v231
	v_add_f32_e32 v23, v195, v23
	v_add_f32_e32 v26, v195, v26
	v_mul_f32_e32 v22, v22, v23
	v_mul_f32_e32 v25, v25, v26
	v_cvt_pk_bf16_f32 v22, v22, v22
	v_cvt_pk_bf16_f32 v25, v25, v25
	global_store_short v[4:5], v22, off offset:1024
	global_store_short v[2:3], v25, off offset:1024
	s_waitcnt vmcnt(30)
	v_lshlrev_b32_e32 v28, 16, v28
	v_lshlrev_b32_e32 v29, 16, v29
	v_lshlrev_b32_e32 v30, 16, v30
	v_lshlrev_b32_e32 v31, 16, v31
	v_lshlrev_b32_e32 v32, 16, v32
	v_lshlrev_b32_e32 v34, 16, v34
	v_mul_f32_e32 v29, v196, v29
	v_mul_f32_e32 v32, v196, v32
	v_fmac_f32_e32 v29, v74, v28
	v_fmac_f32_e32 v32, v74, v31
	v_fmac_f32_e32 v29, v75, v30
	v_fmac_f32_e32 v32, v75, v34
	v_mul_f32_e32 v28, 0x39000000, v232
	v_mul_f32_e32 v31, 0xb9000000, v233
	v_add_f32_e32 v29, v195, v29
	v_add_f32_e32 v32, v195, v32
	v_mul_f32_e32 v28, v28, v29
	v_mul_f32_e32 v31, v31, v32
	v_cvt_pk_bf16_f32 v28, v28, v28
	v_cvt_pk_bf16_f32 v31, v31, v31
	global_store_short v[4:5], v28, off offset:1536
	global_store_short v[2:3], v31, off offset:1536
	s_waitcnt vmcnt(26)
	v_lshlrev_b32_e32 v35, 16, v35
	v_lshlrev_b32_e32 v36, 16, v36
	v_lshlrev_b32_e32 v37, 16, v37
	v_lshlrev_b32_e32 v38, 16, v38
	v_lshlrev_b32_e32 v39, 16, v39
	v_lshlrev_b32_e32 v40, 16, v40
	v_mul_f32_e32 v36, v196, v36
	v_mul_f32_e32 v39, v196, v39
	v_fmac_f32_e32 v36, v74, v35
	v_fmac_f32_e32 v39, v74, v38
	v_fmac_f32_e32 v36, v75, v37
	v_fmac_f32_e32 v39, v75, v40
	v_mul_f32_e32 v35, 0x39000000, v236
	v_mul_f32_e32 v38, 0xb9000000, v237
	v_add_f32_e32 v36, v195, v36
	v_add_f32_e32 v39, v195, v39
	v_mul_f32_e32 v35, v35, v36
	v_mul_f32_e32 v38, v38, v39
	v_cvt_pk_bf16_f32 v35, v35, v35
	v_cvt_pk_bf16_f32 v38, v38, v38
	global_store_short v[4:5], v35, off offset:2048
	global_store_short v[2:3], v38, off offset:2048
	s_waitcnt vmcnt(22)
	v_lshlrev_b32_e32 v41, 16, v41
	v_lshlrev_b32_e32 v42, 16, v42
	v_lshlrev_b32_e32 v43, 16, v43
	v_lshlrev_b32_e32 v44, 16, v44
	v_lshlrev_b32_e32 v45, 16, v45
	v_lshlrev_b32_e32 v46, 16, v46
	v_mul_f32_e32 v42, v196, v42
	v_mul_f32_e32 v45, v196, v45
	v_fmac_f32_e32 v42, v74, v41
	v_fmac_f32_e32 v45, v74, v44
	v_fmac_f32_e32 v42, v75, v43
	v_fmac_f32_e32 v45, v75, v46
	v_mul_f32_e32 v41, 0x39000000, v238
	v_mul_f32_e32 v44, 0xb9000000, v239
	v_add_f32_e32 v42, v195, v42
	v_add_f32_e32 v45, v195, v45
	v_mul_f32_e32 v41, v41, v42
	v_mul_f32_e32 v44, v44, v45
	v_cvt_pk_bf16_f32 v41, v41, v41
	v_cvt_pk_bf16_f32 v44, v44, v44
	global_store_short v[4:5], v41, off offset:2560
	global_store_short v[2:3], v44, off offset:2560
	s_waitcnt vmcnt(18)
	v_lshlrev_b32_e32 v47, 16, v47
	v_lshlrev_b32_e32 v48, 16, v48
	v_lshlrev_b32_e32 v49, 16, v49
	v_lshlrev_b32_e32 v50, 16, v50
	v_lshlrev_b32_e32 v51, 16, v51
	v_lshlrev_b32_e32 v52, 16, v52
	v_mul_f32_e32 v48, v196, v48
	v_mul_f32_e32 v51, v196, v51
	v_fmac_f32_e32 v48, v74, v47
	v_fmac_f32_e32 v51, v74, v50
	v_fmac_f32_e32 v48, v75, v49
	v_fmac_f32_e32 v51, v75, v52
	v_mul_f32_e32 v47, 0x39000000, v240
	v_mul_f32_e32 v50, 0xb9000000, v241
	v_add_f32_e32 v48, v195, v48
	v_add_f32_e32 v51, v195, v51
	v_mul_f32_e32 v47, v47, v48
	v_mul_f32_e32 v50, v50, v51
	v_cvt_pk_bf16_f32 v47, v47, v47
	v_cvt_pk_bf16_f32 v50, v50, v50
	global_store_short v[4:5], v47, off offset:3072
	global_store_short v[2:3], v50, off offset:3072
	s_waitcnt vmcnt(14)
; DI float bf2f(u16 v) { return __uint_as_float(((unsigned)v) << 16); }
; DI float sconv3(const u16* row, int t, int n, float w0, float w1, float w2, float bias) {
;   float xm = (t > 0) ? bf2f(row[t - 1]) : 0.f, x0 = bf2f(row[t]), xp = (t + 1 < n) ? bf2f(row[t + 1]) : 0.f;
;   return w0 * xm + w1 * x0 + w2 * xp + bias;
; DI void hyena_unit(KP p, int l, int c, char* smem) {
;     ...
; #pragma unroll 4
;       for (int jj = 0; jj < 16; ++jj) {
;         const int t = tid + 256 * jj;
;         const f32x2 r = buf[SW(t)];
;         const float y0 = r.x * (1.f / 8192.f), y1 = -r.y * (1.f / 8192.f);
;         const float x0 = sconv3(g0, t, 4096, gw0, gw1, gw2, gb), x1 = sconv3(g1, t, 4096, gw0, gw1, gw2, gb);
;         if (o == 0) { r0[t] = f2bf(x0 * y0); r1[t] = f2bf(x1 * y1); }
;         else { y0p[t] = f2bf(x0 * y0); y1p[t] = f2bf(x1 * y1); }
;       }
	v_lshlrev_b32_e32 v53, 16, v53
	v_lshlrev_b32_e32 v54, 16, v54
	v_lshlrev_b32_e32 v55, 16, v55
	v_lshlrev_b32_e32 v56, 16, v56
	v_lshlrev_b32_e32 v57, 16, v57
	v_lshlrev_b32_e32 v58, 16, v58
	v_mul_f32_e32 v54, v196, v54
	v_mul_f32_e32 v57, v196, v57
	v_fmac_f32_e32 v54, v74, v53
	v_fmac_f32_e32 v57, v74, v56
	v_fmac_f32_e32 v54, v75, v55
	v_fmac_f32_e32 v57, v75, v58
	v_mul_f32_e32 v53, 0x39000000, v244
	v_mul_f32_e32 v56, 0xb9000000, v245
	v_add_f32_e32 v54, v195, v54
	v_add_f32_e32 v57, v195, v57
	v_mul_f32_e32 v53, v53, v54
	v_mul_f32_e32 v56, v56, v57
	v_cvt_pk_bf16_f32 v53, v53, v53
	v_cvt_pk_bf16_f32 v56, v56, v56
	global_store_short v[4:5], v53, off offset:3584
	global_store_short v[2:3], v56, off offset:3584
	ds_read_b64 v[224:225], v203 offset:16384
	ds_read_b64 v[226:227], v203 offset:18432
	ds_read_b64 v[230:231], v203 offset:20480
	ds_read_b64 v[232:233], v203 offset:22528
	ds_read_b64 v[236:237], v203 offset:24576
	ds_read_b64 v[238:239], v203 offset:26624
	ds_read_b64 v[240:241], v203 offset:28672
	ds_read_b64 v[244:245], v203 offset:30720
	global_load_ushort v10, v202, s[6:7] offset:-2
	global_load_ushort v11, v202, s[6:7] offset:0
	global_load_ushort v12, v202, s[6:7] offset:2
	global_load_ushort v13, v202, s[12:13] offset:-2
	global_load_ushort v14, v202, s[12:13] offset:0
	global_load_ushort v15, v202, s[12:13] offset:2
	global_load_ushort v16, v202, s[6:7] offset:510
	global_load_ushort v17, v202, s[6:7] offset:512
	global_load_ushort v18, v202, s[6:7] offset:514
	global_load_ushort v19, v202, s[12:13] offset:510
	global_load_ushort v20, v202, s[12:13] offset:512
	global_load_ushort v21, v202, s[12:13] offset:514
	global_load_ushort v22, v202, s[6:7] offset:1022
	global_load_ushort v23, v202, s[6:7] offset:1024
	global_load_ushort v24, v202, s[6:7] offset:1026
	global_load_ushort v25, v202, s[12:13] offset:1022
	global_load_ushort v26, v202, s[12:13] offset:1024
	global_load_ushort v27, v202, s[12:13] offset:1026
	global_load_ushort v28, v202, s[6:7] offset:1534
	global_load_ushort v29, v202, s[6:7] offset:1536
	global_load_ushort v30, v202, s[6:7] offset:1538
	global_load_ushort v31, v202, s[12:13] offset:1534
	global_load_ushort v32, v202, s[12:13] offset:1536
	global_load_ushort v34, v202, s[12:13] offset:1538
	global_load_ushort v35, v202, s[6:7] offset:2046
	global_load_ushort v36, v202, s[6:7] offset:2048
	global_load_ushort v37, v202, s[6:7] offset:2050
	global_load_ushort v38, v202, s[12:13] offset:2046
	global_load_ushort v39, v202, s[12:13] offset:2048
	global_load_ushort v40, v202, s[12:13] offset:2050
	global_load_ushort v41, v202, s[6:7] offset:2558
	global_load_ushort v42, v202, s[6:7] offset:2560
	global_load_ushort v43, v202, s[6:7] offset:2562
	global_load_ushort v44, v202, s[12:13] offset:2558
	global_load_ushort v45, v202, s[12:13] offset:2560
	global_load_ushort v46, v202, s[12:13] offset:2562
	global_load_ushort v47, v202, s[6:7] offset:3070
	global_load_ushort v48, v202, s[6:7] offset:3072
	global_load_ushort v49, v202, s[6:7] offset:3074
	global_load_ushort v50, v202, s[12:13] offset:3070
	global_load_ushort v51, v202, s[12:13] offset:3072
	global_load_ushort v52, v202, s[12:13] offset:3074
	global_load_ushort v53, v202, s[6:7] offset:3582
	global_load_ushort v54, v202, s[6:7] offset:3584
	global_load_ushort v55, v202, s[6:7] offset:3586
	global_load_ushort v56, v202, s[12:13] offset:3582
	global_load_ushort v57, v202, s[12:13] offset:3584
	global_load_ushort v58, v202, s[12:13] offset:3586
	s_waitcnt vmcnt(42)
	s_waitcnt lgkmcnt(0)
	v_lshlrev_b32_e32 v10, 16, v10
	v_lshlrev_b32_e32 v11, 16, v11
	v_lshlrev_b32_e32 v12, 16, v12
	v_lshlrev_b32_e32 v13, 16, v13
	v_lshlrev_b32_e32 v14, 16, v14
	v_lshlrev_b32_e32 v15, 16, v15
	v_mul_f32_e32 v11, v196, v11
	v_mul_f32_e32 v14, v196, v14
	v_fmac_f32_e32 v11, v74, v10
	v_fmac_f32_e32 v14, v74, v13
	v_fmac_f32_e32 v11, v75, v12
	v_fmac_f32_e32 v14, v75, v15
	v_mul_f32_e32 v10, 0x39000000, v224
	v_mul_f32_e32 v13, 0xb9000000, v225
	v_add_f32_e32 v11, v195, v11
	v_add_f32_e32 v14, v195, v14
	v_mul_f32_e32 v10, v10, v11
	v_mul_f32_e32 v13, v13, v14
	v_cvt_pk_bf16_f32 v10, v10, v10
	v_cvt_pk_bf16_f32 v13, v13, v13
	global_store_short v[204:205], v10, off
	global_store_short v[206:207], v13, off
	s_waitcnt vmcnt(38)
	v_lshlrev_b32_e32 v16, 16, v16
	v_lshlrev_b32_e32 v17, 16, v17
	v_lshlrev_b32_e32 v18, 16, v18
	v_lshlrev_b32_e32 v19, 16, v19
	v_lshlrev_b32_e32 v20, 16, v20
	v_lshlrev_b32_e32 v21, 16, v21
	v_mul_f32_e32 v17, v196, v17
	v_mul_f32_e32 v20, v196, v20
	v_fmac_f32_e32 v17, v74, v16
	v_fmac_f32_e32 v20, v74, v19
	v_fmac_f32_e32 v17, v75, v18
	v_fmac_f32_e32 v20, v75, v21
	v_mul_f32_e32 v16, 0x39000000, v226
	v_mul_f32_e32 v19, 0xb9000000, v227
	v_add_f32_e32 v17, v195, v17
	v_add_f32_e32 v20, v195, v20
	v_mul_f32_e32 v16, v16, v17
	v_mul_f32_e32 v19, v19, v20
	v_cvt_pk_bf16_f32 v16, v16, v16
	v_cvt_pk_bf16_f32 v19, v19, v19
	global_store_short v[204:205], v16, off offset:512
	global_store_short v[206:207], v19, off offset:512
	s_waitcnt vmcnt(34)
; DI float bf2f(u16 v) { return __uint_as_float(((unsigned)v) << 16); }
; DI float sconv3(const u16* row, int t, int n, float w0, float w1, float w2, float bias) {
;   float xm = (t > 0) ? bf2f(row[t - 1]) : 0.f, x0 = bf2f(row[t]), xp = (t + 1 < n) ? bf2f(row[t + 1]) : 0.f;
;   return w0 * xm + w1 * x0 + w2 * xp + bias;
; DI void hyena_unit(KP p, int l, int c, char* smem) {
;     ...
; #pragma unroll 4
;       for (int jj = 0; jj < 16; ++jj) {
;         const int t = tid + 256 * jj;
;         const f32x2 r = buf[SW(t)];
;         const float y0 = r.x * (1.f / 8192.f), y1 = -r.y * (1.f / 8192.f);
;         const float x0 = sconv3(g0, t, 4096, gw0, gw1, gw2, gb), x1 = sconv3(g1, t, 4096, gw0, gw1, gw2, gb);
;         if (o == 0) { r0[t] = f2bf(x0 * y0); r1[t] = f2bf(x1 * y1); }
;         else { y0p[t] = f2bf(x0 * y0); y1p[t] = f2bf(x1 * y1); }
;       }
	v_lshlrev_b32_e32 v22, 16, v22
	v_lshlrev_b32_e32 v23, 16, v23
	v_lshlrev_b32_e32 v24, 16, v24
	v_lshlrev_b32_e32 v25, 16, v25
	v_lshlrev_b32_e32 v26, 16, v26
	v_lshlrev_b32_e32 v27, 16, v27
	v_mul_f32_e32 v23, v196, v23
	v_mul_f32_e32 v26, v196, v26
	v_fmac_f32_e32 v23, v74, v22
	v_fmac_f32_e32 v26, v74, v25
	v_fmac_f32_e32 v23, v75, v24
	v_fmac_f32_e32 v26, v75, v27
	v_mul_f32_e32 v22, 0x39000000, v230
	v_mul_f32_e32 v25, 0xb9000000, v231
	v_add_f32_e32 v23, v195, v23
	v_add_f32_e32 v26, v195, v26
	v_mul_f32_e32 v22, v22, v23
	v_mul_f32_e32 v25, v25, v26
	v_cvt_pk_bf16_f32 v22, v22, v22
	v_cvt_pk_bf16_f32 v25, v25, v25
	global_store_short v[204:205], v22, off offset:1024
	global_store_short v[206:207], v25, off offset:1024
	s_waitcnt vmcnt(30)
	v_lshlrev_b32_e32 v28, 16, v28
	v_lshlrev_b32_e32 v29, 16, v29
	v_lshlrev_b32_e32 v30, 16, v30
	v_lshlrev_b32_e32 v31, 16, v31
	v_lshlrev_b32_e32 v32, 16, v32
	v_lshlrev_b32_e32 v34, 16, v34
	v_mul_f32_e32 v29, v196, v29
	v_mul_f32_e32 v32, v196, v32
	v_fmac_f32_e32 v29, v74, v28
	v_fmac_f32_e32 v32, v74, v31
	v_fmac_f32_e32 v29, v75, v30
	v_fmac_f32_e32 v32, v75, v34
	v_mul_f32_e32 v28, 0x39000000, v232
	v_mul_f32_e32 v31, 0xb9000000, v233
	v_add_f32_e32 v29, v195, v29
	v_add_f32_e32 v32, v195, v32
	v_mul_f32_e32 v28, v28, v29
	v_mul_f32_e32 v31, v31, v32
	v_cvt_pk_bf16_f32 v28, v28, v28
	v_cvt_pk_bf16_f32 v31, v31, v31
	global_store_short v[204:205], v28, off offset:1536
	global_store_short v[206:207], v31, off offset:1536
	s_waitcnt vmcnt(26)
	v_lshlrev_b32_e32 v35, 16, v35
	v_lshlrev_b32_e32 v36, 16, v36
	v_lshlrev_b32_e32 v37, 16, v37
	v_lshlrev_b32_e32 v38, 16, v38
	v_lshlrev_b32_e32 v39, 16, v39
	v_lshlrev_b32_e32 v40, 16, v40
	v_mul_f32_e32 v36, v196, v36
	v_mul_f32_e32 v39, v196, v39
	v_fmac_f32_e32 v36, v74, v35
	v_fmac_f32_e32 v39, v74, v38
	v_fmac_f32_e32 v36, v75, v37
	v_fmac_f32_e32 v39, v75, v40
	v_mul_f32_e32 v35, 0x39000000, v236
	v_mul_f32_e32 v38, 0xb9000000, v237
	v_add_f32_e32 v36, v195, v36
	v_add_f32_e32 v39, v195, v39
	v_mul_f32_e32 v35, v35, v36
	v_mul_f32_e32 v38, v38, v39
	v_cvt_pk_bf16_f32 v35, v35, v35
	v_cvt_pk_bf16_f32 v38, v38, v38
	global_store_short v[204:205], v35, off offset:2048
	global_store_short v[206:207], v38, off offset:2048
	s_waitcnt vmcnt(22)
	v_lshlrev_b32_e32 v41, 16, v41
	v_lshlrev_b32_e32 v42, 16, v42
	v_lshlrev_b32_e32 v43, 16, v43
	v_lshlrev_b32_e32 v44, 16, v44
	v_lshlrev_b32_e32 v45, 16, v45
	v_lshlrev_b32_e32 v46, 16, v46
	v_mul_f32_e32 v42, v196, v42
	v_mul_f32_e32 v45, v196, v45
	v_fmac_f32_e32 v42, v74, v41
	v_fmac_f32_e32 v45, v74, v44
	v_fmac_f32_e32 v42, v75, v43
	v_fmac_f32_e32 v45, v75, v46
	v_mul_f32_e32 v41, 0x39000000, v238
	v_mul_f32_e32 v44, 0xb9000000, v239
	v_add_f32_e32 v42, v195, v42
	v_add_f32_e32 v45, v195, v45
	v_mul_f32_e32 v41, v41, v42
	v_mul_f32_e32 v44, v44, v45
	v_cvt_pk_bf16_f32 v41, v41, v41
	v_cvt_pk_bf16_f32 v44, v44, v44
	global_store_short v[204:205], v41, off offset:2560
	global_store_short v[206:207], v44, off offset:2560
	s_waitcnt vmcnt(18)
	v_lshlrev_b32_e32 v47, 16, v47
	v_lshlrev_b32_e32 v48, 16, v48
	v_lshlrev_b32_e32 v49, 16, v49
	v_lshlrev_b32_e32 v50, 16, v50
	v_lshlrev_b32_e32 v51, 16, v51
	v_lshlrev_b32_e32 v52, 16, v52
	v_mul_f32_e32 v48, v196, v48
	v_mul_f32_e32 v51, v196, v51
	v_fmac_f32_e32 v48, v74, v47
	v_fmac_f32_e32 v51, v74, v50
	v_fmac_f32_e32 v48, v75, v49
	v_fmac_f32_e32 v51, v75, v52
	v_mul_f32_e32 v47, 0x39000000, v240
	v_mul_f32_e32 v50, 0xb9000000, v241
	v_add_f32_e32 v48, v195, v48
	v_add_f32_e32 v51, v195, v51
	v_mul_f32_e32 v47, v47, v48
	v_mul_f32_e32 v50, v50, v51
	v_cvt_pk_bf16_f32 v47, v47, v47
	v_cvt_pk_bf16_f32 v50, v50, v50
	global_store_short v[204:205], v47, off offset:3072
	global_store_short v[206:207], v50, off offset:3072
	s_waitcnt vmcnt(14)
	v_cndmask_b32_e64 v55, v55, 0, s[10:11]
	v_cndmask_b32_e64 v58, v58, 0, s[10:11]
	v_lshlrev_b32_e32 v53, 16, v53
	v_lshlrev_b32_e32 v54, 16, v54
	v_lshlrev_b32_e32 v55, 16, v55
	v_lshlrev_b32_e32 v56, 16, v56
	v_lshlrev_b32_e32 v57, 16, v57
	v_lshlrev_b32_e32 v58, 16, v58
	v_mul_f32_e32 v54, v196, v54
	v_mul_f32_e32 v57, v196, v57
	v_fmac_f32_e32 v54, v74, v53
	v_fmac_f32_e32 v57, v74, v56
	v_fmac_f32_e32 v54, v75, v55
	v_fmac_f32_e32 v57, v75, v58
	v_mul_f32_e32 v53, 0x39000000, v244
	v_mul_f32_e32 v56, 0xb9000000, v245
	v_add_f32_e32 v54, v195, v54
	v_add_f32_e32 v57, v195, v57
	v_mul_f32_e32 v53, v53, v54
	v_mul_f32_e32 v56, v56, v57
	v_cvt_pk_bf16_f32 v53, v53, v53
	v_cvt_pk_bf16_f32 v56, v56, v56
	global_store_short v[204:205], v53, off offset:3584
	global_store_short v[206:207], v56, off offset:3584
	s_branch .LBB0_936
